# speedup vs baseline: 1.0798x; 1.0050x over previous
; #define STAGE_A(P,br,kt) STAGE_G(P,c.A,c.lda,br,(long)(kt)*c.kstr)
; #define STAGE_B(P,br,kt) STAGE_G(P,c.Bt,c.K,br,(long)(kt)*BK)
; #define LDA(dst,b,h) for(int m=0;m<4;++m)for(int k=0;k<2;++k) \
;     dst[m][k]=*reinterpret_cast<const bf16x8*>((char*)SA(b,h)+lds_byte(wr*64+m*16+fr,k*32+fq*8))
; #define LDB(dst,b,h) for(int n=0;n<2;++n)for(int k=0;k<2;++k) \
;     dst[n][k]=*reinterpret_cast<const bf16x8*>((char*)SB(b,h)+lds_byte(wc*32+n*16+fr,k*32+fq*8))
; #define MMA(ai,bj,At,Bt_) do{__builtin_amdgcn_s_setprio(1); \
;     for(int m=0;m<4;++m)for(int n=0;n<2;++n)for(int k=0;k<2;++k) \
;       acc[ai][bj][m][n]=__builtin_amdgcn_mfma_f32_16x16x32_bf16(Bt_[n][k],At[m][k],acc[ai][bj][m][n],0,0,0); \
;     __builtin_amdgcn_s_setprio(0);}while(0)
; #define WAIT_V(n) asm volatile("s_waitcnt vmcnt(" #n ")":::"memory")
; #define WAIT_L(n) asm volatile("s_waitcnt lgkmcnt(" #n ")":::"memory")
; #define BAR __builtin_amdgcn_s_barrier()
; #define SCHED __builtin_amdgcn_sched_barrier(0)
; template <int EPI>
; __device__ __forceinline__ void gemm_run(const GD& c, const bool has_next, const GD& nx, const Ctx& e, bf16* shm, float* rs, float* rs_nxt, float* racc_) {
;     ...
;   for(int t=0;t<nt-2;t+=2){
;     LDB(B0,0,0); SCHED; LDA(At,0,0); STAGE_A(SA(1,1),brow+HALF,t+1);
;     WAIT_L(8); BAR; WAIT_L(0); MMA(0,0,At,B0); BAR; SCHED;
;     LDB(B1,0,1); STAGE_B(SB(0,0),bcol,t+2);
;     BAR; WAIT_L(0); MMA(0,1,At,B1); BAR;
;     LDA(At,0,1); STAGE_A(SA(0,0),brow,t+2);
;     BAR; WAIT_L(0); MMA(1,0,At,B0); BAR; SCHED;
;     STAGE_B(SB(0,1),bcol+HALF,t+2);
;     WAIT_V(6); BAR; MMA(1,1,At,B1); BAR;
.LBB0_267:
	ds_read_b128 v[158:161], v154
	ds_read_b128 v[166:169], v154 offset:1024
	ds_read_b128 v[170:173], v154 offset:2048
	ds_read_b128 v[190:193], v154 offset:3072
	v_add_u32_e32 v162, 0xc000, v141
	v_lshl_add_u64 v[174:175], s[4:5], 0, v[130:131]
	v_readfirstlane_b32 s3, v162
	v_add_u32_e32 v163, 0xe000, v141
	v_lshl_add_u64 v[156:157], v[174:175], 0, s[94:95]
	s_mov_b32 m0, s3
	v_lshl_add_u64 v[186:187], s[4:5], 0, v[132:133]
	v_readfirstlane_b32 s3, v163
	ds_read_b128 v[194:197], v145
	ds_read_b128 v[198:201], v145 offset:1024
	ds_read_b128 v[202:205], v144
	ds_read_b128 v[206:209], v144 offset:1024
	ds_read_b128 v[210:213], v143
	ds_read_b128 v[214:217], v143 offset:1024
	ds_read_b128 v[218:221], v142
	ds_read_b128 v[222:225], v142 offset:1024
	global_load_lds_dwordx4 v[156:157], off
	v_lshl_add_u64 v[156:157], v[186:187], 0, s[94:95]
	s_mov_b32 m0, s3
	s_nop 0
	global_load_lds_dwordx4 v[156:157], off
	s_waitcnt lgkmcnt(8)
	s_barrier
	s_waitcnt lgkmcnt(0)
	s_setprio 1
	v_mfma_f32_16x16x32_bf16 v[126:129], v[158:161], v[194:197], v[126:129]
	v_mfma_f32_16x16x32_bf16 v[122:125], v[170:173], v[194:197], v[122:125]
	v_mfma_f32_16x16x32_bf16 v[118:121], v[158:161], v[202:205], v[118:121]
	v_mfma_f32_16x16x32_bf16 v[114:117], v[170:173], v[202:205], v[114:117]
	v_mfma_f32_16x16x32_bf16 v[110:113], v[158:161], v[210:213], v[110:113]
	v_mfma_f32_16x16x32_bf16 v[106:109], v[170:173], v[210:213], v[106:109]
	v_mfma_f32_16x16x32_bf16 v[102:105], v[158:161], v[218:221], v[102:105]
	v_mfma_f32_16x16x32_bf16 v[98:101], v[170:173], v[218:221], v[98:101]
	v_mfma_f32_16x16x32_bf16 v[126:129], v[166:169], v[198:201], v[126:129]
	v_mfma_f32_16x16x32_bf16 v[122:125], v[190:193], v[198:201], v[122:125]
	v_mfma_f32_16x16x32_bf16 v[118:121], v[166:169], v[206:209], v[118:121]
	v_mfma_f32_16x16x32_bf16 v[114:117], v[190:193], v[206:209], v[114:117]
	v_mfma_f32_16x16x32_bf16 v[110:113], v[166:169], v[214:217], v[110:113]
	v_mfma_f32_16x16x32_bf16 v[106:109], v[190:193], v[214:217], v[106:109]
	v_mfma_f32_16x16x32_bf16 v[102:105], v[166:169], v[222:225], v[102:105]
	v_mfma_f32_16x16x32_bf16 v[98:101], v[190:193], v[222:225], v[98:101]
	s_setprio 0
	s_barrier
	v_add_u32_e32 v155, s33, v147
	v_lshl_add_u64 v[188:189], s[4:5], 0, v[136:137]
	v_readfirstlane_b32 s3, v155
	v_lshl_add_u64 v[156:157], v[188:189], 0, s[68:69]
	s_mov_b32 m0, s3
	ds_read_b128 v[226:229], v153
	ds_read_b128 v[230:233], v153 offset:1024
	ds_read_b128 v[234:237], v153 offset:2048
	ds_read_b128 v[238:241], v153 offset:3072
	global_load_lds_dwordx4 v[156:157], off
	v_add_u32_e32 v156, 0x2000, v155
	v_lshl_add_u64 v[246:247], s[4:5], 0, v[138:139]
	v_readfirstlane_b32 s3, v156
	v_lshl_add_u64 v[242:243], v[246:247], 0, s[68:69]
	s_mov_b32 m0, s3
	s_nop 0
	global_load_lds_dwordx4 v[242:243], off
	s_barrier
	s_waitcnt lgkmcnt(0)
	s_setprio 1
	v_mfma_f32_16x16x32_bf16 v[94:97], v[226:229], v[194:197], v[94:97]
	v_mfma_f32_16x16x32_bf16 v[90:93], v[234:237], v[194:197], v[90:93]
	v_mfma_f32_16x16x32_bf16 v[86:89], v[226:229], v[202:205], v[86:89]
	v_mfma_f32_16x16x32_bf16 v[82:85], v[234:237], v[202:205], v[82:85]
	v_mfma_f32_16x16x32_bf16 v[78:81], v[226:229], v[210:213], v[78:81]
	v_mfma_f32_16x16x32_bf16 v[74:77], v[234:237], v[210:213], v[74:77]
	v_mfma_f32_16x16x32_bf16 v[70:73], v[226:229], v[218:221], v[70:73]
	v_mfma_f32_16x16x32_bf16 v[66:69], v[234:237], v[218:221], v[66:69]
	v_mfma_f32_16x16x32_bf16 v[94:97], v[230:233], v[198:201], v[94:97]
	v_mfma_f32_16x16x32_bf16 v[90:93], v[238:241], v[198:201], v[90:93]
	v_mfma_f32_16x16x32_bf16 v[86:89], v[230:233], v[206:209], v[86:89]
	v_mfma_f32_16x16x32_bf16 v[82:85], v[238:241], v[206:209], v[82:85]
	v_mfma_f32_16x16x32_bf16 v[78:81], v[230:233], v[214:217], v[78:81]
	v_mfma_f32_16x16x32_bf16 v[74:77], v[238:241], v[214:217], v[74:77]
	v_mfma_f32_16x16x32_bf16 v[70:73], v[230:233], v[222:225], v[70:73]
	v_mfma_f32_16x16x32_bf16 v[66:69], v[238:241], v[222:225], v[66:69]
	s_setprio 0
	v_readfirstlane_b32 s3, v141
	v_add_u32_e32 v157, 0x2000, v141
	v_lshl_add_u64 v[242:243], v[174:175], 0, s[84:85]
	s_mov_b32 m0, s3
	v_readfirstlane_b32 s3, v157
	s_barrier
	ds_read_b128 v[194:197], v145 offset:16384
	ds_read_b128 v[198:201], v145 offset:17408
	ds_read_b128 v[202:205], v144 offset:16384
	ds_read_b128 v[206:209], v144 offset:17408
	ds_read_b128 v[210:213], v143 offset:16384
	ds_read_b128 v[214:217], v143 offset:17408
	ds_read_b128 v[218:221], v142 offset:16384
	ds_read_b128 v[222:225], v142 offset:17408
	global_load_lds_dwordx4 v[242:243], off
	v_lshl_add_u64 v[242:243], v[186:187], 0, s[84:85]
	s_mov_b32 m0, s3
	s_nop 0
	global_load_lds_dwordx4 v[242:243], off
	s_barrier
	s_waitcnt lgkmcnt(0)
	s_setprio 1
	v_mfma_f32_16x16x32_bf16 v[62:65], v[158:161], v[194:197], v[62:65]
	v_mfma_f32_16x16x32_bf16 v[58:61], v[170:173], v[194:197], v[58:61]
	v_mfma_f32_16x16x32_bf16 v[54:57], v[158:161], v[202:205], v[54:57]
	v_mfma_f32_16x16x32_bf16 v[50:53], v[170:173], v[202:205], v[50:53]
	v_mfma_f32_16x16x32_bf16 v[46:49], v[158:161], v[210:213], v[46:49]
	v_mfma_f32_16x16x32_bf16 v[42:45], v[170:173], v[210:213], v[42:45]
	v_mfma_f32_16x16x32_bf16 v[38:41], v[158:161], v[218:221], v[38:41]
	v_mfma_f32_16x16x32_bf16 v[34:37], v[170:173], v[218:221], v[34:37]
	v_mfma_f32_16x16x32_bf16 v[62:65], v[166:169], v[198:201], v[62:65]
	v_mfma_f32_16x16x32_bf16 v[58:61], v[190:193], v[198:201], v[58:61]
	v_mfma_f32_16x16x32_bf16 v[54:57], v[166:169], v[206:209], v[54:57]
	v_mfma_f32_16x16x32_bf16 v[50:53], v[190:193], v[206:209], v[50:53]
	v_mfma_f32_16x16x32_bf16 v[46:49], v[166:169], v[214:217], v[46:49]
	v_mfma_f32_16x16x32_bf16 v[42:45], v[190:193], v[214:217], v[42:45]
	v_mfma_f32_16x16x32_bf16 v[38:41], v[166:169], v[222:225], v[38:41]
	v_mfma_f32_16x16x32_bf16 v[34:37], v[190:193], v[222:225], v[34:37]
	s_setprio 0
	s_barrier
; #define STAGE_A(P,br,kt) STAGE_G(P,c.A,c.lda,br,(long)(kt)*c.kstr)
; #define STAGE_B(P,br,kt) STAGE_G(P,c.Bt,c.K,br,(long)(kt)*BK)
; #define LDA(dst,b,h) for(int m=0;m<4;++m)for(int k=0;k<2;++k) \
;     dst[m][k]=*reinterpret_cast<const bf16x8*>((char*)SA(b,h)+lds_byte(wr*64+m*16+fr,k*32+fq*8))
; #define LDB(dst,b,h) for(int n=0;n<2;++n)for(int k=0;k<2;++k) \
;     dst[n][k]=*reinterpret_cast<const bf16x8*>((char*)SB(b,h)+lds_byte(wc*32+n*16+fr,k*32+fq*8))
; #define MMA(ai,bj,At,Bt_) do{__builtin_amdgcn_s_setprio(1); \
;     for(int m=0;m<4;++m)for(int n=0;n<2;++n)for(int k=0;k<2;++k) \
;       acc[ai][bj][m][n]=__builtin_amdgcn_mfma_f32_16x16x32_bf16(Bt_[n][k],At[m][k],acc[ai][bj][m][n],0,0,0); \
;     __builtin_amdgcn_s_setprio(0);}while(0)
; #define WAIT_V(n) asm volatile("s_waitcnt vmcnt(" #n ")":::"memory")
; #define WAIT_L(n) asm volatile("s_waitcnt lgkmcnt(" #n ")":::"memory")
; #define BAR __builtin_amdgcn_s_barrier()
; #define SCHED __builtin_amdgcn_sched_barrier(0)
; template <int EPI>
; __device__ __forceinline__ void gemm_run(const GD& c, const bool has_next, const GD& nx, const Ctx& e, bf16* shm, float* rs, float* rs_nxt, float* racc_) {
;     ...
;     STAGE_B(SB(0,1),bcol+HALF,t+2);
;     WAIT_V(6); BAR; MMA(1,1,At,B1); BAR;
;     LDB(B0,1,0); SCHED; LDA(At,1,0); STAGE_A(SA(0,1),brow+HALF,t+2);
;     WAIT_L(8); BAR; WAIT_L(0); MMA(0,0,At,B0); BAR; SCHED;
;     LDB(B1,1,1); STAGE_B(SB(1,0),bcol,t+3);
;     BAR; WAIT_L(0); MMA(0,1,At,B1); BAR;
;     LDA(At,1,1); STAGE_A(SA(1,0),brow,t+3);
;     BAR; WAIT_L(0); MMA(1,0,At,B0); BAR; SCHED;
	v_add_u32_e32 v158, s86, v147
	v_add_u32_e32 v159, 0x2000, v158
	v_readfirstlane_b32 s3, v158
	v_lshl_add_u64 v[160:161], v[188:189], 0, s[14:15]
	s_mov_b32 m0, s3
	v_readfirstlane_b32 s3, v159
	global_load_lds_dwordx4 v[160:161], off
	v_lshl_add_u64 v[160:161], v[246:247], 0, s[14:15]
	s_mov_b32 m0, s3
	s_nop 0
	global_load_lds_dwordx4 v[160:161], off
	s_waitcnt vmcnt(6)
	s_barrier
	s_setprio 1
	v_mfma_f32_16x16x32_bf16 v[30:33], v[226:229], v[194:197], v[30:33]
	v_mfma_f32_16x16x32_bf16 v[26:29], v[234:237], v[194:197], v[26:29]
	v_mfma_f32_16x16x32_bf16 v[22:25], v[226:229], v[202:205], v[22:25]
	v_mfma_f32_16x16x32_bf16 v[18:21], v[234:237], v[202:205], v[18:21]
	v_mfma_f32_16x16x32_bf16 v[14:17], v[226:229], v[210:213], v[14:17]
	v_mfma_f32_16x16x32_bf16 v[10:13], v[234:237], v[210:213], v[10:13]
	v_mfma_f32_16x16x32_bf16 v[6:9], v[226:229], v[218:221], v[6:9]
	v_mfma_f32_16x16x32_bf16 v[2:5], v[234:237], v[218:221], v[2:5]
	v_mfma_f32_16x16x32_bf16 v[30:33], v[230:233], v[198:201], v[30:33]
	v_mfma_f32_16x16x32_bf16 v[26:29], v[238:241], v[198:201], v[26:29]
	v_mfma_f32_16x16x32_bf16 v[22:25], v[230:233], v[206:209], v[22:25]
	v_mfma_f32_16x16x32_bf16 v[18:21], v[238:241], v[206:209], v[18:21]
	v_mfma_f32_16x16x32_bf16 v[14:17], v[230:233], v[214:217], v[14:17]
	v_mfma_f32_16x16x32_bf16 v[10:13], v[238:241], v[214:217], v[10:13]
	v_mfma_f32_16x16x32_bf16 v[6:9], v[230:233], v[222:225], v[6:9]
	v_mfma_f32_16x16x32_bf16 v[2:5], v[238:241], v[222:225], v[2:5]
	s_setprio 0
	s_barrier
	ds_read_b128 v[166:169], v148
	ds_read_b128 v[170:173], v148 offset:1024
	ds_read_b128 v[190:193], v148 offset:2048
	ds_read_b128 v[194:197], v148 offset:3072
	v_add_u32_e32 v160, 0x4000, v141
	v_add_u32_e32 v161, 0x6000, v141
	v_readfirstlane_b32 s3, v160
	v_lshl_add_u64 v[230:231], v[174:175], 0, s[92:93]
	s_mov_b32 m0, s3
	v_readfirstlane_b32 s3, v161
	ds_read_b128 v[198:201], v145 offset:32768
	ds_read_b128 v[202:205], v145 offset:33792
	ds_read_b128 v[206:209], v144 offset:32768
	ds_read_b128 v[210:213], v144 offset:33792
	ds_read_b128 v[214:217], v143 offset:32768
	ds_read_b128 v[218:221], v143 offset:33792
	ds_read_b128 v[222:225], v142 offset:32768
	ds_read_b128 v[226:229], v142 offset:33792
	global_load_lds_dwordx4 v[230:231], off
	v_lshl_add_u64 v[230:231], v[186:187], 0, s[92:93]
	s_mov_b32 m0, s3
	s_nop 0
	global_load_lds_dwordx4 v[230:231], off
	s_waitcnt lgkmcnt(8)
	s_barrier
	s_waitcnt lgkmcnt(0)
	s_setprio 1
	v_mfma_f32_16x16x32_bf16 v[126:129], v[166:169], v[198:201], v[126:129]
	v_mfma_f32_16x16x32_bf16 v[122:125], v[190:193], v[198:201], v[122:125]
	v_mfma_f32_16x16x32_bf16 v[118:121], v[166:169], v[206:209], v[118:121]
	v_mfma_f32_16x16x32_bf16 v[114:117], v[190:193], v[206:209], v[114:117]
	v_mfma_f32_16x16x32_bf16 v[110:113], v[166:169], v[214:217], v[110:113]
	v_mfma_f32_16x16x32_bf16 v[106:109], v[190:193], v[214:217], v[106:109]
	v_mfma_f32_16x16x32_bf16 v[102:105], v[166:169], v[222:225], v[102:105]
	v_mfma_f32_16x16x32_bf16 v[98:101], v[190:193], v[222:225], v[98:101]
	v_mfma_f32_16x16x32_bf16 v[126:129], v[170:173], v[202:205], v[126:129]
	v_mfma_f32_16x16x32_bf16 v[122:125], v[194:197], v[202:205], v[122:125]
	v_mfma_f32_16x16x32_bf16 v[118:121], v[170:173], v[210:213], v[118:121]
	v_mfma_f32_16x16x32_bf16 v[114:117], v[194:197], v[210:213], v[114:117]
	v_mfma_f32_16x16x32_bf16 v[110:113], v[170:173], v[218:221], v[110:113]
	v_mfma_f32_16x16x32_bf16 v[106:109], v[194:197], v[218:221], v[106:109]
	v_mfma_f32_16x16x32_bf16 v[102:105], v[170:173], v[226:229], v[102:105]
	v_mfma_f32_16x16x32_bf16 v[98:101], v[194:197], v[226:229], v[98:101]
	s_setprio 0
	s_barrier
	v_readfirstlane_b32 s3, v149
	v_add_u32_e32 v176, 0x2000, v149
	v_lshl_add_u64 v[248:249], v[188:189], 0, s[26:27]
	s_mov_b32 m0, s3
	v_readfirstlane_b32 s3, v176
	ds_read_b128 v[230:233], v146
	ds_read_b128 v[234:237], v146 offset:1024
	ds_read_b128 v[238:241], v146 offset:2048
	ds_read_b128 v[242:245], v146 offset:3072
	global_load_lds_dwordx4 v[248:249], off
	v_lshl_add_u64 v[248:249], v[246:247], 0, s[26:27]
	s_mov_b32 m0, s3
	s_nop 0
	global_load_lds_dwordx4 v[248:249], off
	s_barrier
	s_waitcnt lgkmcnt(0)
	s_setprio 1
	v_mfma_f32_16x16x32_bf16 v[94:97], v[230:233], v[198:201], v[94:97]
	v_mfma_f32_16x16x32_bf16 v[90:93], v[238:241], v[198:201], v[90:93]
	v_mfma_f32_16x16x32_bf16 v[86:89], v[230:233], v[206:209], v[86:89]
	v_mfma_f32_16x16x32_bf16 v[82:85], v[238:241], v[206:209], v[82:85]
	v_mfma_f32_16x16x32_bf16 v[78:81], v[230:233], v[214:217], v[78:81]
	v_mfma_f32_16x16x32_bf16 v[74:77], v[238:241], v[214:217], v[74:77]
	v_mfma_f32_16x16x32_bf16 v[70:73], v[230:233], v[222:225], v[70:73]
	v_mfma_f32_16x16x32_bf16 v[66:69], v[238:241], v[222:225], v[66:69]
	v_mfma_f32_16x16x32_bf16 v[94:97], v[234:237], v[202:205], v[94:97]
	v_mfma_f32_16x16x32_bf16 v[90:93], v[242:245], v[202:205], v[90:93]
	v_mfma_f32_16x16x32_bf16 v[86:89], v[234:237], v[210:213], v[86:89]
	v_mfma_f32_16x16x32_bf16 v[82:85], v[242:245], v[210:213], v[82:85]
	v_mfma_f32_16x16x32_bf16 v[78:81], v[234:237], v[218:221], v[78:81]
	v_mfma_f32_16x16x32_bf16 v[74:77], v[242:245], v[218:221], v[74:77]
	v_mfma_f32_16x16x32_bf16 v[70:73], v[234:237], v[226:229], v[70:73]
	v_mfma_f32_16x16x32_bf16 v[66:69], v[242:245], v[226:229], v[66:69]
	s_setprio 0
	v_readfirstlane_b32 s3, v150
	v_lshl_add_u64 v[174:175], v[174:175], 0, s[80:81]
	s_mov_b32 m0, s3
	v_readfirstlane_b32 s3, v151
	s_barrier
; #define STAGE_A(P,br,kt) STAGE_G(P,c.A,c.lda,br,(long)(kt)*c.kstr)
; #define STAGE_B(P,br,kt) STAGE_G(P,c.Bt,c.K,br,(long)(kt)*BK)
; #define LDA(dst,b,h) for(int m=0;m<4;++m)for(int k=0;k<2;++k) \
;     dst[m][k]=*reinterpret_cast<const bf16x8*>((char*)SA(b,h)+lds_byte(wr*64+m*16+fr,k*32+fq*8))
; #define LDB(dst,b,h) for(int n=0;n<2;++n)for(int k=0;k<2;++k) \
;     dst[n][k]=*reinterpret_cast<const bf16x8*>((char*)SB(b,h)+lds_byte(wc*32+n*16+fr,k*32+fq*8))
; #define MMA(ai,bj,At,Bt_) do{__builtin_amdgcn_s_setprio(1); \
;     for(int m=0;m<4;++m)for(int n=0;n<2;++n)for(int k=0;k<2;++k) \
;       acc[ai][bj][m][n]=__builtin_amdgcn_mfma_f32_16x16x32_bf16(Bt_[n][k],At[m][k],acc[ai][bj][m][n],0,0,0); \
;     __builtin_amdgcn_s_setprio(0);}while(0)
; #define WAIT_V(n) asm volatile("s_waitcnt vmcnt(" #n ")":::"memory")
; #define WAIT_L(n) asm volatile("s_waitcnt lgkmcnt(" #n ")":::"memory")
; #define BAR __builtin_amdgcn_s_barrier()
; #define SCHED __builtin_amdgcn_sched_barrier(0)
; template <int EPI>
; __device__ __forceinline__ void gemm_run(const GD& c, const bool has_next, const GD& nx, const Ctx& e, bf16* shm, float* rs, float* rs_nxt, float* racc_) {
;     ...
;     LDA(At,1,1); STAGE_A(SA(1,0),brow,t+3);
;     BAR; WAIT_L(0); MMA(1,0,At,B0); BAR; SCHED;
;     STAGE_B(SB(1,1),bcol+HALF,t+3);
;     WAIT_V(6); BAR; MMA(1,1,At,B1); BAR;
;   }
;   { LDB(B0,0,0); LDA(At,0,0); STAGE_A(SA(1,1),brow+HALF,nt-1);
;     BAR; WAIT_L(0); MMA(0,0,At,B0); BAR;
;     LDB(B1,0,1); BAR; WAIT_L(0); MMA(0,1,At,B1); BAR;
;     LDA(At,0,1); WAIT_V(4); BAR; WAIT_L(0); MMA(1,0,At,B0); MMA(1,1,At,B1); BAR; }
	ds_read_b128 v[198:201], v145 offset:49152
	ds_read_b128 v[202:205], v145 offset:50176
	ds_read_b128 v[206:209], v144 offset:49152
	ds_read_b128 v[210:213], v144 offset:50176
	ds_read_b128 v[214:217], v143 offset:49152
	ds_read_b128 v[218:221], v143 offset:50176
	ds_read_b128 v[222:225], v142 offset:49152
	ds_read_b128 v[226:229], v142 offset:50176
	global_load_lds_dwordx4 v[174:175], off
	v_lshl_add_u64 v[174:175], v[186:187], 0, s[80:81]
	s_mov_b32 m0, s3
	s_nop 0
	global_load_lds_dwordx4 v[174:175], off
	s_barrier
	s_waitcnt lgkmcnt(0)
	s_setprio 1
	v_mfma_f32_16x16x32_bf16 v[62:65], v[166:169], v[198:201], v[62:65]
	v_mfma_f32_16x16x32_bf16 v[58:61], v[190:193], v[198:201], v[58:61]
	v_mfma_f32_16x16x32_bf16 v[54:57], v[166:169], v[206:209], v[54:57]
	v_mfma_f32_16x16x32_bf16 v[50:53], v[190:193], v[206:209], v[50:53]
	v_mfma_f32_16x16x32_bf16 v[46:49], v[166:169], v[214:217], v[46:49]
	v_mfma_f32_16x16x32_bf16 v[42:45], v[190:193], v[214:217], v[42:45]
	v_mfma_f32_16x16x32_bf16 v[38:41], v[166:169], v[222:225], v[38:41]
	v_mfma_f32_16x16x32_bf16 v[34:37], v[190:193], v[222:225], v[34:37]
	v_mfma_f32_16x16x32_bf16 v[62:65], v[170:173], v[202:205], v[62:65]
	v_mfma_f32_16x16x32_bf16 v[58:61], v[194:197], v[202:205], v[58:61]
	v_mfma_f32_16x16x32_bf16 v[54:57], v[170:173], v[210:213], v[54:57]
	v_mfma_f32_16x16x32_bf16 v[50:53], v[194:197], v[210:213], v[50:53]
	v_mfma_f32_16x16x32_bf16 v[46:49], v[170:173], v[218:221], v[46:49]
	v_mfma_f32_16x16x32_bf16 v[42:45], v[194:197], v[218:221], v[42:45]
	v_mfma_f32_16x16x32_bf16 v[38:41], v[170:173], v[226:229], v[38:41]
	v_mfma_f32_16x16x32_bf16 v[34:37], v[194:197], v[226:229], v[34:37]
	s_setprio 0
	s_barrier
	v_readfirstlane_b32 s3, v152
	v_add_u32_e32 v168, 0x2000, v152
	v_lshl_add_u64 v[166:167], v[188:189], 0, s[28:29]
	s_mov_b32 m0, s3
	v_readfirstlane_b32 s3, v168
	global_load_lds_dwordx4 v[166:167], off
	v_lshl_add_u64 v[166:167], v[246:247], 0, s[28:29]
	s_mov_b32 m0, s3
	s_nop 0
	global_load_lds_dwordx4 v[166:167], off
	s_waitcnt vmcnt(6)
	s_barrier
	s_setprio 1
	v_mfma_f32_16x16x32_bf16 v[30:33], v[230:233], v[198:201], v[30:33]
	v_mfma_f32_16x16x32_bf16 v[26:29], v[238:241], v[198:201], v[26:29]
	v_mfma_f32_16x16x32_bf16 v[22:25], v[230:233], v[206:209], v[22:25]
	v_mfma_f32_16x16x32_bf16 v[18:21], v[238:241], v[206:209], v[18:21]
	v_mfma_f32_16x16x32_bf16 v[14:17], v[230:233], v[214:217], v[14:17]
	v_mfma_f32_16x16x32_bf16 v[10:13], v[238:241], v[214:217], v[10:13]
	v_mfma_f32_16x16x32_bf16 v[6:9], v[230:233], v[222:225], v[6:9]
	v_mfma_f32_16x16x32_bf16 v[2:5], v[238:241], v[222:225], v[2:5]
	v_mfma_f32_16x16x32_bf16 v[30:33], v[234:237], v[202:205], v[30:33]
	v_mfma_f32_16x16x32_bf16 v[26:29], v[242:245], v[202:205], v[26:29]
	v_mfma_f32_16x16x32_bf16 v[22:25], v[234:237], v[210:213], v[22:25]
	v_mfma_f32_16x16x32_bf16 v[18:21], v[242:245], v[210:213], v[18:21]
	v_mfma_f32_16x16x32_bf16 v[14:17], v[234:237], v[218:221], v[14:17]
	v_mfma_f32_16x16x32_bf16 v[10:13], v[242:245], v[218:221], v[10:13]
	v_mfma_f32_16x16x32_bf16 v[6:9], v[234:237], v[226:229], v[6:9]
	v_mfma_f32_16x16x32_bf16 v[2:5], v[242:245], v[226:229], v[2:5]
	s_setprio 0
	s_add_i32 s2, s2, 2
	v_lshl_add_u64 v[130:131], v[130:131], 0, s[88:89]
	v_lshl_add_u64 v[132:133], v[132:133], 0, s[88:89]
	v_lshl_add_u64 v[136:137], v[136:137], 0, s[88:89]
	s_cmp_lt_u32 s2, 12
	v_lshl_add_u64 v[138:139], v[138:139], 0, s[88:89]
	s_barrier
	s_cbranch_scc1 .LBB0_267
	s_or_b32 s2, s10, 0x80
	s_ashr_i32 s3, s2, 31
	s_lshl_b64 s[2:3], s[2:3], 11
	s_add_u32 s2, s18, s2
	s_addc_u32 s3, s19, s3
	v_lshl_add_u64 v[150:151], s[2:3], 0, v[0:1]
	s_mov_b64 s[14:15], 0x780
	v_readfirstlane_b32 s11, v162
	v_lshl_add_u64 v[150:151], v[150:151], 0, s[14:15]
	s_mov_b32 m0, s11
	ds_read_b128 v[130:133], v154
	ds_read_b128 v[136:139], v154 offset:1024
	ds_read_b128 v[166:169], v154 offset:2048
	ds_read_b128 v[170:173], v154 offset:3072
	ds_read_b128 v[190:193], v145
	ds_read_b128 v[194:197], v145 offset:1024
	ds_read_b128 v[198:201], v144
	ds_read_b128 v[202:205], v144 offset:1024
	ds_read_b128 v[206:209], v143
	ds_read_b128 v[210:213], v143 offset:1024
	ds_read_b128 v[214:217], v142
	ds_read_b128 v[218:221], v142 offset:1024
	global_load_lds_dwordx4 v[150:151], off
	v_lshl_add_u64 v[150:151], s[2:3], 0, v[134:135]
	v_readfirstlane_b32 s2, v163
	v_lshl_add_u64 v[150:151], v[150:151], 0, s[14:15]
	s_mov_b32 m0, s2
	s_nop 0
	global_load_lds_dwordx4 v[150:151], off
	s_barrier
	s_waitcnt lgkmcnt(0)
	s_setprio 1
	v_mfma_f32_16x16x32_bf16 v[126:129], v[130:133], v[190:193], v[126:129]
	v_mfma_f32_16x16x32_bf16 v[122:125], v[166:169], v[190:193], v[122:125]
	v_mfma_f32_16x16x32_bf16 v[118:121], v[130:133], v[198:201], v[118:121]
	v_mfma_f32_16x16x32_bf16 v[106:109], v[166:169], v[206:209], v[106:109]
	v_mfma_f32_16x16x32_bf16 v[102:105], v[130:133], v[214:217], v[102:105]
	v_mfma_f32_16x16x32_bf16 v[126:129], v[136:139], v[194:197], v[126:129]
	v_mfma_f32_16x16x32_bf16 v[122:125], v[170:173], v[194:197], v[122:125]
	v_mfma_f32_16x16x32_bf16 v[118:121], v[136:139], v[202:205], v[118:121]
	v_mfma_f32_16x16x32_bf16 v[114:117], v[166:169], v[198:201], v[114:117]
	v_mfma_f32_16x16x32_bf16 v[110:113], v[130:133], v[206:209], v[110:113]
	v_mfma_f32_16x16x32_bf16 v[106:109], v[170:173], v[210:213], v[106:109]
	v_mfma_f32_16x16x32_bf16 v[102:105], v[136:139], v[218:221], v[102:105]
	v_mfma_f32_16x16x32_bf16 v[98:101], v[166:169], v[214:217], v[98:101]
	v_mfma_f32_16x16x32_bf16 v[222:225], v[170:173], v[202:205], v[114:117]
	v_mfma_f32_16x16x32_bf16 v[226:229], v[136:139], v[210:213], v[110:113]
	v_mfma_f32_16x16x32_bf16 v[230:233], v[170:173], v[218:221], v[98:101]
	s_setprio 0
	s_barrier
; #define STAGE_A(P,br,kt) STAGE_G(P,c.A,c.lda,br,(long)(kt)*c.kstr)
; #define LDA(dst,b,h) for(int m=0;m<4;++m)for(int k=0;k<2;++k) \
;     dst[m][k]=*reinterpret_cast<const bf16x8*>((char*)SA(b,h)+lds_byte(wr*64+m*16+fr,k*32+fq*8))
; #define LDB(dst,b,h) for(int n=0;n<2;++n)for(int k=0;k<2;++k) \
;     dst[n][k]=*reinterpret_cast<const bf16x8*>((char*)SB(b,h)+lds_byte(wc*32+n*16+fr,k*32+fq*8))
; #define MMA(ai,bj,At,Bt_) do{__builtin_amdgcn_s_setprio(1); \
;     for(int m=0;m<4;++m)for(int n=0;n<2;++n)for(int k=0;k<2;++k) \
;       acc[ai][bj][m][n]=__builtin_amdgcn_mfma_f32_16x16x32_bf16(Bt_[n][k],At[m][k],acc[ai][bj][m][n],0,0,0); \
;     __builtin_amdgcn_s_setprio(0);}while(0)
; #define WAIT_V(n) asm volatile("s_waitcnt vmcnt(" #n ")":::"memory")
; #define WAIT_L(n) asm volatile("s_waitcnt lgkmcnt(" #n ")":::"memory")
; #define BAR __builtin_amdgcn_s_barrier()
; template <int EPI>
; __device__ __forceinline__ void gemm_run(const GD& c, const bool has_next, const GD& nx, const Ctx& e, bf16* shm, float* rs, float* rs_nxt, float* racc_) {
;     ...
;   { LDB(B0,0,0); LDA(At,0,0); STAGE_A(SA(1,1),brow+HALF,nt-1);
;     BAR; WAIT_L(0); MMA(0,0,At,B0); BAR;
;     LDB(B1,0,1); BAR; WAIT_L(0); MMA(0,1,At,B1); BAR;
;     LDA(At,0,1); WAIT_V(4); BAR; WAIT_L(0); MMA(1,0,At,B0); MMA(1,1,At,B1); BAR; }
	s_nop 2
	ds_read_b128 v[98:101], v153
	ds_read_b128 v[110:113], v153 offset:1024
	ds_read_b128 v[114:117], v153 offset:2048
	ds_read_b128 v[150:153], v153 offset:3072
	s_barrier
	s_waitcnt lgkmcnt(0)
	s_setprio 1
	v_mfma_f32_16x16x32_bf16 v[90:93], v[114:117], v[190:193], v[90:93]
	v_mfma_f32_16x16x32_bf16 v[86:89], v[98:101], v[198:201], v[86:89]
	v_mfma_f32_16x16x32_bf16 v[74:77], v[114:117], v[206:209], v[74:77]
	v_mfma_f32_16x16x32_bf16 v[70:73], v[98:101], v[214:217], v[70:73]
	v_mfma_f32_16x16x32_bf16 v[66:69], v[114:117], v[214:217], v[66:69]
	v_mfma_f32_16x16x32_bf16 v[94:97], v[98:101], v[190:193], v[94:97]
	v_mfma_f32_16x16x32_bf16 v[90:93], v[150:153], v[194:197], v[90:93]
	v_mfma_f32_16x16x32_bf16 v[86:89], v[110:113], v[202:205], v[86:89]
	v_mfma_f32_16x16x32_bf16 v[82:85], v[114:117], v[198:201], v[82:85]
	v_mfma_f32_16x16x32_bf16 v[78:81], v[98:101], v[206:209], v[78:81]
	v_mfma_f32_16x16x32_bf16 v[74:77], v[150:153], v[210:213], v[74:77]
	v_mfma_f32_16x16x32_bf16 v[70:73], v[110:113], v[218:221], v[70:73]
	v_mfma_f32_16x16x32_bf16 v[66:69], v[150:153], v[218:221], v[66:69]
	v_mfma_f32_16x16x32_bf16 v[234:237], v[110:113], v[194:197], v[94:97]
	v_mfma_f32_16x16x32_bf16 v[190:193], v[150:153], v[202:205], v[82:85]
	v_mfma_f32_16x16x32_bf16 v[194:197], v[110:113], v[210:213], v[78:81]
	s_setprio 0
	s_barrier
	s_nop 0
	ds_read_b128 v[78:81], v145 offset:16384
	ds_read_b128 v[82:85], v145 offset:17408
	ds_read_b128 v[94:97], v144 offset:16384
	ds_read_b128 v[198:201], v144 offset:17408
	ds_read_b128 v[202:205], v143 offset:16384
	ds_read_b128 v[206:209], v143 offset:17408
	ds_read_b128 v[210:213], v142 offset:16384
	ds_read_b128 v[214:217], v142 offset:17408
	s_waitcnt vmcnt(4)
	s_barrier
	s_waitcnt lgkmcnt(0)
	s_setprio 1
	v_mfma_f32_16x16x32_bf16 v[62:65], v[130:133], v[78:81], v[62:65]
	v_mfma_f32_16x16x32_bf16 v[58:61], v[166:169], v[78:81], v[58:61]
	v_mfma_f32_16x16x32_bf16 v[54:57], v[130:133], v[94:97], v[54:57]
	v_mfma_f32_16x16x32_bf16 v[42:45], v[166:169], v[202:205], v[42:45]
	v_mfma_f32_16x16x32_bf16 v[38:41], v[130:133], v[210:213], v[38:41]
	v_mfma_f32_16x16x32_bf16 v[62:65], v[136:139], v[82:85], v[62:65]
	v_mfma_f32_16x16x32_bf16 v[58:61], v[170:173], v[82:85], v[58:61]
	v_mfma_f32_16x16x32_bf16 v[54:57], v[136:139], v[198:201], v[54:57]
	v_mfma_f32_16x16x32_bf16 v[50:53], v[166:169], v[94:97], v[50:53]
	v_mfma_f32_16x16x32_bf16 v[46:49], v[130:133], v[202:205], v[46:49]
	v_mfma_f32_16x16x32_bf16 v[42:45], v[170:173], v[206:209], v[42:45]
	v_mfma_f32_16x16x32_bf16 v[38:41], v[136:139], v[214:217], v[38:41]
	v_mfma_f32_16x16x32_bf16 v[34:37], v[166:169], v[210:213], v[34:37]
	v_mfma_f32_16x16x32_bf16 v[218:221], v[170:173], v[198:201], v[50:53]
	v_mfma_f32_16x16x32_bf16 v[238:241], v[136:139], v[206:209], v[46:49]
	v_mfma_f32_16x16x32_bf16 v[136:139], v[170:173], v[214:217], v[34:37]
	s_setprio 0
	s_setprio 1
	v_mfma_f32_16x16x32_bf16 v[26:29], v[114:117], v[78:81], v[26:29]
	v_mfma_f32_16x16x32_bf16 v[22:25], v[98:101], v[94:97], v[22:25]
	v_mfma_f32_16x16x32_bf16 v[10:13], v[114:117], v[202:205], v[10:13]
	v_mfma_f32_16x16x32_bf16 v[6:9], v[98:101], v[210:213], v[6:9]
	v_mfma_f32_16x16x32_bf16 v[30:33], v[98:101], v[78:81], v[30:33]
	v_mfma_f32_16x16x32_bf16 v[26:29], v[150:153], v[82:85], v[26:29]
	v_mfma_f32_16x16x32_bf16 v[22:25], v[110:113], v[198:201], v[22:25]
	v_mfma_f32_16x16x32_bf16 v[18:21], v[114:117], v[94:97], v[18:21]
	v_mfma_f32_16x16x32_bf16 v[14:17], v[98:101], v[202:205], v[14:17]
	v_mfma_f32_16x16x32_bf16 v[10:13], v[150:153], v[206:209], v[10:13]
	v_mfma_f32_16x16x32_bf16 v[6:9], v[110:113], v[214:217], v[6:9]
	v_mfma_f32_16x16x32_bf16 v[2:5], v[114:117], v[210:213], v[2:5]
	v_mfma_f32_16x16x32_bf16 v[166:169], v[110:113], v[82:85], v[30:33]
	v_mfma_f32_16x16x32_bf16 v[170:173], v[150:153], v[198:201], v[18:21]
	v_mfma_f32_16x16x32_bf16 v[198:201], v[110:113], v[206:209], v[14:17]
	v_mfma_f32_16x16x32_bf16 v[2:5], v[150:153], v[214:217], v[2:5]
	s_setprio 0
	s_barrier
	ds_read_b128 v[14:17], v148
	ds_read_b128 v[18:21], v148 offset:1024
	ds_read_b128 v[150:153], v148 offset:2048
	ds_read_b128 v[202:205], v148 offset:3072
	ds_read_b128 v[30:33], v145 offset:32768
	ds_read_b128 v[34:37], v145 offset:33792
	ds_read_b128 v[46:49], v144 offset:32768
	ds_read_b128 v[50:53], v144 offset:33792
	ds_read_b128 v[206:209], v143 offset:32768
	ds_read_b128 v[210:213], v143 offset:33792
	ds_read_b128 v[214:217], v142 offset:32768
	ds_read_b128 v[242:245], v142 offset:33792
	s_waitcnt vmcnt(2)
	s_barrier
; #define LDA(dst,b,h) for(int m=0;m<4;++m)for(int k=0;k<2;++k) \
;     dst[m][k]=*reinterpret_cast<const bf16x8*>((char*)SA(b,h)+lds_byte(wr*64+m*16+fr,k*32+fq*8))
; #define LDB(dst,b,h) for(int n=0;n<2;++n)for(int k=0;k<2;++k) \
;     dst[n][k]=*reinterpret_cast<const bf16x8*>((char*)SB(b,h)+lds_byte(wc*32+n*16+fr,k*32+fq*8))
; #define MMA(ai,bj,At,Bt_) do{__builtin_amdgcn_s_setprio(1); \
;     for(int m=0;m<4;++m)for(int n=0;n<2;++n)for(int k=0;k<2;++k) \
;       acc[ai][bj][m][n]=__builtin_amdgcn_mfma_f32_16x16x32_bf16(Bt_[n][k],At[m][k],acc[ai][bj][m][n],0,0,0); \
;     __builtin_amdgcn_s_setprio(0);}while(0)
; #define WAIT_V(n) asm volatile("s_waitcnt vmcnt(" #n ")":::"memory")
; #define WAIT_L(n) asm volatile("s_waitcnt lgkmcnt(" #n ")":::"memory")
; #define BAR __builtin_amdgcn_s_barrier()
; template <int EPI>
; __device__ __forceinline__ void gemm_run(const GD& c, const bool has_next, const GD& nx, const Ctx& e, bf16* shm, float* rs, float* rs_nxt, float* racc_) {
;     ...
;   { LDB(B0,1,0); LDA(At,1,0); WAIT_V(2); BAR; WAIT_L(0); MMA(0,0,At,B0); BAR;
;     LDB(B1,1,1); WAIT_V(0); BAR; WAIT_L(0); MMA(0,1,At,B1); BAR;
;     LDA(At,1,1); BAR; WAIT_L(0); MMA(1,0,At,B0); MMA(1,1,At,B1); BAR; }
;   if(wr==0)BAR;
	s_waitcnt lgkmcnt(0)
	s_setprio 1
	v_mfma_f32_16x16x32_bf16 v[78:81], v[14:17], v[30:33], v[126:129]
	v_mfma_f32_16x16x32_bf16 v[130:133], v[18:21], v[34:37], v[78:81]
	v_mfma_f32_16x16x32_bf16 v[78:81], v[150:153], v[30:33], v[122:125]
	v_mfma_f32_16x16x32_bf16 v[126:129], v[202:205], v[34:37], v[78:81]
	v_mfma_f32_16x16x32_bf16 v[78:81], v[14:17], v[46:49], v[118:121]
	v_mfma_f32_16x16x32_bf16 v[114:117], v[18:21], v[50:53], v[78:81]
	v_mfma_f32_16x16x32_bf16 v[78:81], v[150:153], v[46:49], v[222:225]
	v_mfma_f32_16x16x32_bf16 v[110:113], v[202:205], v[50:53], v[78:81]
	v_mfma_f32_16x16x32_bf16 v[78:81], v[14:17], v[206:209], v[226:229]
	v_mfma_f32_16x16x32_bf16 v[98:101], v[18:21], v[210:213], v[78:81]
	v_mfma_f32_16x16x32_bf16 v[78:81], v[150:153], v[206:209], v[106:109]
	v_mfma_f32_16x16x32_bf16 v[94:97], v[202:205], v[210:213], v[78:81]
	v_mfma_f32_16x16x32_bf16 v[78:81], v[14:17], v[214:217], v[102:105]
	v_mfma_f32_16x16x32_bf16 v[82:85], v[18:21], v[242:245], v[78:81]
	v_mfma_f32_16x16x32_bf16 v[78:81], v[150:153], v[214:217], v[230:233]
	v_mfma_f32_16x16x32_bf16 v[78:81], v[202:205], v[242:245], v[78:81]
	s_setprio 0
	s_barrier
	ds_read_b128 v[222:225], v146
	ds_read_b128 v[226:229], v146 offset:1024
	ds_read_b128 v[230:233], v146 offset:2048
	ds_read_b128 v[146:149], v146 offset:3072
	s_waitcnt vmcnt(0)
	s_barrier
	s_waitcnt lgkmcnt(0)
	s_setprio 1
	v_mfma_f32_16x16x32_bf16 v[102:105], v[222:225], v[30:33], v[234:237]
	v_mfma_f32_16x16x32_bf16 v[30:33], v[230:233], v[30:33], v[90:93]
	v_mfma_f32_16x16x32_bf16 v[118:121], v[146:149], v[34:37], v[30:33]
	v_mfma_f32_16x16x32_bf16 v[30:33], v[222:225], v[46:49], v[86:89]
	v_mfma_f32_16x16x32_bf16 v[106:109], v[226:229], v[50:53], v[30:33]
	v_mfma_f32_16x16x32_bf16 v[30:33], v[230:233], v[46:49], v[190:193]
	v_mfma_f32_16x16x32_bf16 v[122:125], v[226:229], v[34:37], v[102:105]
	v_mfma_f32_16x16x32_bf16 v[102:105], v[146:149], v[50:53], v[30:33]
	v_mfma_f32_16x16x32_bf16 v[30:33], v[222:225], v[206:209], v[194:197]
	v_mfma_f32_16x16x32_bf16 v[90:93], v[226:229], v[210:213], v[30:33]
	v_mfma_f32_16x16x32_bf16 v[30:33], v[230:233], v[206:209], v[74:77]
	v_mfma_f32_16x16x32_bf16 v[86:89], v[146:149], v[210:213], v[30:33]
	v_mfma_f32_16x16x32_bf16 v[30:33], v[222:225], v[214:217], v[70:73]
	v_mfma_f32_16x16x32_bf16 v[74:77], v[226:229], v[242:245], v[30:33]
	v_mfma_f32_16x16x32_bf16 v[30:33], v[230:233], v[214:217], v[66:69]
	v_mfma_f32_16x16x32_bf16 v[70:73], v[146:149], v[242:245], v[30:33]
	s_setprio 0
	s_barrier
	ds_read_b128 v[190:193], v145 offset:49152
	ds_read_b128 v[194:197], v145 offset:50176
	ds_read_b128 v[206:209], v144 offset:49152
	ds_read_b128 v[210:213], v144 offset:50176
	ds_read_b128 v[214:217], v143 offset:49152
	ds_read_b128 v[234:237], v143 offset:50176
	ds_read_b128 v[242:245], v142 offset:49152
	ds_read_b128 v[142:145], v142 offset:50176
	s_barrier
	s_waitcnt lgkmcnt(0)
	s_setprio 1
	v_mfma_f32_16x16x32_bf16 v[30:33], v[14:17], v[190:193], v[62:65]
	v_mfma_f32_16x16x32_bf16 v[66:69], v[18:21], v[194:197], v[30:33]
	v_mfma_f32_16x16x32_bf16 v[30:33], v[150:153], v[190:193], v[58:61]
	v_mfma_f32_16x16x32_bf16 v[62:65], v[202:205], v[194:197], v[30:33]
	v_mfma_f32_16x16x32_bf16 v[30:33], v[14:17], v[206:209], v[54:57]
	v_mfma_f32_16x16x32_bf16 v[50:53], v[18:21], v[210:213], v[30:33]
	v_mfma_f32_16x16x32_bf16 v[30:33], v[150:153], v[206:209], v[218:221]
	v_mfma_f32_16x16x32_bf16 v[46:49], v[202:205], v[210:213], v[30:33]
	v_mfma_f32_16x16x32_bf16 v[30:33], v[14:17], v[214:217], v[238:241]
	v_mfma_f32_16x16x32_bf16 v[14:17], v[14:17], v[242:245], v[38:41]
	v_mfma_f32_16x16x32_bf16 v[34:37], v[18:21], v[234:237], v[30:33]
	v_mfma_f32_16x16x32_bf16 v[30:33], v[150:153], v[214:217], v[42:45]
	v_mfma_f32_16x16x32_bf16 v[18:21], v[18:21], v[142:145], v[14:17]
	v_mfma_f32_16x16x32_bf16 v[14:17], v[150:153], v[242:245], v[136:139]
	v_mfma_f32_16x16x32_bf16 v[30:33], v[202:205], v[234:237], v[30:33]
	v_mfma_f32_16x16x32_bf16 v[14:17], v[202:205], v[142:145], v[14:17]
	s_setprio 0
	s_setprio 1
	v_mfma_f32_16x16x32_bf16 v[22:25], v[222:225], v[206:209], v[22:25]
	v_mfma_f32_16x16x32_bf16 v[38:41], v[222:225], v[190:193], v[166:169]
	v_mfma_f32_16x16x32_bf16 v[42:45], v[226:229], v[210:213], v[22:25]
	v_mfma_f32_16x16x32_bf16 v[22:25], v[230:233], v[206:209], v[170:173]
	v_mfma_f32_16x16x32_bf16 v[58:61], v[226:229], v[194:197], v[38:41]
	v_mfma_f32_16x16x32_bf16 v[26:29], v[230:233], v[190:193], v[26:29]
	v_mfma_f32_16x16x32_bf16 v[38:41], v[146:149], v[210:213], v[22:25]
	v_mfma_f32_16x16x32_bf16 v[22:25], v[222:225], v[214:217], v[198:201]
	v_mfma_f32_16x16x32_bf16 v[10:13], v[230:233], v[214:217], v[10:13]
	v_mfma_f32_16x16x32_bf16 v[6:9], v[222:225], v[242:245], v[6:9]
	v_mfma_f32_16x16x32_bf16 v[2:5], v[230:233], v[242:245], v[2:5]
	v_mfma_f32_16x16x32_bf16 v[54:57], v[146:149], v[194:197], v[26:29]
	v_mfma_f32_16x16x32_bf16 v[26:29], v[226:229], v[234:237], v[22:25]
	v_mfma_f32_16x16x32_bf16 v[22:25], v[146:149], v[234:237], v[10:13]
	v_mfma_f32_16x16x32_bf16 v[10:13], v[226:229], v[142:145], v[6:9]
	v_mfma_f32_16x16x32_bf16 v[6:9], v[146:149], v[142:145], v[2:5]
	s_setprio 0
	v_cmp_gt_u32_e32 vcc, s96, v140
	s_barrier
	s_and_saveexec_b64 s[2:3], vcc
	s_cbranch_execz .LBB0_270
	s_barrier

; #define STAGE_A(P,br,kt) STAGE_G(P,c.A,c.lda,br,(long)(kt)*c.kstr)
; #define STAGE_B(P,br,kt) STAGE_G(P,c.Bt,c.K,br,(long)(kt)*BK)
; #define LDA(dst,b,h) for(int m=0;m<4;++m)for(int k=0;k<2;++k) \
;     dst[m][k]=*reinterpret_cast<const bf16x8*>((char*)SA(b,h)+lds_byte(wr*64+m*16+fr,k*32+fq*8))
; #define LDB(dst,b,h) for(int n=0;n<2;++n)for(int k=0;k<2;++k) \
;     dst[n][k]=*reinterpret_cast<const bf16x8*>((char*)SB(b,h)+lds_byte(wc*32+n*16+fr,k*32+fq*8))
; #define MMA(ai,bj,At,Bt_) do{__builtin_amdgcn_s_setprio(1); \
;     for(int m=0;m<4;++m)for(int n=0;n<2;++n)for(int k=0;k<2;++k) \
;       acc[ai][bj][m][n]=__builtin_amdgcn_mfma_f32_16x16x32_bf16(Bt_[n][k],At[m][k],acc[ai][bj][m][n],0,0,0); \
;     __builtin_amdgcn_s_setprio(0);}while(0)
; #define WAIT_V(n) asm volatile("s_waitcnt vmcnt(" #n ")":::"memory")
; #define WAIT_L(n) asm volatile("s_waitcnt lgkmcnt(" #n ")":::"memory")
; #define BAR __builtin_amdgcn_s_barrier()
; #define SCHED __builtin_amdgcn_sched_barrier(0)
; template <int EPI>
; __device__ __forceinline__ void gemm_run(const GD& c, const bool has_next, const GD& nx, const Ctx& e, bf16* shm, float* rs, float* rs_nxt, float* racc_) {
;     ...
;   for(int t=0;t<nt-2;t+=2){
;     LDB(B0,0,0); SCHED; LDA(At,0,0); STAGE_A(SA(1,1),brow+HALF,t+1);
;     WAIT_L(8); BAR; WAIT_L(0); MMA(0,0,At,B0); BAR; SCHED;
;     LDB(B1,0,1); STAGE_B(SB(0,0),bcol,t+2);
;     BAR; WAIT_L(0); MMA(0,1,At,B1); BAR;
;     LDA(At,0,1); STAGE_A(SA(0,0),brow,t+2);
;     BAR; WAIT_L(0); MMA(1,0,At,B0); BAR; SCHED;
;     STAGE_B(SB(0,1),bcol+HALF,t+2);
;     WAIT_V(6); BAR; MMA(1,1,At,B1); BAR;
.LBB0_326:
	ds_read_b128 v[168:171], v155
	ds_read_b128 v[172:175], v155 offset:1024
	ds_read_b128 v[190:193], v155 offset:2048
	ds_read_b128 v[194:197], v155 offset:3072
	v_add_u32_e32 v163, 0xc000, v142
	v_lshl_add_u64 v[186:187], s[6:7], 0, v[132:133]
	v_readfirstlane_b32 s3, v163
	v_add_u32_e32 v166, 0xe000, v142
	v_lshl_add_u64 v[156:157], v[186:187], 0, s[90:91]
	s_mov_b32 m0, s3
	v_lshl_add_u64 v[188:189], s[6:7], 0, v[134:135]
	v_readfirstlane_b32 s3, v166
	ds_read_b128 v[158:161], v146
	ds_read_b128 v[198:201], v146 offset:1024
	ds_read_b128 v[202:205], v145
	ds_read_b128 v[206:209], v145 offset:1024
	ds_read_b128 v[210:213], v144
	ds_read_b128 v[214:217], v144 offset:1024
	ds_read_b128 v[218:221], v143
	ds_read_b128 v[222:225], v143 offset:1024
	global_load_lds_dwordx4 v[156:157], off
	v_lshl_add_u64 v[156:157], v[188:189], 0, s[90:91]
	s_mov_b32 m0, s3
	s_nop 0
	global_load_lds_dwordx4 v[156:157], off
	s_waitcnt lgkmcnt(8)
	s_barrier
	s_waitcnt lgkmcnt(0)
	s_setprio 1
	v_mfma_f32_16x16x32_bf16 v[126:129], v[168:171], v[158:161], v[126:129]
	v_mfma_f32_16x16x32_bf16 v[122:125], v[190:193], v[158:161], v[122:125]
	v_mfma_f32_16x16x32_bf16 v[118:121], v[168:171], v[202:205], v[118:121]
	v_mfma_f32_16x16x32_bf16 v[114:117], v[190:193], v[202:205], v[114:117]
	v_mfma_f32_16x16x32_bf16 v[110:113], v[168:171], v[210:213], v[110:113]
	v_mfma_f32_16x16x32_bf16 v[106:109], v[190:193], v[210:213], v[106:109]
	v_mfma_f32_16x16x32_bf16 v[102:105], v[168:171], v[218:221], v[102:105]
	v_mfma_f32_16x16x32_bf16 v[98:101], v[190:193], v[218:221], v[98:101]
	v_mfma_f32_16x16x32_bf16 v[126:129], v[172:175], v[198:201], v[126:129]
	v_mfma_f32_16x16x32_bf16 v[122:125], v[194:197], v[198:201], v[122:125]
	v_mfma_f32_16x16x32_bf16 v[118:121], v[172:175], v[206:209], v[118:121]
	v_mfma_f32_16x16x32_bf16 v[114:117], v[194:197], v[206:209], v[114:117]
	v_mfma_f32_16x16x32_bf16 v[110:113], v[172:175], v[214:217], v[110:113]
	v_mfma_f32_16x16x32_bf16 v[106:109], v[194:197], v[214:217], v[106:109]
	v_mfma_f32_16x16x32_bf16 v[102:105], v[172:175], v[222:225], v[102:105]
	v_mfma_f32_16x16x32_bf16 v[98:101], v[194:197], v[222:225], v[98:101]
	s_setprio 0
	s_barrier
	v_add_u32_e32 v156, s33, v147
	v_lshl_add_u64 v[246:247], s[6:7], 0, v[136:137]
	v_readfirstlane_b32 s3, v156
	v_add_u32_e32 v157, 0x2000, v156
	v_lshl_add_u64 v[242:243], v[246:247], 0, s[26:27]
	s_mov_b32 m0, s3
	v_lshl_add_u64 v[248:249], s[6:7], 0, v[138:139]
	v_readfirstlane_b32 s3, v157
	ds_read_b128 v[226:229], v154
	ds_read_b128 v[230:233], v154 offset:1024
	ds_read_b128 v[234:237], v154 offset:2048
	ds_read_b128 v[238:241], v154 offset:3072
	global_load_lds_dwordx4 v[242:243], off
	v_lshl_add_u64 v[242:243], v[248:249], 0, s[26:27]
	s_mov_b32 m0, s3
	s_nop 0
	global_load_lds_dwordx4 v[242:243], off
	s_barrier
	s_waitcnt lgkmcnt(0)
	s_setprio 1
	v_mfma_f32_16x16x32_bf16 v[94:97], v[226:229], v[158:161], v[94:97]
	v_mfma_f32_16x16x32_bf16 v[90:93], v[234:237], v[158:161], v[90:93]
	v_mfma_f32_16x16x32_bf16 v[86:89], v[226:229], v[202:205], v[86:89]
	v_mfma_f32_16x16x32_bf16 v[82:85], v[234:237], v[202:205], v[82:85]
	v_mfma_f32_16x16x32_bf16 v[78:81], v[226:229], v[210:213], v[78:81]
	v_mfma_f32_16x16x32_bf16 v[74:77], v[234:237], v[210:213], v[74:77]
	v_mfma_f32_16x16x32_bf16 v[70:73], v[226:229], v[218:221], v[70:73]
	v_mfma_f32_16x16x32_bf16 v[66:69], v[234:237], v[218:221], v[66:69]
	v_mfma_f32_16x16x32_bf16 v[94:97], v[230:233], v[198:201], v[94:97]
	v_mfma_f32_16x16x32_bf16 v[90:93], v[238:241], v[198:201], v[90:93]
	v_mfma_f32_16x16x32_bf16 v[86:89], v[230:233], v[206:209], v[86:89]
	v_mfma_f32_16x16x32_bf16 v[82:85], v[238:241], v[206:209], v[82:85]
	v_mfma_f32_16x16x32_bf16 v[78:81], v[230:233], v[214:217], v[78:81]
	v_mfma_f32_16x16x32_bf16 v[74:77], v[238:241], v[214:217], v[74:77]
	v_mfma_f32_16x16x32_bf16 v[70:73], v[230:233], v[222:225], v[70:73]
	v_mfma_f32_16x16x32_bf16 v[66:69], v[238:241], v[222:225], v[66:69]
	s_setprio 0
	v_readfirstlane_b32 s3, v142
	v_lshl_add_u64 v[158:159], v[186:187], 0, s[0:1]
	s_mov_b32 m0, s3
	s_barrier
	ds_read_b128 v[198:201], v146 offset:16384
	ds_read_b128 v[202:205], v146 offset:17408
	ds_read_b128 v[206:209], v145 offset:16384
	ds_read_b128 v[210:213], v145 offset:17408
	ds_read_b128 v[214:217], v144 offset:16384
	ds_read_b128 v[218:221], v144 offset:17408
	ds_read_b128 v[222:225], v143 offset:16384
	ds_read_b128 v[242:245], v143 offset:17408
	global_load_lds_dwordx4 v[158:159], off
	v_add_u32_e32 v158, 0x2000, v142
	v_lshl_add_u64 v[160:161], v[188:189], 0, s[0:1]
	v_readfirstlane_b32 s3, v158
	s_mov_b32 m0, s3
	s_nop 0
	global_load_lds_dwordx4 v[160:161], off
	s_barrier
	s_waitcnt lgkmcnt(0)
	s_setprio 1
	v_mfma_f32_16x16x32_bf16 v[62:65], v[168:171], v[198:201], v[62:65]
	v_mfma_f32_16x16x32_bf16 v[58:61], v[190:193], v[198:201], v[58:61]
	v_mfma_f32_16x16x32_bf16 v[54:57], v[168:171], v[206:209], v[54:57]
	v_mfma_f32_16x16x32_bf16 v[50:53], v[190:193], v[206:209], v[50:53]
	v_mfma_f32_16x16x32_bf16 v[46:49], v[168:171], v[214:217], v[46:49]
	v_mfma_f32_16x16x32_bf16 v[42:45], v[190:193], v[214:217], v[42:45]
	v_mfma_f32_16x16x32_bf16 v[38:41], v[168:171], v[222:225], v[38:41]
	v_mfma_f32_16x16x32_bf16 v[34:37], v[190:193], v[222:225], v[34:37]
	v_mfma_f32_16x16x32_bf16 v[62:65], v[172:175], v[202:205], v[62:65]
	v_mfma_f32_16x16x32_bf16 v[58:61], v[194:197], v[202:205], v[58:61]
	v_mfma_f32_16x16x32_bf16 v[54:57], v[172:175], v[210:213], v[54:57]
	v_mfma_f32_16x16x32_bf16 v[50:53], v[194:197], v[210:213], v[50:53]
	v_mfma_f32_16x16x32_bf16 v[46:49], v[172:175], v[218:221], v[46:49]
	v_mfma_f32_16x16x32_bf16 v[42:45], v[194:197], v[218:221], v[42:45]
	v_mfma_f32_16x16x32_bf16 v[38:41], v[172:175], v[242:245], v[38:41]
	v_mfma_f32_16x16x32_bf16 v[34:37], v[194:197], v[242:245], v[34:37]
	s_setprio 0
	s_barrier
; #define STAGE_A(P,br,kt) STAGE_G(P,c.A,c.lda,br,(long)(kt)*c.kstr)
; #define STAGE_B(P,br,kt) STAGE_G(P,c.Bt,c.K,br,(long)(kt)*BK)
; #define LDA(dst,b,h) for(int m=0;m<4;++m)for(int k=0;k<2;++k) \
;     dst[m][k]=*reinterpret_cast<const bf16x8*>((char*)SA(b,h)+lds_byte(wr*64+m*16+fr,k*32+fq*8))
; #define LDB(dst,b,h) for(int n=0;n<2;++n)for(int k=0;k<2;++k) \
;     dst[n][k]=*reinterpret_cast<const bf16x8*>((char*)SB(b,h)+lds_byte(wc*32+n*16+fr,k*32+fq*8))
; #define MMA(ai,bj,At,Bt_) do{__builtin_amdgcn_s_setprio(1); \
;     for(int m=0;m<4;++m)for(int n=0;n<2;++n)for(int k=0;k<2;++k) \
;       acc[ai][bj][m][n]=__builtin_amdgcn_mfma_f32_16x16x32_bf16(Bt_[n][k],At[m][k],acc[ai][bj][m][n],0,0,0); \
;     __builtin_amdgcn_s_setprio(0);}while(0)
; #define WAIT_V(n) asm volatile("s_waitcnt vmcnt(" #n ")":::"memory")
; #define WAIT_L(n) asm volatile("s_waitcnt lgkmcnt(" #n ")":::"memory")
; #define BAR __builtin_amdgcn_s_barrier()
; #define SCHED __builtin_amdgcn_sched_barrier(0)
; template <int EPI>
; __device__ __forceinline__ void gemm_run(const GD& c, const bool has_next, const GD& nx, const Ctx& e, bf16* shm, float* rs, float* rs_nxt, float* racc_) {
;     ...
;     STAGE_B(SB(0,1),bcol+HALF,t+2);
;     WAIT_V(6); BAR; MMA(1,1,At,B1); BAR;
;     LDB(B0,1,0); SCHED; LDA(At,1,0); STAGE_A(SA(0,1),brow+HALF,t+2);
;     WAIT_L(8); BAR; WAIT_L(0); MMA(0,0,At,B0); BAR; SCHED;
;     LDB(B1,1,1); STAGE_B(SB(1,0),bcol,t+3);
;     BAR; WAIT_L(0); MMA(0,1,At,B1); BAR;
;     LDA(At,1,1); STAGE_A(SA(1,0),brow,t+3);
;     BAR; WAIT_L(0); MMA(1,0,At,B0); BAR; SCHED;
;     STAGE_B(SB(1,1),bcol+HALF,t+3);
	v_add_u32_e32 v159, s86, v147
	v_lshl_add_u64 v[160:161], v[246:247], 0, s[28:29]
	v_readfirstlane_b32 s3, v159
	s_mov_b32 m0, s3
	v_lshl_add_u64 v[168:169], v[248:249], 0, s[28:29]
	global_load_lds_dwordx4 v[160:161], off
	v_add_u32_e32 v160, 0x2000, v159
	s_nop 0
	v_readfirstlane_b32 s3, v160
	s_mov_b32 m0, s3
	s_nop 0
	global_load_lds_dwordx4 v[168:169], off
	s_waitcnt vmcnt(6)
	s_barrier
	s_setprio 1
	v_mfma_f32_16x16x32_bf16 v[30:33], v[226:229], v[198:201], v[30:33]
	v_mfma_f32_16x16x32_bf16 v[26:29], v[234:237], v[198:201], v[26:29]
	v_mfma_f32_16x16x32_bf16 v[22:25], v[226:229], v[206:209], v[22:25]
	v_mfma_f32_16x16x32_bf16 v[18:21], v[234:237], v[206:209], v[18:21]
	v_mfma_f32_16x16x32_bf16 v[14:17], v[226:229], v[214:217], v[14:17]
	v_mfma_f32_16x16x32_bf16 v[10:13], v[234:237], v[214:217], v[10:13]
	v_mfma_f32_16x16x32_bf16 v[6:9], v[226:229], v[222:225], v[6:9]
	v_mfma_f32_16x16x32_bf16 v[2:5], v[234:237], v[222:225], v[2:5]
	v_mfma_f32_16x16x32_bf16 v[30:33], v[230:233], v[202:205], v[30:33]
	v_mfma_f32_16x16x32_bf16 v[26:29], v[238:241], v[202:205], v[26:29]
	v_mfma_f32_16x16x32_bf16 v[22:25], v[230:233], v[210:213], v[22:25]
	v_mfma_f32_16x16x32_bf16 v[18:21], v[238:241], v[210:213], v[18:21]
	v_mfma_f32_16x16x32_bf16 v[14:17], v[230:233], v[218:221], v[14:17]
	v_mfma_f32_16x16x32_bf16 v[10:13], v[238:241], v[218:221], v[10:13]
	v_mfma_f32_16x16x32_bf16 v[6:9], v[230:233], v[242:245], v[6:9]
	v_mfma_f32_16x16x32_bf16 v[2:5], v[238:241], v[242:245], v[2:5]
	s_setprio 0
	s_barrier
	ds_read_b128 v[168:171], v150
	ds_read_b128 v[172:175], v150 offset:1024
	ds_read_b128 v[190:193], v150 offset:2048
	ds_read_b128 v[194:197], v150 offset:3072
	v_add_u32_e32 v161, 0x4000, v142
	v_add_u32_e32 v162, 0x6000, v142
	v_readfirstlane_b32 s3, v161
	v_lshl_add_u64 v[230:231], v[186:187], 0, s[76:77]
	s_mov_b32 m0, s3
	v_readfirstlane_b32 s3, v162
	ds_read_b128 v[198:201], v146 offset:32768
	ds_read_b128 v[202:205], v146 offset:33792
	ds_read_b128 v[206:209], v145 offset:32768
	ds_read_b128 v[210:213], v145 offset:33792
	ds_read_b128 v[214:217], v144 offset:32768
	ds_read_b128 v[218:221], v144 offset:33792
	ds_read_b128 v[222:225], v143 offset:32768
	ds_read_b128 v[226:229], v143 offset:33792
	global_load_lds_dwordx4 v[230:231], off
	v_lshl_add_u64 v[230:231], v[188:189], 0, s[76:77]
	s_mov_b32 m0, s3
	s_nop 0
	global_load_lds_dwordx4 v[230:231], off
	s_waitcnt lgkmcnt(8)
	s_barrier
	s_waitcnt lgkmcnt(0)
	s_setprio 1
	v_mfma_f32_16x16x32_bf16 v[126:129], v[168:171], v[198:201], v[126:129]
	v_mfma_f32_16x16x32_bf16 v[122:125], v[190:193], v[198:201], v[122:125]
	v_mfma_f32_16x16x32_bf16 v[118:121], v[168:171], v[206:209], v[118:121]
	v_mfma_f32_16x16x32_bf16 v[114:117], v[190:193], v[206:209], v[114:117]
	v_mfma_f32_16x16x32_bf16 v[110:113], v[168:171], v[214:217], v[110:113]
	v_mfma_f32_16x16x32_bf16 v[106:109], v[190:193], v[214:217], v[106:109]
	v_mfma_f32_16x16x32_bf16 v[102:105], v[168:171], v[222:225], v[102:105]
	v_mfma_f32_16x16x32_bf16 v[98:101], v[190:193], v[222:225], v[98:101]
	v_mfma_f32_16x16x32_bf16 v[126:129], v[172:175], v[202:205], v[126:129]
	v_mfma_f32_16x16x32_bf16 v[122:125], v[194:197], v[202:205], v[122:125]
	v_mfma_f32_16x16x32_bf16 v[118:121], v[172:175], v[210:213], v[118:121]
	v_mfma_f32_16x16x32_bf16 v[114:117], v[194:197], v[210:213], v[114:117]
	v_mfma_f32_16x16x32_bf16 v[110:113], v[172:175], v[218:221], v[110:113]
	v_mfma_f32_16x16x32_bf16 v[106:109], v[194:197], v[218:221], v[106:109]
	v_mfma_f32_16x16x32_bf16 v[102:105], v[172:175], v[226:229], v[102:105]
	v_mfma_f32_16x16x32_bf16 v[98:101], v[194:197], v[226:229], v[98:101]
	s_setprio 0
	s_barrier
	v_readfirstlane_b32 s3, v149
	v_add_u32_e32 v167, 0x2000, v149
	v_lshl_add_u64 v[250:251], v[246:247], 0, s[30:31]
	s_mov_b32 m0, s3
	v_readfirstlane_b32 s3, v167
	ds_read_b128 v[230:233], v148
	ds_read_b128 v[234:237], v148 offset:1024
	ds_read_b128 v[238:241], v148 offset:2048
	ds_read_b128 v[242:245], v148 offset:3072
	global_load_lds_dwordx4 v[250:251], off
	v_lshl_add_u64 v[250:251], v[248:249], 0, s[30:31]
	s_mov_b32 m0, s3
	s_nop 0
	global_load_lds_dwordx4 v[250:251], off
	s_barrier
	s_waitcnt lgkmcnt(0)
	s_setprio 1
	v_mfma_f32_16x16x32_bf16 v[94:97], v[230:233], v[198:201], v[94:97]
	v_mfma_f32_16x16x32_bf16 v[90:93], v[238:241], v[198:201], v[90:93]
	v_mfma_f32_16x16x32_bf16 v[86:89], v[230:233], v[206:209], v[86:89]
	v_mfma_f32_16x16x32_bf16 v[82:85], v[238:241], v[206:209], v[82:85]
	v_mfma_f32_16x16x32_bf16 v[78:81], v[230:233], v[214:217], v[78:81]
	v_mfma_f32_16x16x32_bf16 v[74:77], v[238:241], v[214:217], v[74:77]
	v_mfma_f32_16x16x32_bf16 v[70:73], v[230:233], v[222:225], v[70:73]
	v_mfma_f32_16x16x32_bf16 v[66:69], v[238:241], v[222:225], v[66:69]
	v_mfma_f32_16x16x32_bf16 v[94:97], v[234:237], v[202:205], v[94:97]
	v_mfma_f32_16x16x32_bf16 v[90:93], v[242:245], v[202:205], v[90:93]
	v_mfma_f32_16x16x32_bf16 v[86:89], v[234:237], v[210:213], v[86:89]
	v_mfma_f32_16x16x32_bf16 v[82:85], v[242:245], v[210:213], v[82:85]
	v_mfma_f32_16x16x32_bf16 v[78:81], v[234:237], v[218:221], v[78:81]
	v_mfma_f32_16x16x32_bf16 v[74:77], v[242:245], v[218:221], v[74:77]
	v_mfma_f32_16x16x32_bf16 v[70:73], v[234:237], v[226:229], v[70:73]
	v_mfma_f32_16x16x32_bf16 v[66:69], v[242:245], v[226:229], v[66:69]
	s_setprio 0
	v_readfirstlane_b32 s3, v151
	v_lshl_add_u64 v[186:187], v[186:187], 0, s[74:75]
	s_mov_b32 m0, s3
	v_readfirstlane_b32 s3, v152
	s_barrier
; #define STAGE_A(P,br,kt) STAGE_G(P,c.A,c.lda,br,(long)(kt)*c.kstr)
; #define STAGE_B(P,br,kt) STAGE_G(P,c.Bt,c.K,br,(long)(kt)*BK)
; #define LDA(dst,b,h) for(int m=0;m<4;++m)for(int k=0;k<2;++k) \
;     dst[m][k]=*reinterpret_cast<const bf16x8*>((char*)SA(b,h)+lds_byte(wr*64+m*16+fr,k*32+fq*8))
; #define LDB(dst,b,h) for(int n=0;n<2;++n)for(int k=0;k<2;++k) \
;     dst[n][k]=*reinterpret_cast<const bf16x8*>((char*)SB(b,h)+lds_byte(wc*32+n*16+fr,k*32+fq*8))
; #define MMA(ai,bj,At,Bt_) do{__builtin_amdgcn_s_setprio(1); \
;     for(int m=0;m<4;++m)for(int n=0;n<2;++n)for(int k=0;k<2;++k) \
;       acc[ai][bj][m][n]=__builtin_amdgcn_mfma_f32_16x16x32_bf16(Bt_[n][k],At[m][k],acc[ai][bj][m][n],0,0,0); \
;     __builtin_amdgcn_s_setprio(0);}while(0)
; #define WAIT_V(n) asm volatile("s_waitcnt vmcnt(" #n ")":::"memory")
; #define WAIT_L(n) asm volatile("s_waitcnt lgkmcnt(" #n ")":::"memory")
; #define BAR __builtin_amdgcn_s_barrier()
; #define SCHED __builtin_amdgcn_sched_barrier(0)
; template <int EPI>
; __device__ __forceinline__ void gemm_run(const GD& c, const bool has_next, const GD& nx, const Ctx& e, bf16* shm, float* rs, float* rs_nxt, float* racc_) {
;     ...
;     LDB(B1,1,1); STAGE_B(SB(1,0),bcol,t+3);
;     BAR; WAIT_L(0); MMA(0,1,At,B1); BAR;
;     LDA(At,1,1); STAGE_A(SA(1,0),brow,t+3);
;     BAR; WAIT_L(0); MMA(1,0,At,B0); BAR; SCHED;
;     STAGE_B(SB(1,1),bcol+HALF,t+3);
;     WAIT_V(6); BAR; MMA(1,1,At,B1); BAR;
;   }
;   { LDB(B0,0,0); LDA(At,0,0); STAGE_A(SA(1,1),brow+HALF,nt-1);
;     BAR; WAIT_L(0); MMA(0,0,At,B0); BAR;
	ds_read_b128 v[198:201], v146 offset:49152
	ds_read_b128 v[202:205], v146 offset:50176
	ds_read_b128 v[206:209], v145 offset:49152
	ds_read_b128 v[210:213], v145 offset:50176
	ds_read_b128 v[214:217], v144 offset:49152
	ds_read_b128 v[218:221], v144 offset:50176
	ds_read_b128 v[222:225], v143 offset:49152
	ds_read_b128 v[226:229], v143 offset:50176
	global_load_lds_dwordx4 v[186:187], off
	v_lshl_add_u64 v[186:187], v[188:189], 0, s[74:75]
	s_mov_b32 m0, s3
	s_nop 0
	global_load_lds_dwordx4 v[186:187], off
	s_barrier
	s_waitcnt lgkmcnt(0)
	s_setprio 1
	v_mfma_f32_16x16x32_bf16 v[62:65], v[168:171], v[198:201], v[62:65]
	v_mfma_f32_16x16x32_bf16 v[58:61], v[190:193], v[198:201], v[58:61]
	v_mfma_f32_16x16x32_bf16 v[54:57], v[168:171], v[206:209], v[54:57]
	v_mfma_f32_16x16x32_bf16 v[50:53], v[190:193], v[206:209], v[50:53]
	v_mfma_f32_16x16x32_bf16 v[46:49], v[168:171], v[214:217], v[46:49]
	v_mfma_f32_16x16x32_bf16 v[42:45], v[190:193], v[214:217], v[42:45]
	v_mfma_f32_16x16x32_bf16 v[38:41], v[168:171], v[222:225], v[38:41]
	v_mfma_f32_16x16x32_bf16 v[34:37], v[190:193], v[222:225], v[34:37]
	v_mfma_f32_16x16x32_bf16 v[62:65], v[172:175], v[202:205], v[62:65]
	v_mfma_f32_16x16x32_bf16 v[58:61], v[194:197], v[202:205], v[58:61]
	v_mfma_f32_16x16x32_bf16 v[54:57], v[172:175], v[210:213], v[54:57]
	v_mfma_f32_16x16x32_bf16 v[50:53], v[194:197], v[210:213], v[50:53]
	v_mfma_f32_16x16x32_bf16 v[46:49], v[172:175], v[218:221], v[46:49]
	v_mfma_f32_16x16x32_bf16 v[42:45], v[194:197], v[218:221], v[42:45]
	v_mfma_f32_16x16x32_bf16 v[38:41], v[172:175], v[226:229], v[38:41]
	v_mfma_f32_16x16x32_bf16 v[34:37], v[194:197], v[226:229], v[34:37]
	s_setprio 0
	s_barrier
	v_readfirstlane_b32 s3, v153
	v_add_u32_e32 v167, 0x2000, v153
	v_lshl_add_u64 v[168:169], v[246:247], 0, s[34:35]
	s_mov_b32 m0, s3
	v_readfirstlane_b32 s3, v167
	global_load_lds_dwordx4 v[168:169], off
	v_lshl_add_u64 v[168:169], v[248:249], 0, s[34:35]
	s_mov_b32 m0, s3
	s_nop 0
	global_load_lds_dwordx4 v[168:169], off
	s_waitcnt vmcnt(6)
	s_barrier
	s_setprio 1
	v_mfma_f32_16x16x32_bf16 v[30:33], v[230:233], v[198:201], v[30:33]
	v_mfma_f32_16x16x32_bf16 v[26:29], v[238:241], v[198:201], v[26:29]
	v_mfma_f32_16x16x32_bf16 v[22:25], v[230:233], v[206:209], v[22:25]
	v_mfma_f32_16x16x32_bf16 v[18:21], v[238:241], v[206:209], v[18:21]
	v_mfma_f32_16x16x32_bf16 v[14:17], v[230:233], v[214:217], v[14:17]
	v_mfma_f32_16x16x32_bf16 v[10:13], v[238:241], v[214:217], v[10:13]
	v_mfma_f32_16x16x32_bf16 v[6:9], v[230:233], v[222:225], v[6:9]
	v_mfma_f32_16x16x32_bf16 v[2:5], v[238:241], v[222:225], v[2:5]
	v_mfma_f32_16x16x32_bf16 v[30:33], v[234:237], v[202:205], v[30:33]
	v_mfma_f32_16x16x32_bf16 v[26:29], v[242:245], v[202:205], v[26:29]
	v_mfma_f32_16x16x32_bf16 v[22:25], v[234:237], v[210:213], v[22:25]
	v_mfma_f32_16x16x32_bf16 v[18:21], v[242:245], v[210:213], v[18:21]
	v_mfma_f32_16x16x32_bf16 v[14:17], v[234:237], v[218:221], v[14:17]
	v_mfma_f32_16x16x32_bf16 v[10:13], v[242:245], v[218:221], v[10:13]
	v_mfma_f32_16x16x32_bf16 v[6:9], v[234:237], v[226:229], v[6:9]
	v_mfma_f32_16x16x32_bf16 v[2:5], v[242:245], v[226:229], v[2:5]
	s_setprio 0
	s_add_i32 s2, s2, 2
	v_lshl_add_u64 v[132:133], v[132:133], 0, s[88:89]
	v_lshl_add_u64 v[134:135], v[134:135], 0, s[88:89]
	v_lshl_add_u64 v[136:137], v[136:137], 0, s[88:89]
	s_cmp_lt_u32 s2, 38
	v_lshl_add_u64 v[138:139], v[138:139], 0, s[88:89]
	s_barrier
	s_cbranch_scc1 .LBB0_326
	s_or_b32 s2, s15, 0x80
	s_mul_hi_i32 s3, s2, 0x1500
	s_mulk_i32 s2, 0x1500
	s_add_u32 s2, s21, s2
	s_addc_u32 s3, s22, s3
	v_readfirstlane_b32 s26, v163
	v_lshl_add_u64 v[152:153], s[2:3], 0, v[0:1]
	s_mov_b32 m0, s26
	ds_read_b128 v[132:135], v155
	ds_read_b128 v[136:139], v155 offset:1024
	ds_read_b128 v[168:171], v155 offset:2048
	ds_read_b128 v[172:175], v155 offset:3072
	ds_read_b128 v[190:193], v146
	ds_read_b128 v[194:197], v146 offset:1024
	ds_read_b128 v[198:201], v145
	ds_read_b128 v[202:205], v145 offset:1024
	ds_read_b128 v[206:209], v144
	ds_read_b128 v[210:213], v144 offset:1024
	ds_read_b128 v[214:217], v143
	ds_read_b128 v[218:221], v143 offset:1024
	global_load_lds_dwordx4 v[152:153], off
	v_lshl_add_u64 v[152:153], s[2:3], 0, v[130:131]
	v_readfirstlane_b32 s2, v166
	s_mov_b32 m0, s2
	s_nop 0
	global_load_lds_dwordx4 v[152:153], off
	s_barrier
	s_waitcnt lgkmcnt(0)
	s_setprio 1
	v_mfma_f32_16x16x32_bf16 v[126:129], v[132:135], v[190:193], v[126:129]
	v_mfma_f32_16x16x32_bf16 v[122:125], v[168:171], v[190:193], v[122:125]
	v_mfma_f32_16x16x32_bf16 v[118:121], v[132:135], v[198:201], v[118:121]
	v_mfma_f32_16x16x32_bf16 v[114:117], v[168:171], v[198:201], v[114:117]
	v_mfma_f32_16x16x32_bf16 v[102:105], v[132:135], v[214:217], v[102:105]
	v_mfma_f32_16x16x32_bf16 v[98:101], v[168:171], v[214:217], v[98:101]
	v_mfma_f32_16x16x32_bf16 v[126:129], v[136:139], v[194:197], v[126:129]
	v_mfma_f32_16x16x32_bf16 v[122:125], v[172:175], v[194:197], v[122:125]
	v_mfma_f32_16x16x32_bf16 v[118:121], v[136:139], v[202:205], v[118:121]
	v_mfma_f32_16x16x32_bf16 v[114:117], v[172:175], v[202:205], v[114:117]
	v_mfma_f32_16x16x32_bf16 v[110:113], v[132:135], v[206:209], v[110:113]
	v_mfma_f32_16x16x32_bf16 v[106:109], v[168:171], v[206:209], v[106:109]
	v_mfma_f32_16x16x32_bf16 v[102:105], v[136:139], v[218:221], v[102:105]
	v_mfma_f32_16x16x32_bf16 v[98:101], v[172:175], v[218:221], v[98:101]
	v_mfma_f32_16x16x32_bf16 v[222:225], v[136:139], v[210:213], v[110:113]
	v_mfma_f32_16x16x32_bf16 v[226:229], v[172:175], v[210:213], v[106:109]
	s_setprio 0
	s_barrier
	s_nop 1
	ds_read_b128 v[106:109], v154
	ds_read_b128 v[110:113], v154 offset:1024
	ds_read_b128 v[230:233], v154 offset:2048
	ds_read_b128 v[152:155], v154 offset:3072
	s_barrier
; #define STAGE_A(P,br,kt) STAGE_G(P,c.A,c.lda,br,(long)(kt)*c.kstr)
; #define LDA(dst,b,h) for(int m=0;m<4;++m)for(int k=0;k<2;++k) \
;     dst[m][k]=*reinterpret_cast<const bf16x8*>((char*)SA(b,h)+lds_byte(wr*64+m*16+fr,k*32+fq*8))
; #define LDB(dst,b,h) for(int n=0;n<2;++n)for(int k=0;k<2;++k) \
;     dst[n][k]=*reinterpret_cast<const bf16x8*>((char*)SB(b,h)+lds_byte(wc*32+n*16+fr,k*32+fq*8))
; #define MMA(ai,bj,At,Bt_) do{__builtin_amdgcn_s_setprio(1); \
;     for(int m=0;m<4;++m)for(int n=0;n<2;++n)for(int k=0;k<2;++k) \
;       acc[ai][bj][m][n]=__builtin_amdgcn_mfma_f32_16x16x32_bf16(Bt_[n][k],At[m][k],acc[ai][bj][m][n],0,0,0); \
;     __builtin_amdgcn_s_setprio(0);}while(0)
; #define WAIT_V(n) asm volatile("s_waitcnt vmcnt(" #n ")":::"memory")
; #define WAIT_L(n) asm volatile("s_waitcnt lgkmcnt(" #n ")":::"memory")
; #define BAR __builtin_amdgcn_s_barrier()
; template <int EPI>
; __device__ __forceinline__ void gemm_run(const GD& c, const bool has_next, const GD& nx, const Ctx& e, bf16* shm, float* rs, float* rs_nxt, float* racc_) {
;     ...
;   { LDB(B0,0,0); LDA(At,0,0); STAGE_A(SA(1,1),brow+HALF,nt-1);
;     BAR; WAIT_L(0); MMA(0,0,At,B0); BAR;
;     LDB(B1,0,1); BAR; WAIT_L(0); MMA(0,1,At,B1); BAR;
;     LDA(At,0,1); WAIT_V(4); BAR; WAIT_L(0); MMA(1,0,At,B0); MMA(1,1,At,B1); BAR; }
;   { LDB(B0,1,0); LDA(At,1,0); WAIT_V(2); BAR; WAIT_L(0); MMA(0,0,At,B0); BAR;
	s_waitcnt lgkmcnt(0)
	s_setprio 1
	v_mfma_f32_16x16x32_bf16 v[86:89], v[106:109], v[198:201], v[86:89]
	v_mfma_f32_16x16x32_bf16 v[82:85], v[230:233], v[198:201], v[82:85]
	v_mfma_f32_16x16x32_bf16 v[70:73], v[106:109], v[214:217], v[70:73]
	v_mfma_f32_16x16x32_bf16 v[66:69], v[230:233], v[214:217], v[66:69]
	v_mfma_f32_16x16x32_bf16 v[94:97], v[106:109], v[190:193], v[94:97]
	v_mfma_f32_16x16x32_bf16 v[90:93], v[230:233], v[190:193], v[90:93]
	v_mfma_f32_16x16x32_bf16 v[86:89], v[110:113], v[202:205], v[86:89]
	v_mfma_f32_16x16x32_bf16 v[82:85], v[152:155], v[202:205], v[82:85]
	v_mfma_f32_16x16x32_bf16 v[78:81], v[106:109], v[206:209], v[78:81]
	v_mfma_f32_16x16x32_bf16 v[74:77], v[230:233], v[206:209], v[74:77]
	v_mfma_f32_16x16x32_bf16 v[70:73], v[110:113], v[218:221], v[70:73]
	v_mfma_f32_16x16x32_bf16 v[66:69], v[152:155], v[218:221], v[66:69]
	v_mfma_f32_16x16x32_bf16 v[234:237], v[110:113], v[194:197], v[94:97]
	v_mfma_f32_16x16x32_bf16 v[190:193], v[152:155], v[194:197], v[90:93]
	v_mfma_f32_16x16x32_bf16 v[194:197], v[110:113], v[210:213], v[78:81]
	v_mfma_f32_16x16x32_bf16 v[198:201], v[152:155], v[210:213], v[74:77]
	s_setprio 0
	s_barrier
	s_nop 0
	ds_read_b128 v[74:77], v146 offset:16384
	ds_read_b128 v[78:81], v146 offset:17408
	ds_read_b128 v[90:93], v145 offset:16384
	ds_read_b128 v[94:97], v145 offset:17408
	ds_read_b128 v[202:205], v144 offset:16384
	ds_read_b128 v[206:209], v144 offset:17408
	ds_read_b128 v[210:213], v143 offset:16384
	ds_read_b128 v[214:217], v143 offset:17408
	s_waitcnt vmcnt(4)
	s_barrier
	s_waitcnt lgkmcnt(0)
	s_setprio 1
	v_mfma_f32_16x16x32_bf16 v[62:65], v[132:135], v[74:77], v[62:65]
	v_mfma_f32_16x16x32_bf16 v[58:61], v[168:171], v[74:77], v[58:61]
	v_mfma_f32_16x16x32_bf16 v[54:57], v[132:135], v[90:93], v[54:57]
	v_mfma_f32_16x16x32_bf16 v[50:53], v[168:171], v[90:93], v[50:53]
	v_mfma_f32_16x16x32_bf16 v[38:41], v[132:135], v[210:213], v[38:41]
	v_mfma_f32_16x16x32_bf16 v[34:37], v[168:171], v[210:213], v[34:37]
	v_mfma_f32_16x16x32_bf16 v[62:65], v[136:139], v[78:81], v[62:65]
	v_mfma_f32_16x16x32_bf16 v[58:61], v[172:175], v[78:81], v[58:61]
	v_mfma_f32_16x16x32_bf16 v[54:57], v[136:139], v[94:97], v[54:57]
	v_mfma_f32_16x16x32_bf16 v[50:53], v[172:175], v[94:97], v[50:53]
	v_mfma_f32_16x16x32_bf16 v[46:49], v[132:135], v[202:205], v[46:49]
	v_mfma_f32_16x16x32_bf16 v[42:45], v[168:171], v[202:205], v[42:45]
	v_mfma_f32_16x16x32_bf16 v[38:41], v[136:139], v[214:217], v[38:41]
	v_mfma_f32_16x16x32_bf16 v[34:37], v[172:175], v[214:217], v[34:37]
	v_mfma_f32_16x16x32_bf16 v[218:221], v[136:139], v[206:209], v[46:49]
	v_mfma_f32_16x16x32_bf16 v[238:241], v[172:175], v[206:209], v[42:45]
	s_setprio 0
	s_setprio 1
	v_mfma_f32_16x16x32_bf16 v[22:25], v[106:109], v[90:93], v[22:25]
	v_mfma_f32_16x16x32_bf16 v[18:21], v[230:233], v[90:93], v[18:21]
	v_mfma_f32_16x16x32_bf16 v[6:9], v[106:109], v[210:213], v[6:9]
	v_mfma_f32_16x16x32_bf16 v[2:5], v[230:233], v[210:213], v[2:5]
	v_mfma_f32_16x16x32_bf16 v[30:33], v[106:109], v[74:77], v[30:33]
	v_mfma_f32_16x16x32_bf16 v[26:29], v[230:233], v[74:77], v[26:29]
	v_mfma_f32_16x16x32_bf16 v[22:25], v[110:113], v[94:97], v[22:25]
	v_mfma_f32_16x16x32_bf16 v[18:21], v[152:155], v[94:97], v[18:21]
	v_mfma_f32_16x16x32_bf16 v[14:17], v[106:109], v[202:205], v[14:17]
	v_mfma_f32_16x16x32_bf16 v[10:13], v[230:233], v[202:205], v[10:13]
	v_mfma_f32_16x16x32_bf16 v[6:9], v[110:113], v[214:217], v[6:9]
	v_mfma_f32_16x16x32_bf16 v[2:5], v[152:155], v[214:217], v[2:5]
	v_mfma_f32_16x16x32_bf16 v[132:135], v[110:113], v[78:81], v[30:33]
	v_mfma_f32_16x16x32_bf16 v[136:139], v[152:155], v[78:81], v[26:29]
	v_mfma_f32_16x16x32_bf16 v[166:169], v[110:113], v[206:209], v[14:17]
	v_mfma_f32_16x16x32_bf16 v[170:173], v[152:155], v[206:209], v[10:13]
	s_setprio 0
	s_barrier
	s_nop 0
	ds_read_b128 v[10:13], v150
	ds_read_b128 v[14:17], v150 offset:1024
	ds_read_b128 v[152:155], v150 offset:2048
	ds_read_b128 v[202:205], v150 offset:3072
	ds_read_b128 v[26:29], v146 offset:32768
	ds_read_b128 v[30:33], v146 offset:33792
	ds_read_b128 v[42:45], v145 offset:32768
	ds_read_b128 v[46:49], v145 offset:33792
	ds_read_b128 v[206:209], v144 offset:32768
	ds_read_b128 v[210:213], v144 offset:33792
	ds_read_b128 v[214:217], v143 offset:32768
	ds_read_b128 v[230:233], v143 offset:33792
	s_waitcnt vmcnt(2)
	s_barrier
; #define LDA(dst,b,h) for(int m=0;m<4;++m)for(int k=0;k<2;++k) \
;     dst[m][k]=*reinterpret_cast<const bf16x8*>((char*)SA(b,h)+lds_byte(wr*64+m*16+fr,k*32+fq*8))
; #define LDB(dst,b,h) for(int n=0;n<2;++n)for(int k=0;k<2;++k) \
;     dst[n][k]=*reinterpret_cast<const bf16x8*>((char*)SB(b,h)+lds_byte(wc*32+n*16+fr,k*32+fq*8))
; #define MMA(ai,bj,At,Bt_) do{__builtin_amdgcn_s_setprio(1); \
;     for(int m=0;m<4;++m)for(int n=0;n<2;++n)for(int k=0;k<2;++k) \
;       acc[ai][bj][m][n]=__builtin_amdgcn_mfma_f32_16x16x32_bf16(Bt_[n][k],At[m][k],acc[ai][bj][m][n],0,0,0); \
;     __builtin_amdgcn_s_setprio(0);}while(0)
; #define WAIT_V(n) asm volatile("s_waitcnt vmcnt(" #n ")":::"memory")
; #define WAIT_L(n) asm volatile("s_waitcnt lgkmcnt(" #n ")":::"memory")
; #define BAR __builtin_amdgcn_s_barrier()
; template <int EPI>
; __device__ __forceinline__ void gemm_run(const GD& c, const bool has_next, const GD& nx, const Ctx& e, bf16* shm, float* rs, float* rs_nxt, float* racc_) {
;     ...
;   { LDB(B0,1,0); LDA(At,1,0); WAIT_V(2); BAR; WAIT_L(0); MMA(0,0,At,B0); BAR;
;     LDB(B1,1,1); WAIT_V(0); BAR; WAIT_L(0); MMA(0,1,At,B1); BAR;
;     LDA(At,1,1); BAR; WAIT_L(0); MMA(1,0,At,B0); MMA(1,1,At,B1); BAR; }
;   if(wr==0)BAR;
	s_waitcnt lgkmcnt(0)
	s_setprio 1
	v_mfma_f32_16x16x32_bf16 v[74:77], v[10:13], v[26:29], v[126:129]
	v_mfma_f32_16x16x32_bf16 v[126:129], v[14:17], v[30:33], v[74:77]
	v_mfma_f32_16x16x32_bf16 v[74:77], v[152:155], v[26:29], v[122:125]
	v_mfma_f32_16x16x32_bf16 v[122:125], v[202:205], v[30:33], v[74:77]
	v_mfma_f32_16x16x32_bf16 v[74:77], v[10:13], v[42:45], v[118:121]
	v_mfma_f32_16x16x32_bf16 v[110:113], v[14:17], v[46:49], v[74:77]
	v_mfma_f32_16x16x32_bf16 v[74:77], v[152:155], v[42:45], v[114:117]
	v_mfma_f32_16x16x32_bf16 v[106:109], v[202:205], v[46:49], v[74:77]
	v_mfma_f32_16x16x32_bf16 v[74:77], v[10:13], v[206:209], v[222:225]
	v_mfma_f32_16x16x32_bf16 v[94:97], v[14:17], v[210:213], v[74:77]
	v_mfma_f32_16x16x32_bf16 v[74:77], v[152:155], v[206:209], v[226:229]
	v_mfma_f32_16x16x32_bf16 v[90:93], v[202:205], v[210:213], v[74:77]
	v_mfma_f32_16x16x32_bf16 v[74:77], v[10:13], v[214:217], v[102:105]
	v_mfma_f32_16x16x32_bf16 v[78:81], v[14:17], v[230:233], v[74:77]
	v_mfma_f32_16x16x32_bf16 v[74:77], v[152:155], v[214:217], v[98:101]
	v_mfma_f32_16x16x32_bf16 v[74:77], v[202:205], v[230:233], v[74:77]
	s_setprio 0
	s_barrier
	ds_read_b128 v[222:225], v148
	ds_read_b128 v[226:229], v148 offset:1024
	ds_read_b128 v[242:245], v148 offset:2048
	ds_read_b128 v[148:151], v148 offset:3072
	s_waitcnt vmcnt(0)
	s_barrier
	s_waitcnt lgkmcnt(0)
	s_setprio 1
	v_mfma_f32_16x16x32_bf16 v[98:101], v[222:225], v[26:29], v[234:237]
	v_mfma_f32_16x16x32_bf16 v[26:29], v[242:245], v[26:29], v[190:193]
	v_mfma_f32_16x16x32_bf16 v[114:117], v[148:151], v[30:33], v[26:29]
	v_mfma_f32_16x16x32_bf16 v[26:29], v[222:225], v[42:45], v[86:89]
	v_mfma_f32_16x16x32_bf16 v[102:105], v[226:229], v[46:49], v[26:29]
	v_mfma_f32_16x16x32_bf16 v[26:29], v[242:245], v[42:45], v[82:85]
	v_mfma_f32_16x16x32_bf16 v[118:121], v[226:229], v[30:33], v[98:101]
	v_mfma_f32_16x16x32_bf16 v[98:101], v[148:151], v[46:49], v[26:29]
	v_mfma_f32_16x16x32_bf16 v[26:29], v[222:225], v[206:209], v[194:197]
	v_mfma_f32_16x16x32_bf16 v[86:89], v[226:229], v[210:213], v[26:29]
	v_mfma_f32_16x16x32_bf16 v[26:29], v[242:245], v[206:209], v[198:201]
	v_mfma_f32_16x16x32_bf16 v[82:85], v[148:151], v[210:213], v[26:29]
	v_mfma_f32_16x16x32_bf16 v[26:29], v[222:225], v[214:217], v[70:73]
	v_mfma_f32_16x16x32_bf16 v[70:73], v[226:229], v[230:233], v[26:29]
	v_mfma_f32_16x16x32_bf16 v[26:29], v[242:245], v[214:217], v[66:69]
	v_mfma_f32_16x16x32_bf16 v[66:69], v[148:151], v[230:233], v[26:29]
	s_setprio 0
	s_barrier
	ds_read_b128 v[190:193], v146 offset:49152
	ds_read_b128 v[194:197], v146 offset:50176
	ds_read_b128 v[198:201], v145 offset:49152
	ds_read_b128 v[206:209], v145 offset:50176
	ds_read_b128 v[210:213], v144 offset:49152
	ds_read_b128 v[144:147], v144 offset:50176
	ds_read_b128 v[214:217], v143 offset:49152
	ds_read_b128 v[230:233], v143 offset:50176
	s_barrier
	s_waitcnt lgkmcnt(0)
	s_setprio 1
	v_mfma_f32_16x16x32_bf16 v[26:29], v[10:13], v[190:193], v[62:65]
	v_mfma_f32_16x16x32_bf16 v[62:65], v[14:17], v[194:197], v[26:29]
	v_mfma_f32_16x16x32_bf16 v[26:29], v[152:155], v[190:193], v[58:61]
	v_mfma_f32_16x16x32_bf16 v[58:61], v[202:205], v[194:197], v[26:29]
	v_mfma_f32_16x16x32_bf16 v[26:29], v[10:13], v[198:201], v[54:57]
	v_mfma_f32_16x16x32_bf16 v[46:49], v[14:17], v[206:209], v[26:29]
	v_mfma_f32_16x16x32_bf16 v[26:29], v[152:155], v[198:201], v[50:53]
	v_mfma_f32_16x16x32_bf16 v[42:45], v[202:205], v[206:209], v[26:29]
	v_mfma_f32_16x16x32_bf16 v[26:29], v[10:13], v[210:213], v[218:221]
	v_mfma_f32_16x16x32_bf16 v[10:13], v[10:13], v[214:217], v[38:41]
	v_mfma_f32_16x16x32_bf16 v[30:33], v[14:17], v[144:147], v[26:29]
	v_mfma_f32_16x16x32_bf16 v[26:29], v[152:155], v[210:213], v[238:241]
	v_mfma_f32_16x16x32_bf16 v[14:17], v[14:17], v[230:233], v[10:13]
	v_mfma_f32_16x16x32_bf16 v[10:13], v[152:155], v[214:217], v[34:37]
	v_mfma_f32_16x16x32_bf16 v[26:29], v[202:205], v[144:147], v[26:29]
	v_mfma_f32_16x16x32_bf16 v[10:13], v[202:205], v[230:233], v[10:13]
	s_setprio 0
	s_setprio 1
	v_mfma_f32_16x16x32_bf16 v[34:37], v[222:225], v[190:193], v[132:135]
	v_mfma_f32_16x16x32_bf16 v[54:57], v[226:229], v[194:197], v[34:37]
	v_mfma_f32_16x16x32_bf16 v[34:37], v[242:245], v[190:193], v[136:139]
	v_mfma_f32_16x16x32_bf16 v[18:21], v[242:245], v[198:201], v[18:21]
	v_mfma_f32_16x16x32_bf16 v[50:53], v[148:151], v[194:197], v[34:37]
	v_mfma_f32_16x16x32_bf16 v[22:25], v[222:225], v[198:201], v[22:25]
	v_mfma_f32_16x16x32_bf16 v[34:37], v[148:151], v[206:209], v[18:21]
	v_mfma_f32_16x16x32_bf16 v[18:21], v[222:225], v[210:213], v[166:169]
	v_mfma_f32_16x16x32_bf16 v[38:41], v[226:229], v[206:209], v[22:25]
	v_mfma_f32_16x16x32_bf16 v[22:25], v[226:229], v[144:147], v[18:21]
	v_mfma_f32_16x16x32_bf16 v[18:21], v[242:245], v[210:213], v[170:173]
	v_mfma_f32_16x16x32_bf16 v[6:9], v[222:225], v[214:217], v[6:9]
	v_mfma_f32_16x16x32_bf16 v[2:5], v[242:245], v[214:217], v[2:5]
	v_mfma_f32_16x16x32_bf16 v[18:21], v[148:151], v[144:147], v[18:21]
	v_mfma_f32_16x16x32_bf16 v[6:9], v[226:229], v[230:233], v[6:9]
	v_mfma_f32_16x16x32_bf16 v[2:5], v[148:151], v[230:233], v[2:5]
	s_setprio 0
	v_cmp_gt_u32_e32 vcc, s96, v141
	s_barrier
	s_and_saveexec_b64 s[2:3], vcc
	s_cbranch_execz .LBB0_329
	s_barrier

; #define STAGE_A(P,br,kt) STAGE_G(P,c.A,c.lda,br,(long)(kt)*c.kstr)
; #define STAGE_B(P,br,kt) STAGE_G(P,c.Bt,c.K,br,(long)(kt)*BK)
; #define LDA(dst,b,h) for(int m=0;m<4;++m)for(int k=0;k<2;++k) \
;     dst[m][k]=*reinterpret_cast<const bf16x8*>((char*)SA(b,h)+lds_byte(wr*64+m*16+fr,k*32+fq*8))
; #define LDB(dst,b,h) for(int n=0;n<2;++n)for(int k=0;k<2;++k) \
;     dst[n][k]=*reinterpret_cast<const bf16x8*>((char*)SB(b,h)+lds_byte(wc*32+n*16+fr,k*32+fq*8))
; #define MMA(ai,bj,At,Bt_) do{__builtin_amdgcn_s_setprio(1); \
;     for(int m=0;m<4;++m)for(int n=0;n<2;++n)for(int k=0;k<2;++k) \
;       acc[ai][bj][m][n]=__builtin_amdgcn_mfma_f32_16x16x32_bf16(Bt_[n][k],At[m][k],acc[ai][bj][m][n],0,0,0); \
;     __builtin_amdgcn_s_setprio(0);}while(0)
; #define WAIT_V(n) asm volatile("s_waitcnt vmcnt(" #n ")":::"memory")
; #define WAIT_L(n) asm volatile("s_waitcnt lgkmcnt(" #n ")":::"memory")
; #define BAR __builtin_amdgcn_s_barrier()
; #define SCHED __builtin_amdgcn_sched_barrier(0)
; template <int EPI>
; __device__ __forceinline__ void gemm_run(const GD& c, const bool has_next, const GD& nx, const Ctx& e, bf16* shm, float* rs, float* rs_nxt, float* racc_) {
;     ...
;   for(int t=0;t<nt-2;t+=2){
;     LDB(B0,0,0); SCHED; LDA(At,0,0); STAGE_A(SA(1,1),brow+HALF,t+1);
;     WAIT_L(8); BAR; WAIT_L(0); MMA(0,0,At,B0); BAR; SCHED;
;     LDB(B1,0,1); STAGE_B(SB(0,0),bcol,t+2);
;     BAR; WAIT_L(0); MMA(0,1,At,B1); BAR;
;     LDA(At,0,1); STAGE_A(SA(0,0),brow,t+2);
;     BAR; WAIT_L(0); MMA(1,0,At,B0); BAR; SCHED;
;     STAGE_B(SB(0,1),bcol+HALF,t+2);
;     WAIT_V(6); BAR; MMA(1,1,At,B1); BAR;
.LBB0_357:
	ds_read_b128 v[158:161], v155
	ds_read_b128 v[166:169], v155 offset:1024
	ds_read_b128 v[170:173], v155 offset:2048
	ds_read_b128 v[190:193], v155 offset:3072
	v_add_u32_e32 v156, 0xc000, v150
	v_lshl_add_u64 v[162:163], v[132:133], 0, s[4:5]
	v_readfirstlane_b32 s12, v156
	v_lshl_add_u64 v[174:175], v[162:163], 0, s[90:91]
	s_mov_b32 m0, s12
	v_add_u32_e32 v157, 0xe000, v150
	ds_read_b128 v[194:197], v145
	ds_read_b128 v[198:201], v145 offset:1024
	ds_read_b128 v[202:205], v144
	ds_read_b128 v[206:209], v144 offset:1024
	ds_read_b128 v[210:213], v143
	ds_read_b128 v[214:217], v143 offset:1024
	ds_read_b128 v[218:221], v142
	ds_read_b128 v[222:225], v142 offset:1024
	global_load_lds_dwordx4 v[174:175], off
	v_lshl_add_u64 v[174:175], v[134:135], 0, s[4:5]
	v_readfirstlane_b32 s12, v157
	v_lshl_add_u64 v[186:187], v[174:175], 0, s[90:91]
	s_mov_b32 m0, s12
	s_nop 0
	global_load_lds_dwordx4 v[186:187], off
	s_waitcnt lgkmcnt(8)
	s_barrier
	s_waitcnt lgkmcnt(0)
	s_setprio 1
	v_mfma_f32_16x16x32_bf16 v[126:129], v[158:161], v[194:197], v[126:129]
	v_mfma_f32_16x16x32_bf16 v[122:125], v[170:173], v[194:197], v[122:125]
	v_mfma_f32_16x16x32_bf16 v[118:121], v[158:161], v[202:205], v[118:121]
	v_mfma_f32_16x16x32_bf16 v[114:117], v[170:173], v[202:205], v[114:117]
	v_mfma_f32_16x16x32_bf16 v[110:113], v[158:161], v[210:213], v[110:113]
	v_mfma_f32_16x16x32_bf16 v[106:109], v[170:173], v[210:213], v[106:109]
	v_mfma_f32_16x16x32_bf16 v[102:105], v[158:161], v[218:221], v[102:105]
	v_mfma_f32_16x16x32_bf16 v[98:101], v[170:173], v[218:221], v[98:101]
	v_mfma_f32_16x16x32_bf16 v[126:129], v[166:169], v[198:201], v[126:129]
	v_mfma_f32_16x16x32_bf16 v[122:125], v[190:193], v[198:201], v[122:125]
	v_mfma_f32_16x16x32_bf16 v[118:121], v[166:169], v[206:209], v[118:121]
	v_mfma_f32_16x16x32_bf16 v[114:117], v[190:193], v[206:209], v[114:117]
	v_mfma_f32_16x16x32_bf16 v[110:113], v[166:169], v[214:217], v[110:113]
	v_mfma_f32_16x16x32_bf16 v[106:109], v[190:193], v[214:217], v[106:109]
	v_mfma_f32_16x16x32_bf16 v[102:105], v[166:169], v[222:225], v[102:105]
	v_mfma_f32_16x16x32_bf16 v[98:101], v[190:193], v[222:225], v[98:101]
	s_setprio 0
	s_barrier
	v_add_u32_e32 v176, s33, v146
	v_lshl_add_u64 v[186:187], v[136:137], 0, s[4:5]
	v_readfirstlane_b32 s12, v176
	v_lshl_add_u64 v[188:189], v[186:187], 0, s[26:27]
	s_mov_b32 m0, s12
	v_add_u32_e32 v176, 0x2000, v176
	ds_read_b128 v[226:229], v154
	ds_read_b128 v[230:233], v154 offset:1024
	ds_read_b128 v[234:237], v154 offset:2048
	ds_read_b128 v[238:241], v154 offset:3072
	global_load_lds_dwordx4 v[188:189], off
	v_lshl_add_u64 v[188:189], v[138:139], 0, s[4:5]
	v_readfirstlane_b32 s12, v176
	v_lshl_add_u64 v[242:243], v[188:189], 0, s[26:27]
	s_mov_b32 m0, s12
	s_add_i32 s11, s11, 2
	global_load_lds_dwordx4 v[242:243], off
	s_barrier
	s_waitcnt lgkmcnt(0)
	s_setprio 1
	v_mfma_f32_16x16x32_bf16 v[94:97], v[226:229], v[194:197], v[94:97]
	v_mfma_f32_16x16x32_bf16 v[90:93], v[234:237], v[194:197], v[90:93]
	v_mfma_f32_16x16x32_bf16 v[86:89], v[226:229], v[202:205], v[86:89]
	v_mfma_f32_16x16x32_bf16 v[82:85], v[234:237], v[202:205], v[82:85]
	v_mfma_f32_16x16x32_bf16 v[78:81], v[226:229], v[210:213], v[78:81]
	v_mfma_f32_16x16x32_bf16 v[74:77], v[234:237], v[210:213], v[74:77]
	v_mfma_f32_16x16x32_bf16 v[70:73], v[226:229], v[218:221], v[70:73]
	v_mfma_f32_16x16x32_bf16 v[66:69], v[234:237], v[218:221], v[66:69]
	v_mfma_f32_16x16x32_bf16 v[94:97], v[230:233], v[198:201], v[94:97]
	v_mfma_f32_16x16x32_bf16 v[90:93], v[238:241], v[198:201], v[90:93]
	v_mfma_f32_16x16x32_bf16 v[86:89], v[230:233], v[206:209], v[86:89]
	v_mfma_f32_16x16x32_bf16 v[82:85], v[238:241], v[206:209], v[82:85]
	v_mfma_f32_16x16x32_bf16 v[78:81], v[230:233], v[214:217], v[78:81]
	v_mfma_f32_16x16x32_bf16 v[74:77], v[238:241], v[214:217], v[74:77]
	v_mfma_f32_16x16x32_bf16 v[70:73], v[230:233], v[222:225], v[70:73]
	v_mfma_f32_16x16x32_bf16 v[66:69], v[238:241], v[222:225], v[66:69]
	s_setprio 0
	v_readfirstlane_b32 s12, v150
	v_add_u32_e32 v176, 0x2000, v150
	v_lshl_add_u64 v[242:243], v[162:163], 0, s[0:1]
	s_mov_b32 m0, s12
	v_readfirstlane_b32 s12, v176
	s_barrier
	ds_read_b128 v[194:197], v145 offset:16384
	ds_read_b128 v[198:201], v145 offset:17408
	ds_read_b128 v[202:205], v144 offset:16384
	ds_read_b128 v[206:209], v144 offset:17408
	ds_read_b128 v[210:213], v143 offset:16384
	ds_read_b128 v[214:217], v143 offset:17408
	ds_read_b128 v[218:221], v142 offset:16384
	ds_read_b128 v[222:225], v142 offset:17408
	global_load_lds_dwordx4 v[242:243], off
	v_lshl_add_u64 v[242:243], v[174:175], 0, s[0:1]
	s_mov_b32 m0, s12
	s_nop 0
	global_load_lds_dwordx4 v[242:243], off
	s_barrier
	s_waitcnt lgkmcnt(0)
	s_setprio 1
	v_mfma_f32_16x16x32_bf16 v[62:65], v[158:161], v[194:197], v[62:65]
	v_mfma_f32_16x16x32_bf16 v[58:61], v[170:173], v[194:197], v[58:61]
	v_mfma_f32_16x16x32_bf16 v[54:57], v[158:161], v[202:205], v[54:57]
	v_mfma_f32_16x16x32_bf16 v[50:53], v[170:173], v[202:205], v[50:53]
	v_mfma_f32_16x16x32_bf16 v[46:49], v[158:161], v[210:213], v[46:49]
	v_mfma_f32_16x16x32_bf16 v[42:45], v[170:173], v[210:213], v[42:45]
	v_mfma_f32_16x16x32_bf16 v[38:41], v[158:161], v[218:221], v[38:41]
	v_mfma_f32_16x16x32_bf16 v[34:37], v[170:173], v[218:221], v[34:37]
	v_mfma_f32_16x16x32_bf16 v[62:65], v[166:169], v[198:201], v[62:65]
	v_mfma_f32_16x16x32_bf16 v[58:61], v[190:193], v[198:201], v[58:61]
	v_mfma_f32_16x16x32_bf16 v[54:57], v[166:169], v[206:209], v[54:57]
	v_mfma_f32_16x16x32_bf16 v[50:53], v[190:193], v[206:209], v[50:53]
	v_mfma_f32_16x16x32_bf16 v[46:49], v[166:169], v[214:217], v[46:49]
	v_mfma_f32_16x16x32_bf16 v[42:45], v[190:193], v[214:217], v[42:45]
	v_mfma_f32_16x16x32_bf16 v[38:41], v[166:169], v[222:225], v[38:41]
	v_mfma_f32_16x16x32_bf16 v[34:37], v[190:193], v[222:225], v[34:37]
	s_setprio 0
	s_barrier
; #define STAGE_A(P,br,kt) STAGE_G(P,c.A,c.lda,br,(long)(kt)*c.kstr)
; #define STAGE_B(P,br,kt) STAGE_G(P,c.Bt,c.K,br,(long)(kt)*BK)
; #define LDA(dst,b,h) for(int m=0;m<4;++m)for(int k=0;k<2;++k) \
;     dst[m][k]=*reinterpret_cast<const bf16x8*>((char*)SA(b,h)+lds_byte(wr*64+m*16+fr,k*32+fq*8))
; #define LDB(dst,b,h) for(int n=0;n<2;++n)for(int k=0;k<2;++k) \
;     dst[n][k]=*reinterpret_cast<const bf16x8*>((char*)SB(b,h)+lds_byte(wc*32+n*16+fr,k*32+fq*8))
; #define MMA(ai,bj,At,Bt_) do{__builtin_amdgcn_s_setprio(1); \
;     for(int m=0;m<4;++m)for(int n=0;n<2;++n)for(int k=0;k<2;++k) \
;       acc[ai][bj][m][n]=__builtin_amdgcn_mfma_f32_16x16x32_bf16(Bt_[n][k],At[m][k],acc[ai][bj][m][n],0,0,0); \
;     __builtin_amdgcn_s_setprio(0);}while(0)
; #define WAIT_V(n) asm volatile("s_waitcnt vmcnt(" #n ")":::"memory")
; #define WAIT_L(n) asm volatile("s_waitcnt lgkmcnt(" #n ")":::"memory")
; #define BAR __builtin_amdgcn_s_barrier()
; #define SCHED __builtin_amdgcn_sched_barrier(0)
; template <int EPI>
; __device__ __forceinline__ void gemm_run(const GD& c, const bool has_next, const GD& nx, const Ctx& e, bf16* shm, float* rs, float* rs_nxt, float* racc_) {
;     ...
;     STAGE_B(SB(0,1),bcol+HALF,t+2);
;     WAIT_V(6); BAR; MMA(1,1,At,B1); BAR;
;     LDB(B0,1,0); SCHED; LDA(At,1,0); STAGE_A(SA(0,1),brow+HALF,t+2);
;     WAIT_L(8); BAR; WAIT_L(0); MMA(0,0,At,B0); BAR; SCHED;
;     LDB(B1,1,1); STAGE_B(SB(1,0),bcol,t+3);
;     BAR; WAIT_L(0); MMA(0,1,At,B1); BAR;
;     LDA(At,1,1); STAGE_A(SA(1,0),brow,t+3);
;     BAR; WAIT_L(0); MMA(1,0,At,B0); BAR; SCHED;
;     STAGE_B(SB(1,1),bcol+HALF,t+3);
	v_add_u32_e32 v160, s86, v146
	v_lshl_add_u64 v[158:159], v[186:187], 0, s[28:29]
	v_readfirstlane_b32 s12, v160
	v_add_u32_e32 v160, 0x2000, v160
	s_mov_b32 m0, s12
	v_readfirstlane_b32 s12, v160
	global_load_lds_dwordx4 v[158:159], off
	v_lshl_add_u64 v[158:159], v[188:189], 0, s[28:29]
	s_mov_b32 m0, s12
	s_nop 0
	global_load_lds_dwordx4 v[158:159], off
	s_waitcnt vmcnt(6)
	s_barrier
	s_setprio 1
	v_mfma_f32_16x16x32_bf16 v[30:33], v[226:229], v[194:197], v[30:33]
	v_mfma_f32_16x16x32_bf16 v[26:29], v[234:237], v[194:197], v[26:29]
	v_mfma_f32_16x16x32_bf16 v[22:25], v[226:229], v[202:205], v[22:25]
	v_mfma_f32_16x16x32_bf16 v[18:21], v[234:237], v[202:205], v[18:21]
	v_mfma_f32_16x16x32_bf16 v[14:17], v[226:229], v[210:213], v[14:17]
	v_mfma_f32_16x16x32_bf16 v[10:13], v[234:237], v[210:213], v[10:13]
	v_mfma_f32_16x16x32_bf16 v[6:9], v[226:229], v[218:221], v[6:9]
	v_mfma_f32_16x16x32_bf16 v[2:5], v[234:237], v[218:221], v[2:5]
	v_mfma_f32_16x16x32_bf16 v[30:33], v[230:233], v[198:201], v[30:33]
	v_mfma_f32_16x16x32_bf16 v[26:29], v[238:241], v[198:201], v[26:29]
	v_mfma_f32_16x16x32_bf16 v[22:25], v[230:233], v[206:209], v[22:25]
	v_mfma_f32_16x16x32_bf16 v[18:21], v[238:241], v[206:209], v[18:21]
	v_mfma_f32_16x16x32_bf16 v[14:17], v[230:233], v[214:217], v[14:17]
	v_mfma_f32_16x16x32_bf16 v[10:13], v[238:241], v[214:217], v[10:13]
	v_mfma_f32_16x16x32_bf16 v[6:9], v[230:233], v[222:225], v[6:9]
	v_mfma_f32_16x16x32_bf16 v[2:5], v[238:241], v[222:225], v[2:5]
	s_setprio 0
	s_barrier
	ds_read_b128 v[158:161], v149
	ds_read_b128 v[166:169], v149 offset:1024
	ds_read_b128 v[170:173], v149 offset:2048
	ds_read_b128 v[190:193], v149 offset:3072
	v_add_u32_e32 v176, 0x4000, v150
	v_lshl_add_u64 v[226:227], v[162:163], 0, s[76:77]
	v_readfirstlane_b32 s12, v176
	v_add_u32_e32 v176, 0x6000, v150
	s_mov_b32 m0, s12
	v_readfirstlane_b32 s12, v176
	ds_read_b128 v[194:197], v145 offset:32768
	ds_read_b128 v[198:201], v145 offset:33792
	ds_read_b128 v[202:205], v144 offset:32768
	ds_read_b128 v[206:209], v144 offset:33792
	ds_read_b128 v[210:213], v143 offset:32768
	ds_read_b128 v[214:217], v143 offset:33792
	ds_read_b128 v[218:221], v142 offset:32768
	ds_read_b128 v[222:225], v142 offset:33792
	global_load_lds_dwordx4 v[226:227], off
	v_lshl_add_u64 v[226:227], v[174:175], 0, s[76:77]
	s_mov_b32 m0, s12
	s_nop 0
	global_load_lds_dwordx4 v[226:227], off
	s_waitcnt lgkmcnt(8)
	s_barrier
	s_waitcnt lgkmcnt(0)
	s_setprio 1
	v_mfma_f32_16x16x32_bf16 v[126:129], v[158:161], v[194:197], v[126:129]
	v_mfma_f32_16x16x32_bf16 v[122:125], v[170:173], v[194:197], v[122:125]
	v_mfma_f32_16x16x32_bf16 v[118:121], v[158:161], v[202:205], v[118:121]
	v_mfma_f32_16x16x32_bf16 v[114:117], v[170:173], v[202:205], v[114:117]
	v_mfma_f32_16x16x32_bf16 v[110:113], v[158:161], v[210:213], v[110:113]
	v_mfma_f32_16x16x32_bf16 v[106:109], v[170:173], v[210:213], v[106:109]
	v_mfma_f32_16x16x32_bf16 v[102:105], v[158:161], v[218:221], v[102:105]
	v_mfma_f32_16x16x32_bf16 v[98:101], v[170:173], v[218:221], v[98:101]
	v_mfma_f32_16x16x32_bf16 v[126:129], v[166:169], v[198:201], v[126:129]
	v_mfma_f32_16x16x32_bf16 v[122:125], v[190:193], v[198:201], v[122:125]
	v_mfma_f32_16x16x32_bf16 v[118:121], v[166:169], v[206:209], v[118:121]
	v_mfma_f32_16x16x32_bf16 v[114:117], v[190:193], v[206:209], v[114:117]
	v_mfma_f32_16x16x32_bf16 v[110:113], v[166:169], v[214:217], v[110:113]
	v_mfma_f32_16x16x32_bf16 v[106:109], v[190:193], v[214:217], v[106:109]
	v_mfma_f32_16x16x32_bf16 v[102:105], v[166:169], v[222:225], v[102:105]
	v_mfma_f32_16x16x32_bf16 v[98:101], v[190:193], v[222:225], v[98:101]
	s_setprio 0
	s_barrier
	v_readfirstlane_b32 s12, v148
	v_add_u32_e32 v176, 0x2000, v148
	v_lshl_add_u64 v[242:243], v[186:187], 0, s[30:31]
	s_mov_b32 m0, s12
	v_readfirstlane_b32 s12, v176
	ds_read_b128 v[226:229], v147
	ds_read_b128 v[230:233], v147 offset:1024
	ds_read_b128 v[234:237], v147 offset:2048
	ds_read_b128 v[238:241], v147 offset:3072
	global_load_lds_dwordx4 v[242:243], off
	v_lshl_add_u64 v[242:243], v[188:189], 0, s[30:31]
	s_mov_b32 m0, s12
	s_nop 0
	global_load_lds_dwordx4 v[242:243], off
	s_barrier
	s_waitcnt lgkmcnt(0)
	s_setprio 1
	v_mfma_f32_16x16x32_bf16 v[94:97], v[226:229], v[194:197], v[94:97]
	v_mfma_f32_16x16x32_bf16 v[90:93], v[234:237], v[194:197], v[90:93]
	v_mfma_f32_16x16x32_bf16 v[86:89], v[226:229], v[202:205], v[86:89]
	v_mfma_f32_16x16x32_bf16 v[82:85], v[234:237], v[202:205], v[82:85]
	v_mfma_f32_16x16x32_bf16 v[78:81], v[226:229], v[210:213], v[78:81]
	v_mfma_f32_16x16x32_bf16 v[74:77], v[234:237], v[210:213], v[74:77]
	v_mfma_f32_16x16x32_bf16 v[70:73], v[226:229], v[218:221], v[70:73]
	v_mfma_f32_16x16x32_bf16 v[66:69], v[234:237], v[218:221], v[66:69]
	v_mfma_f32_16x16x32_bf16 v[94:97], v[230:233], v[198:201], v[94:97]
	v_mfma_f32_16x16x32_bf16 v[90:93], v[238:241], v[198:201], v[90:93]
	v_mfma_f32_16x16x32_bf16 v[86:89], v[230:233], v[206:209], v[86:89]
	v_mfma_f32_16x16x32_bf16 v[82:85], v[238:241], v[206:209], v[82:85]
	v_mfma_f32_16x16x32_bf16 v[78:81], v[230:233], v[214:217], v[78:81]
	v_mfma_f32_16x16x32_bf16 v[74:77], v[238:241], v[214:217], v[74:77]
	v_mfma_f32_16x16x32_bf16 v[70:73], v[230:233], v[222:225], v[70:73]
	v_mfma_f32_16x16x32_bf16 v[66:69], v[238:241], v[222:225], v[66:69]
	s_setprio 0
	v_readfirstlane_b32 s12, v151
	v_lshl_add_u64 v[162:163], v[162:163], 0, s[74:75]
	s_mov_b32 m0, s12
	v_readfirstlane_b32 s12, v152
	s_barrier
; #define STAGE_A(P,br,kt) STAGE_G(P,c.A,c.lda,br,(long)(kt)*c.kstr)
; #define STAGE_B(P,br,kt) STAGE_G(P,c.Bt,c.K,br,(long)(kt)*BK)
; #define LDA(dst,b,h) for(int m=0;m<4;++m)for(int k=0;k<2;++k) \
;     dst[m][k]=*reinterpret_cast<const bf16x8*>((char*)SA(b,h)+lds_byte(wr*64+m*16+fr,k*32+fq*8))
; #define LDB(dst,b,h) for(int n=0;n<2;++n)for(int k=0;k<2;++k) \
;     dst[n][k]=*reinterpret_cast<const bf16x8*>((char*)SB(b,h)+lds_byte(wc*32+n*16+fr,k*32+fq*8))
; #define MMA(ai,bj,At,Bt_) do{__builtin_amdgcn_s_setprio(1); \
;     for(int m=0;m<4;++m)for(int n=0;n<2;++n)for(int k=0;k<2;++k) \
;       acc[ai][bj][m][n]=__builtin_amdgcn_mfma_f32_16x16x32_bf16(Bt_[n][k],At[m][k],acc[ai][bj][m][n],0,0,0); \
;     __builtin_amdgcn_s_setprio(0);}while(0)
; #define WAIT_V(n) asm volatile("s_waitcnt vmcnt(" #n ")":::"memory")
; #define WAIT_L(n) asm volatile("s_waitcnt lgkmcnt(" #n ")":::"memory")
; #define BAR __builtin_amdgcn_s_barrier()
; #define SCHED __builtin_amdgcn_sched_barrier(0)
; template <int EPI>
; __device__ __forceinline__ void gemm_run(const GD& c, const bool has_next, const GD& nx, const Ctx& e, bf16* shm, float* rs, float* rs_nxt, float* racc_) {
;     ...
;     LDB(B1,1,1); STAGE_B(SB(1,0),bcol,t+3);
;     BAR; WAIT_L(0); MMA(0,1,At,B1); BAR;
;     LDA(At,1,1); STAGE_A(SA(1,0),brow,t+3);
;     BAR; WAIT_L(0); MMA(1,0,At,B0); BAR; SCHED;
;     STAGE_B(SB(1,1),bcol+HALF,t+3);
;     WAIT_V(6); BAR; MMA(1,1,At,B1); BAR;
;   }
;   { LDB(B0,0,0); LDA(At,0,0); STAGE_A(SA(1,1),brow+HALF,nt-1);
;     BAR; WAIT_L(0); MMA(0,0,At,B0); BAR;
	ds_read_b128 v[194:197], v145 offset:49152
	ds_read_b128 v[198:201], v145 offset:50176
	ds_read_b128 v[202:205], v144 offset:49152
	ds_read_b128 v[206:209], v144 offset:50176
	ds_read_b128 v[210:213], v143 offset:49152
	ds_read_b128 v[214:217], v143 offset:50176
	ds_read_b128 v[218:221], v142 offset:49152
	ds_read_b128 v[222:225], v142 offset:50176
	global_load_lds_dwordx4 v[162:163], off
	v_lshl_add_u64 v[162:163], v[174:175], 0, s[74:75]
	s_mov_b32 m0, s12
	s_nop 0
	global_load_lds_dwordx4 v[162:163], off
	s_barrier
	s_waitcnt lgkmcnt(0)
	s_setprio 1
	v_mfma_f32_16x16x32_bf16 v[62:65], v[158:161], v[194:197], v[62:65]
	v_mfma_f32_16x16x32_bf16 v[58:61], v[170:173], v[194:197], v[58:61]
	v_mfma_f32_16x16x32_bf16 v[54:57], v[158:161], v[202:205], v[54:57]
	v_mfma_f32_16x16x32_bf16 v[50:53], v[170:173], v[202:205], v[50:53]
	v_mfma_f32_16x16x32_bf16 v[46:49], v[158:161], v[210:213], v[46:49]
	v_mfma_f32_16x16x32_bf16 v[42:45], v[170:173], v[210:213], v[42:45]
	v_mfma_f32_16x16x32_bf16 v[38:41], v[158:161], v[218:221], v[38:41]
	v_mfma_f32_16x16x32_bf16 v[34:37], v[170:173], v[218:221], v[34:37]
	v_mfma_f32_16x16x32_bf16 v[62:65], v[166:169], v[198:201], v[62:65]
	v_mfma_f32_16x16x32_bf16 v[58:61], v[190:193], v[198:201], v[58:61]
	v_mfma_f32_16x16x32_bf16 v[54:57], v[166:169], v[206:209], v[54:57]
	v_mfma_f32_16x16x32_bf16 v[50:53], v[190:193], v[206:209], v[50:53]
	v_mfma_f32_16x16x32_bf16 v[46:49], v[166:169], v[214:217], v[46:49]
	v_mfma_f32_16x16x32_bf16 v[42:45], v[190:193], v[214:217], v[42:45]
	v_mfma_f32_16x16x32_bf16 v[38:41], v[166:169], v[222:225], v[38:41]
	v_mfma_f32_16x16x32_bf16 v[34:37], v[190:193], v[222:225], v[34:37]
	s_setprio 0
	s_barrier
	v_readfirstlane_b32 s12, v153
	v_add_u32_e32 v160, 0x2000, v153
	v_lshl_add_u64 v[158:159], v[186:187], 0, s[34:35]
	s_mov_b32 m0, s12
	v_readfirstlane_b32 s12, v160
	global_load_lds_dwordx4 v[158:159], off
	v_lshl_add_u64 v[158:159], v[188:189], 0, s[34:35]
	s_mov_b32 m0, s12
	s_nop 0
	global_load_lds_dwordx4 v[158:159], off
	s_waitcnt vmcnt(6)
	s_barrier
	s_setprio 1
	v_mfma_f32_16x16x32_bf16 v[30:33], v[226:229], v[194:197], v[30:33]
	v_mfma_f32_16x16x32_bf16 v[26:29], v[234:237], v[194:197], v[26:29]
	v_mfma_f32_16x16x32_bf16 v[22:25], v[226:229], v[202:205], v[22:25]
	v_mfma_f32_16x16x32_bf16 v[18:21], v[234:237], v[202:205], v[18:21]
	v_mfma_f32_16x16x32_bf16 v[14:17], v[226:229], v[210:213], v[14:17]
	v_mfma_f32_16x16x32_bf16 v[10:13], v[234:237], v[210:213], v[10:13]
	v_mfma_f32_16x16x32_bf16 v[6:9], v[226:229], v[218:221], v[6:9]
	v_mfma_f32_16x16x32_bf16 v[2:5], v[234:237], v[218:221], v[2:5]
	v_mfma_f32_16x16x32_bf16 v[30:33], v[230:233], v[198:201], v[30:33]
	v_mfma_f32_16x16x32_bf16 v[26:29], v[238:241], v[198:201], v[26:29]
	v_mfma_f32_16x16x32_bf16 v[22:25], v[230:233], v[206:209], v[22:25]
	v_mfma_f32_16x16x32_bf16 v[18:21], v[238:241], v[206:209], v[18:21]
	v_mfma_f32_16x16x32_bf16 v[14:17], v[230:233], v[214:217], v[14:17]
	v_mfma_f32_16x16x32_bf16 v[10:13], v[238:241], v[214:217], v[10:13]
	v_mfma_f32_16x16x32_bf16 v[6:9], v[230:233], v[222:225], v[6:9]
	v_mfma_f32_16x16x32_bf16 v[2:5], v[238:241], v[222:225], v[2:5]
	s_setprio 0
	v_lshl_add_u64 v[132:133], v[132:133], 0, s[88:89]
	v_lshl_add_u64 v[134:135], v[134:135], 0, s[88:89]
	v_lshl_add_u64 v[136:137], v[136:137], 0, s[88:89]
	s_cmp_lt_u32 s11, s10
	v_lshl_add_u64 v[138:139], v[138:139], 0, s[88:89]
	s_barrier
	s_cbranch_scc1 .LBB0_357
	s_lshl_b32 s4, s9, 7
	s_add_u32 s2, s2, s4
	s_addc_u32 s3, s3, 0
	s_movk_i32 s10, 0xff80
	v_lshl_add_u64 v[162:163], s[2:3], 0, v[0:1]
	s_mov_b32 s11, -1
	v_readfirstlane_b32 s4, v156
	v_lshl_add_u64 v[162:163], v[162:163], 0, s[10:11]
	s_mov_b32 m0, s4
	v_lshl_add_u64 v[130:131], s[2:3], 0, v[130:131]
	v_readfirstlane_b32 s2, v157
	ds_read_b128 v[132:135], v155
	ds_read_b128 v[136:139], v155 offset:1024
	ds_read_b128 v[150:153], v155 offset:2048
	ds_read_b128 v[158:161], v155 offset:3072
	ds_read_b128 v[166:169], v145
	ds_read_b128 v[170:173], v145 offset:1024
	ds_read_b128 v[190:193], v144
	ds_read_b128 v[194:197], v144 offset:1024
	ds_read_b128 v[198:201], v143
	ds_read_b128 v[202:205], v143 offset:1024
	ds_read_b128 v[206:209], v142
	ds_read_b128 v[210:213], v142 offset:1024
	global_load_lds_dwordx4 v[162:163], off
	v_lshl_add_u64 v[130:131], v[130:131], 0, s[10:11]
	s_mov_b32 m0, s2
	s_nop 0
	global_load_lds_dwordx4 v[130:131], off
	s_barrier
	s_waitcnt lgkmcnt(0)
	s_setprio 1
	v_mfma_f32_16x16x32_bf16 v[126:129], v[132:135], v[166:169], v[126:129]
	v_mfma_f32_16x16x32_bf16 v[122:125], v[150:153], v[166:169], v[122:125]
	v_mfma_f32_16x16x32_bf16 v[118:121], v[132:135], v[190:193], v[118:121]
	v_mfma_f32_16x16x32_bf16 v[114:117], v[150:153], v[190:193], v[114:117]
	v_mfma_f32_16x16x32_bf16 v[110:113], v[132:135], v[198:201], v[110:113]
	v_mfma_f32_16x16x32_bf16 v[106:109], v[150:153], v[198:201], v[106:109]
	v_mfma_f32_16x16x32_bf16 v[102:105], v[132:135], v[206:209], v[102:105]
	v_mfma_f32_16x16x32_bf16 v[98:101], v[150:153], v[206:209], v[98:101]
	v_mfma_f32_16x16x32_bf16 v[126:129], v[136:139], v[170:173], v[126:129]
	v_mfma_f32_16x16x32_bf16 v[122:125], v[158:161], v[170:173], v[122:125]
	v_mfma_f32_16x16x32_bf16 v[118:121], v[136:139], v[194:197], v[118:121]
	v_mfma_f32_16x16x32_bf16 v[114:117], v[158:161], v[194:197], v[114:117]
	v_mfma_f32_16x16x32_bf16 v[110:113], v[136:139], v[202:205], v[110:113]
	v_mfma_f32_16x16x32_bf16 v[106:109], v[158:161], v[202:205], v[106:109]
	v_mfma_f32_16x16x32_bf16 v[102:105], v[136:139], v[210:213], v[102:105]
	v_mfma_f32_16x16x32_bf16 v[98:101], v[158:161], v[210:213], v[98:101]
	s_setprio 0
	s_barrier
; #define STAGE_A(P,br,kt) STAGE_G(P,c.A,c.lda,br,(long)(kt)*c.kstr)
; #define LDA(dst,b,h) for(int m=0;m<4;++m)for(int k=0;k<2;++k) \
;     dst[m][k]=*reinterpret_cast<const bf16x8*>((char*)SA(b,h)+lds_byte(wr*64+m*16+fr,k*32+fq*8))
; #define LDB(dst,b,h) for(int n=0;n<2;++n)for(int k=0;k<2;++k) \
;     dst[n][k]=*reinterpret_cast<const bf16x8*>((char*)SB(b,h)+lds_byte(wc*32+n*16+fr,k*32+fq*8))
; #define MMA(ai,bj,At,Bt_) do{__builtin_amdgcn_s_setprio(1); \
;     for(int m=0;m<4;++m)for(int n=0;n<2;++n)for(int k=0;k<2;++k) \
;       acc[ai][bj][m][n]=__builtin_amdgcn_mfma_f32_16x16x32_bf16(Bt_[n][k],At[m][k],acc[ai][bj][m][n],0,0,0); \
;     __builtin_amdgcn_s_setprio(0);}while(0)
; #define WAIT_V(n) asm volatile("s_waitcnt vmcnt(" #n ")":::"memory")
; #define WAIT_L(n) asm volatile("s_waitcnt lgkmcnt(" #n ")":::"memory")
; #define BAR __builtin_amdgcn_s_barrier()
; template <int EPI>
; __device__ __forceinline__ void gemm_run(const GD& c, const bool has_next, const GD& nx, const Ctx& e, bf16* shm, float* rs, float* rs_nxt, float* racc_) {
;     ...
;   { LDB(B0,0,0); LDA(At,0,0); STAGE_A(SA(1,1),brow+HALF,nt-1);
;     BAR; WAIT_L(0); MMA(0,0,At,B0); BAR;
;     LDB(B1,0,1); BAR; WAIT_L(0); MMA(0,1,At,B1); BAR;
;     LDA(At,0,1); WAIT_V(4); BAR; WAIT_L(0); MMA(1,0,At,B0); MMA(1,1,At,B1); BAR; }
;   { LDB(B0,1,0); LDA(At,1,0); WAIT_V(2); BAR; WAIT_L(0); MMA(0,0,At,B0); BAR;
	ds_read_b128 v[214:217], v154
	ds_read_b128 v[218:221], v154 offset:1024
	ds_read_b128 v[222:225], v154 offset:2048
	ds_read_b128 v[154:157], v154 offset:3072
	s_barrier
	s_waitcnt lgkmcnt(0)
	s_setprio 1
	v_mfma_f32_16x16x32_bf16 v[94:97], v[214:217], v[166:169], v[94:97]
	v_mfma_f32_16x16x32_bf16 v[90:93], v[222:225], v[166:169], v[90:93]
	v_mfma_f32_16x16x32_bf16 v[86:89], v[214:217], v[190:193], v[86:89]
	v_mfma_f32_16x16x32_bf16 v[82:85], v[222:225], v[190:193], v[82:85]
	v_mfma_f32_16x16x32_bf16 v[74:77], v[222:225], v[198:201], v[74:77]
	v_mfma_f32_16x16x32_bf16 v[70:73], v[214:217], v[206:209], v[70:73]
	v_mfma_f32_16x16x32_bf16 v[94:97], v[218:221], v[170:173], v[94:97]
	v_mfma_f32_16x16x32_bf16 v[90:93], v[154:157], v[170:173], v[90:93]
	v_mfma_f32_16x16x32_bf16 v[86:89], v[218:221], v[194:197], v[86:89]
	v_mfma_f32_16x16x32_bf16 v[82:85], v[154:157], v[194:197], v[82:85]
	v_mfma_f32_16x16x32_bf16 v[78:81], v[214:217], v[198:201], v[78:81]
	v_mfma_f32_16x16x32_bf16 v[74:77], v[154:157], v[202:205], v[74:77]
	v_mfma_f32_16x16x32_bf16 v[70:73], v[218:221], v[210:213], v[70:73]
	v_mfma_f32_16x16x32_bf16 v[66:69], v[222:225], v[206:209], v[66:69]
	v_mfma_f32_16x16x32_bf16 v[166:169], v[218:221], v[202:205], v[78:81]
	v_mfma_f32_16x16x32_bf16 v[170:173], v[154:157], v[210:213], v[66:69]
	s_setprio 0
	s_barrier
	s_nop 3
	ds_read_b128 v[66:69], v145 offset:16384
	ds_read_b128 v[78:81], v145 offset:17408
	ds_read_b128 v[190:193], v144 offset:16384
	ds_read_b128 v[194:197], v144 offset:17408
	ds_read_b128 v[198:201], v143 offset:16384
	ds_read_b128 v[202:205], v143 offset:17408
	ds_read_b128 v[206:209], v142 offset:16384
	ds_read_b128 v[210:213], v142 offset:17408
	s_waitcnt vmcnt(4)
	s_barrier
	s_waitcnt lgkmcnt(0)
	s_setprio 1
	v_mfma_f32_16x16x32_bf16 v[62:65], v[132:135], v[66:69], v[62:65]
	v_mfma_f32_16x16x32_bf16 v[54:57], v[132:135], v[190:193], v[54:57]
	v_mfma_f32_16x16x32_bf16 v[46:49], v[132:135], v[198:201], v[46:49]
	v_mfma_f32_16x16x32_bf16 v[38:41], v[132:135], v[206:209], v[38:41]
	v_mfma_f32_16x16x32_bf16 v[62:65], v[136:139], v[78:81], v[62:65]
	v_mfma_f32_16x16x32_bf16 v[58:61], v[150:153], v[66:69], v[58:61]
	v_mfma_f32_16x16x32_bf16 v[54:57], v[136:139], v[194:197], v[54:57]
	v_mfma_f32_16x16x32_bf16 v[50:53], v[150:153], v[190:193], v[50:53]
	v_mfma_f32_16x16x32_bf16 v[46:49], v[136:139], v[202:205], v[46:49]
	v_mfma_f32_16x16x32_bf16 v[42:45], v[150:153], v[198:201], v[42:45]
	v_mfma_f32_16x16x32_bf16 v[38:41], v[136:139], v[210:213], v[38:41]
	v_mfma_f32_16x16x32_bf16 v[34:37], v[150:153], v[206:209], v[34:37]
	v_mfma_f32_16x16x32_bf16 v[226:229], v[158:161], v[78:81], v[58:61]
	v_mfma_f32_16x16x32_bf16 v[230:233], v[158:161], v[194:197], v[50:53]
	v_mfma_f32_16x16x32_bf16 v[234:237], v[158:161], v[202:205], v[42:45]
	v_mfma_f32_16x16x32_bf16 v[130:133], v[158:161], v[210:213], v[34:37]
	s_setprio 0
	s_setprio 1
	v_mfma_f32_16x16x32_bf16 v[30:33], v[214:217], v[66:69], v[30:33]
	v_mfma_f32_16x16x32_bf16 v[26:29], v[222:225], v[66:69], v[26:29]
	v_mfma_f32_16x16x32_bf16 v[22:25], v[214:217], v[190:193], v[22:25]
	v_mfma_f32_16x16x32_bf16 v[18:21], v[222:225], v[190:193], v[18:21]
	v_mfma_f32_16x16x32_bf16 v[14:17], v[214:217], v[198:201], v[14:17]
	v_mfma_f32_16x16x32_bf16 v[10:13], v[222:225], v[198:201], v[10:13]
	v_mfma_f32_16x16x32_bf16 v[6:9], v[214:217], v[206:209], v[6:9]
	v_mfma_f32_16x16x32_bf16 v[2:5], v[222:225], v[206:209], v[2:5]
	v_mfma_f32_16x16x32_bf16 v[134:137], v[218:221], v[78:81], v[30:33]
	v_mfma_f32_16x16x32_bf16 v[150:153], v[154:157], v[78:81], v[26:29]
	v_mfma_f32_16x16x32_bf16 v[158:161], v[218:221], v[194:197], v[22:25]
	v_mfma_f32_16x16x32_bf16 v[190:193], v[154:157], v[194:197], v[18:21]
	v_mfma_f32_16x16x32_bf16 v[194:197], v[218:221], v[202:205], v[14:17]
	v_mfma_f32_16x16x32_bf16 v[198:201], v[154:157], v[202:205], v[10:13]
	v_mfma_f32_16x16x32_bf16 v[202:205], v[218:221], v[210:213], v[6:9]
	v_mfma_f32_16x16x32_bf16 v[154:157], v[154:157], v[210:213], v[2:5]
	s_setprio 0
	s_barrier
	ds_read_b128 v[34:37], v149
	ds_read_b128 v[206:209], v149 offset:1024
	ds_read_b128 v[210:213], v149 offset:2048
	ds_read_b128 v[214:217], v149 offset:3072
	ds_read_b128 v[42:45], v145 offset:32768
	ds_read_b128 v[50:53], v145 offset:33792
	ds_read_b128 v[58:61], v144 offset:32768
	ds_read_b128 v[66:69], v144 offset:33792
	ds_read_b128 v[218:221], v143 offset:32768
	ds_read_b128 v[222:225], v143 offset:33792
	ds_read_b128 v[238:241], v142 offset:32768
	ds_read_b128 v[242:245], v142 offset:33792
	s_waitcnt vmcnt(2)
	s_barrier
; #define LDA(dst,b,h) for(int m=0;m<4;++m)for(int k=0;k<2;++k) \
;     dst[m][k]=*reinterpret_cast<const bf16x8*>((char*)SA(b,h)+lds_byte(wr*64+m*16+fr,k*32+fq*8))
; #define LDB(dst,b,h) for(int n=0;n<2;++n)for(int k=0;k<2;++k) \
;     dst[n][k]=*reinterpret_cast<const bf16x8*>((char*)SB(b,h)+lds_byte(wc*32+n*16+fr,k*32+fq*8))
; #define MMA(ai,bj,At,Bt_) do{__builtin_amdgcn_s_setprio(1); \
;     for(int m=0;m<4;++m)for(int n=0;n<2;++n)for(int k=0;k<2;++k) \
;       acc[ai][bj][m][n]=__builtin_amdgcn_mfma_f32_16x16x32_bf16(Bt_[n][k],At[m][k],acc[ai][bj][m][n],0,0,0); \
;     __builtin_amdgcn_s_setprio(0);}while(0)
; #define WAIT_V(n) asm volatile("s_waitcnt vmcnt(" #n ")":::"memory")
; #define WAIT_L(n) asm volatile("s_waitcnt lgkmcnt(" #n ")":::"memory")
; #define BAR __builtin_amdgcn_s_barrier()
; template <int EPI>
; __device__ __forceinline__ void gemm_run(const GD& c, const bool has_next, const GD& nx, const Ctx& e, bf16* shm, float* rs, float* rs_nxt, float* racc_) {
;     ...
;   { LDB(B0,1,0); LDA(At,1,0); WAIT_V(2); BAR; WAIT_L(0); MMA(0,0,At,B0); BAR;
;     LDB(B1,1,1); WAIT_V(0); BAR; WAIT_L(0); MMA(0,1,At,B1); BAR;
;     LDA(At,1,1); BAR; WAIT_L(0); MMA(1,0,At,B0); MMA(1,1,At,B1); BAR; }
;   if(wr==0)BAR;
	s_waitcnt lgkmcnt(0)
	s_setprio 1
	v_mfma_f32_16x16x32_bf16 v[2:5], v[34:37], v[42:45], v[126:129]
	v_mfma_f32_16x16x32_bf16 v[26:29], v[206:209], v[50:53], v[2:5]
	v_mfma_f32_16x16x32_bf16 v[2:5], v[210:213], v[42:45], v[122:125]
	v_mfma_f32_16x16x32_bf16 v[30:33], v[214:217], v[50:53], v[2:5]
	v_mfma_f32_16x16x32_bf16 v[2:5], v[34:37], v[58:61], v[118:121]
	v_mfma_f32_16x16x32_bf16 v[18:21], v[206:209], v[66:69], v[2:5]
	v_mfma_f32_16x16x32_bf16 v[2:5], v[210:213], v[58:61], v[114:117]
	v_mfma_f32_16x16x32_bf16 v[22:25], v[214:217], v[66:69], v[2:5]
	v_mfma_f32_16x16x32_bf16 v[2:5], v[34:37], v[218:221], v[110:113]
	v_mfma_f32_16x16x32_bf16 v[10:13], v[206:209], v[222:225], v[2:5]
	v_mfma_f32_16x16x32_bf16 v[2:5], v[210:213], v[218:221], v[106:109]
	v_mfma_f32_16x16x32_bf16 v[14:17], v[214:217], v[222:225], v[2:5]
	v_mfma_f32_16x16x32_bf16 v[2:5], v[34:37], v[238:241], v[102:105]
	v_mfma_f32_16x16x32_bf16 v[6:9], v[210:213], v[238:241], v[98:101]
	v_mfma_f32_16x16x32_bf16 v[2:5], v[206:209], v[242:245], v[2:5]
	v_mfma_f32_16x16x32_bf16 v[6:9], v[214:217], v[242:245], v[6:9]
	s_setprio 0
	s_barrier
	ds_read_b128 v[246:249], v147
	ds_read_b128 v[250:253], v147 offset:1024
	ds_read_b128 v[186:189], v147 offset:2048
	ds_read_b128 v[146:149], v147 offset:3072
	s_waitcnt vmcnt(0)
	s_barrier
	s_waitcnt lgkmcnt(0)
	s_setprio 1
	v_mfma_f32_16x16x32_bf16 v[78:81], v[246:249], v[42:45], v[94:97]
	v_mfma_f32_16x16x32_bf16 v[42:45], v[186:189], v[42:45], v[90:93]
	v_mfma_f32_16x16x32_bf16 v[102:105], v[146:149], v[50:53], v[42:45]
	v_mfma_f32_16x16x32_bf16 v[42:45], v[246:249], v[58:61], v[86:89]
	v_mfma_f32_16x16x32_bf16 v[98:101], v[250:253], v[50:53], v[78:81]
	v_mfma_f32_16x16x32_bf16 v[78:81], v[250:253], v[66:69], v[42:45]
	v_mfma_f32_16x16x32_bf16 v[42:45], v[186:189], v[58:61], v[82:85]
	v_mfma_f32_16x16x32_bf16 v[86:89], v[146:149], v[66:69], v[42:45]
	v_mfma_f32_16x16x32_bf16 v[42:45], v[246:249], v[218:221], v[166:169]
	v_mfma_f32_16x16x32_bf16 v[58:61], v[250:253], v[222:225], v[42:45]
	v_mfma_f32_16x16x32_bf16 v[42:45], v[186:189], v[218:221], v[74:77]
	v_mfma_f32_16x16x32_bf16 v[66:69], v[146:149], v[222:225], v[42:45]
	v_mfma_f32_16x16x32_bf16 v[42:45], v[246:249], v[238:241], v[70:73]
	v_mfma_f32_16x16x32_bf16 v[50:53], v[186:189], v[238:241], v[170:173]
	v_mfma_f32_16x16x32_bf16 v[42:45], v[250:253], v[242:245], v[42:45]
	v_mfma_f32_16x16x32_bf16 v[50:53], v[146:149], v[242:245], v[50:53]
	s_setprio 0
	s_barrier
	ds_read_b128 v[74:77], v145 offset:49152
	ds_read_b128 v[94:97], v145 offset:50176
	ds_read_b128 v[106:109], v144 offset:49152
	ds_read_b128 v[110:113], v144 offset:50176
	ds_read_b128 v[166:169], v143 offset:49152
	ds_read_b128 v[170:173], v143 offset:50176
	ds_read_b128 v[218:221], v142 offset:49152
	ds_read_b128 v[142:145], v142 offset:50176
	s_barrier
	s_waitcnt lgkmcnt(0)
	s_setprio 1
	v_mfma_f32_16x16x32_bf16 v[62:65], v[34:37], v[74:77], v[62:65]
	v_mfma_f32_16x16x32_bf16 v[82:85], v[206:209], v[94:97], v[62:65]
	v_mfma_f32_16x16x32_bf16 v[62:65], v[210:213], v[74:77], v[226:229]
	v_mfma_f32_16x16x32_bf16 v[54:57], v[34:37], v[106:109], v[54:57]
	v_mfma_f32_16x16x32_bf16 v[90:93], v[214:217], v[94:97], v[62:65]
	v_mfma_f32_16x16x32_bf16 v[62:65], v[206:209], v[110:113], v[54:57]
	v_mfma_f32_16x16x32_bf16 v[54:57], v[210:213], v[106:109], v[230:233]
	v_mfma_f32_16x16x32_bf16 v[70:73], v[214:217], v[110:113], v[54:57]
	v_mfma_f32_16x16x32_bf16 v[46:49], v[34:37], v[166:169], v[46:49]
	v_mfma_f32_16x16x32_bf16 v[54:57], v[210:213], v[166:169], v[234:237]
	v_mfma_f32_16x16x32_bf16 v[34:37], v[34:37], v[218:221], v[38:41]
	v_mfma_f32_16x16x32_bf16 v[38:41], v[210:213], v[218:221], v[130:133]
	v_mfma_f32_16x16x32_bf16 v[46:49], v[206:209], v[170:173], v[46:49]
	v_mfma_f32_16x16x32_bf16 v[54:57], v[214:217], v[170:173], v[54:57]
	v_mfma_f32_16x16x32_bf16 v[34:37], v[206:209], v[142:145], v[34:37]
	v_mfma_f32_16x16x32_bf16 v[38:41], v[214:217], v[142:145], v[38:41]
	s_setprio 0
	s_setprio 1
	v_mfma_f32_16x16x32_bf16 v[114:117], v[246:249], v[74:77], v[134:137]
	v_mfma_f32_16x16x32_bf16 v[74:77], v[186:189], v[74:77], v[150:153]
	v_mfma_f32_16x16x32_bf16 v[126:129], v[146:149], v[94:97], v[74:77]
	v_mfma_f32_16x16x32_bf16 v[74:77], v[246:249], v[106:109], v[158:161]
	v_mfma_f32_16x16x32_bf16 v[122:125], v[250:253], v[94:97], v[114:117]
	v_mfma_f32_16x16x32_bf16 v[114:117], v[250:253], v[110:113], v[74:77]
	v_mfma_f32_16x16x32_bf16 v[74:77], v[186:189], v[106:109], v[190:193]
	v_mfma_f32_16x16x32_bf16 v[118:121], v[146:149], v[110:113], v[74:77]
	v_mfma_f32_16x16x32_bf16 v[74:77], v[246:249], v[166:169], v[194:197]
	v_mfma_f32_16x16x32_bf16 v[106:109], v[250:253], v[170:173], v[74:77]
	v_mfma_f32_16x16x32_bf16 v[74:77], v[186:189], v[166:169], v[198:201]
	v_mfma_f32_16x16x32_bf16 v[110:113], v[146:149], v[170:173], v[74:77]
	v_mfma_f32_16x16x32_bf16 v[74:77], v[246:249], v[218:221], v[202:205]
	v_mfma_f32_16x16x32_bf16 v[94:97], v[250:253], v[142:145], v[74:77]
	v_mfma_f32_16x16x32_bf16 v[74:77], v[186:189], v[218:221], v[154:157]
	v_mfma_f32_16x16x32_bf16 v[74:77], v[146:149], v[142:145], v[74:77]
	s_setprio 0
	v_cmp_gt_u32_e32 vcc, s96, v141
	s_barrier
	s_and_saveexec_b64 s[2:3], vcc
	s_cbranch_execz .LBB0_353
	s_barrier
	s_branch .LBB0_353

; #define STAGE_A(P,br,kt) STAGE_G(P,c.A,c.lda,br,(long)(kt)*c.kstr)
; #define STAGE_B(P,br,kt) STAGE_G(P,c.Bt,c.K,br,(long)(kt)*BK)
; #define LDA(dst,b,h) for(int m=0;m<4;++m)for(int k=0;k<2;++k) \
;     dst[m][k]=*reinterpret_cast<const bf16x8*>((char*)SA(b,h)+lds_byte(wr*64+m*16+fr,k*32+fq*8))
; #define LDB(dst,b,h) for(int n=0;n<2;++n)for(int k=0;k<2;++k) \
;     dst[n][k]=*reinterpret_cast<const bf16x8*>((char*)SB(b,h)+lds_byte(wc*32+n*16+fr,k*32+fq*8))
; #define MMA(ai,bj,At,Bt_) do{__builtin_amdgcn_s_setprio(1); \
;     for(int m=0;m<4;++m)for(int n=0;n<2;++n)for(int k=0;k<2;++k) \
;       acc[ai][bj][m][n]=__builtin_amdgcn_mfma_f32_16x16x32_bf16(Bt_[n][k],At[m][k],acc[ai][bj][m][n],0,0,0); \
;     __builtin_amdgcn_s_setprio(0);}while(0)
; #define WAIT_V(n) asm volatile("s_waitcnt vmcnt(" #n ")":::"memory")
; #define WAIT_L(n) asm volatile("s_waitcnt lgkmcnt(" #n ")":::"memory")
; #define BAR __builtin_amdgcn_s_barrier()
; #define SCHED __builtin_amdgcn_sched_barrier(0)
; template <int EPI>
; __device__ __forceinline__ void gemm_run(const GD& c, const bool has_next, const GD& nx, const Ctx& e, bf16* shm, float* rs, float* rs_nxt, float* racc_) {
;     ...
;   for(int t=0;t<nt-2;t+=2){
;     LDB(B0,0,0); SCHED; LDA(At,0,0); STAGE_A(SA(1,1),brow+HALF,t+1);
;     WAIT_L(8); BAR; WAIT_L(0); MMA(0,0,At,B0); BAR; SCHED;
;     LDB(B1,0,1); STAGE_B(SB(0,0),bcol,t+2);
;     BAR; WAIT_L(0); MMA(0,1,At,B1); BAR;
;     LDA(At,0,1); STAGE_A(SA(0,0),brow,t+2);
;     BAR; WAIT_L(0); MMA(1,0,At,B0); BAR; SCHED;
;     STAGE_B(SB(0,1),bcol+HALF,t+2);
;     WAIT_V(6); BAR; MMA(1,1,At,B1); BAR;
.LBB0_464:
	ds_read_b128 v[158:161], v154
	ds_read_b128 v[166:169], v154 offset:1024
	ds_read_b128 v[170:173], v154 offset:2048
	ds_read_b128 v[190:193], v154 offset:3072
	v_add_u32_e32 v162, 0xc000, v141
	v_lshl_add_u64 v[174:175], s[14:15], 0, v[130:131]
	v_readfirstlane_b32 s3, v162
	v_add_u32_e32 v163, 0xe000, v141
	v_lshl_add_u64 v[156:157], v[174:175], 0, s[94:95]
	s_mov_b32 m0, s3
	v_lshl_add_u64 v[186:187], s[14:15], 0, v[132:133]
	v_readfirstlane_b32 s3, v163
	ds_read_b128 v[194:197], v145
	ds_read_b128 v[198:201], v145 offset:1024
	ds_read_b128 v[202:205], v144
	ds_read_b128 v[206:209], v144 offset:1024
	ds_read_b128 v[210:213], v143
	ds_read_b128 v[214:217], v143 offset:1024
	ds_read_b128 v[218:221], v142
	ds_read_b128 v[222:225], v142 offset:1024
	global_load_lds_dwordx4 v[156:157], off
	v_lshl_add_u64 v[156:157], v[186:187], 0, s[94:95]
	s_mov_b32 m0, s3
	s_nop 0
	global_load_lds_dwordx4 v[156:157], off
	s_waitcnt lgkmcnt(8)
	s_barrier
	s_waitcnt lgkmcnt(0)
	s_setprio 1
	v_mfma_f32_16x16x32_bf16 v[126:129], v[158:161], v[194:197], v[126:129]
	v_mfma_f32_16x16x32_bf16 v[122:125], v[170:173], v[194:197], v[122:125]
	v_mfma_f32_16x16x32_bf16 v[118:121], v[158:161], v[202:205], v[118:121]
	v_mfma_f32_16x16x32_bf16 v[114:117], v[170:173], v[202:205], v[114:117]
	v_mfma_f32_16x16x32_bf16 v[110:113], v[158:161], v[210:213], v[110:113]
	v_mfma_f32_16x16x32_bf16 v[106:109], v[170:173], v[210:213], v[106:109]
	v_mfma_f32_16x16x32_bf16 v[102:105], v[158:161], v[218:221], v[102:105]
	v_mfma_f32_16x16x32_bf16 v[98:101], v[170:173], v[218:221], v[98:101]
	v_mfma_f32_16x16x32_bf16 v[126:129], v[166:169], v[198:201], v[126:129]
	v_mfma_f32_16x16x32_bf16 v[122:125], v[190:193], v[198:201], v[122:125]
	v_mfma_f32_16x16x32_bf16 v[118:121], v[166:169], v[206:209], v[118:121]
	v_mfma_f32_16x16x32_bf16 v[114:117], v[190:193], v[206:209], v[114:117]
	v_mfma_f32_16x16x32_bf16 v[110:113], v[166:169], v[214:217], v[110:113]
	v_mfma_f32_16x16x32_bf16 v[106:109], v[190:193], v[214:217], v[106:109]
	v_mfma_f32_16x16x32_bf16 v[102:105], v[166:169], v[222:225], v[102:105]
	v_mfma_f32_16x16x32_bf16 v[98:101], v[190:193], v[222:225], v[98:101]
	s_setprio 0
	s_barrier
	v_add_u32_e32 v155, s33, v147
	v_lshl_add_u64 v[246:247], s[14:15], 0, v[136:137]
	v_readfirstlane_b32 s3, v155
	v_lshl_add_u64 v[156:157], v[246:247], 0, s[6:7]
	s_mov_b32 m0, s3
	ds_read_b128 v[226:229], v153
	ds_read_b128 v[230:233], v153 offset:1024
	ds_read_b128 v[234:237], v153 offset:2048
	ds_read_b128 v[238:241], v153 offset:3072
	global_load_lds_dwordx4 v[156:157], off
	v_add_u32_e32 v156, 0x2000, v155
	v_lshl_add_u64 v[248:249], s[14:15], 0, v[138:139]
	v_readfirstlane_b32 s3, v156
	v_lshl_add_u64 v[242:243], v[248:249], 0, s[6:7]
	s_mov_b32 m0, s3
	s_nop 0
	global_load_lds_dwordx4 v[242:243], off
	s_barrier
	s_waitcnt lgkmcnt(0)
	s_setprio 1
	v_mfma_f32_16x16x32_bf16 v[94:97], v[226:229], v[194:197], v[94:97]
	v_mfma_f32_16x16x32_bf16 v[90:93], v[234:237], v[194:197], v[90:93]
	v_mfma_f32_16x16x32_bf16 v[86:89], v[226:229], v[202:205], v[86:89]
	v_mfma_f32_16x16x32_bf16 v[82:85], v[234:237], v[202:205], v[82:85]
	v_mfma_f32_16x16x32_bf16 v[78:81], v[226:229], v[210:213], v[78:81]
	v_mfma_f32_16x16x32_bf16 v[74:77], v[234:237], v[210:213], v[74:77]
	v_mfma_f32_16x16x32_bf16 v[70:73], v[226:229], v[218:221], v[70:73]
	v_mfma_f32_16x16x32_bf16 v[66:69], v[234:237], v[218:221], v[66:69]
	v_mfma_f32_16x16x32_bf16 v[94:97], v[230:233], v[198:201], v[94:97]
	v_mfma_f32_16x16x32_bf16 v[90:93], v[238:241], v[198:201], v[90:93]
	v_mfma_f32_16x16x32_bf16 v[86:89], v[230:233], v[206:209], v[86:89]
	v_mfma_f32_16x16x32_bf16 v[82:85], v[238:241], v[206:209], v[82:85]
	v_mfma_f32_16x16x32_bf16 v[78:81], v[230:233], v[214:217], v[78:81]
	v_mfma_f32_16x16x32_bf16 v[74:77], v[238:241], v[214:217], v[74:77]
	v_mfma_f32_16x16x32_bf16 v[70:73], v[230:233], v[222:225], v[70:73]
	v_mfma_f32_16x16x32_bf16 v[66:69], v[238:241], v[222:225], v[66:69]
	s_setprio 0
	v_readfirstlane_b32 s3, v141
	v_add_u32_e32 v157, 0x2000, v141
	v_lshl_add_u64 v[242:243], v[174:175], 0, s[84:85]
	s_mov_b32 m0, s3
	v_readfirstlane_b32 s3, v157
	s_barrier
	ds_read_b128 v[194:197], v145 offset:16384
	ds_read_b128 v[198:201], v145 offset:17408
	ds_read_b128 v[202:205], v144 offset:16384
	ds_read_b128 v[206:209], v144 offset:17408
	ds_read_b128 v[210:213], v143 offset:16384
	ds_read_b128 v[214:217], v143 offset:17408
	ds_read_b128 v[218:221], v142 offset:16384
	ds_read_b128 v[222:225], v142 offset:17408
	global_load_lds_dwordx4 v[242:243], off
	v_lshl_add_u64 v[242:243], v[186:187], 0, s[84:85]
	s_mov_b32 m0, s3
	s_nop 0
	global_load_lds_dwordx4 v[242:243], off
	s_barrier
	s_waitcnt lgkmcnt(0)
	s_setprio 1
	v_mfma_f32_16x16x32_bf16 v[62:65], v[158:161], v[194:197], v[62:65]
	v_mfma_f32_16x16x32_bf16 v[58:61], v[170:173], v[194:197], v[58:61]
	v_mfma_f32_16x16x32_bf16 v[54:57], v[158:161], v[202:205], v[54:57]
	v_mfma_f32_16x16x32_bf16 v[50:53], v[170:173], v[202:205], v[50:53]
	v_mfma_f32_16x16x32_bf16 v[46:49], v[158:161], v[210:213], v[46:49]
	v_mfma_f32_16x16x32_bf16 v[42:45], v[170:173], v[210:213], v[42:45]
	v_mfma_f32_16x16x32_bf16 v[38:41], v[158:161], v[218:221], v[38:41]
	v_mfma_f32_16x16x32_bf16 v[34:37], v[170:173], v[218:221], v[34:37]
	v_mfma_f32_16x16x32_bf16 v[62:65], v[166:169], v[198:201], v[62:65]
	v_mfma_f32_16x16x32_bf16 v[58:61], v[190:193], v[198:201], v[58:61]
	v_mfma_f32_16x16x32_bf16 v[54:57], v[166:169], v[206:209], v[54:57]
	v_mfma_f32_16x16x32_bf16 v[50:53], v[190:193], v[206:209], v[50:53]
	v_mfma_f32_16x16x32_bf16 v[46:49], v[166:169], v[214:217], v[46:49]
	v_mfma_f32_16x16x32_bf16 v[42:45], v[190:193], v[214:217], v[42:45]
	v_mfma_f32_16x16x32_bf16 v[38:41], v[166:169], v[222:225], v[38:41]
	v_mfma_f32_16x16x32_bf16 v[34:37], v[190:193], v[222:225], v[34:37]
	s_setprio 0
	s_barrier
; #define STAGE_A(P,br,kt) STAGE_G(P,c.A,c.lda,br,(long)(kt)*c.kstr)
; #define STAGE_B(P,br,kt) STAGE_G(P,c.Bt,c.K,br,(long)(kt)*BK)
; #define LDA(dst,b,h) for(int m=0;m<4;++m)for(int k=0;k<2;++k) \
;     dst[m][k]=*reinterpret_cast<const bf16x8*>((char*)SA(b,h)+lds_byte(wr*64+m*16+fr,k*32+fq*8))
; #define LDB(dst,b,h) for(int n=0;n<2;++n)for(int k=0;k<2;++k) \
;     dst[n][k]=*reinterpret_cast<const bf16x8*>((char*)SB(b,h)+lds_byte(wc*32+n*16+fr,k*32+fq*8))
; #define MMA(ai,bj,At,Bt_) do{__builtin_amdgcn_s_setprio(1); \
;     for(int m=0;m<4;++m)for(int n=0;n<2;++n)for(int k=0;k<2;++k) \
;       acc[ai][bj][m][n]=__builtin_amdgcn_mfma_f32_16x16x32_bf16(Bt_[n][k],At[m][k],acc[ai][bj][m][n],0,0,0); \
;     __builtin_amdgcn_s_setprio(0);}while(0)
; #define WAIT_V(n) asm volatile("s_waitcnt vmcnt(" #n ")":::"memory")
; #define WAIT_L(n) asm volatile("s_waitcnt lgkmcnt(" #n ")":::"memory")
; #define BAR __builtin_amdgcn_s_barrier()
; #define SCHED __builtin_amdgcn_sched_barrier(0)
; template <int EPI>
; __device__ __forceinline__ void gemm_run(const GD& c, const bool has_next, const GD& nx, const Ctx& e, bf16* shm, float* rs, float* rs_nxt, float* racc_) {
;     ...
;     STAGE_B(SB(0,1),bcol+HALF,t+2);
;     WAIT_V(6); BAR; MMA(1,1,At,B1); BAR;
;     LDB(B0,1,0); SCHED; LDA(At,1,0); STAGE_A(SA(0,1),brow+HALF,t+2);
;     WAIT_L(8); BAR; WAIT_L(0); MMA(0,0,At,B0); BAR; SCHED;
;     LDB(B1,1,1); STAGE_B(SB(1,0),bcol,t+3);
;     BAR; WAIT_L(0); MMA(0,1,At,B1); BAR;
;     LDA(At,1,1); STAGE_A(SA(1,0),brow,t+3);
;     BAR; WAIT_L(0); MMA(1,0,At,B0); BAR; SCHED;
;     STAGE_B(SB(1,1),bcol+HALF,t+3);
	v_add_u32_e32 v158, s86, v147
	v_add_u32_e32 v159, 0x2000, v158
	v_readfirstlane_b32 s3, v158
	v_lshl_add_u64 v[160:161], v[246:247], 0, s[40:41]
	s_mov_b32 m0, s3
	v_readfirstlane_b32 s3, v159
	global_load_lds_dwordx4 v[160:161], off
	v_lshl_add_u64 v[160:161], v[248:249], 0, s[40:41]
	s_mov_b32 m0, s3
	s_nop 0
	global_load_lds_dwordx4 v[160:161], off
	s_waitcnt vmcnt(6)
	s_barrier
	s_setprio 1
	v_mfma_f32_16x16x32_bf16 v[30:33], v[226:229], v[194:197], v[30:33]
	v_mfma_f32_16x16x32_bf16 v[26:29], v[234:237], v[194:197], v[26:29]
	v_mfma_f32_16x16x32_bf16 v[22:25], v[226:229], v[202:205], v[22:25]
	v_mfma_f32_16x16x32_bf16 v[18:21], v[234:237], v[202:205], v[18:21]
	v_mfma_f32_16x16x32_bf16 v[14:17], v[226:229], v[210:213], v[14:17]
	v_mfma_f32_16x16x32_bf16 v[10:13], v[234:237], v[210:213], v[10:13]
	v_mfma_f32_16x16x32_bf16 v[6:9], v[226:229], v[218:221], v[6:9]
	v_mfma_f32_16x16x32_bf16 v[2:5], v[234:237], v[218:221], v[2:5]
	v_mfma_f32_16x16x32_bf16 v[30:33], v[230:233], v[198:201], v[30:33]
	v_mfma_f32_16x16x32_bf16 v[26:29], v[238:241], v[198:201], v[26:29]
	v_mfma_f32_16x16x32_bf16 v[22:25], v[230:233], v[206:209], v[22:25]
	v_mfma_f32_16x16x32_bf16 v[18:21], v[238:241], v[206:209], v[18:21]
	v_mfma_f32_16x16x32_bf16 v[14:17], v[230:233], v[214:217], v[14:17]
	v_mfma_f32_16x16x32_bf16 v[10:13], v[238:241], v[214:217], v[10:13]
	v_mfma_f32_16x16x32_bf16 v[6:9], v[230:233], v[222:225], v[6:9]
	v_mfma_f32_16x16x32_bf16 v[2:5], v[238:241], v[222:225], v[2:5]
	s_setprio 0
	s_barrier
	ds_read_b128 v[166:169], v148
	ds_read_b128 v[170:173], v148 offset:1024
	ds_read_b128 v[190:193], v148 offset:2048
	ds_read_b128 v[194:197], v148 offset:3072
	v_add_u32_e32 v160, 0x4000, v141
	v_add_u32_e32 v161, 0x6000, v141
	v_readfirstlane_b32 s3, v160
	v_lshl_add_u64 v[230:231], v[174:175], 0, s[92:93]
	s_mov_b32 m0, s3
	v_readfirstlane_b32 s3, v161
	ds_read_b128 v[198:201], v145 offset:32768
	ds_read_b128 v[202:205], v145 offset:33792
	ds_read_b128 v[206:209], v144 offset:32768
	ds_read_b128 v[210:213], v144 offset:33792
	ds_read_b128 v[214:217], v143 offset:32768
	ds_read_b128 v[218:221], v143 offset:33792
	ds_read_b128 v[222:225], v142 offset:32768
	ds_read_b128 v[226:229], v142 offset:33792
	global_load_lds_dwordx4 v[230:231], off
	v_lshl_add_u64 v[230:231], v[186:187], 0, s[92:93]
	s_mov_b32 m0, s3
	s_nop 0
	global_load_lds_dwordx4 v[230:231], off
	s_waitcnt lgkmcnt(8)
	s_barrier
	s_waitcnt lgkmcnt(0)
	s_setprio 1
	v_mfma_f32_16x16x32_bf16 v[126:129], v[166:169], v[198:201], v[126:129]
	v_mfma_f32_16x16x32_bf16 v[122:125], v[190:193], v[198:201], v[122:125]
	v_mfma_f32_16x16x32_bf16 v[118:121], v[166:169], v[206:209], v[118:121]
	v_mfma_f32_16x16x32_bf16 v[114:117], v[190:193], v[206:209], v[114:117]
	v_mfma_f32_16x16x32_bf16 v[110:113], v[166:169], v[214:217], v[110:113]
	v_mfma_f32_16x16x32_bf16 v[106:109], v[190:193], v[214:217], v[106:109]
	v_mfma_f32_16x16x32_bf16 v[102:105], v[166:169], v[222:225], v[102:105]
	v_mfma_f32_16x16x32_bf16 v[98:101], v[190:193], v[222:225], v[98:101]
	v_mfma_f32_16x16x32_bf16 v[126:129], v[170:173], v[202:205], v[126:129]
	v_mfma_f32_16x16x32_bf16 v[122:125], v[194:197], v[202:205], v[122:125]
	v_mfma_f32_16x16x32_bf16 v[118:121], v[170:173], v[210:213], v[118:121]
	v_mfma_f32_16x16x32_bf16 v[114:117], v[194:197], v[210:213], v[114:117]
	v_mfma_f32_16x16x32_bf16 v[110:113], v[170:173], v[218:221], v[110:113]
	v_mfma_f32_16x16x32_bf16 v[106:109], v[194:197], v[218:221], v[106:109]
	v_mfma_f32_16x16x32_bf16 v[102:105], v[170:173], v[226:229], v[102:105]
	v_mfma_f32_16x16x32_bf16 v[98:101], v[194:197], v[226:229], v[98:101]
	s_setprio 0
	s_barrier
	v_readfirstlane_b32 s3, v149
	v_add_u32_e32 v176, 0x2000, v149
	v_lshl_add_u64 v[250:251], v[246:247], 0, s[42:43]
	s_mov_b32 m0, s3
	v_readfirstlane_b32 s3, v176
	ds_read_b128 v[230:233], v146
	ds_read_b128 v[234:237], v146 offset:1024
	ds_read_b128 v[238:241], v146 offset:2048
	ds_read_b128 v[242:245], v146 offset:3072
	global_load_lds_dwordx4 v[250:251], off
	v_lshl_add_u64 v[250:251], v[248:249], 0, s[42:43]
	s_mov_b32 m0, s3
	s_nop 0
	global_load_lds_dwordx4 v[250:251], off
	s_barrier
	s_waitcnt lgkmcnt(0)
	s_setprio 1
	v_mfma_f32_16x16x32_bf16 v[94:97], v[230:233], v[198:201], v[94:97]
	v_mfma_f32_16x16x32_bf16 v[90:93], v[238:241], v[198:201], v[90:93]
	v_mfma_f32_16x16x32_bf16 v[86:89], v[230:233], v[206:209], v[86:89]
	v_mfma_f32_16x16x32_bf16 v[82:85], v[238:241], v[206:209], v[82:85]
	v_mfma_f32_16x16x32_bf16 v[78:81], v[230:233], v[214:217], v[78:81]
	v_mfma_f32_16x16x32_bf16 v[74:77], v[238:241], v[214:217], v[74:77]
	v_mfma_f32_16x16x32_bf16 v[70:73], v[230:233], v[222:225], v[70:73]
	v_mfma_f32_16x16x32_bf16 v[66:69], v[238:241], v[222:225], v[66:69]
	v_mfma_f32_16x16x32_bf16 v[94:97], v[234:237], v[202:205], v[94:97]
	v_mfma_f32_16x16x32_bf16 v[90:93], v[242:245], v[202:205], v[90:93]
	v_mfma_f32_16x16x32_bf16 v[86:89], v[234:237], v[210:213], v[86:89]
	v_mfma_f32_16x16x32_bf16 v[82:85], v[242:245], v[210:213], v[82:85]
	v_mfma_f32_16x16x32_bf16 v[78:81], v[234:237], v[218:221], v[78:81]
	v_mfma_f32_16x16x32_bf16 v[74:77], v[242:245], v[218:221], v[74:77]
	v_mfma_f32_16x16x32_bf16 v[70:73], v[234:237], v[226:229], v[70:73]
	v_mfma_f32_16x16x32_bf16 v[66:69], v[242:245], v[226:229], v[66:69]
	s_setprio 0
	v_readfirstlane_b32 s3, v150
	v_lshl_add_u64 v[174:175], v[174:175], 0, s[80:81]
	s_mov_b32 m0, s3
	v_readfirstlane_b32 s3, v151
	s_barrier
; #define STAGE_A(P,br,kt) STAGE_G(P,c.A,c.lda,br,(long)(kt)*c.kstr)
; #define STAGE_B(P,br,kt) STAGE_G(P,c.Bt,c.K,br,(long)(kt)*BK)
; #define LDA(dst,b,h) for(int m=0;m<4;++m)for(int k=0;k<2;++k) \
;     dst[m][k]=*reinterpret_cast<const bf16x8*>((char*)SA(b,h)+lds_byte(wr*64+m*16+fr,k*32+fq*8))
; #define LDB(dst,b,h) for(int n=0;n<2;++n)for(int k=0;k<2;++k) \
;     dst[n][k]=*reinterpret_cast<const bf16x8*>((char*)SB(b,h)+lds_byte(wc*32+n*16+fr,k*32+fq*8))
; #define MMA(ai,bj,At,Bt_) do{__builtin_amdgcn_s_setprio(1); \
;     for(int m=0;m<4;++m)for(int n=0;n<2;++n)for(int k=0;k<2;++k) \
;       acc[ai][bj][m][n]=__builtin_amdgcn_mfma_f32_16x16x32_bf16(Bt_[n][k],At[m][k],acc[ai][bj][m][n],0,0,0); \
;     __builtin_amdgcn_s_setprio(0);}while(0)
; #define WAIT_V(n) asm volatile("s_waitcnt vmcnt(" #n ")":::"memory")
; #define WAIT_L(n) asm volatile("s_waitcnt lgkmcnt(" #n ")":::"memory")
; #define BAR __builtin_amdgcn_s_barrier()
; #define SCHED __builtin_amdgcn_sched_barrier(0)
; template <int EPI>
; __device__ __forceinline__ void gemm_run(const GD& c, const bool has_next, const GD& nx, const Ctx& e, bf16* shm, float* rs, float* rs_nxt, float* racc_) {
;     ...
;     LDB(B1,1,1); STAGE_B(SB(1,0),bcol,t+3);
;     BAR; WAIT_L(0); MMA(0,1,At,B1); BAR;
;     LDA(At,1,1); STAGE_A(SA(1,0),brow,t+3);
;     BAR; WAIT_L(0); MMA(1,0,At,B0); BAR; SCHED;
;     STAGE_B(SB(1,1),bcol+HALF,t+3);
;     WAIT_V(6); BAR; MMA(1,1,At,B1); BAR;
;   }
;   { LDB(B0,0,0); LDA(At,0,0); STAGE_A(SA(1,1),brow+HALF,nt-1);
;     BAR; WAIT_L(0); MMA(0,0,At,B0); BAR;
	ds_read_b128 v[198:201], v145 offset:49152
	ds_read_b128 v[202:205], v145 offset:50176
	ds_read_b128 v[206:209], v144 offset:49152
	ds_read_b128 v[210:213], v144 offset:50176
	ds_read_b128 v[214:217], v143 offset:49152
	ds_read_b128 v[218:221], v143 offset:50176
	ds_read_b128 v[222:225], v142 offset:49152
	ds_read_b128 v[226:229], v142 offset:50176
	global_load_lds_dwordx4 v[174:175], off
	v_lshl_add_u64 v[174:175], v[186:187], 0, s[80:81]
	s_mov_b32 m0, s3
	s_nop 0
	global_load_lds_dwordx4 v[174:175], off
	s_barrier
	s_waitcnt lgkmcnt(0)
	s_setprio 1
	v_mfma_f32_16x16x32_bf16 v[62:65], v[166:169], v[198:201], v[62:65]
	v_mfma_f32_16x16x32_bf16 v[58:61], v[190:193], v[198:201], v[58:61]
	v_mfma_f32_16x16x32_bf16 v[54:57], v[166:169], v[206:209], v[54:57]
	v_mfma_f32_16x16x32_bf16 v[50:53], v[190:193], v[206:209], v[50:53]
	v_mfma_f32_16x16x32_bf16 v[46:49], v[166:169], v[214:217], v[46:49]
	v_mfma_f32_16x16x32_bf16 v[42:45], v[190:193], v[214:217], v[42:45]
	v_mfma_f32_16x16x32_bf16 v[38:41], v[166:169], v[222:225], v[38:41]
	v_mfma_f32_16x16x32_bf16 v[34:37], v[190:193], v[222:225], v[34:37]
	v_mfma_f32_16x16x32_bf16 v[62:65], v[170:173], v[202:205], v[62:65]
	v_mfma_f32_16x16x32_bf16 v[58:61], v[194:197], v[202:205], v[58:61]
	v_mfma_f32_16x16x32_bf16 v[54:57], v[170:173], v[210:213], v[54:57]
	v_mfma_f32_16x16x32_bf16 v[50:53], v[194:197], v[210:213], v[50:53]
	v_mfma_f32_16x16x32_bf16 v[46:49], v[170:173], v[218:221], v[46:49]
	v_mfma_f32_16x16x32_bf16 v[42:45], v[194:197], v[218:221], v[42:45]
	v_mfma_f32_16x16x32_bf16 v[38:41], v[170:173], v[226:229], v[38:41]
	v_mfma_f32_16x16x32_bf16 v[34:37], v[194:197], v[226:229], v[34:37]
	s_setprio 0
	s_barrier
	v_readfirstlane_b32 s3, v152
	v_add_u32_e32 v168, 0x2000, v152
	v_lshl_add_u64 v[166:167], v[246:247], 0, s[44:45]
	s_mov_b32 m0, s3
	v_readfirstlane_b32 s3, v168
	global_load_lds_dwordx4 v[166:167], off
	v_lshl_add_u64 v[166:167], v[248:249], 0, s[44:45]
	s_mov_b32 m0, s3
	s_nop 0
	global_load_lds_dwordx4 v[166:167], off
	s_waitcnt vmcnt(6)
	s_barrier
	s_setprio 1
	v_mfma_f32_16x16x32_bf16 v[30:33], v[230:233], v[198:201], v[30:33]
	v_mfma_f32_16x16x32_bf16 v[26:29], v[238:241], v[198:201], v[26:29]
	v_mfma_f32_16x16x32_bf16 v[22:25], v[230:233], v[206:209], v[22:25]
	v_mfma_f32_16x16x32_bf16 v[18:21], v[238:241], v[206:209], v[18:21]
	v_mfma_f32_16x16x32_bf16 v[14:17], v[230:233], v[214:217], v[14:17]
	v_mfma_f32_16x16x32_bf16 v[10:13], v[238:241], v[214:217], v[10:13]
	v_mfma_f32_16x16x32_bf16 v[6:9], v[230:233], v[222:225], v[6:9]
	v_mfma_f32_16x16x32_bf16 v[2:5], v[238:241], v[222:225], v[2:5]
	v_mfma_f32_16x16x32_bf16 v[30:33], v[234:237], v[202:205], v[30:33]
	v_mfma_f32_16x16x32_bf16 v[26:29], v[242:245], v[202:205], v[26:29]
	v_mfma_f32_16x16x32_bf16 v[22:25], v[234:237], v[210:213], v[22:25]
	v_mfma_f32_16x16x32_bf16 v[18:21], v[242:245], v[210:213], v[18:21]
	v_mfma_f32_16x16x32_bf16 v[14:17], v[234:237], v[218:221], v[14:17]
	v_mfma_f32_16x16x32_bf16 v[10:13], v[242:245], v[218:221], v[10:13]
	v_mfma_f32_16x16x32_bf16 v[6:9], v[234:237], v[226:229], v[6:9]
	v_mfma_f32_16x16x32_bf16 v[2:5], v[242:245], v[226:229], v[2:5]
	s_setprio 0
	s_add_i32 s2, s2, 2
	v_lshl_add_u64 v[130:131], v[130:131], 0, s[88:89]
	v_lshl_add_u64 v[132:133], v[132:133], 0, s[88:89]
	v_lshl_add_u64 v[136:137], v[136:137], 0, s[88:89]
	s_cmp_lt_u32 s2, 12
	v_lshl_add_u64 v[138:139], v[138:139], 0, s[88:89]
	s_barrier
	s_cbranch_scc1 .LBB0_464
	s_or_b32 s2, s36, 0x80
	s_ashr_i32 s3, s2, 31
	s_lshl_b64 s[2:3], s[2:3], 11
	s_add_u32 s2, s50, s2
	s_addc_u32 s3, s51, s3
	v_lshl_add_u64 v[150:151], s[2:3], 0, v[0:1]
	s_mov_b64 s[40:41], 0x780
	v_readfirstlane_b32 s6, v162
	v_lshl_add_u64 v[150:151], v[150:151], 0, s[40:41]
	s_mov_b32 m0, s6
	ds_read_b128 v[130:133], v154
	ds_read_b128 v[136:139], v154 offset:1024
	ds_read_b128 v[166:169], v154 offset:2048
	ds_read_b128 v[170:173], v154 offset:3072
	ds_read_b128 v[190:193], v145
	ds_read_b128 v[194:197], v145 offset:1024
	ds_read_b128 v[198:201], v144
	ds_read_b128 v[202:205], v144 offset:1024
	ds_read_b128 v[206:209], v143
	ds_read_b128 v[210:213], v143 offset:1024
	ds_read_b128 v[214:217], v142
	ds_read_b128 v[218:221], v142 offset:1024
	global_load_lds_dwordx4 v[150:151], off
	v_lshl_add_u64 v[150:151], s[2:3], 0, v[134:135]
	v_readfirstlane_b32 s2, v163
	v_lshl_add_u64 v[150:151], v[150:151], 0, s[40:41]
	s_mov_b32 m0, s2
	s_nop 0
	global_load_lds_dwordx4 v[150:151], off
	s_barrier
	s_waitcnt lgkmcnt(0)
	s_setprio 1
	v_mfma_f32_16x16x32_bf16 v[126:129], v[130:133], v[190:193], v[126:129]
	v_mfma_f32_16x16x32_bf16 v[122:125], v[166:169], v[190:193], v[122:125]
	v_mfma_f32_16x16x32_bf16 v[118:121], v[130:133], v[198:201], v[118:121]
	v_mfma_f32_16x16x32_bf16 v[106:109], v[166:169], v[206:209], v[106:109]
	v_mfma_f32_16x16x32_bf16 v[102:105], v[130:133], v[214:217], v[102:105]
	v_mfma_f32_16x16x32_bf16 v[126:129], v[136:139], v[194:197], v[126:129]
	v_mfma_f32_16x16x32_bf16 v[122:125], v[170:173], v[194:197], v[122:125]
	v_mfma_f32_16x16x32_bf16 v[118:121], v[136:139], v[202:205], v[118:121]
	v_mfma_f32_16x16x32_bf16 v[114:117], v[166:169], v[198:201], v[114:117]
	v_mfma_f32_16x16x32_bf16 v[110:113], v[130:133], v[206:209], v[110:113]
	v_mfma_f32_16x16x32_bf16 v[106:109], v[170:173], v[210:213], v[106:109]
	v_mfma_f32_16x16x32_bf16 v[102:105], v[136:139], v[218:221], v[102:105]
	v_mfma_f32_16x16x32_bf16 v[98:101], v[166:169], v[214:217], v[98:101]
	v_mfma_f32_16x16x32_bf16 v[222:225], v[170:173], v[202:205], v[114:117]
	v_mfma_f32_16x16x32_bf16 v[226:229], v[136:139], v[210:213], v[110:113]
	v_mfma_f32_16x16x32_bf16 v[230:233], v[170:173], v[218:221], v[98:101]
	s_setprio 0
	s_barrier
; #define STAGE_A(P,br,kt) STAGE_G(P,c.A,c.lda,br,(long)(kt)*c.kstr)
; #define LDA(dst,b,h) for(int m=0;m<4;++m)for(int k=0;k<2;++k) \
;     dst[m][k]=*reinterpret_cast<const bf16x8*>((char*)SA(b,h)+lds_byte(wr*64+m*16+fr,k*32+fq*8))
; #define LDB(dst,b,h) for(int n=0;n<2;++n)for(int k=0;k<2;++k) \
;     dst[n][k]=*reinterpret_cast<const bf16x8*>((char*)SB(b,h)+lds_byte(wc*32+n*16+fr,k*32+fq*8))
; #define MMA(ai,bj,At,Bt_) do{__builtin_amdgcn_s_setprio(1); \
;     for(int m=0;m<4;++m)for(int n=0;n<2;++n)for(int k=0;k<2;++k) \
;       acc[ai][bj][m][n]=__builtin_amdgcn_mfma_f32_16x16x32_bf16(Bt_[n][k],At[m][k],acc[ai][bj][m][n],0,0,0); \
;     __builtin_amdgcn_s_setprio(0);}while(0)
; #define WAIT_V(n) asm volatile("s_waitcnt vmcnt(" #n ")":::"memory")
; #define WAIT_L(n) asm volatile("s_waitcnt lgkmcnt(" #n ")":::"memory")
; #define BAR __builtin_amdgcn_s_barrier()
; template <int EPI>
; __device__ __forceinline__ void gemm_run(const GD& c, const bool has_next, const GD& nx, const Ctx& e, bf16* shm, float* rs, float* rs_nxt, float* racc_) {
;     ...
;   { LDB(B0,0,0); LDA(At,0,0); STAGE_A(SA(1,1),brow+HALF,nt-1);
;     BAR; WAIT_L(0); MMA(0,0,At,B0); BAR;
;     LDB(B1,0,1); BAR; WAIT_L(0); MMA(0,1,At,B1); BAR;
;     LDA(At,0,1); WAIT_V(4); BAR; WAIT_L(0); MMA(1,0,At,B0); MMA(1,1,At,B1); BAR; }
;   { LDB(B0,1,0); LDA(At,1,0); WAIT_V(2); BAR; WAIT_L(0); MMA(0,0,At,B0); BAR;
	s_nop 2
	ds_read_b128 v[98:101], v153
	ds_read_b128 v[110:113], v153 offset:1024
	ds_read_b128 v[114:117], v153 offset:2048
	ds_read_b128 v[150:153], v153 offset:3072
	s_barrier
	s_waitcnt lgkmcnt(0)
	s_setprio 1
	v_mfma_f32_16x16x32_bf16 v[90:93], v[114:117], v[190:193], v[90:93]
	v_mfma_f32_16x16x32_bf16 v[86:89], v[98:101], v[198:201], v[86:89]
	v_mfma_f32_16x16x32_bf16 v[74:77], v[114:117], v[206:209], v[74:77]
	v_mfma_f32_16x16x32_bf16 v[70:73], v[98:101], v[214:217], v[70:73]
	v_mfma_f32_16x16x32_bf16 v[66:69], v[114:117], v[214:217], v[66:69]
	v_mfma_f32_16x16x32_bf16 v[94:97], v[98:101], v[190:193], v[94:97]
	v_mfma_f32_16x16x32_bf16 v[90:93], v[150:153], v[194:197], v[90:93]
	v_mfma_f32_16x16x32_bf16 v[86:89], v[110:113], v[202:205], v[86:89]
	v_mfma_f32_16x16x32_bf16 v[82:85], v[114:117], v[198:201], v[82:85]
	v_mfma_f32_16x16x32_bf16 v[78:81], v[98:101], v[206:209], v[78:81]
	v_mfma_f32_16x16x32_bf16 v[74:77], v[150:153], v[210:213], v[74:77]
	v_mfma_f32_16x16x32_bf16 v[70:73], v[110:113], v[218:221], v[70:73]
	v_mfma_f32_16x16x32_bf16 v[66:69], v[150:153], v[218:221], v[66:69]
	v_mfma_f32_16x16x32_bf16 v[234:237], v[110:113], v[194:197], v[94:97]
	v_mfma_f32_16x16x32_bf16 v[190:193], v[150:153], v[202:205], v[82:85]
	v_mfma_f32_16x16x32_bf16 v[194:197], v[110:113], v[210:213], v[78:81]
	s_setprio 0
	s_barrier
	s_nop 0
	ds_read_b128 v[78:81], v145 offset:16384
	ds_read_b128 v[82:85], v145 offset:17408
	ds_read_b128 v[94:97], v144 offset:16384
	ds_read_b128 v[198:201], v144 offset:17408
	ds_read_b128 v[202:205], v143 offset:16384
	ds_read_b128 v[206:209], v143 offset:17408
	ds_read_b128 v[210:213], v142 offset:16384
	ds_read_b128 v[214:217], v142 offset:17408
	s_waitcnt vmcnt(4)
	s_barrier
	s_waitcnt lgkmcnt(0)
	s_setprio 1
	v_mfma_f32_16x16x32_bf16 v[62:65], v[130:133], v[78:81], v[62:65]
	v_mfma_f32_16x16x32_bf16 v[58:61], v[166:169], v[78:81], v[58:61]
	v_mfma_f32_16x16x32_bf16 v[54:57], v[130:133], v[94:97], v[54:57]
	v_mfma_f32_16x16x32_bf16 v[42:45], v[166:169], v[202:205], v[42:45]
	v_mfma_f32_16x16x32_bf16 v[38:41], v[130:133], v[210:213], v[38:41]
	v_mfma_f32_16x16x32_bf16 v[62:65], v[136:139], v[82:85], v[62:65]
	v_mfma_f32_16x16x32_bf16 v[58:61], v[170:173], v[82:85], v[58:61]
	v_mfma_f32_16x16x32_bf16 v[54:57], v[136:139], v[198:201], v[54:57]
	v_mfma_f32_16x16x32_bf16 v[50:53], v[166:169], v[94:97], v[50:53]
	v_mfma_f32_16x16x32_bf16 v[46:49], v[130:133], v[202:205], v[46:49]
	v_mfma_f32_16x16x32_bf16 v[42:45], v[170:173], v[206:209], v[42:45]
	v_mfma_f32_16x16x32_bf16 v[38:41], v[136:139], v[214:217], v[38:41]
	v_mfma_f32_16x16x32_bf16 v[34:37], v[166:169], v[210:213], v[34:37]
	v_mfma_f32_16x16x32_bf16 v[218:221], v[170:173], v[198:201], v[50:53]
	v_mfma_f32_16x16x32_bf16 v[238:241], v[136:139], v[206:209], v[46:49]
	v_mfma_f32_16x16x32_bf16 v[136:139], v[170:173], v[214:217], v[34:37]
	s_setprio 0
	s_setprio 1
	v_mfma_f32_16x16x32_bf16 v[26:29], v[114:117], v[78:81], v[26:29]
	v_mfma_f32_16x16x32_bf16 v[22:25], v[98:101], v[94:97], v[22:25]
	v_mfma_f32_16x16x32_bf16 v[10:13], v[114:117], v[202:205], v[10:13]
	v_mfma_f32_16x16x32_bf16 v[6:9], v[98:101], v[210:213], v[6:9]
	v_mfma_f32_16x16x32_bf16 v[30:33], v[98:101], v[78:81], v[30:33]
	v_mfma_f32_16x16x32_bf16 v[26:29], v[150:153], v[82:85], v[26:29]
	v_mfma_f32_16x16x32_bf16 v[22:25], v[110:113], v[198:201], v[22:25]
	v_mfma_f32_16x16x32_bf16 v[18:21], v[114:117], v[94:97], v[18:21]
	v_mfma_f32_16x16x32_bf16 v[14:17], v[98:101], v[202:205], v[14:17]
	v_mfma_f32_16x16x32_bf16 v[10:13], v[150:153], v[206:209], v[10:13]
	v_mfma_f32_16x16x32_bf16 v[6:9], v[110:113], v[214:217], v[6:9]
	v_mfma_f32_16x16x32_bf16 v[2:5], v[114:117], v[210:213], v[2:5]
	v_mfma_f32_16x16x32_bf16 v[166:169], v[110:113], v[82:85], v[30:33]
	v_mfma_f32_16x16x32_bf16 v[170:173], v[150:153], v[198:201], v[18:21]
	v_mfma_f32_16x16x32_bf16 v[198:201], v[110:113], v[206:209], v[14:17]
	v_mfma_f32_16x16x32_bf16 v[2:5], v[150:153], v[214:217], v[2:5]
	s_setprio 0
	s_barrier
	ds_read_b128 v[14:17], v148
	ds_read_b128 v[18:21], v148 offset:1024
	ds_read_b128 v[150:153], v148 offset:2048
	ds_read_b128 v[202:205], v148 offset:3072
	ds_read_b128 v[30:33], v145 offset:32768
	ds_read_b128 v[34:37], v145 offset:33792
	ds_read_b128 v[46:49], v144 offset:32768
	ds_read_b128 v[50:53], v144 offset:33792
	ds_read_b128 v[206:209], v143 offset:32768
	ds_read_b128 v[210:213], v143 offset:33792
	ds_read_b128 v[214:217], v142 offset:32768
	ds_read_b128 v[242:245], v142 offset:33792
	s_waitcnt vmcnt(2)
	s_barrier
; #define LDA(dst,b,h) for(int m=0;m<4;++m)for(int k=0;k<2;++k) \
;     dst[m][k]=*reinterpret_cast<const bf16x8*>((char*)SA(b,h)+lds_byte(wr*64+m*16+fr,k*32+fq*8))
; #define LDB(dst,b,h) for(int n=0;n<2;++n)for(int k=0;k<2;++k) \
;     dst[n][k]=*reinterpret_cast<const bf16x8*>((char*)SB(b,h)+lds_byte(wc*32+n*16+fr,k*32+fq*8))
; #define MMA(ai,bj,At,Bt_) do{__builtin_amdgcn_s_setprio(1); \
;     for(int m=0;m<4;++m)for(int n=0;n<2;++n)for(int k=0;k<2;++k) \
;       acc[ai][bj][m][n]=__builtin_amdgcn_mfma_f32_16x16x32_bf16(Bt_[n][k],At[m][k],acc[ai][bj][m][n],0,0,0); \
;     __builtin_amdgcn_s_setprio(0);}while(0)
; #define WAIT_V(n) asm volatile("s_waitcnt vmcnt(" #n ")":::"memory")
; #define WAIT_L(n) asm volatile("s_waitcnt lgkmcnt(" #n ")":::"memory")
; #define BAR __builtin_amdgcn_s_barrier()
; template <int EPI>
; __device__ __forceinline__ void gemm_run(const GD& c, const bool has_next, const GD& nx, const Ctx& e, bf16* shm, float* rs, float* rs_nxt, float* racc_) {
;     ...
;   { LDB(B0,1,0); LDA(At,1,0); WAIT_V(2); BAR; WAIT_L(0); MMA(0,0,At,B0); BAR;
;     LDB(B1,1,1); WAIT_V(0); BAR; WAIT_L(0); MMA(0,1,At,B1); BAR;
;     LDA(At,1,1); BAR; WAIT_L(0); MMA(1,0,At,B0); MMA(1,1,At,B1); BAR; }
;   if(wr==0)BAR;
	s_waitcnt lgkmcnt(0)
	s_setprio 1
	v_mfma_f32_16x16x32_bf16 v[78:81], v[14:17], v[30:33], v[126:129]
	v_mfma_f32_16x16x32_bf16 v[130:133], v[18:21], v[34:37], v[78:81]
	v_mfma_f32_16x16x32_bf16 v[78:81], v[150:153], v[30:33], v[122:125]
	v_mfma_f32_16x16x32_bf16 v[126:129], v[202:205], v[34:37], v[78:81]
	v_mfma_f32_16x16x32_bf16 v[78:81], v[14:17], v[46:49], v[118:121]
	v_mfma_f32_16x16x32_bf16 v[114:117], v[18:21], v[50:53], v[78:81]
	v_mfma_f32_16x16x32_bf16 v[78:81], v[150:153], v[46:49], v[222:225]
	v_mfma_f32_16x16x32_bf16 v[110:113], v[202:205], v[50:53], v[78:81]
	v_mfma_f32_16x16x32_bf16 v[78:81], v[14:17], v[206:209], v[226:229]
	v_mfma_f32_16x16x32_bf16 v[98:101], v[18:21], v[210:213], v[78:81]
	v_mfma_f32_16x16x32_bf16 v[78:81], v[150:153], v[206:209], v[106:109]
	v_mfma_f32_16x16x32_bf16 v[94:97], v[202:205], v[210:213], v[78:81]
	v_mfma_f32_16x16x32_bf16 v[78:81], v[14:17], v[214:217], v[102:105]
	v_mfma_f32_16x16x32_bf16 v[82:85], v[18:21], v[242:245], v[78:81]
	v_mfma_f32_16x16x32_bf16 v[78:81], v[150:153], v[214:217], v[230:233]
	v_mfma_f32_16x16x32_bf16 v[78:81], v[202:205], v[242:245], v[78:81]
	s_setprio 0
	s_barrier
	ds_read_b128 v[222:225], v146
	ds_read_b128 v[226:229], v146 offset:1024
	ds_read_b128 v[230:233], v146 offset:2048
	ds_read_b128 v[146:149], v146 offset:3072
	s_waitcnt vmcnt(0)
	s_barrier
	s_waitcnt lgkmcnt(0)
	s_setprio 1
	v_mfma_f32_16x16x32_bf16 v[102:105], v[222:225], v[30:33], v[234:237]
	v_mfma_f32_16x16x32_bf16 v[30:33], v[230:233], v[30:33], v[90:93]
	v_mfma_f32_16x16x32_bf16 v[118:121], v[146:149], v[34:37], v[30:33]
	v_mfma_f32_16x16x32_bf16 v[30:33], v[222:225], v[46:49], v[86:89]
	v_mfma_f32_16x16x32_bf16 v[106:109], v[226:229], v[50:53], v[30:33]
	v_mfma_f32_16x16x32_bf16 v[30:33], v[230:233], v[46:49], v[190:193]
	v_mfma_f32_16x16x32_bf16 v[122:125], v[226:229], v[34:37], v[102:105]
	v_mfma_f32_16x16x32_bf16 v[102:105], v[146:149], v[50:53], v[30:33]
	v_mfma_f32_16x16x32_bf16 v[30:33], v[222:225], v[206:209], v[194:197]
	v_mfma_f32_16x16x32_bf16 v[90:93], v[226:229], v[210:213], v[30:33]
	v_mfma_f32_16x16x32_bf16 v[30:33], v[230:233], v[206:209], v[74:77]
	v_mfma_f32_16x16x32_bf16 v[86:89], v[146:149], v[210:213], v[30:33]
	v_mfma_f32_16x16x32_bf16 v[30:33], v[222:225], v[214:217], v[70:73]
	v_mfma_f32_16x16x32_bf16 v[74:77], v[226:229], v[242:245], v[30:33]
	v_mfma_f32_16x16x32_bf16 v[30:33], v[230:233], v[214:217], v[66:69]
	v_mfma_f32_16x16x32_bf16 v[70:73], v[146:149], v[242:245], v[30:33]
	s_setprio 0
	s_barrier
	ds_read_b128 v[190:193], v145 offset:49152
	ds_read_b128 v[194:197], v145 offset:50176
	ds_read_b128 v[206:209], v144 offset:49152
	ds_read_b128 v[210:213], v144 offset:50176
	ds_read_b128 v[214:217], v143 offset:49152
	ds_read_b128 v[234:237], v143 offset:50176
	ds_read_b128 v[242:245], v142 offset:49152
	ds_read_b128 v[142:145], v142 offset:50176
	s_barrier
	s_waitcnt lgkmcnt(0)
	s_setprio 1
	v_mfma_f32_16x16x32_bf16 v[30:33], v[14:17], v[190:193], v[62:65]
	v_mfma_f32_16x16x32_bf16 v[66:69], v[18:21], v[194:197], v[30:33]
	v_mfma_f32_16x16x32_bf16 v[30:33], v[150:153], v[190:193], v[58:61]
	v_mfma_f32_16x16x32_bf16 v[62:65], v[202:205], v[194:197], v[30:33]
	v_mfma_f32_16x16x32_bf16 v[30:33], v[14:17], v[206:209], v[54:57]
	v_mfma_f32_16x16x32_bf16 v[50:53], v[18:21], v[210:213], v[30:33]
	v_mfma_f32_16x16x32_bf16 v[30:33], v[150:153], v[206:209], v[218:221]
	v_mfma_f32_16x16x32_bf16 v[46:49], v[202:205], v[210:213], v[30:33]
	v_mfma_f32_16x16x32_bf16 v[30:33], v[14:17], v[214:217], v[238:241]
	v_mfma_f32_16x16x32_bf16 v[14:17], v[14:17], v[242:245], v[38:41]
	v_mfma_f32_16x16x32_bf16 v[34:37], v[18:21], v[234:237], v[30:33]
	v_mfma_f32_16x16x32_bf16 v[30:33], v[150:153], v[214:217], v[42:45]
	v_mfma_f32_16x16x32_bf16 v[18:21], v[18:21], v[142:145], v[14:17]
	v_mfma_f32_16x16x32_bf16 v[14:17], v[150:153], v[242:245], v[136:139]
	v_mfma_f32_16x16x32_bf16 v[30:33], v[202:205], v[234:237], v[30:33]
	v_mfma_f32_16x16x32_bf16 v[14:17], v[202:205], v[142:145], v[14:17]
	s_setprio 0
	s_setprio 1
	v_mfma_f32_16x16x32_bf16 v[22:25], v[222:225], v[206:209], v[22:25]
	v_mfma_f32_16x16x32_bf16 v[38:41], v[222:225], v[190:193], v[166:169]
	v_mfma_f32_16x16x32_bf16 v[42:45], v[226:229], v[210:213], v[22:25]
	v_mfma_f32_16x16x32_bf16 v[22:25], v[230:233], v[206:209], v[170:173]
	v_mfma_f32_16x16x32_bf16 v[58:61], v[226:229], v[194:197], v[38:41]
	v_mfma_f32_16x16x32_bf16 v[26:29], v[230:233], v[190:193], v[26:29]
	v_mfma_f32_16x16x32_bf16 v[38:41], v[146:149], v[210:213], v[22:25]
	v_mfma_f32_16x16x32_bf16 v[22:25], v[222:225], v[214:217], v[198:201]
	v_mfma_f32_16x16x32_bf16 v[10:13], v[230:233], v[214:217], v[10:13]
	v_mfma_f32_16x16x32_bf16 v[6:9], v[222:225], v[242:245], v[6:9]
	v_mfma_f32_16x16x32_bf16 v[2:5], v[230:233], v[242:245], v[2:5]
	v_mfma_f32_16x16x32_bf16 v[54:57], v[146:149], v[194:197], v[26:29]
	v_mfma_f32_16x16x32_bf16 v[26:29], v[226:229], v[234:237], v[22:25]
	v_mfma_f32_16x16x32_bf16 v[22:25], v[146:149], v[234:237], v[10:13]
	v_mfma_f32_16x16x32_bf16 v[10:13], v[226:229], v[142:145], v[6:9]
	v_mfma_f32_16x16x32_bf16 v[6:9], v[146:149], v[142:145], v[2:5]
	s_setprio 0
	v_cmp_gt_u32_e32 vcc, s96, v140
	s_barrier
	s_and_saveexec_b64 s[2:3], vcc
	s_cbranch_execz .LBB0_467
	s_barrier

; #define STAGE_A(P,br,kt) STAGE_G(P,c.A,c.lda,br,(long)(kt)*c.kstr)
; #define STAGE_B(P,br,kt) STAGE_G(P,c.Bt,c.K,br,(long)(kt)*BK)
; #define LDA(dst,b,h) for(int m=0;m<4;++m)for(int k=0;k<2;++k) \
;     dst[m][k]=*reinterpret_cast<const bf16x8*>((char*)SA(b,h)+lds_byte(wr*64+m*16+fr,k*32+fq*8))
; #define LDB(dst,b,h) for(int n=0;n<2;++n)for(int k=0;k<2;++k) \
;     dst[n][k]=*reinterpret_cast<const bf16x8*>((char*)SB(b,h)+lds_byte(wc*32+n*16+fr,k*32+fq*8))
; #define MMA(ai,bj,At,Bt_) do{__builtin_amdgcn_s_setprio(1); \
;     for(int m=0;m<4;++m)for(int n=0;n<2;++n)for(int k=0;k<2;++k) \
;       acc[ai][bj][m][n]=__builtin_amdgcn_mfma_f32_16x16x32_bf16(Bt_[n][k],At[m][k],acc[ai][bj][m][n],0,0,0); \
;     __builtin_amdgcn_s_setprio(0);}while(0)
; #define WAIT_V(n) asm volatile("s_waitcnt vmcnt(" #n ")":::"memory")
; #define WAIT_L(n) asm volatile("s_waitcnt lgkmcnt(" #n ")":::"memory")
; #define BAR __builtin_amdgcn_s_barrier()
; #define SCHED __builtin_amdgcn_sched_barrier(0)
; template <int EPI>
; __device__ __forceinline__ void gemm_run(const GD& c, const bool has_next, const GD& nx, const Ctx& e, bf16* shm, float* rs, float* rs_nxt, float* racc_) {
;     ...
;   for(int t=0;t<nt-2;t+=2){
;     LDB(B0,0,0); SCHED; LDA(At,0,0); STAGE_A(SA(1,1),brow+HALF,t+1);
;     WAIT_L(8); BAR; WAIT_L(0); MMA(0,0,At,B0); BAR; SCHED;
;     LDB(B1,0,1); STAGE_B(SB(0,0),bcol,t+2);
;     BAR; WAIT_L(0); MMA(0,1,At,B1); BAR;
;     LDA(At,0,1); STAGE_A(SA(0,0),brow,t+2);
;     BAR; WAIT_L(0); MMA(1,0,At,B0); BAR; SCHED;
;     STAGE_B(SB(0,1),bcol+HALF,t+2);
;     WAIT_V(6); BAR; MMA(1,1,At,B1); BAR;
.LBB0_689:
	ds_read_b128 v[156:159], v146
	ds_read_b128 v[160:163], v146 offset:1024
	ds_read_b128 v[166:169], v146 offset:2048
	ds_read_b128 v[172:175], v146 offset:3072
	s_lshl_b32 s42, s39, 7
	s_add_u32 s40, s22, s42
	s_addc_u32 s41, s23, 0
	v_add_u32_e32 v147, 0xc000, v133
	v_lshl_add_u64 v[234:235], s[40:41], 0, v[0:1]
	v_readfirstlane_b32 s43, v147
	v_add_u32_e32 v155, 0xe000, v133
	v_lshl_add_u64 v[148:149], v[234:235], 0, s[66:67]
	s_mov_b32 m0, s43
	v_lshl_add_u64 v[236:237], s[40:41], 0, v[130:131]
	v_readfirstlane_b32 s40, v155
	ds_read_b128 v[150:153], v137
	ds_read_b128 v[186:189], v137 offset:1024
	ds_read_b128 v[190:193], v136
	ds_read_b128 v[194:197], v136 offset:1024
	ds_read_b128 v[198:201], v135
	ds_read_b128 v[202:205], v135 offset:1024
	ds_read_b128 v[206:209], v134
	ds_read_b128 v[210:213], v134 offset:1024
	global_load_lds_dwordx4 v[148:149], off
	v_lshl_add_u64 v[148:149], v[236:237], 0, s[66:67]
	s_mov_b32 m0, s40
	s_nop 0
	global_load_lds_dwordx4 v[148:149], off
	s_waitcnt lgkmcnt(8)
	s_barrier
	s_waitcnt lgkmcnt(0)
	s_setprio 1
	v_mfma_f32_16x16x32_bf16 v[126:129], v[156:159], v[150:153], v[126:129]
	v_mfma_f32_16x16x32_bf16 v[122:125], v[166:169], v[150:153], v[122:125]
	v_mfma_f32_16x16x32_bf16 v[118:121], v[156:159], v[190:193], v[118:121]
	v_mfma_f32_16x16x32_bf16 v[114:117], v[166:169], v[190:193], v[114:117]
	v_mfma_f32_16x16x32_bf16 v[110:113], v[156:159], v[198:201], v[110:113]
	v_mfma_f32_16x16x32_bf16 v[106:109], v[166:169], v[198:201], v[106:109]
	v_mfma_f32_16x16x32_bf16 v[102:105], v[156:159], v[206:209], v[102:105]
	v_mfma_f32_16x16x32_bf16 v[98:101], v[166:169], v[206:209], v[98:101]
	v_mfma_f32_16x16x32_bf16 v[126:129], v[160:163], v[186:189], v[126:129]
	v_mfma_f32_16x16x32_bf16 v[122:125], v[172:175], v[186:189], v[122:125]
	v_mfma_f32_16x16x32_bf16 v[118:121], v[160:163], v[194:197], v[118:121]
	v_mfma_f32_16x16x32_bf16 v[114:117], v[172:175], v[194:197], v[114:117]
	v_mfma_f32_16x16x32_bf16 v[110:113], v[160:163], v[202:205], v[110:113]
	v_mfma_f32_16x16x32_bf16 v[106:109], v[172:175], v[202:205], v[106:109]
	v_mfma_f32_16x16x32_bf16 v[102:105], v[160:163], v[210:213], v[102:105]
	v_mfma_f32_16x16x32_bf16 v[98:101], v[172:175], v[210:213], v[98:101]
	s_setprio 0
	s_barrier
	s_add_u32 s40, s2, s42
	s_addc_u32 s41, s3, 0
	v_lshl_add_u64 v[148:149], s[40:41], 0, v[0:1]
	v_lshl_add_u64 v[230:231], v[148:149], 0, s[88:89]
	v_add_u32_e32 v148, s33, v139
	v_add_u32_e32 v149, 0x2000, v148
	v_readfirstlane_b32 s43, v148
	s_mov_b32 m0, s43
	ds_read_b128 v[214:217], v144
	ds_read_b128 v[218:221], v144 offset:1024
	ds_read_b128 v[222:225], v144 offset:2048
	ds_read_b128 v[226:229], v144 offset:3072
	global_load_lds_dwordx4 v[230:231], off
	v_lshl_add_u64 v[230:231], s[40:41], 0, v[130:131]
	v_readfirstlane_b32 s40, v149
	v_lshl_add_u64 v[230:231], v[230:231], 0, s[88:89]
	s_mov_b32 m0, s40
	s_nop 0
	global_load_lds_dwordx4 v[230:231], off
	s_barrier
	s_waitcnt lgkmcnt(0)
	s_setprio 1
	v_mfma_f32_16x16x32_bf16 v[94:97], v[214:217], v[150:153], v[94:97]
	v_mfma_f32_16x16x32_bf16 v[90:93], v[222:225], v[150:153], v[90:93]
	v_mfma_f32_16x16x32_bf16 v[86:89], v[214:217], v[190:193], v[86:89]
	v_mfma_f32_16x16x32_bf16 v[82:85], v[222:225], v[190:193], v[82:85]
	v_mfma_f32_16x16x32_bf16 v[78:81], v[214:217], v[198:201], v[78:81]
	v_mfma_f32_16x16x32_bf16 v[74:77], v[222:225], v[198:201], v[74:77]
	v_mfma_f32_16x16x32_bf16 v[70:73], v[214:217], v[206:209], v[70:73]
	v_mfma_f32_16x16x32_bf16 v[66:69], v[222:225], v[206:209], v[66:69]
	v_mfma_f32_16x16x32_bf16 v[94:97], v[218:221], v[186:189], v[94:97]
	v_mfma_f32_16x16x32_bf16 v[90:93], v[226:229], v[186:189], v[90:93]
	v_mfma_f32_16x16x32_bf16 v[86:89], v[218:221], v[194:197], v[86:89]
	v_mfma_f32_16x16x32_bf16 v[82:85], v[226:229], v[194:197], v[82:85]
	v_mfma_f32_16x16x32_bf16 v[78:81], v[218:221], v[202:205], v[78:81]
	v_mfma_f32_16x16x32_bf16 v[74:77], v[226:229], v[202:205], v[74:77]
	v_mfma_f32_16x16x32_bf16 v[70:73], v[218:221], v[210:213], v[70:73]
	v_mfma_f32_16x16x32_bf16 v[66:69], v[226:229], v[210:213], v[66:69]
	s_setprio 0
	s_add_u32 s40, s14, s42
	s_addc_u32 s41, s15, 0
	v_lshl_add_u64 v[150:151], s[40:41], 0, v[0:1]
	v_readfirstlane_b32 s43, v133
	v_lshl_add_u64 v[150:151], v[150:151], 0, s[88:89]
	s_mov_b32 m0, s43
	s_barrier
	ds_read_b128 v[186:189], v137 offset:16384
	ds_read_b128 v[190:193], v137 offset:17408
	ds_read_b128 v[194:197], v136 offset:16384
	ds_read_b128 v[198:201], v136 offset:17408
	ds_read_b128 v[202:205], v135 offset:16384
	ds_read_b128 v[206:209], v135 offset:17408
	ds_read_b128 v[210:213], v134 offset:16384
	ds_read_b128 v[230:233], v134 offset:17408
	global_load_lds_dwordx4 v[150:151], off
	v_lshl_add_u64 v[150:151], s[40:41], 0, v[130:131]
	v_lshl_add_u64 v[152:153], v[150:151], 0, s[88:89]
	v_add_u32_e32 v150, 0x2000, v133
	s_nop 0
	v_readfirstlane_b32 s40, v150
	s_mov_b32 m0, s40
	s_nop 0
	global_load_lds_dwordx4 v[152:153], off
	s_barrier
	s_waitcnt lgkmcnt(0)
	s_setprio 1
	v_mfma_f32_16x16x32_bf16 v[62:65], v[156:159], v[186:189], v[62:65]
	v_mfma_f32_16x16x32_bf16 v[58:61], v[166:169], v[186:189], v[58:61]
	v_mfma_f32_16x16x32_bf16 v[54:57], v[156:159], v[194:197], v[54:57]
	v_mfma_f32_16x16x32_bf16 v[50:53], v[166:169], v[194:197], v[50:53]
	v_mfma_f32_16x16x32_bf16 v[46:49], v[156:159], v[202:205], v[46:49]
	v_mfma_f32_16x16x32_bf16 v[42:45], v[166:169], v[202:205], v[42:45]
	v_mfma_f32_16x16x32_bf16 v[38:41], v[156:159], v[210:213], v[38:41]
	v_mfma_f32_16x16x32_bf16 v[34:37], v[166:169], v[210:213], v[34:37]
	v_mfma_f32_16x16x32_bf16 v[62:65], v[160:163], v[190:193], v[62:65]
	v_mfma_f32_16x16x32_bf16 v[58:61], v[172:175], v[190:193], v[58:61]
	v_mfma_f32_16x16x32_bf16 v[54:57], v[160:163], v[198:201], v[54:57]
	v_mfma_f32_16x16x32_bf16 v[50:53], v[172:175], v[198:201], v[50:53]
	v_mfma_f32_16x16x32_bf16 v[46:49], v[160:163], v[206:209], v[46:49]
	v_mfma_f32_16x16x32_bf16 v[42:45], v[172:175], v[206:209], v[42:45]
	v_mfma_f32_16x16x32_bf16 v[38:41], v[160:163], v[230:233], v[38:41]
	v_mfma_f32_16x16x32_bf16 v[34:37], v[172:175], v[230:233], v[34:37]
	s_setprio 0
	s_barrier
; #define STAGE_A(P,br,kt) STAGE_G(P,c.A,c.lda,br,(long)(kt)*c.kstr)
; #define STAGE_B(P,br,kt) STAGE_G(P,c.Bt,c.K,br,(long)(kt)*BK)
; #define LDA(dst,b,h) for(int m=0;m<4;++m)for(int k=0;k<2;++k) \
;     dst[m][k]=*reinterpret_cast<const bf16x8*>((char*)SA(b,h)+lds_byte(wr*64+m*16+fr,k*32+fq*8))
; #define LDB(dst,b,h) for(int n=0;n<2;++n)for(int k=0;k<2;++k) \
;     dst[n][k]=*reinterpret_cast<const bf16x8*>((char*)SB(b,h)+lds_byte(wc*32+n*16+fr,k*32+fq*8))
; #define MMA(ai,bj,At,Bt_) do{__builtin_amdgcn_s_setprio(1); \
;     for(int m=0;m<4;++m)for(int n=0;n<2;++n)for(int k=0;k<2;++k) \
;       acc[ai][bj][m][n]=__builtin_amdgcn_mfma_f32_16x16x32_bf16(Bt_[n][k],At[m][k],acc[ai][bj][m][n],0,0,0); \
;     __builtin_amdgcn_s_setprio(0);}while(0)
; #define WAIT_V(n) asm volatile("s_waitcnt vmcnt(" #n ")":::"memory")
; #define WAIT_L(n) asm volatile("s_waitcnt lgkmcnt(" #n ")":::"memory")
; #define BAR __builtin_amdgcn_s_barrier()
; #define SCHED __builtin_amdgcn_sched_barrier(0)
; template <int EPI>
; __device__ __forceinline__ void gemm_run(const GD& c, const bool has_next, const GD& nx, const Ctx& e, bf16* shm, float* rs, float* rs_nxt, float* racc_) {
;     ...
;     STAGE_B(SB(0,1),bcol+HALF,t+2);
;     WAIT_V(6); BAR; MMA(1,1,At,B1); BAR;
;     LDB(B0,1,0); SCHED; LDA(At,1,0); STAGE_A(SA(0,1),brow+HALF,t+2);
;     WAIT_L(8); BAR; WAIT_L(0); MMA(0,0,At,B0); BAR; SCHED;
;     LDB(B1,1,1); STAGE_B(SB(1,0),bcol,t+3);
;     BAR; WAIT_L(0); MMA(0,1,At,B1); BAR;
;     LDA(At,1,1); STAGE_A(SA(1,0),brow,t+3);
;     BAR; WAIT_L(0); MMA(1,0,At,B0); BAR; SCHED;
;     STAGE_B(SB(1,1),bcol+HALF,t+3);
	s_add_u32 s40, s20, s42
	s_addc_u32 s41, s21, 0
	v_add_u32_e32 v151, s86, v139
	v_lshl_add_u64 v[152:153], s[40:41], 0, v[0:1]
	v_readfirstlane_b32 s42, v151
	v_lshl_add_u64 v[152:153], v[152:153], 0, s[88:89]
	s_mov_b32 m0, s42
	s_nop 0
	global_load_lds_dwordx4 v[152:153], off
	v_lshl_add_u64 v[152:153], s[40:41], 0, v[130:131]
	v_lshl_add_u64 v[156:157], v[152:153], 0, s[88:89]
	v_add_u32_e32 v152, 0x2000, v151
	s_nop 0
	v_readfirstlane_b32 s40, v152
	s_mov_b32 m0, s40
	s_nop 0
	global_load_lds_dwordx4 v[156:157], off
	s_waitcnt vmcnt(6)
	s_barrier
	s_setprio 1
	v_mfma_f32_16x16x32_bf16 v[30:33], v[214:217], v[186:189], v[30:33]
	v_mfma_f32_16x16x32_bf16 v[26:29], v[222:225], v[186:189], v[26:29]
	v_mfma_f32_16x16x32_bf16 v[22:25], v[214:217], v[194:197], v[22:25]
	v_mfma_f32_16x16x32_bf16 v[18:21], v[222:225], v[194:197], v[18:21]
	v_mfma_f32_16x16x32_bf16 v[14:17], v[214:217], v[202:205], v[14:17]
	v_mfma_f32_16x16x32_bf16 v[10:13], v[222:225], v[202:205], v[10:13]
	v_mfma_f32_16x16x32_bf16 v[6:9], v[214:217], v[210:213], v[6:9]
	v_mfma_f32_16x16x32_bf16 v[2:5], v[222:225], v[210:213], v[2:5]
	v_mfma_f32_16x16x32_bf16 v[30:33], v[218:221], v[190:193], v[30:33]
	v_mfma_f32_16x16x32_bf16 v[26:29], v[226:229], v[190:193], v[26:29]
	v_mfma_f32_16x16x32_bf16 v[22:25], v[218:221], v[198:201], v[22:25]
	v_mfma_f32_16x16x32_bf16 v[18:21], v[226:229], v[198:201], v[18:21]
	v_mfma_f32_16x16x32_bf16 v[14:17], v[218:221], v[206:209], v[14:17]
	v_mfma_f32_16x16x32_bf16 v[10:13], v[226:229], v[206:209], v[10:13]
	v_mfma_f32_16x16x32_bf16 v[6:9], v[218:221], v[230:233], v[6:9]
	v_mfma_f32_16x16x32_bf16 v[2:5], v[226:229], v[230:233], v[2:5]
	s_setprio 0
	s_barrier
	ds_read_b128 v[156:159], v140
	ds_read_b128 v[160:163], v140 offset:1024
	ds_read_b128 v[166:169], v140 offset:2048
	ds_read_b128 v[172:175], v140 offset:3072
	v_add_u32_e32 v153, 0x4000, v133
	v_add_u32_e32 v154, 0x6000, v133
	v_readfirstlane_b32 s40, v153
	v_lshl_add_u64 v[218:219], v[234:235], 0, s[88:89]
	s_mov_b32 m0, s40
	v_readfirstlane_b32 s40, v154
	ds_read_b128 v[186:189], v137 offset:32768
	ds_read_b128 v[190:193], v137 offset:33792
	ds_read_b128 v[194:197], v136 offset:32768
	ds_read_b128 v[198:201], v136 offset:33792
	ds_read_b128 v[202:205], v135 offset:32768
	ds_read_b128 v[206:209], v135 offset:33792
	ds_read_b128 v[210:213], v134 offset:32768
	ds_read_b128 v[214:217], v134 offset:33792
	global_load_lds_dwordx4 v[218:219], off
	v_lshl_add_u64 v[218:219], v[236:237], 0, s[88:89]
	s_mov_b32 m0, s40
	s_nop 0
	global_load_lds_dwordx4 v[218:219], off
	s_waitcnt lgkmcnt(8)
	s_barrier
	s_waitcnt lgkmcnt(0)
	s_setprio 1
	v_mfma_f32_16x16x32_bf16 v[126:129], v[156:159], v[186:189], v[126:129]
	v_mfma_f32_16x16x32_bf16 v[122:125], v[166:169], v[186:189], v[122:125]
	v_mfma_f32_16x16x32_bf16 v[118:121], v[156:159], v[194:197], v[118:121]
	v_mfma_f32_16x16x32_bf16 v[114:117], v[166:169], v[194:197], v[114:117]
	v_mfma_f32_16x16x32_bf16 v[110:113], v[156:159], v[202:205], v[110:113]
	v_mfma_f32_16x16x32_bf16 v[106:109], v[166:169], v[202:205], v[106:109]
	v_mfma_f32_16x16x32_bf16 v[102:105], v[156:159], v[210:213], v[102:105]
	v_mfma_f32_16x16x32_bf16 v[98:101], v[166:169], v[210:213], v[98:101]
	v_mfma_f32_16x16x32_bf16 v[126:129], v[160:163], v[190:193], v[126:129]
	v_mfma_f32_16x16x32_bf16 v[122:125], v[172:175], v[190:193], v[122:125]
	v_mfma_f32_16x16x32_bf16 v[118:121], v[160:163], v[198:201], v[118:121]
	v_mfma_f32_16x16x32_bf16 v[114:117], v[172:175], v[198:201], v[114:117]
	v_mfma_f32_16x16x32_bf16 v[110:113], v[160:163], v[206:209], v[110:113]
	v_mfma_f32_16x16x32_bf16 v[106:109], v[172:175], v[206:209], v[106:109]
	v_mfma_f32_16x16x32_bf16 v[102:105], v[160:163], v[214:217], v[102:105]
	v_mfma_f32_16x16x32_bf16 v[98:101], v[172:175], v[214:217], v[98:101]
	s_setprio 0
	s_barrier
	s_add_i32 s82, s39, 3
	s_lshl_b64 s[40:41], s[82:83], 7
	s_add_u32 s42, s2, s40
	s_addc_u32 s43, s3, s41
	v_readfirstlane_b32 s39, v141
	v_add_u32_e32 v170, 0x2000, v141
	v_lshl_add_u64 v[234:235], s[42:43], 0, v[0:1]
	s_mov_b32 m0, s39
	v_readfirstlane_b32 s39, v170
	ds_read_b128 v[218:221], v138
	ds_read_b128 v[222:225], v138 offset:1024
	ds_read_b128 v[226:229], v138 offset:2048
	ds_read_b128 v[230:233], v138 offset:3072
	global_load_lds_dwordx4 v[234:235], off
	v_lshl_add_u64 v[234:235], s[42:43], 0, v[130:131]
	s_mov_b32 m0, s39
	s_nop 0
	global_load_lds_dwordx4 v[234:235], off
	s_barrier
	s_waitcnt lgkmcnt(0)
	s_setprio 1
	v_mfma_f32_16x16x32_bf16 v[94:97], v[218:221], v[186:189], v[94:97]
	v_mfma_f32_16x16x32_bf16 v[90:93], v[226:229], v[186:189], v[90:93]
	v_mfma_f32_16x16x32_bf16 v[86:89], v[218:221], v[194:197], v[86:89]
	v_mfma_f32_16x16x32_bf16 v[82:85], v[226:229], v[194:197], v[82:85]
	v_mfma_f32_16x16x32_bf16 v[78:81], v[218:221], v[202:205], v[78:81]
	v_mfma_f32_16x16x32_bf16 v[74:77], v[226:229], v[202:205], v[74:77]
	v_mfma_f32_16x16x32_bf16 v[70:73], v[218:221], v[210:213], v[70:73]
	v_mfma_f32_16x16x32_bf16 v[66:69], v[226:229], v[210:213], v[66:69]
	v_mfma_f32_16x16x32_bf16 v[94:97], v[222:225], v[190:193], v[94:97]
	v_mfma_f32_16x16x32_bf16 v[90:93], v[230:233], v[190:193], v[90:93]
	v_mfma_f32_16x16x32_bf16 v[86:89], v[222:225], v[198:201], v[86:89]
	v_mfma_f32_16x16x32_bf16 v[82:85], v[230:233], v[198:201], v[82:85]
	v_mfma_f32_16x16x32_bf16 v[78:81], v[222:225], v[206:209], v[78:81]
	v_mfma_f32_16x16x32_bf16 v[74:77], v[230:233], v[206:209], v[74:77]
	v_mfma_f32_16x16x32_bf16 v[70:73], v[222:225], v[214:217], v[70:73]
	v_mfma_f32_16x16x32_bf16 v[66:69], v[230:233], v[214:217], v[66:69]
	s_setprio 0
	s_add_u32 s42, s14, s40
	s_addc_u32 s43, s15, s41
	v_readfirstlane_b32 s39, v142
	v_lshl_add_u64 v[234:235], s[42:43], 0, v[0:1]
	s_mov_b32 m0, s39
	v_readfirstlane_b32 s39, v143
	s_barrier
; #define STAGE_A(P,br,kt) STAGE_G(P,c.A,c.lda,br,(long)(kt)*c.kstr)
; #define STAGE_B(P,br,kt) STAGE_G(P,c.Bt,c.K,br,(long)(kt)*BK)
; #define LDA(dst,b,h) for(int m=0;m<4;++m)for(int k=0;k<2;++k) \
;     dst[m][k]=*reinterpret_cast<const bf16x8*>((char*)SA(b,h)+lds_byte(wr*64+m*16+fr,k*32+fq*8))
; #define LDB(dst,b,h) for(int n=0;n<2;++n)for(int k=0;k<2;++k) \
;     dst[n][k]=*reinterpret_cast<const bf16x8*>((char*)SB(b,h)+lds_byte(wc*32+n*16+fr,k*32+fq*8))
; #define MMA(ai,bj,At,Bt_) do{__builtin_amdgcn_s_setprio(1); \
;     for(int m=0;m<4;++m)for(int n=0;n<2;++n)for(int k=0;k<2;++k) \
;       acc[ai][bj][m][n]=__builtin_amdgcn_mfma_f32_16x16x32_bf16(Bt_[n][k],At[m][k],acc[ai][bj][m][n],0,0,0); \
;     __builtin_amdgcn_s_setprio(0);}while(0)
; #define WAIT_V(n) asm volatile("s_waitcnt vmcnt(" #n ")":::"memory")
; #define WAIT_L(n) asm volatile("s_waitcnt lgkmcnt(" #n ")":::"memory")
; #define BAR __builtin_amdgcn_s_barrier()
; #define SCHED __builtin_amdgcn_sched_barrier(0)
; template <int EPI>
; __device__ __forceinline__ void gemm_run(const GD& c, const bool has_next, const GD& nx, const Ctx& e, bf16* shm, float* rs, float* rs_nxt, float* racc_) {
;     ...
;     LDB(B1,1,1); STAGE_B(SB(1,0),bcol,t+3);
;     BAR; WAIT_L(0); MMA(0,1,At,B1); BAR;
;     LDA(At,1,1); STAGE_A(SA(1,0),brow,t+3);
;     BAR; WAIT_L(0); MMA(1,0,At,B0); BAR; SCHED;
;     STAGE_B(SB(1,1),bcol+HALF,t+3);
;     WAIT_V(6); BAR; MMA(1,1,At,B1); BAR;
;   }
;   { LDB(B0,0,0); LDA(At,0,0); STAGE_A(SA(1,1),brow+HALF,nt-1);
;     BAR; WAIT_L(0); MMA(0,0,At,B0); BAR;
	ds_read_b128 v[186:189], v137 offset:49152
	ds_read_b128 v[190:193], v137 offset:50176
	ds_read_b128 v[194:197], v136 offset:49152
	ds_read_b128 v[198:201], v136 offset:50176
	ds_read_b128 v[202:205], v135 offset:49152
	ds_read_b128 v[206:209], v135 offset:50176
	ds_read_b128 v[210:213], v134 offset:49152
	ds_read_b128 v[214:217], v134 offset:50176
	global_load_lds_dwordx4 v[234:235], off
	v_lshl_add_u64 v[234:235], s[42:43], 0, v[130:131]
	s_mov_b32 m0, s39
	s_nop 0
	global_load_lds_dwordx4 v[234:235], off
	s_barrier
	s_waitcnt lgkmcnt(0)
	s_setprio 1
	v_mfma_f32_16x16x32_bf16 v[62:65], v[156:159], v[186:189], v[62:65]
	v_mfma_f32_16x16x32_bf16 v[58:61], v[166:169], v[186:189], v[58:61]
	v_mfma_f32_16x16x32_bf16 v[54:57], v[156:159], v[194:197], v[54:57]
	v_mfma_f32_16x16x32_bf16 v[50:53], v[166:169], v[194:197], v[50:53]
	v_mfma_f32_16x16x32_bf16 v[46:49], v[156:159], v[202:205], v[46:49]
	v_mfma_f32_16x16x32_bf16 v[42:45], v[166:169], v[202:205], v[42:45]
	v_mfma_f32_16x16x32_bf16 v[38:41], v[156:159], v[210:213], v[38:41]
	v_mfma_f32_16x16x32_bf16 v[34:37], v[166:169], v[210:213], v[34:37]
	v_mfma_f32_16x16x32_bf16 v[62:65], v[160:163], v[190:193], v[62:65]
	v_mfma_f32_16x16x32_bf16 v[58:61], v[172:175], v[190:193], v[58:61]
	v_mfma_f32_16x16x32_bf16 v[54:57], v[160:163], v[198:201], v[54:57]
	v_mfma_f32_16x16x32_bf16 v[50:53], v[172:175], v[198:201], v[50:53]
	v_mfma_f32_16x16x32_bf16 v[46:49], v[160:163], v[206:209], v[46:49]
	v_mfma_f32_16x16x32_bf16 v[42:45], v[172:175], v[206:209], v[42:45]
	v_mfma_f32_16x16x32_bf16 v[38:41], v[160:163], v[214:217], v[38:41]
	v_mfma_f32_16x16x32_bf16 v[34:37], v[172:175], v[214:217], v[34:37]
	s_setprio 0
	s_barrier
	s_add_u32 s40, s20, s40
	s_addc_u32 s41, s21, s41
	v_readfirstlane_b32 s39, v145
	v_add_u32_e32 v158, 0x2000, v145
	v_lshl_add_u64 v[156:157], s[40:41], 0, v[0:1]
	s_mov_b32 m0, s39
	v_readfirstlane_b32 s39, v158
	global_load_lds_dwordx4 v[156:157], off
	v_lshl_add_u64 v[156:157], s[40:41], 0, v[130:131]
	s_mov_b32 m0, s39
	s_nop 0
	global_load_lds_dwordx4 v[156:157], off
	s_waitcnt vmcnt(6)
	s_barrier
	s_setprio 1
	v_mfma_f32_16x16x32_bf16 v[30:33], v[218:221], v[186:189], v[30:33]
	v_mfma_f32_16x16x32_bf16 v[26:29], v[226:229], v[186:189], v[26:29]
	v_mfma_f32_16x16x32_bf16 v[22:25], v[218:221], v[194:197], v[22:25]
	v_mfma_f32_16x16x32_bf16 v[18:21], v[226:229], v[194:197], v[18:21]
	v_mfma_f32_16x16x32_bf16 v[14:17], v[218:221], v[202:205], v[14:17]
	v_mfma_f32_16x16x32_bf16 v[10:13], v[226:229], v[202:205], v[10:13]
	v_mfma_f32_16x16x32_bf16 v[6:9], v[218:221], v[210:213], v[6:9]
	v_mfma_f32_16x16x32_bf16 v[2:5], v[226:229], v[210:213], v[2:5]
	v_mfma_f32_16x16x32_bf16 v[30:33], v[222:225], v[190:193], v[30:33]
	v_mfma_f32_16x16x32_bf16 v[26:29], v[230:233], v[190:193], v[26:29]
	v_mfma_f32_16x16x32_bf16 v[22:25], v[222:225], v[198:201], v[22:25]
	v_mfma_f32_16x16x32_bf16 v[18:21], v[230:233], v[198:201], v[18:21]
	v_mfma_f32_16x16x32_bf16 v[14:17], v[222:225], v[206:209], v[14:17]
	v_mfma_f32_16x16x32_bf16 v[10:13], v[230:233], v[206:209], v[10:13]
	v_mfma_f32_16x16x32_bf16 v[6:9], v[222:225], v[214:217], v[6:9]
	v_mfma_f32_16x16x32_bf16 v[2:5], v[230:233], v[214:217], v[2:5]
	s_setprio 0
	s_mov_b32 s39, 2
	s_and_b64 vcc, exec, s[24:25]
	s_mov_b64 s[24:25], 0
	s_barrier
	s_cbranch_vccnz .LBB0_689
	v_lshl_add_u64 v[142:143], s[22:23], 0, v[0:1]
	s_mov_b64 s[14:15], 0x280
	v_readfirstlane_b32 s2, v147
	v_lshl_add_u64 v[142:143], v[142:143], 0, s[14:15]
	s_mov_b32 m0, s2
	ds_read_b128 v[156:159], v146
	ds_read_b128 v[160:163], v146 offset:1024
	ds_read_b128 v[166:169], v146 offset:2048
	ds_read_b128 v[172:175], v146 offset:3072
	ds_read_b128 v[186:189], v137
	ds_read_b128 v[190:193], v137 offset:1024
	ds_read_b128 v[194:197], v136
	ds_read_b128 v[198:201], v136 offset:1024
	ds_read_b128 v[202:205], v135
	ds_read_b128 v[206:209], v135 offset:1024
	ds_read_b128 v[210:213], v134
	ds_read_b128 v[214:217], v134 offset:1024
	global_load_lds_dwordx4 v[142:143], off
	v_lshl_add_u64 v[142:143], s[22:23], 0, v[130:131]
	v_readfirstlane_b32 s2, v155
	v_lshl_add_u64 v[142:143], v[142:143], 0, s[14:15]
	s_mov_b32 m0, s2
	s_nop 0
	global_load_lds_dwordx4 v[142:143], off
	s_barrier
	s_waitcnt lgkmcnt(0)
	s_setprio 1
	v_mfma_f32_16x16x32_bf16 v[126:129], v[156:159], v[186:189], v[126:129]
	v_mfma_f32_16x16x32_bf16 v[122:125], v[166:169], v[186:189], v[122:125]
	v_mfma_f32_16x16x32_bf16 v[118:121], v[156:159], v[194:197], v[118:121]
	v_mfma_f32_16x16x32_bf16 v[110:113], v[156:159], v[202:205], v[110:113]
	v_mfma_f32_16x16x32_bf16 v[106:109], v[166:169], v[202:205], v[106:109]
	v_mfma_f32_16x16x32_bf16 v[126:129], v[160:163], v[190:193], v[126:129]
	v_mfma_f32_16x16x32_bf16 v[122:125], v[172:175], v[190:193], v[122:125]
	v_mfma_f32_16x16x32_bf16 v[118:121], v[160:163], v[198:201], v[118:121]
	v_mfma_f32_16x16x32_bf16 v[114:117], v[166:169], v[194:197], v[114:117]
	v_mfma_f32_16x16x32_bf16 v[110:113], v[160:163], v[206:209], v[110:113]
	v_mfma_f32_16x16x32_bf16 v[106:109], v[172:175], v[206:209], v[106:109]
	v_mfma_f32_16x16x32_bf16 v[102:105], v[156:159], v[210:213], v[102:105]
	v_mfma_f32_16x16x32_bf16 v[98:101], v[166:169], v[210:213], v[98:101]
	v_mfma_f32_16x16x32_bf16 v[218:221], v[172:175], v[198:201], v[114:117]
	v_mfma_f32_16x16x32_bf16 v[222:225], v[160:163], v[214:217], v[102:105]
	v_mfma_f32_16x16x32_bf16 v[226:229], v[172:175], v[214:217], v[98:101]
	s_setprio 0
	s_barrier
	s_nop 2
	ds_read_b128 v[98:101], v144
	ds_read_b128 v[102:105], v144 offset:1024
	ds_read_b128 v[114:117], v144 offset:2048
	ds_read_b128 v[142:145], v144 offset:3072
	s_barrier
; #define STAGE_A(P,br,kt) STAGE_G(P,c.A,c.lda,br,(long)(kt)*c.kstr)
; #define LDA(dst,b,h) for(int m=0;m<4;++m)for(int k=0;k<2;++k) \
;     dst[m][k]=*reinterpret_cast<const bf16x8*>((char*)SA(b,h)+lds_byte(wr*64+m*16+fr,k*32+fq*8))
; #define LDB(dst,b,h) for(int n=0;n<2;++n)for(int k=0;k<2;++k) \
;     dst[n][k]=*reinterpret_cast<const bf16x8*>((char*)SB(b,h)+lds_byte(wc*32+n*16+fr,k*32+fq*8))
; #define MMA(ai,bj,At,Bt_) do{__builtin_amdgcn_s_setprio(1); \
;     for(int m=0;m<4;++m)for(int n=0;n<2;++n)for(int k=0;k<2;++k) \
;       acc[ai][bj][m][n]=__builtin_amdgcn_mfma_f32_16x16x32_bf16(Bt_[n][k],At[m][k],acc[ai][bj][m][n],0,0,0); \
;     __builtin_amdgcn_s_setprio(0);}while(0)
; #define WAIT_V(n) asm volatile("s_waitcnt vmcnt(" #n ")":::"memory")
; #define WAIT_L(n) asm volatile("s_waitcnt lgkmcnt(" #n ")":::"memory")
; #define BAR __builtin_amdgcn_s_barrier()
; template <int EPI>
; __device__ __forceinline__ void gemm_run(const GD& c, const bool has_next, const GD& nx, const Ctx& e, bf16* shm, float* rs, float* rs_nxt, float* racc_) {
;     ...
;   { LDB(B0,0,0); LDA(At,0,0); STAGE_A(SA(1,1),brow+HALF,nt-1);
;     BAR; WAIT_L(0); MMA(0,0,At,B0); BAR;
;     LDB(B1,0,1); BAR; WAIT_L(0); MMA(0,1,At,B1); BAR;
;     LDA(At,0,1); WAIT_V(4); BAR; WAIT_L(0); MMA(1,0,At,B0); MMA(1,1,At,B1); BAR; }
;   { LDB(B0,1,0); LDA(At,1,0); WAIT_V(2); BAR; WAIT_L(0); MMA(0,0,At,B0); BAR;
	s_waitcnt lgkmcnt(0)
	s_setprio 1
	v_mfma_f32_16x16x32_bf16 v[94:97], v[98:101], v[186:189], v[94:97]
	v_mfma_f32_16x16x32_bf16 v[90:93], v[114:117], v[186:189], v[90:93]
	v_mfma_f32_16x16x32_bf16 v[82:85], v[114:117], v[194:197], v[82:85]
	v_mfma_f32_16x16x32_bf16 v[78:81], v[98:101], v[202:205], v[78:81]
	v_mfma_f32_16x16x32_bf16 v[94:97], v[102:105], v[190:193], v[94:97]
	v_mfma_f32_16x16x32_bf16 v[90:93], v[142:145], v[190:193], v[90:93]
	v_mfma_f32_16x16x32_bf16 v[86:89], v[98:101], v[194:197], v[86:89]
	v_mfma_f32_16x16x32_bf16 v[82:85], v[142:145], v[198:201], v[82:85]
	v_mfma_f32_16x16x32_bf16 v[78:81], v[102:105], v[206:209], v[78:81]
	v_mfma_f32_16x16x32_bf16 v[74:77], v[114:117], v[202:205], v[74:77]
	v_mfma_f32_16x16x32_bf16 v[70:73], v[98:101], v[210:213], v[70:73]
	v_mfma_f32_16x16x32_bf16 v[66:69], v[114:117], v[210:213], v[66:69]
	v_mfma_f32_16x16x32_bf16 v[186:189], v[102:105], v[198:201], v[86:89]
	v_mfma_f32_16x16x32_bf16 v[190:193], v[142:145], v[206:209], v[74:77]
	v_mfma_f32_16x16x32_bf16 v[194:197], v[102:105], v[214:217], v[70:73]
	v_mfma_f32_16x16x32_bf16 v[198:201], v[142:145], v[214:217], v[66:69]
	s_setprio 0
	s_barrier
	s_nop 1
	ds_read_b128 v[66:69], v137 offset:16384
	ds_read_b128 v[70:73], v137 offset:17408
	ds_read_b128 v[74:77], v136 offset:16384
	ds_read_b128 v[86:89], v136 offset:17408
	ds_read_b128 v[202:205], v135 offset:16384
	ds_read_b128 v[206:209], v135 offset:17408
	ds_read_b128 v[210:213], v134 offset:16384
	ds_read_b128 v[214:217], v134 offset:17408
	s_waitcnt vmcnt(4)
	s_barrier
	s_waitcnt lgkmcnt(0)
	s_setprio 1
	v_mfma_f32_16x16x32_bf16 v[62:65], v[156:159], v[66:69], v[62:65]
	v_mfma_f32_16x16x32_bf16 v[58:61], v[166:169], v[66:69], v[58:61]
	v_mfma_f32_16x16x32_bf16 v[46:49], v[156:159], v[202:205], v[46:49]
	v_mfma_f32_16x16x32_bf16 v[42:45], v[166:169], v[202:205], v[42:45]
	v_mfma_f32_16x16x32_bf16 v[62:65], v[160:163], v[70:73], v[62:65]
	v_mfma_f32_16x16x32_bf16 v[58:61], v[172:175], v[70:73], v[58:61]
	v_mfma_f32_16x16x32_bf16 v[54:57], v[156:159], v[74:77], v[54:57]
	v_mfma_f32_16x16x32_bf16 v[50:53], v[166:169], v[74:77], v[50:53]
	v_mfma_f32_16x16x32_bf16 v[46:49], v[160:163], v[206:209], v[46:49]
	v_mfma_f32_16x16x32_bf16 v[42:45], v[172:175], v[206:209], v[42:45]
	v_mfma_f32_16x16x32_bf16 v[38:41], v[156:159], v[210:213], v[38:41]
	v_mfma_f32_16x16x32_bf16 v[34:37], v[166:169], v[210:213], v[34:37]
	v_mfma_f32_16x16x32_bf16 v[230:233], v[160:163], v[86:89], v[54:57]
	v_mfma_f32_16x16x32_bf16 v[234:237], v[172:175], v[86:89], v[50:53]
	v_mfma_f32_16x16x32_bf16 v[156:159], v[160:163], v[214:217], v[38:41]
	v_mfma_f32_16x16x32_bf16 v[160:163], v[172:175], v[214:217], v[34:37]
	s_setprio 0
	s_setprio 1
	v_mfma_f32_16x16x32_bf16 v[30:33], v[98:101], v[66:69], v[30:33]
	v_mfma_f32_16x16x32_bf16 v[26:29], v[114:117], v[66:69], v[26:29]
	v_mfma_f32_16x16x32_bf16 v[14:17], v[98:101], v[202:205], v[14:17]
	v_mfma_f32_16x16x32_bf16 v[10:13], v[114:117], v[202:205], v[10:13]
	v_mfma_f32_16x16x32_bf16 v[30:33], v[102:105], v[70:73], v[30:33]
	v_mfma_f32_16x16x32_bf16 v[26:29], v[142:145], v[70:73], v[26:29]
	v_mfma_f32_16x16x32_bf16 v[22:25], v[98:101], v[74:77], v[22:25]
	v_mfma_f32_16x16x32_bf16 v[18:21], v[114:117], v[74:77], v[18:21]
	v_mfma_f32_16x16x32_bf16 v[14:17], v[102:105], v[206:209], v[14:17]
	v_mfma_f32_16x16x32_bf16 v[10:13], v[142:145], v[206:209], v[10:13]
	v_mfma_f32_16x16x32_bf16 v[6:9], v[98:101], v[210:213], v[6:9]
	v_mfma_f32_16x16x32_bf16 v[2:5], v[114:117], v[210:213], v[2:5]
	v_mfma_f32_16x16x32_bf16 v[166:169], v[102:105], v[86:89], v[22:25]
	v_mfma_f32_16x16x32_bf16 v[172:175], v[142:145], v[86:89], v[18:21]
	v_mfma_f32_16x16x32_bf16 v[202:205], v[102:105], v[214:217], v[6:9]
	v_mfma_f32_16x16x32_bf16 v[142:145], v[142:145], v[214:217], v[2:5]
	s_setprio 0
	s_barrier
	s_nop 1
	ds_read_b128 v[2:5], v140
	ds_read_b128 v[6:9], v140 offset:1024
	ds_read_b128 v[206:209], v140 offset:2048
	ds_read_b128 v[210:213], v140 offset:3072
	ds_read_b128 v[18:21], v137 offset:32768
	ds_read_b128 v[22:25], v137 offset:33792
	ds_read_b128 v[34:37], v136 offset:32768
	ds_read_b128 v[38:41], v136 offset:33792
	ds_read_b128 v[50:53], v135 offset:32768
	ds_read_b128 v[54:57], v135 offset:33792
	ds_read_b128 v[214:217], v134 offset:32768
	ds_read_b128 v[238:241], v134 offset:33792
	s_waitcnt vmcnt(2)
	s_barrier
; #define LDA(dst,b,h) for(int m=0;m<4;++m)for(int k=0;k<2;++k) \
;     dst[m][k]=*reinterpret_cast<const bf16x8*>((char*)SA(b,h)+lds_byte(wr*64+m*16+fr,k*32+fq*8))
; #define LDB(dst,b,h) for(int n=0;n<2;++n)for(int k=0;k<2;++k) \
;     dst[n][k]=*reinterpret_cast<const bf16x8*>((char*)SB(b,h)+lds_byte(wc*32+n*16+fr,k*32+fq*8))
; #define MMA(ai,bj,At,Bt_) do{__builtin_amdgcn_s_setprio(1); \
;     for(int m=0;m<4;++m)for(int n=0;n<2;++n)for(int k=0;k<2;++k) \
;       acc[ai][bj][m][n]=__builtin_amdgcn_mfma_f32_16x16x32_bf16(Bt_[n][k],At[m][k],acc[ai][bj][m][n],0,0,0); \
;     __builtin_amdgcn_s_setprio(0);}while(0)
; #define WAIT_V(n) asm volatile("s_waitcnt vmcnt(" #n ")":::"memory")
; #define WAIT_L(n) asm volatile("s_waitcnt lgkmcnt(" #n ")":::"memory")
; #define BAR __builtin_amdgcn_s_barrier()
; template <int EPI>
; __device__ __forceinline__ void gemm_run(const GD& c, const bool has_next, const GD& nx, const Ctx& e, bf16* shm, float* rs, float* rs_nxt, float* racc_) {
;     ...
;   { LDB(B0,1,0); LDA(At,1,0); WAIT_V(2); BAR; WAIT_L(0); MMA(0,0,At,B0); BAR;
;     LDB(B1,1,1); WAIT_V(0); BAR; WAIT_L(0); MMA(0,1,At,B1); BAR;
;     LDA(At,1,1); BAR; WAIT_L(0); MMA(1,0,At,B0); MMA(1,1,At,B1); BAR; }
;   if(wr==0)BAR;
	s_waitcnt lgkmcnt(0)
	s_setprio 1
	v_mfma_f32_16x16x32_bf16 v[66:69], v[2:5], v[18:21], v[126:129]
	v_mfma_f32_16x16x32_bf16 v[114:117], v[6:9], v[22:25], v[66:69]
	v_mfma_f32_16x16x32_bf16 v[66:69], v[206:209], v[18:21], v[122:125]
	v_mfma_f32_16x16x32_bf16 v[126:129], v[210:213], v[22:25], v[66:69]
	v_mfma_f32_16x16x32_bf16 v[66:69], v[2:5], v[34:37], v[118:121]
	v_mfma_f32_16x16x32_bf16 v[98:101], v[6:9], v[38:41], v[66:69]
	v_mfma_f32_16x16x32_bf16 v[66:69], v[206:209], v[34:37], v[218:221]
	v_mfma_f32_16x16x32_bf16 v[102:105], v[210:213], v[38:41], v[66:69]
	v_mfma_f32_16x16x32_bf16 v[66:69], v[2:5], v[50:53], v[110:113]
	v_mfma_f32_16x16x32_bf16 v[74:77], v[6:9], v[54:57], v[66:69]
	v_mfma_f32_16x16x32_bf16 v[66:69], v[206:209], v[50:53], v[106:109]
	v_mfma_f32_16x16x32_bf16 v[86:89], v[210:213], v[54:57], v[66:69]
	v_mfma_f32_16x16x32_bf16 v[66:69], v[2:5], v[214:217], v[222:225]
	v_mfma_f32_16x16x32_bf16 v[70:73], v[206:209], v[214:217], v[226:229]
	v_mfma_f32_16x16x32_bf16 v[66:69], v[6:9], v[238:241], v[66:69]
	v_mfma_f32_16x16x32_bf16 v[70:73], v[210:213], v[238:241], v[70:73]
	s_setprio 0
	s_barrier
	ds_read_b128 v[218:221], v138
	ds_read_b128 v[222:225], v138 offset:1024
	ds_read_b128 v[226:229], v138 offset:2048
	ds_read_b128 v[138:141], v138 offset:3072
	s_waitcnt vmcnt(0)
	s_barrier
	s_waitcnt lgkmcnt(0)
	s_setprio 1
	v_mfma_f32_16x16x32_bf16 v[94:97], v[218:221], v[18:21], v[94:97]
	v_mfma_f32_16x16x32_bf16 v[18:21], v[226:229], v[18:21], v[90:93]
	v_mfma_f32_16x16x32_bf16 v[122:125], v[138:141], v[22:25], v[18:21]
	v_mfma_f32_16x16x32_bf16 v[18:21], v[218:221], v[34:37], v[186:189]
	v_mfma_f32_16x16x32_bf16 v[106:109], v[222:225], v[38:41], v[18:21]
	v_mfma_f32_16x16x32_bf16 v[18:21], v[226:229], v[34:37], v[82:85]
	v_mfma_f32_16x16x32_bf16 v[110:113], v[138:141], v[38:41], v[18:21]
	v_mfma_f32_16x16x32_bf16 v[18:21], v[218:221], v[50:53], v[78:81]
	v_mfma_f32_16x16x32_bf16 v[90:93], v[222:225], v[54:57], v[18:21]
	v_mfma_f32_16x16x32_bf16 v[18:21], v[226:229], v[50:53], v[190:193]
	v_mfma_f32_16x16x32_bf16 v[118:121], v[222:225], v[22:25], v[94:97]
	v_mfma_f32_16x16x32_bf16 v[94:97], v[138:141], v[54:57], v[18:21]
	v_mfma_f32_16x16x32_bf16 v[18:21], v[218:221], v[214:217], v[194:197]
	v_mfma_f32_16x16x32_bf16 v[78:81], v[222:225], v[238:241], v[18:21]
	v_mfma_f32_16x16x32_bf16 v[18:21], v[226:229], v[214:217], v[198:201]
	v_mfma_f32_16x16x32_bf16 v[82:85], v[138:141], v[238:241], v[18:21]
	s_setprio 0
	s_barrier
	ds_read_b128 v[186:189], v137 offset:49152
	ds_read_b128 v[190:193], v137 offset:50176
	ds_read_b128 v[194:197], v136 offset:49152
	ds_read_b128 v[198:201], v136 offset:50176
	ds_read_b128 v[214:217], v135 offset:49152
	ds_read_b128 v[238:241], v135 offset:50176
	ds_read_b128 v[242:245], v134 offset:49152
	ds_read_b128 v[134:137], v134 offset:50176
	s_barrier
	s_waitcnt lgkmcnt(0)
	s_setprio 1
	v_mfma_f32_16x16x32_bf16 v[18:21], v[2:5], v[186:189], v[62:65]
	v_mfma_f32_16x16x32_bf16 v[50:53], v[6:9], v[190:193], v[18:21]
	v_mfma_f32_16x16x32_bf16 v[18:21], v[206:209], v[186:189], v[58:61]
	v_mfma_f32_16x16x32_bf16 v[54:57], v[210:213], v[190:193], v[18:21]
	v_mfma_f32_16x16x32_bf16 v[18:21], v[2:5], v[194:197], v[230:233]
	v_mfma_f32_16x16x32_bf16 v[34:37], v[6:9], v[198:201], v[18:21]
	v_mfma_f32_16x16x32_bf16 v[18:21], v[206:209], v[194:197], v[234:237]
	v_mfma_f32_16x16x32_bf16 v[38:41], v[210:213], v[198:201], v[18:21]
	v_mfma_f32_16x16x32_bf16 v[18:21], v[2:5], v[214:217], v[46:49]
	v_mfma_f32_16x16x32_bf16 v[2:5], v[2:5], v[242:245], v[156:159]
	v_mfma_f32_16x16x32_bf16 v[18:21], v[6:9], v[238:241], v[18:21]
	v_mfma_f32_16x16x32_bf16 v[22:25], v[206:209], v[214:217], v[42:45]
	v_mfma_f32_16x16x32_bf16 v[2:5], v[6:9], v[134:137], v[2:5]
	v_mfma_f32_16x16x32_bf16 v[6:9], v[206:209], v[242:245], v[160:163]
	v_mfma_f32_16x16x32_bf16 v[22:25], v[210:213], v[238:241], v[22:25]
	v_mfma_f32_16x16x32_bf16 v[6:9], v[210:213], v[134:137], v[6:9]
	s_setprio 0
	s_setprio 1
	v_mfma_f32_16x16x32_bf16 v[26:29], v[226:229], v[186:189], v[26:29]
	v_mfma_f32_16x16x32_bf16 v[62:65], v[138:141], v[190:193], v[26:29]
	v_mfma_f32_16x16x32_bf16 v[26:29], v[218:221], v[194:197], v[166:169]
	v_mfma_f32_16x16x32_bf16 v[30:33], v[218:221], v[186:189], v[30:33]
	v_mfma_f32_16x16x32_bf16 v[42:45], v[222:225], v[198:201], v[26:29]
	v_mfma_f32_16x16x32_bf16 v[26:29], v[226:229], v[194:197], v[172:175]
	v_mfma_f32_16x16x32_bf16 v[14:17], v[218:221], v[214:217], v[14:17]
	v_mfma_f32_16x16x32_bf16 v[10:13], v[226:229], v[214:217], v[10:13]
	v_mfma_f32_16x16x32_bf16 v[58:61], v[222:225], v[190:193], v[30:33]
	v_mfma_f32_16x16x32_bf16 v[46:49], v[138:141], v[198:201], v[26:29]
	v_mfma_f32_16x16x32_bf16 v[26:29], v[222:225], v[238:241], v[14:17]
	v_mfma_f32_16x16x32_bf16 v[30:33], v[138:141], v[238:241], v[10:13]
	v_mfma_f32_16x16x32_bf16 v[10:13], v[218:221], v[242:245], v[202:205]
	v_mfma_f32_16x16x32_bf16 v[14:17], v[226:229], v[242:245], v[142:145]
	v_mfma_f32_16x16x32_bf16 v[10:13], v[222:225], v[134:137], v[10:13]
	v_mfma_f32_16x16x32_bf16 v[14:17], v[138:141], v[134:137], v[14:17]
	s_setprio 0
	v_cmp_gt_u32_e32 vcc, s96, v132
	s_barrier
	s_and_saveexec_b64 s[2:3], vcc
	s_cbranch_execz .LBB0_692
	s_barrier

; #define STAGE_A(P,br,kt) STAGE_G(P,c.A,c.lda,br,(long)(kt)*c.kstr)
; #define STAGE_B(P,br,kt) STAGE_G(P,c.Bt,c.K,br,(long)(kt)*BK)
; #define LDA(dst,b,h) for(int m=0;m<4;++m)for(int k=0;k<2;++k) \
;     dst[m][k]=*reinterpret_cast<const bf16x8*>((char*)SA(b,h)+lds_byte(wr*64+m*16+fr,k*32+fq*8))
; #define LDB(dst,b,h) for(int n=0;n<2;++n)for(int k=0;k<2;++k) \
;     dst[n][k]=*reinterpret_cast<const bf16x8*>((char*)SB(b,h)+lds_byte(wc*32+n*16+fr,k*32+fq*8))
; #define MMA(ai,bj,At,Bt_) do{__builtin_amdgcn_s_setprio(1); \
;     for(int m=0;m<4;++m)for(int n=0;n<2;++n)for(int k=0;k<2;++k) \
;       acc[ai][bj][m][n]=__builtin_amdgcn_mfma_f32_16x16x32_bf16(Bt_[n][k],At[m][k],acc[ai][bj][m][n],0,0,0); \
;     __builtin_amdgcn_s_setprio(0);}while(0)
; #define WAIT_V(n) asm volatile("s_waitcnt vmcnt(" #n ")":::"memory")
; #define WAIT_L(n) asm volatile("s_waitcnt lgkmcnt(" #n ")":::"memory")
; #define BAR __builtin_amdgcn_s_barrier()
; #define SCHED __builtin_amdgcn_sched_barrier(0)
; template <int EPI>
; __device__ __forceinline__ void gemm_run(const GD& c, const bool has_next, const GD& nx, const Ctx& e, bf16* shm, float* rs, float* rs_nxt, float* racc_) {
;     ...
;   int tidv = threadIdx.x; asm volatile("" : "+v"(tidv));
;   int wid = tidv >> 6, lane = tidv & 63, wr = wid >> 2, wc = wid & 3, fr = lane & 15, fq = lane >> 4;
;   f32x4 acc[2][2][4][2] = {};
;   bf16x8 At[4][2], B0[2][2], B1[2][2];
;   const int nt = c.nt;
;   if(wr==1)BAR;
;   WAIT_V(0); BAR;
;   STAGE_B(SB(1,0),bcol,1); STAGE_A(SA(1,0),brow,1); STAGE_B(SB(1,1),bcol+HALF,1);
;   BAR;
;   for(int t=0;t<nt-2;t+=2){
;     LDB(B0,0,0); SCHED; LDA(At,0,0); STAGE_A(SA(1,1),brow+HALF,t+1);
;     WAIT_L(8); BAR; WAIT_L(0); MMA(0,0,At,B0); BAR; SCHED;
.LBB0_745:
	s_or_b64 exec, exec, s[2:3]
	v_bfe_i32 v2, v92, 27, 1
	v_lshlrev_b32_e32 v20, 4, v92
	v_lshrrev_b32_e32 v2, 22, v2
	v_add_u32_e32 v2, v20, v2
	v_and_b32_e32 v2, 0xfffffc00, v2
	v_sub_u32_e32 v2, v20, v2
	v_lshrrev_b32_e32 v3, 4, v2
	v_bitop3_b32 v2, v3, v2, 32 bitop3:0x6c
	v_ashrrev_i32_e32 v0, 31, v92
	v_ashrrev_i32_e32 v4, 31, v2
	v_lshrrev_b32_e32 v0, 26, v0
	v_lshrrev_b32_e32 v4, 26, v4
	v_add_u32_e32 v0, v92, v0
	v_add_u32_e32 v4, v2, v4
	s_lshl_b32 s2, s31, 8
	v_ashrrev_i32_e32 v0, 6, v0
	v_lshrrev_b32_e32 v5, 6, v4
	v_and_b32_e32 v4, 0xc0, v4
	s_ashr_i32 s3, s2, 31
	v_lshlrev_b32_e32 v3, 3, v0
	v_lshlrev_b32_e32 v0, 5, v0
	v_sub_u32_e32 v2, v2, v4
	s_lshl_b32 s12, s20, 8
	s_lshl_b64 s[20:21], s[2:3], 9
	v_and_b32_e32 v3, 0x7ffff0, v3
	v_and_b32_e32 v0, 32, v0
	v_ashrrev_i16_sdwa v2, v177, sext(v2) dst_sel:DWORD dst_unused:UNUSED_PAD src0_sel:DWORD src1_sel:BYTE_0
	s_add_u32 s34, s25, s20
	v_add_u32_sdwa v0, v0, sext(v2) dst_sel:DWORD dst_unused:UNUSED_PAD src0_sel:DWORD src1_sel:WORD_0
	v_add_lshl_u32 v2, v5, v3, 9
	v_readlane_b32 s38, v254, 23
	s_addc_u32 s35, s26, s21
	v_lshl_add_u32 v0, v0, 1, v2
	v_add_u32_e32 v6, s38, v20
	v_lshl_add_u64 v[2:3], s[34:35], 0, v[0:1]
	v_readfirstlane_b32 s20, v6
	v_lshl_add_u64 v[4:5], v[2:3], 0, s[66:67]
	s_mov_b32 m0, s20
	v_add_u32_e32 v21, 0x2000, v20
	s_waitcnt vmcnt(0)
	s_barrier
	global_load_lds_dwordx4 v[4:5], off
	v_ashrrev_i32_e32 v4, 31, v21
	v_lshrrev_b32_e32 v4, 22, v4
	v_add_u32_e32 v4, v21, v4
	v_ashrrev_i32_e32 v4, 10, v4
	v_mul_i32_i24_e32 v5, 0x400, v4
	v_sub_u32_e32 v5, v21, v5
	v_lshrrev_b32_e32 v6, 4, v5
	v_bitop3_b32 v5, v6, v5, 32 bitop3:0x6c
	v_ashrrev_i32_e32 v7, 31, v5
	v_lshrrev_b32_e32 v7, 26, v7
	v_add_u32_e32 v7, v5, v7
	v_lshrrev_b32_e32 v8, 6, v7
	v_and_b32_e32 v7, 0xc0, v7
	v_lshlrev_b32_e32 v6, 3, v4
	v_lshlrev_b32_e32 v4, 5, v4
	v_sub_u32_e32 v5, v5, v7
	s_ashr_i32 s13, s12, 31
	v_and_b32_e32 v6, 0x7ffff0, v6
	v_and_b32_e32 v4, 32, v4
	v_ashrrev_i16_sdwa v5, v177, sext(v5) dst_sel:DWORD dst_unused:UNUSED_PAD src0_sel:DWORD src1_sel:BYTE_0
	s_lshl_b64 s[36:37], s[12:13], 9
	v_add_u32_sdwa v4, v4, sext(v5) dst_sel:DWORD dst_unused:UNUSED_PAD src0_sel:DWORD src1_sel:WORD_0
	v_add_lshl_u32 v5, v8, v6, 9
	s_add_u32 s36, s23, s36
	v_lshl_add_u32 v90, v4, 1, v5
	v_mov_b32_e32 v91, v1
	v_add_u32_e32 v6, s38, v21
	s_addc_u32 s37, s24, s37
	v_add_u32_e32 v93, 0, v20
	s_bitset1_b32 s2, 7
	v_lshl_add_u64 v[12:13], s[34:35], 0, v[90:91]
	v_readfirstlane_b32 s34, v6
	v_add_u32_e32 v6, 0x8000, v93
	s_ashr_i32 s3, s2, 31
	v_lshl_add_u64 v[4:5], v[12:13], 0, s[66:67]
	s_mov_b32 m0, s34
	v_lshl_add_u64 v[8:9], s[36:37], 0, v[0:1]
	v_readfirstlane_b32 s21, v6
	v_add_u32_e32 v6, 0xa000, v93
	s_lshl_b64 s[2:3], s[2:3], 9
	global_load_lds_dwordx4 v[4:5], off
	v_lshl_add_u64 v[4:5], v[8:9], 0, s[66:67]
	s_mov_b32 m0, s21
	v_lshl_add_u64 v[10:11], s[36:37], 0, v[90:91]
	v_readfirstlane_b32 s13, v6
	s_add_u32 s36, s25, s2
	v_readlane_b32 s35, v254, 24
	global_load_lds_dwordx4 v[4:5], off
	v_lshl_add_u64 v[4:5], v[10:11], 0, s[66:67]
	s_mov_b32 m0, s13
	s_addc_u32 s37, s26, s3
	v_add_u32_e32 v16, s35, v20
	global_load_lds_dwordx4 v[4:5], off
	v_lshl_add_u64 v[4:5], s[36:37], 0, v[0:1]
	v_readfirstlane_b32 s2, v16
	v_lshl_add_u64 v[6:7], v[4:5], 0, s[66:67]
	s_mov_b32 m0, s2
	v_add_u32_e32 v19, s35, v21
	global_load_lds_dwordx4 v[6:7], off
	v_lshl_add_u64 v[6:7], s[36:37], 0, v[90:91]
	v_readfirstlane_b32 s3, v19
	v_lshl_add_u64 v[16:17], v[6:7], 0, s[66:67]
	s_mov_b32 m0, s3
	v_and_b32_e32 v15, 15, v92
	global_load_lds_dwordx4 v[16:17], off
	v_lshlrev_b32_e32 v19, 2, v92
	v_and_b32_e32 v18, 48, v92
	v_lshlrev_b32_e32 v16, 6, v92
	v_lshlrev_b32_e32 v15, 6, v15
	v_and_b32_e32 v22, 32, v19
	v_and_b32_e32 v17, 0x3000, v16
	v_bitop3_b32 v15, v15, v22, v18 bitop3:0x36
	v_add3_u32 v139, s33, v15, v17
	v_and_b32_e32 v16, 0x3c0, v16
	s_barrier
	v_bitop3_b32 v16, v16, v22, v18 bitop3:0x36
	v_add_u32_e32 v138, s33, v20
	v_add_u32_e32 v126, s33, v21
	v_add_u32_e32 v96, s86, v20
	v_add_u32_e32 v176, s86, v21
	ds_read_b128 v[20:23], v139
	ds_read_b128 v[24:27], v139 offset:1024
	ds_read_b128 v[28:31], v139 offset:2048
	ds_read_b128 v[32:35], v139 offset:3072
	v_lshlrev_b32_e32 v14, 13, v14
	s_or_b32 s36, s12, 0x80
	v_add3_u32 v19, 0, v15, v14
	v_add3_u32 v18, 0, v16, v14
	v_add_u32_e32 v68, 0xc000, v93
	v_add_u32_e32 v70, 0xe000, v93
	v_add_u32_e32 v97, 0x2000, v93
	v_add_u32_e32 v95, 0x4000, v93
	v_add_u32_e32 v94, 0x6000, v93
	s_ashr_i32 s37, s36, 31
	v_add3_u32 v170, s86, v15, v17
	v_add3_u32 v182, s38, v15, v17
	v_add3_u32 v183, s35, v15, v17
	s_lshl_b64 s[36:37], s[36:37], 9
	s_add_u32 s38, s23, s36
	s_addc_u32 s39, s24, s37
	v_lshl_add_u64 v[14:15], s[38:39], 0, v[0:1]
	v_readfirstlane_b32 s36, v68
	v_lshl_add_u64 v[16:17], v[14:15], 0, s[66:67]
	s_mov_b32 m0, s36
	ds_read_b128 v[36:39], v19
	ds_read_b128 v[40:43], v19 offset:1024
	ds_read_b128 v[44:47], v18 offset:2048
	ds_read_b128 v[48:51], v18 offset:3072
	ds_read_b128 v[52:55], v18 offset:4096
	ds_read_b128 v[56:59], v18 offset:5120
	ds_read_b128 v[60:63], v18 offset:6144
	ds_read_b128 v[64:67], v18 offset:7168
	global_load_lds_dwordx4 v[16:17], off
	v_lshl_add_u64 v[16:17], s[38:39], 0, v[90:91]
	v_readfirstlane_b32 s35, v70
	v_lshl_add_u64 v[68:69], v[16:17], 0, s[66:67]
	s_mov_b32 m0, s35
	s_nop 0
	global_load_lds_dwordx4 v[68:69], off
	s_waitcnt lgkmcnt(8)
	s_barrier
; #define STAGE_A(P,br,kt) STAGE_G(P,c.A,c.lda,br,(long)(kt)*c.kstr)
; #define STAGE_B(P,br,kt) STAGE_G(P,c.Bt,c.K,br,(long)(kt)*BK)
; #define LDA(dst,b,h) for(int m=0;m<4;++m)for(int k=0;k<2;++k) \
;     dst[m][k]=*reinterpret_cast<const bf16x8*>((char*)SA(b,h)+lds_byte(wr*64+m*16+fr,k*32+fq*8))
; #define LDB(dst,b,h) for(int n=0;n<2;++n)for(int k=0;k<2;++k) \
;     dst[n][k]=*reinterpret_cast<const bf16x8*>((char*)SB(b,h)+lds_byte(wc*32+n*16+fr,k*32+fq*8))
; #define MMA(ai,bj,At,Bt_) do{__builtin_amdgcn_s_setprio(1); \
;     for(int m=0;m<4;++m)for(int n=0;n<2;++n)for(int k=0;k<2;++k) \
;       acc[ai][bj][m][n]=__builtin_amdgcn_mfma_f32_16x16x32_bf16(Bt_[n][k],At[m][k],acc[ai][bj][m][n],0,0,0); \
;     __builtin_amdgcn_s_setprio(0);}while(0)
; #define WAIT_V(n) asm volatile("s_waitcnt vmcnt(" #n ")":::"memory")
; #define WAIT_L(n) asm volatile("s_waitcnt lgkmcnt(" #n ")":::"memory")
; #define BAR __builtin_amdgcn_s_barrier()
; #define SCHED __builtin_amdgcn_sched_barrier(0)
; template <int EPI>
; __device__ __forceinline__ void gemm_run(const GD& c, const bool has_next, const GD& nx, const Ctx& e, bf16* shm, float* rs, float* rs_nxt, float* racc_) {
;     ...
;   for(int t=0;t<nt-2;t+=2){
;     LDB(B0,0,0); SCHED; LDA(At,0,0); STAGE_A(SA(1,1),brow+HALF,t+1);
;     WAIT_L(8); BAR; WAIT_L(0); MMA(0,0,At,B0); BAR; SCHED;
;     LDB(B1,0,1); STAGE_B(SB(0,0),bcol,t+2);
;     BAR; WAIT_L(0); MMA(0,1,At,B1); BAR;
;     LDA(At,0,1); STAGE_A(SA(0,0),brow,t+2);
;     BAR; WAIT_L(0); MMA(1,0,At,B0); BAR; SCHED;
;     STAGE_B(SB(0,1),bcol+HALF,t+2);
;     WAIT_V(6); BAR; MMA(1,1,At,B1); BAR;
	s_waitcnt lgkmcnt(0)
	s_setprio 1
	v_mfma_f32_16x16x32_bf16 v[68:71], v[20:23], v[36:39], 0
	v_mfma_f32_16x16x32_bf16 v[72:75], v[28:31], v[36:39], 0
	v_mfma_f32_16x16x32_bf16 v[76:79], v[20:23], v[44:47], 0
	v_mfma_f32_16x16x32_bf16 v[80:83], v[28:31], v[44:47], 0
	v_mfma_f32_16x16x32_bf16 v[84:87], v[20:23], v[52:55], 0
	v_mfma_f32_16x16x32_bf16 v[98:101], v[28:31], v[52:55], 0
	v_mfma_f32_16x16x32_bf16 v[102:105], v[20:23], v[60:63], 0
	v_mfma_f32_16x16x32_bf16 v[106:109], v[28:31], v[60:63], 0
	v_mfma_f32_16x16x32_bf16 v[68:71], v[24:27], v[40:43], v[68:71]
	v_mfma_f32_16x16x32_bf16 v[72:75], v[32:35], v[40:43], v[72:75]
	v_mfma_f32_16x16x32_bf16 v[76:79], v[24:27], v[48:51], v[76:79]
	v_mfma_f32_16x16x32_bf16 v[80:83], v[32:35], v[48:51], v[80:83]
	v_mfma_f32_16x16x32_bf16 v[84:87], v[24:27], v[56:59], v[84:87]
	v_mfma_f32_16x16x32_bf16 v[98:101], v[32:35], v[56:59], v[98:101]
	v_mfma_f32_16x16x32_bf16 v[102:105], v[24:27], v[64:67], v[102:105]
	v_mfma_f32_16x16x32_bf16 v[106:109], v[32:35], v[64:67], v[106:109]
	s_setprio 0
	s_barrier
	v_readfirstlane_b32 s37, v138
	v_lshl_add_u64 v[88:89], v[2:3], 0, s[88:89]
	s_mov_b32 m0, s37
	v_readfirstlane_b32 s37, v126
	ds_read_b128 v[110:113], v170
	ds_read_b128 v[114:117], v170 offset:1024
	ds_read_b128 v[118:121], v170 offset:2048
	ds_read_b128 v[122:125], v170 offset:3072
	global_load_lds_dwordx4 v[88:89], off
	v_lshl_add_u64 v[88:89], v[12:13], 0, s[88:89]
	s_mov_b32 m0, s37
	s_nop 0
	global_load_lds_dwordx4 v[88:89], off
	s_barrier
	s_waitcnt lgkmcnt(0)
	s_setprio 1
	v_mfma_f32_16x16x32_bf16 v[126:129], v[110:113], v[36:39], 0
	v_mfma_f32_16x16x32_bf16 v[36:39], v[118:121], v[36:39], 0
	v_mfma_f32_16x16x32_bf16 v[126:129], v[114:117], v[40:43], v[126:129]
	v_mfma_f32_16x16x32_bf16 v[36:39], v[122:125], v[40:43], v[36:39]
	v_mfma_f32_16x16x32_bf16 v[40:43], v[110:113], v[44:47], 0
	v_mfma_f32_16x16x32_bf16 v[44:47], v[118:121], v[44:47], 0
	v_mfma_f32_16x16x32_bf16 v[40:43], v[114:117], v[48:51], v[40:43]
	v_mfma_f32_16x16x32_bf16 v[44:47], v[122:125], v[48:51], v[44:47]
	v_mfma_f32_16x16x32_bf16 v[48:51], v[110:113], v[52:55], 0
	v_mfma_f32_16x16x32_bf16 v[52:55], v[118:121], v[52:55], 0
	v_mfma_f32_16x16x32_bf16 v[48:51], v[114:117], v[56:59], v[48:51]
	v_mfma_f32_16x16x32_bf16 v[52:55], v[122:125], v[56:59], v[52:55]
	v_mfma_f32_16x16x32_bf16 v[56:59], v[110:113], v[60:63], 0
	v_mfma_f32_16x16x32_bf16 v[60:63], v[118:121], v[60:63], 0
	v_mfma_f32_16x16x32_bf16 v[56:59], v[114:117], v[64:67], v[56:59]
	v_mfma_f32_16x16x32_bf16 v[60:63], v[122:125], v[64:67], v[60:63]
	s_setprio 0
	v_readfirstlane_b32 s37, v93
	v_lshl_add_u64 v[88:89], v[8:9], 0, s[88:89]
	s_mov_b32 m0, s37
	v_readfirstlane_b32 s37, v97
	s_barrier
	ds_read_b128 v[64:67], v19 offset:16384
	ds_read_b128 v[130:133], v19 offset:17408
	ds_read_b128 v[134:137], v18 offset:18432
	ds_read_b128 v[140:143], v18 offset:19456
	ds_read_b128 v[144:147], v18 offset:20480
	ds_read_b128 v[148:151], v18 offset:21504
	ds_read_b128 v[152:155], v18 offset:22528
	ds_read_b128 v[156:159], v18 offset:23552
	global_load_lds_dwordx4 v[88:89], off
	v_lshl_add_u64 v[88:89], v[10:11], 0, s[88:89]
	s_mov_b32 m0, s37
	s_nop 0
	global_load_lds_dwordx4 v[88:89], off
	s_barrier
	s_waitcnt lgkmcnt(0)
	s_setprio 1
	v_mfma_f32_16x16x32_bf16 v[160:163], v[20:23], v[64:67], 0
	v_mfma_f32_16x16x32_bf16 v[172:175], v[20:23], v[134:137], 0
	v_mfma_f32_16x16x32_bf16 v[190:193], v[20:23], v[144:147], 0
	v_mfma_f32_16x16x32_bf16 v[20:23], v[20:23], v[152:155], 0
	v_mfma_f32_16x16x32_bf16 v[160:163], v[24:27], v[130:133], v[160:163]
	v_mfma_f32_16x16x32_bf16 v[172:175], v[24:27], v[140:143], v[172:175]
	v_mfma_f32_16x16x32_bf16 v[190:193], v[24:27], v[148:151], v[190:193]
	v_mfma_f32_16x16x32_bf16 v[20:23], v[24:27], v[156:159], v[20:23]
	v_mfma_f32_16x16x32_bf16 v[24:27], v[28:31], v[152:155], 0
	v_mfma_f32_16x16x32_bf16 v[166:169], v[28:31], v[64:67], 0
	v_mfma_f32_16x16x32_bf16 v[186:189], v[28:31], v[134:137], 0
	v_mfma_f32_16x16x32_bf16 v[194:197], v[28:31], v[144:147], 0
	v_mfma_f32_16x16x32_bf16 v[24:27], v[32:35], v[156:159], v[24:27]
	v_mfma_f32_16x16x32_bf16 v[166:169], v[32:35], v[130:133], v[166:169]
	v_mfma_f32_16x16x32_bf16 v[186:189], v[32:35], v[140:143], v[186:189]
	v_mfma_f32_16x16x32_bf16 v[194:197], v[32:35], v[148:151], v[194:197]
	s_setprio 0
	s_barrier
	v_readfirstlane_b32 s37, v96
	v_lshl_add_u64 v[28:29], v[4:5], 0, s[88:89]
	s_mov_b32 m0, s37
	v_readfirstlane_b32 s37, v176
	global_load_lds_dwordx4 v[28:29], off
	v_lshl_add_u64 v[28:29], v[6:7], 0, s[88:89]
	s_mov_b32 m0, s37
	s_nop 0
	global_load_lds_dwordx4 v[28:29], off
	s_waitcnt vmcnt(6)
	s_barrier
	s_setprio 1
	v_mfma_f32_16x16x32_bf16 v[28:31], v[110:113], v[64:67], 0
	v_mfma_f32_16x16x32_bf16 v[32:35], v[118:121], v[64:67], 0
	v_mfma_f32_16x16x32_bf16 v[28:31], v[114:117], v[130:133], v[28:31]
	v_mfma_f32_16x16x32_bf16 v[32:35], v[122:125], v[130:133], v[32:35]
	v_mfma_f32_16x16x32_bf16 v[64:67], v[110:113], v[134:137], 0
	v_mfma_f32_16x16x32_bf16 v[130:133], v[118:121], v[134:137], 0
	v_mfma_f32_16x16x32_bf16 v[134:137], v[110:113], v[144:147], 0
	v_mfma_f32_16x16x32_bf16 v[110:113], v[110:113], v[152:155], 0
	v_mfma_f32_16x16x32_bf16 v[64:67], v[114:117], v[140:143], v[64:67]
	v_mfma_f32_16x16x32_bf16 v[134:137], v[114:117], v[148:151], v[134:137]
	v_mfma_f32_16x16x32_bf16 v[110:113], v[114:117], v[156:159], v[110:113]
	v_mfma_f32_16x16x32_bf16 v[114:117], v[118:121], v[152:155], 0
	v_mfma_f32_16x16x32_bf16 v[130:133], v[122:125], v[140:143], v[130:133]
	v_mfma_f32_16x16x32_bf16 v[140:143], v[118:121], v[144:147], 0
	v_mfma_f32_16x16x32_bf16 v[114:117], v[122:125], v[156:159], v[114:117]
	v_mfma_f32_16x16x32_bf16 v[140:143], v[122:125], v[148:151], v[140:143]
	s_setprio 0
	s_barrier
; #define STAGE_A(P,br,kt) STAGE_G(P,c.A,c.lda,br,(long)(kt)*c.kstr)
; #define STAGE_B(P,br,kt) STAGE_G(P,c.Bt,c.K,br,(long)(kt)*BK)
; #define LDA(dst,b,h) for(int m=0;m<4;++m)for(int k=0;k<2;++k) \
;     dst[m][k]=*reinterpret_cast<const bf16x8*>((char*)SA(b,h)+lds_byte(wr*64+m*16+fr,k*32+fq*8))
; #define LDB(dst,b,h) for(int n=0;n<2;++n)for(int k=0;k<2;++k) \
;     dst[n][k]=*reinterpret_cast<const bf16x8*>((char*)SB(b,h)+lds_byte(wc*32+n*16+fr,k*32+fq*8))
; #define MMA(ai,bj,At,Bt_) do{__builtin_amdgcn_s_setprio(1); \
;     for(int m=0;m<4;++m)for(int n=0;n<2;++n)for(int k=0;k<2;++k) \
;       acc[ai][bj][m][n]=__builtin_amdgcn_mfma_f32_16x16x32_bf16(Bt_[n][k],At[m][k],acc[ai][bj][m][n],0,0,0); \
;     __builtin_amdgcn_s_setprio(0);}while(0)
; #define WAIT_V(n) asm volatile("s_waitcnt vmcnt(" #n ")":::"memory")
; #define WAIT_L(n) asm volatile("s_waitcnt lgkmcnt(" #n ")":::"memory")
; #define BAR __builtin_amdgcn_s_barrier()
; #define SCHED __builtin_amdgcn_sched_barrier(0)
; template <int EPI>
; __device__ __forceinline__ void gemm_run(const GD& c, const bool has_next, const GD& nx, const Ctx& e, bf16* shm, float* rs, float* rs_nxt, float* racc_) {
;     ...
;     LDB(B0,1,0); SCHED; LDA(At,1,0); STAGE_A(SA(0,1),brow+HALF,t+2);
;     WAIT_L(8); BAR; WAIT_L(0); MMA(0,0,At,B0); BAR; SCHED;
;     LDB(B1,1,1); STAGE_B(SB(1,0),bcol,t+3);
;     BAR; WAIT_L(0); MMA(0,1,At,B1); BAR;
;     LDA(At,1,1); STAGE_A(SA(1,0),brow,t+3);
;     BAR; WAIT_L(0); MMA(1,0,At,B0); BAR; SCHED;
;     STAGE_B(SB(1,1),bcol+HALF,t+3);
;     WAIT_V(6); BAR; MMA(1,1,At,B1); BAR;
	ds_read_b128 v[118:121], v182
	ds_read_b128 v[122:125], v182 offset:1024
	ds_read_b128 v[144:147], v182 offset:2048
	ds_read_b128 v[148:151], v182 offset:3072
	v_readfirstlane_b32 s37, v95
	v_lshl_add_u64 v[88:89], v[14:15], 0, s[88:89]
	s_mov_b32 m0, s37
	v_readfirstlane_b32 s37, v94
	ds_read_b128 v[152:155], v19 offset:32768
	ds_read_b128 v[156:159], v19 offset:33792
	ds_read_b128 v[198:201], v18 offset:34816
	ds_read_b128 v[202:205], v18 offset:35840
	ds_read_b128 v[206:209], v18 offset:36864
	ds_read_b128 v[210:213], v18 offset:37888
	ds_read_b128 v[214:217], v18 offset:38912
	ds_read_b128 v[218:221], v18 offset:39936
	global_load_lds_dwordx4 v[88:89], off
	v_lshl_add_u64 v[88:89], v[16:17], 0, s[88:89]
	s_mov_b32 m0, s37
	s_nop 0
	global_load_lds_dwordx4 v[88:89], off
	s_waitcnt lgkmcnt(8)
	s_barrier
	s_waitcnt lgkmcnt(0)
	s_setprio 1
	v_mfma_f32_16x16x32_bf16 v[68:71], v[118:121], v[152:155], v[68:71]
	v_mfma_f32_16x16x32_bf16 v[72:75], v[144:147], v[152:155], v[72:75]
	v_mfma_f32_16x16x32_bf16 v[76:79], v[118:121], v[198:201], v[76:79]
	v_mfma_f32_16x16x32_bf16 v[80:83], v[144:147], v[198:201], v[80:83]
	v_mfma_f32_16x16x32_bf16 v[84:87], v[118:121], v[206:209], v[84:87]
	v_mfma_f32_16x16x32_bf16 v[98:101], v[144:147], v[206:209], v[98:101]
	v_mfma_f32_16x16x32_bf16 v[102:105], v[118:121], v[214:217], v[102:105]
	v_mfma_f32_16x16x32_bf16 v[106:109], v[144:147], v[214:217], v[106:109]
	v_mfma_f32_16x16x32_bf16 v[68:71], v[122:125], v[156:159], v[68:71]
	v_mfma_f32_16x16x32_bf16 v[72:75], v[148:151], v[156:159], v[72:75]
	v_mfma_f32_16x16x32_bf16 v[76:79], v[122:125], v[202:205], v[76:79]
	v_mfma_f32_16x16x32_bf16 v[80:83], v[148:151], v[202:205], v[80:83]
	v_mfma_f32_16x16x32_bf16 v[84:87], v[122:125], v[210:213], v[84:87]
	v_mfma_f32_16x16x32_bf16 v[98:101], v[148:151], v[210:213], v[98:101]
	v_mfma_f32_16x16x32_bf16 v[102:105], v[122:125], v[218:221], v[102:105]
	v_mfma_f32_16x16x32_bf16 v[106:109], v[148:151], v[218:221], v[106:109]
	s_setprio 0
	s_barrier
	s_mov_b64 s[38:39], 0x180
	s_mov_b32 m0, s20
	v_lshl_add_u64 v[2:3], v[2:3], 0, s[38:39]
	ds_read_b128 v[222:225], v183
	ds_read_b128 v[226:229], v183 offset:1024
	ds_read_b128 v[230:233], v183 offset:2048
	ds_read_b128 v[234:237], v183 offset:3072
	global_load_lds_dwordx4 v[2:3], off
	v_lshl_add_u64 v[2:3], v[12:13], 0, s[38:39]
	s_mov_b32 m0, s34
	s_nop 0
	global_load_lds_dwordx4 v[2:3], off
	s_barrier
	s_waitcnt lgkmcnt(0)
	s_setprio 1
	v_mfma_f32_16x16x32_bf16 v[126:129], v[222:225], v[152:155], v[126:129]
	v_mfma_f32_16x16x32_bf16 v[36:39], v[230:233], v[152:155], v[36:39]
	v_mfma_f32_16x16x32_bf16 v[40:43], v[222:225], v[198:201], v[40:43]
	v_mfma_f32_16x16x32_bf16 v[44:47], v[230:233], v[198:201], v[44:47]
	v_mfma_f32_16x16x32_bf16 v[48:51], v[222:225], v[206:209], v[48:51]
	v_mfma_f32_16x16x32_bf16 v[52:55], v[230:233], v[206:209], v[52:55]
	v_mfma_f32_16x16x32_bf16 v[56:59], v[222:225], v[214:217], v[56:59]
	v_mfma_f32_16x16x32_bf16 v[60:63], v[230:233], v[214:217], v[60:63]
	v_mfma_f32_16x16x32_bf16 v[126:129], v[226:229], v[156:159], v[126:129]
	v_mfma_f32_16x16x32_bf16 v[36:39], v[234:237], v[156:159], v[36:39]
	v_mfma_f32_16x16x32_bf16 v[40:43], v[226:229], v[202:205], v[40:43]
	v_mfma_f32_16x16x32_bf16 v[44:47], v[234:237], v[202:205], v[44:47]
	v_mfma_f32_16x16x32_bf16 v[48:51], v[226:229], v[210:213], v[48:51]
	v_mfma_f32_16x16x32_bf16 v[52:55], v[234:237], v[210:213], v[52:55]
	v_mfma_f32_16x16x32_bf16 v[56:59], v[226:229], v[218:221], v[56:59]
	v_mfma_f32_16x16x32_bf16 v[60:63], v[234:237], v[218:221], v[60:63]
	s_setprio 0
	s_mov_b32 m0, s21
	v_lshl_add_u64 v[2:3], v[8:9], 0, s[38:39]
	s_barrier
	ds_read_b128 v[152:155], v19 offset:49152
	ds_read_b128 v[156:159], v19 offset:50176
	ds_read_b128 v[198:201], v18 offset:51200
	ds_read_b128 v[202:205], v18 offset:52224
	ds_read_b128 v[206:209], v18 offset:53248
	ds_read_b128 v[210:213], v18 offset:54272
	ds_read_b128 v[214:217], v18 offset:55296
	ds_read_b128 v[218:221], v18 offset:56320
	global_load_lds_dwordx4 v[2:3], off
	v_lshl_add_u64 v[2:3], v[10:11], 0, s[38:39]
	s_mov_b32 m0, s13
	s_nop 0
	global_load_lds_dwordx4 v[2:3], off
	s_barrier
	s_waitcnt lgkmcnt(0)
	s_setprio 1
	v_mfma_f32_16x16x32_bf16 v[8:11], v[118:121], v[152:155], v[160:163]
	v_mfma_f32_16x16x32_bf16 v[20:23], v[118:121], v[214:217], v[20:23]
	v_mfma_f32_16x16x32_bf16 v[24:27], v[144:147], v[214:217], v[24:27]
	v_mfma_f32_16x16x32_bf16 v[8:11], v[122:125], v[156:159], v[8:11]
	v_mfma_f32_16x16x32_bf16 v[160:163], v[144:147], v[152:155], v[166:169]
	v_mfma_f32_16x16x32_bf16 v[166:169], v[118:121], v[198:201], v[172:175]
	v_mfma_f32_16x16x32_bf16 v[172:175], v[144:147], v[198:201], v[186:189]
	v_mfma_f32_16x16x32_bf16 v[186:189], v[118:121], v[206:209], v[190:193]
	v_mfma_f32_16x16x32_bf16 v[190:193], v[144:147], v[206:209], v[194:197]
	v_mfma_f32_16x16x32_bf16 v[20:23], v[122:125], v[218:221], v[20:23]
	v_mfma_f32_16x16x32_bf16 v[24:27], v[148:151], v[218:221], v[24:27]
	v_mfma_f32_16x16x32_bf16 v[160:163], v[148:151], v[156:159], v[160:163]
	v_mfma_f32_16x16x32_bf16 v[166:169], v[122:125], v[202:205], v[166:169]
	v_mfma_f32_16x16x32_bf16 v[172:175], v[148:151], v[202:205], v[172:175]
	v_mfma_f32_16x16x32_bf16 v[186:189], v[122:125], v[210:213], v[186:189]
	v_mfma_f32_16x16x32_bf16 v[190:193], v[148:151], v[210:213], v[190:193]
	s_setprio 0
	s_barrier
	s_mov_b32 m0, s2
	v_lshl_add_u64 v[2:3], v[4:5], 0, s[38:39]
	global_load_lds_dwordx4 v[2:3], off
	v_lshl_add_u64 v[2:3], v[6:7], 0, s[38:39]
	s_mov_b32 m0, s3
	s_nop 0
	global_load_lds_dwordx4 v[2:3], off
	s_waitcnt vmcnt(6)
	s_barrier
; #define STAGE_A(P,br,kt) STAGE_G(P,c.A,c.lda,br,(long)(kt)*c.kstr)
; #define LDA(dst,b,h) for(int m=0;m<4;++m)for(int k=0;k<2;++k) \
;     dst[m][k]=*reinterpret_cast<const bf16x8*>((char*)SA(b,h)+lds_byte(wr*64+m*16+fr,k*32+fq*8))
; #define LDB(dst,b,h) for(int n=0;n<2;++n)for(int k=0;k<2;++k) \
;     dst[n][k]=*reinterpret_cast<const bf16x8*>((char*)SB(b,h)+lds_byte(wc*32+n*16+fr,k*32+fq*8))
; #define MMA(ai,bj,At,Bt_) do{__builtin_amdgcn_s_setprio(1); \
;     for(int m=0;m<4;++m)for(int n=0;n<2;++n)for(int k=0;k<2;++k) \
;       acc[ai][bj][m][n]=__builtin_amdgcn_mfma_f32_16x16x32_bf16(Bt_[n][k],At[m][k],acc[ai][bj][m][n],0,0,0); \
;     __builtin_amdgcn_s_setprio(0);}while(0)
; #define WAIT_V(n) asm volatile("s_waitcnt vmcnt(" #n ")":::"memory")
; #define WAIT_L(n) asm volatile("s_waitcnt lgkmcnt(" #n ")":::"memory")
; #define BAR __builtin_amdgcn_s_barrier()
; template <int EPI>
; __device__ __forceinline__ void gemm_run(const GD& c, const bool has_next, const GD& nx, const Ctx& e, bf16* shm, float* rs, float* rs_nxt, float* racc_) {
;     ...
;     WAIT_V(6); BAR; MMA(1,1,At,B1); BAR;
;   }
;   { LDB(B0,0,0); LDA(At,0,0); STAGE_A(SA(1,1),brow+HALF,nt-1);
;     BAR; WAIT_L(0); MMA(0,0,At,B0); BAR;
;     LDB(B1,0,1); BAR; WAIT_L(0); MMA(0,1,At,B1); BAR;
;     LDA(At,0,1); WAIT_V(4); BAR; WAIT_L(0); MMA(1,0,At,B0); MMA(1,1,At,B1); BAR; }
	s_setprio 1
	v_mfma_f32_16x16x32_bf16 v[2:5], v[222:225], v[152:155], v[28:31]
	v_mfma_f32_16x16x32_bf16 v[28:31], v[230:233], v[152:155], v[32:35]
	v_mfma_f32_16x16x32_bf16 v[32:35], v[222:225], v[198:201], v[64:67]
	v_mfma_f32_16x16x32_bf16 v[64:67], v[230:233], v[198:201], v[130:133]
	v_mfma_f32_16x16x32_bf16 v[118:121], v[222:225], v[206:209], v[134:137]
	v_mfma_f32_16x16x32_bf16 v[122:125], v[230:233], v[206:209], v[140:143]
	v_mfma_f32_16x16x32_bf16 v[110:113], v[222:225], v[214:217], v[110:113]
	v_mfma_f32_16x16x32_bf16 v[114:117], v[230:233], v[214:217], v[114:117]
	v_mfma_f32_16x16x32_bf16 v[2:5], v[226:229], v[156:159], v[2:5]
	v_mfma_f32_16x16x32_bf16 v[28:31], v[234:237], v[156:159], v[28:31]
	v_mfma_f32_16x16x32_bf16 v[32:35], v[226:229], v[202:205], v[32:35]
	v_mfma_f32_16x16x32_bf16 v[64:67], v[234:237], v[202:205], v[64:67]
	v_mfma_f32_16x16x32_bf16 v[118:121], v[226:229], v[210:213], v[118:121]
	v_mfma_f32_16x16x32_bf16 v[122:125], v[234:237], v[210:213], v[122:125]
	v_mfma_f32_16x16x32_bf16 v[110:113], v[226:229], v[218:221], v[110:113]
	v_mfma_f32_16x16x32_bf16 v[114:117], v[234:237], v[218:221], v[114:117]
	s_setprio 0
	s_mov_b32 m0, s36
	v_lshl_add_u64 v[6:7], v[14:15], 0, s[38:39]
	s_barrier
	ds_read_b128 v[130:133], v139
	ds_read_b128 v[134:137], v139 offset:1024
	ds_read_b128 v[140:143], v139 offset:2048
	ds_read_b128 v[144:147], v139 offset:3072
	ds_read_b128 v[148:151], v19
	ds_read_b128 v[152:155], v19 offset:1024
	ds_read_b128 v[156:159], v18 offset:2048
	ds_read_b128 v[194:197], v18 offset:3072
	ds_read_b128 v[198:201], v18 offset:4096
	ds_read_b128 v[202:205], v18 offset:5120
	ds_read_b128 v[206:209], v18 offset:6144
	ds_read_b128 v[210:213], v18 offset:7168
	global_load_lds_dwordx4 v[6:7], off
	v_lshl_add_u64 v[6:7], v[16:17], 0, s[38:39]
	s_mov_b32 m0, s35
	s_nop 0
	global_load_lds_dwordx4 v[6:7], off
	s_barrier
	s_waitcnt lgkmcnt(0)
	s_setprio 1
	v_mfma_f32_16x16x32_bf16 v[12:15], v[130:133], v[148:151], v[68:71]
	v_mfma_f32_16x16x32_bf16 v[68:71], v[140:143], v[148:151], v[72:75]
	v_mfma_f32_16x16x32_bf16 v[72:75], v[130:133], v[156:159], v[76:79]
	v_mfma_f32_16x16x32_bf16 v[76:79], v[140:143], v[156:159], v[80:83]
	v_mfma_f32_16x16x32_bf16 v[80:83], v[130:133], v[198:201], v[84:87]
	v_mfma_f32_16x16x32_bf16 v[84:87], v[140:143], v[198:201], v[98:101]
	v_mfma_f32_16x16x32_bf16 v[98:101], v[130:133], v[206:209], v[102:105]
	v_mfma_f32_16x16x32_bf16 v[102:105], v[140:143], v[206:209], v[106:109]
	v_mfma_f32_16x16x32_bf16 v[12:15], v[134:137], v[152:155], v[12:15]
	v_mfma_f32_16x16x32_bf16 v[68:71], v[144:147], v[152:155], v[68:71]
	v_mfma_f32_16x16x32_bf16 v[72:75], v[134:137], v[194:197], v[72:75]
	v_mfma_f32_16x16x32_bf16 v[76:79], v[144:147], v[194:197], v[76:79]
	v_mfma_f32_16x16x32_bf16 v[80:83], v[134:137], v[202:205], v[80:83]
	v_mfma_f32_16x16x32_bf16 v[84:87], v[144:147], v[202:205], v[84:87]
	v_mfma_f32_16x16x32_bf16 v[98:101], v[134:137], v[210:213], v[98:101]
	v_mfma_f32_16x16x32_bf16 v[102:105], v[144:147], v[210:213], v[102:105]
	s_setprio 0
	s_barrier
	ds_read_b128 v[106:109], v170
	ds_read_b128 v[214:217], v170 offset:1024
	ds_read_b128 v[218:221], v170 offset:2048
	ds_read_b128 v[222:225], v170 offset:3072
	s_barrier
	s_waitcnt lgkmcnt(0)
	s_setprio 1
	v_mfma_f32_16x16x32_bf16 v[36:39], v[218:221], v[148:151], v[36:39]
	v_mfma_f32_16x16x32_bf16 v[126:129], v[106:109], v[148:151], v[126:129]
	v_mfma_f32_16x16x32_bf16 v[148:151], v[222:225], v[152:155], v[36:39]
	v_mfma_f32_16x16x32_bf16 v[36:39], v[106:109], v[156:159], v[40:43]
	v_mfma_f32_16x16x32_bf16 v[126:129], v[214:217], v[152:155], v[126:129]
	v_mfma_f32_16x16x32_bf16 v[152:155], v[214:217], v[194:197], v[36:39]
	v_mfma_f32_16x16x32_bf16 v[36:39], v[218:221], v[156:159], v[44:47]
	v_mfma_f32_16x16x32_bf16 v[156:159], v[222:225], v[194:197], v[36:39]
	v_mfma_f32_16x16x32_bf16 v[36:39], v[106:109], v[198:201], v[48:51]
	v_mfma_f32_16x16x32_bf16 v[46:49], v[214:217], v[202:205], v[36:39]
	v_mfma_f32_16x16x32_bf16 v[36:39], v[218:221], v[198:201], v[52:55]
	v_mfma_f32_16x16x32_bf16 v[50:53], v[222:225], v[202:205], v[36:39]
	v_mfma_f32_16x16x32_bf16 v[36:39], v[106:109], v[206:209], v[56:59]
	v_mfma_f32_16x16x32_bf16 v[54:57], v[214:217], v[210:213], v[36:39]
	v_mfma_f32_16x16x32_bf16 v[36:39], v[218:221], v[206:209], v[60:63]
	v_mfma_f32_16x16x32_bf16 v[194:197], v[222:225], v[210:213], v[36:39]
	s_setprio 0
	s_barrier
	s_nop 4
	ds_read_b128 v[36:39], v19 offset:16384
	ds_read_b128 v[40:43], v19 offset:17408
	ds_read_b128 v[58:61], v18 offset:18432
	ds_read_b128 v[198:201], v18 offset:19456
	ds_read_b128 v[202:205], v18 offset:20480
	ds_read_b128 v[206:209], v18 offset:21504
	ds_read_b128 v[210:213], v18 offset:22528
	ds_read_b128 v[226:229], v18 offset:23552
	s_waitcnt vmcnt(4)
	s_barrier
; #define LDA(dst,b,h) for(int m=0;m<4;++m)for(int k=0;k<2;++k) \
;     dst[m][k]=*reinterpret_cast<const bf16x8*>((char*)SA(b,h)+lds_byte(wr*64+m*16+fr,k*32+fq*8))
; #define LDB(dst,b,h) for(int n=0;n<2;++n)for(int k=0;k<2;++k) \
;     dst[n][k]=*reinterpret_cast<const bf16x8*>((char*)SB(b,h)+lds_byte(wc*32+n*16+fr,k*32+fq*8))
; #define MMA(ai,bj,At,Bt_) do{__builtin_amdgcn_s_setprio(1); \
;     for(int m=0;m<4;++m)for(int n=0;n<2;++n)for(int k=0;k<2;++k) \
;       acc[ai][bj][m][n]=__builtin_amdgcn_mfma_f32_16x16x32_bf16(Bt_[n][k],At[m][k],acc[ai][bj][m][n],0,0,0); \
;     __builtin_amdgcn_s_setprio(0);}while(0)
; #define WAIT_V(n) asm volatile("s_waitcnt vmcnt(" #n ")":::"memory")
; #define WAIT_L(n) asm volatile("s_waitcnt lgkmcnt(" #n ")":::"memory")
; #define BAR __builtin_amdgcn_s_barrier()
; template <int EPI>
; __device__ __forceinline__ void gemm_run(const GD& c, const bool has_next, const GD& nx, const Ctx& e, bf16* shm, float* rs, float* rs_nxt, float* racc_) {
;     ...
;     LDA(At,0,1); WAIT_V(4); BAR; WAIT_L(0); MMA(1,0,At,B0); MMA(1,1,At,B1); BAR; }
;   { LDB(B0,1,0); LDA(At,1,0); WAIT_V(2); BAR; WAIT_L(0); MMA(0,0,At,B0); BAR;
;     LDB(B1,1,1); WAIT_V(0); BAR; WAIT_L(0); MMA(0,1,At,B1); BAR;
	s_waitcnt lgkmcnt(0)
	s_setprio 1
	v_mfma_f32_16x16x32_bf16 v[20:23], v[130:133], v[210:213], v[20:23]
	v_mfma_f32_16x16x32_bf16 v[6:9], v[130:133], v[36:39], v[8:11]
	v_mfma_f32_16x16x32_bf16 v[166:169], v[130:133], v[58:61], v[166:169]
	v_mfma_f32_16x16x32_bf16 v[186:189], v[130:133], v[202:205], v[186:189]
	v_mfma_f32_16x16x32_bf16 v[130:133], v[134:137], v[226:229], v[20:23]
	v_mfma_f32_16x16x32_bf16 v[20:23], v[140:143], v[210:213], v[24:27]
	v_mfma_f32_16x16x32_bf16 v[6:9], v[134:137], v[40:43], v[6:9]
	v_mfma_f32_16x16x32_bf16 v[160:163], v[140:143], v[36:39], v[160:163]
	v_mfma_f32_16x16x32_bf16 v[166:169], v[134:137], v[198:201], v[166:169]
	v_mfma_f32_16x16x32_bf16 v[172:175], v[140:143], v[58:61], v[172:175]
	v_mfma_f32_16x16x32_bf16 v[186:189], v[134:137], v[206:209], v[186:189]
	v_mfma_f32_16x16x32_bf16 v[190:193], v[140:143], v[202:205], v[190:193]
	v_mfma_f32_16x16x32_bf16 v[134:137], v[144:147], v[226:229], v[20:23]
	v_mfma_f32_16x16x32_bf16 v[160:163], v[144:147], v[40:43], v[160:163]
	v_mfma_f32_16x16x32_bf16 v[172:175], v[144:147], v[198:201], v[172:175]
	v_mfma_f32_16x16x32_bf16 v[190:193], v[144:147], v[206:209], v[190:193]
	s_setprio 0
	s_setprio 1
	v_mfma_f32_16x16x32_bf16 v[2:5], v[106:109], v[36:39], v[2:5]
	v_mfma_f32_16x16x32_bf16 v[140:143], v[214:217], v[40:43], v[2:5]
	v_mfma_f32_16x16x32_bf16 v[2:5], v[218:221], v[36:39], v[28:31]
	v_mfma_f32_16x16x32_bf16 v[144:147], v[222:225], v[40:43], v[2:5]
	v_mfma_f32_16x16x32_bf16 v[2:5], v[106:109], v[58:61], v[32:35]
	v_mfma_f32_16x16x32_bf16 v[230:233], v[214:217], v[198:201], v[2:5]
	v_mfma_f32_16x16x32_bf16 v[2:5], v[218:221], v[58:61], v[64:67]
	v_mfma_f32_16x16x32_bf16 v[198:201], v[222:225], v[198:201], v[2:5]
	v_mfma_f32_16x16x32_bf16 v[2:5], v[106:109], v[202:205], v[118:121]
	v_mfma_f32_16x16x32_bf16 v[234:237], v[214:217], v[206:209], v[2:5]
	v_mfma_f32_16x16x32_bf16 v[2:5], v[218:221], v[202:205], v[122:125]
	v_mfma_f32_16x16x32_bf16 v[202:205], v[222:225], v[206:209], v[2:5]
	v_mfma_f32_16x16x32_bf16 v[2:5], v[106:109], v[210:213], v[110:113]
	v_mfma_f32_16x16x32_bf16 v[206:209], v[214:217], v[226:229], v[2:5]
	v_mfma_f32_16x16x32_bf16 v[2:5], v[218:221], v[210:213], v[114:117]
	v_mfma_f32_16x16x32_bf16 v[210:213], v[222:225], v[226:229], v[2:5]
	s_setprio 0
	s_barrier
	s_nop 4
	ds_read_b128 v[2:5], v182
	ds_read_b128 v[214:217], v182 offset:1024
	ds_read_b128 v[218:221], v182 offset:2048
	ds_read_b128 v[222:225], v182 offset:3072
	ds_read_b128 v[20:23], v19 offset:32768
	ds_read_b128 v[24:27], v19 offset:33792
	ds_read_b128 v[62:65], v18 offset:34816
	ds_read_b128 v[106:109], v18 offset:35840
	ds_read_b128 v[122:125], v18 offset:36864
	ds_read_b128 v[226:229], v18 offset:37888
	ds_read_b128 v[238:241], v18 offset:38912
	ds_read_b128 v[242:245], v18 offset:39936
	s_waitcnt vmcnt(2)
	s_barrier
	s_waitcnt lgkmcnt(0)
	s_setprio 1
	v_mfma_f32_16x16x32_bf16 v[10:13], v[2:5], v[20:23], v[12:15]
	v_mfma_f32_16x16x32_bf16 v[42:45], v[214:217], v[24:27], v[10:13]
	v_mfma_f32_16x16x32_bf16 v[10:13], v[218:221], v[20:23], v[68:71]
	v_mfma_f32_16x16x32_bf16 v[58:61], v[222:225], v[24:27], v[10:13]
	v_mfma_f32_16x16x32_bf16 v[10:13], v[2:5], v[62:65], v[72:75]
	v_mfma_f32_16x16x32_bf16 v[38:41], v[214:217], v[106:109], v[10:13]
	v_mfma_f32_16x16x32_bf16 v[10:13], v[218:221], v[62:65], v[76:79]
	v_mfma_f32_16x16x32_bf16 v[66:69], v[222:225], v[106:109], v[10:13]
	v_mfma_f32_16x16x32_bf16 v[10:13], v[2:5], v[122:125], v[80:83]
	v_mfma_f32_16x16x32_bf16 v[34:37], v[214:217], v[226:229], v[10:13]
	v_mfma_f32_16x16x32_bf16 v[10:13], v[218:221], v[122:125], v[84:87]
	v_mfma_f32_16x16x32_bf16 v[70:73], v[222:225], v[226:229], v[10:13]
	v_mfma_f32_16x16x32_bf16 v[10:13], v[2:5], v[238:241], v[98:101]
	v_mfma_f32_16x16x32_bf16 v[30:33], v[214:217], v[242:245], v[10:13]
	v_mfma_f32_16x16x32_bf16 v[10:13], v[218:221], v[238:241], v[102:105]
	v_mfma_f32_16x16x32_bf16 v[78:81], v[222:225], v[242:245], v[10:13]
	s_setprio 0
	s_barrier
; #define LDA(dst,b,h) for(int m=0;m<4;++m)for(int k=0;k<2;++k) \
;     dst[m][k]=*reinterpret_cast<const bf16x8*>((char*)SA(b,h)+lds_byte(wr*64+m*16+fr,k*32+fq*8))
; #define LDB(dst,b,h) for(int n=0;n<2;++n)for(int k=0;k<2;++k) \
;     dst[n][k]=*reinterpret_cast<const bf16x8*>((char*)SB(b,h)+lds_byte(wc*32+n*16+fr,k*32+fq*8))
; #define MMA(ai,bj,At,Bt_) do{__builtin_amdgcn_s_setprio(1); \
;     for(int m=0;m<4;++m)for(int n=0;n<2;++n)for(int k=0;k<2;++k) \
;       acc[ai][bj][m][n]=__builtin_amdgcn_mfma_f32_16x16x32_bf16(Bt_[n][k],At[m][k],acc[ai][bj][m][n],0,0,0); \
;     __builtin_amdgcn_s_setprio(0);}while(0)
; #define WAIT_V(n) asm volatile("s_waitcnt vmcnt(" #n ")":::"memory")
; #define WAIT_L(n) asm volatile("s_waitcnt lgkmcnt(" #n ")":::"memory")
; #define BAR __builtin_amdgcn_s_barrier()
; template <int EPI>
; __device__ __forceinline__ void gemm_run(const GD& c, const bool has_next, const GD& nx, const Ctx& e, bf16* shm, float* rs, float* rs_nxt, float* racc_) {
;     ...
;     LDB(B1,1,1); WAIT_V(0); BAR; WAIT_L(0); MMA(0,1,At,B1); BAR;
;     LDA(At,1,1); BAR; WAIT_L(0); MMA(1,0,At,B0); MMA(1,1,At,B1); BAR; }
;   if(wr==0)BAR;
	s_nop 4
	ds_read_b128 v[10:13], v183
	ds_read_b128 v[14:17], v183 offset:1024
	ds_read_b128 v[246:249], v183 offset:2048
	ds_read_b128 v[250:253], v183 offset:3072
	s_waitcnt vmcnt(0)
	s_barrier
	s_waitcnt lgkmcnt(0)
	s_setprio 1
	v_mfma_f32_16x16x32_bf16 v[74:77], v[10:13], v[20:23], v[126:129]
	v_mfma_f32_16x16x32_bf16 v[20:23], v[246:249], v[20:23], v[148:151]
	v_mfma_f32_16x16x32_bf16 v[82:85], v[250:253], v[24:27], v[20:23]
	v_mfma_f32_16x16x32_bf16 v[20:23], v[10:13], v[62:65], v[152:155]
	v_mfma_f32_16x16x32_bf16 v[114:117], v[14:17], v[106:109], v[20:23]
	v_mfma_f32_16x16x32_bf16 v[20:23], v[246:249], v[62:65], v[156:159]
	v_mfma_f32_16x16x32_bf16 v[110:113], v[14:17], v[24:27], v[74:77]
	v_mfma_f32_16x16x32_bf16 v[74:77], v[250:253], v[106:109], v[20:23]
	v_mfma_f32_16x16x32_bf16 v[20:23], v[10:13], v[122:125], v[46:49]
	v_mfma_f32_16x16x32_bf16 v[118:121], v[14:17], v[226:229], v[20:23]
	v_mfma_f32_16x16x32_bf16 v[20:23], v[246:249], v[122:125], v[50:53]
	v_mfma_f32_16x16x32_bf16 v[62:65], v[250:253], v[226:229], v[20:23]
	v_mfma_f32_16x16x32_bf16 v[20:23], v[10:13], v[238:241], v[54:57]
	v_mfma_f32_16x16x32_bf16 v[122:125], v[14:17], v[242:245], v[20:23]
	v_mfma_f32_16x16x32_bf16 v[20:23], v[246:249], v[238:241], v[194:197]
	v_mfma_f32_16x16x32_bf16 v[54:57], v[250:253], v[242:245], v[20:23]
	s_setprio 0
	s_barrier
	ds_read_b128 v[46:49], v19 offset:49152
	ds_read_b128 v[50:53], v19 offset:50176
	ds_read_b128 v[148:151], v18 offset:51200
	ds_read_b128 v[152:155], v18 offset:52224
	ds_read_b128 v[156:159], v18 offset:53248
	ds_read_b128 v[194:197], v18 offset:54272
	ds_read_b128 v[226:229], v18 offset:55296
	ds_read_b128 v[238:241], v18 offset:56320
	s_barrier
	s_waitcnt lgkmcnt(0)
	s_setprio 1
	v_mfma_f32_16x16x32_bf16 v[6:9], v[2:5], v[46:49], v[6:9]
	v_mfma_f32_16x16x32_bf16 v[26:29], v[214:217], v[50:53], v[6:9]
	v_mfma_f32_16x16x32_bf16 v[6:9], v[218:221], v[46:49], v[160:163]
	v_mfma_f32_16x16x32_bf16 v[98:101], v[222:225], v[50:53], v[6:9]
	v_mfma_f32_16x16x32_bf16 v[6:9], v[2:5], v[148:151], v[166:169]
	v_mfma_f32_16x16x32_bf16 v[22:25], v[214:217], v[152:155], v[6:9]
	v_mfma_f32_16x16x32_bf16 v[6:9], v[218:221], v[148:151], v[172:175]
	v_mfma_f32_16x16x32_bf16 v[102:105], v[222:225], v[152:155], v[6:9]
	v_mfma_f32_16x16x32_bf16 v[6:9], v[2:5], v[156:159], v[186:189]
	v_mfma_f32_16x16x32_bf16 v[18:21], v[214:217], v[194:197], v[6:9]
	v_mfma_f32_16x16x32_bf16 v[6:9], v[218:221], v[156:159], v[190:193]
	v_mfma_f32_16x16x32_bf16 v[106:109], v[222:225], v[194:197], v[6:9]
	v_mfma_f32_16x16x32_bf16 v[2:5], v[2:5], v[226:229], v[130:133]
	v_mfma_f32_16x16x32_bf16 v[6:9], v[218:221], v[226:229], v[134:137]
	v_mfma_f32_16x16x32_bf16 v[2:5], v[214:217], v[238:241], v[2:5]
	v_mfma_f32_16x16x32_bf16 v[6:9], v[222:225], v[238:241], v[6:9]
	s_setprio 0
	s_setprio 1
	v_mfma_f32_16x16x32_bf16 v[86:89], v[10:13], v[46:49], v[140:143]
	v_mfma_f32_16x16x32_bf16 v[46:49], v[246:249], v[46:49], v[144:147]
	v_mfma_f32_16x16x32_bf16 v[126:129], v[14:17], v[50:53], v[86:89]
	v_mfma_f32_16x16x32_bf16 v[86:89], v[250:253], v[50:53], v[46:49]
	v_mfma_f32_16x16x32_bf16 v[46:49], v[10:13], v[148:151], v[230:233]
	v_mfma_f32_16x16x32_bf16 v[130:133], v[14:17], v[152:155], v[46:49]
	v_mfma_f32_16x16x32_bf16 v[46:49], v[246:249], v[148:151], v[198:201]
	v_mfma_f32_16x16x32_bf16 v[50:53], v[250:253], v[152:155], v[46:49]
	v_mfma_f32_16x16x32_bf16 v[46:49], v[10:13], v[156:159], v[234:237]
	v_mfma_f32_16x16x32_bf16 v[10:13], v[10:13], v[226:229], v[206:209]
	v_mfma_f32_16x16x32_bf16 v[134:137], v[14:17], v[194:197], v[46:49]
	v_mfma_f32_16x16x32_bf16 v[46:49], v[246:249], v[156:159], v[202:205]
	v_mfma_f32_16x16x32_bf16 v[10:13], v[14:17], v[238:241], v[10:13]
	v_mfma_f32_16x16x32_bf16 v[14:17], v[246:249], v[226:229], v[210:213]
	v_mfma_f32_16x16x32_bf16 v[46:49], v[250:253], v[194:197], v[46:49]
	v_mfma_f32_16x16x32_bf16 v[14:17], v[250:253], v[238:241], v[14:17]
	s_setprio 0
	v_cmp_gt_u32_e32 vcc, s96, v92
	s_barrier
	s_and_saveexec_b64 s[2:3], vcc
	s_cbranch_execz .LBB0_747
	s_barrier

; #define STAGE_A(P,br,kt) STAGE_G(P,c.A,c.lda,br,(long)(kt)*c.kstr)
; #define STAGE_B(P,br,kt) STAGE_G(P,c.Bt,c.K,br,(long)(kt)*BK)
; #define LDA(dst,b,h) for(int m=0;m<4;++m)for(int k=0;k<2;++k) \
;     dst[m][k]=*reinterpret_cast<const bf16x8*>((char*)SA(b,h)+lds_byte(wr*64+m*16+fr,k*32+fq*8))
; #define LDB(dst,b,h) for(int n=0;n<2;++n)for(int k=0;k<2;++k) \
;     dst[n][k]=*reinterpret_cast<const bf16x8*>((char*)SB(b,h)+lds_byte(wc*32+n*16+fr,k*32+fq*8))
; #define MMA(ai,bj,At,Bt_) do{__builtin_amdgcn_s_setprio(1); \
;     for(int m=0;m<4;++m)for(int n=0;n<2;++n)for(int k=0;k<2;++k) \
;       acc[ai][bj][m][n]=__builtin_amdgcn_mfma_f32_16x16x32_bf16(Bt_[n][k],At[m][k],acc[ai][bj][m][n],0,0,0); \
;     __builtin_amdgcn_s_setprio(0);}while(0)
; #define WAIT_V(n) asm volatile("s_waitcnt vmcnt(" #n ")":::"memory")
; #define WAIT_L(n) asm volatile("s_waitcnt lgkmcnt(" #n ")":::"memory")
; #define BAR __builtin_amdgcn_s_barrier()
; #define SCHED __builtin_amdgcn_sched_barrier(0)
; template <int EPI>
; __device__ __forceinline__ void gemm_run(const GD& c, const bool has_next, const GD& nx, const Ctx& e, bf16* shm, float* rs, float* rs_nxt, float* racc_) {
;     ...
;   for(int t=0;t<nt-2;t+=2){
;     LDB(B0,0,0); SCHED; LDA(At,0,0); STAGE_A(SA(1,1),brow+HALF,t+1);
;     WAIT_L(8); BAR; WAIT_L(0); MMA(0,0,At,B0); BAR; SCHED;
;     LDB(B1,0,1); STAGE_B(SB(0,0),bcol,t+2);
;     BAR; WAIT_L(0); MMA(0,1,At,B1); BAR;
;     LDA(At,0,1); STAGE_A(SA(0,0),brow,t+2);
;     BAR; WAIT_L(0); MMA(1,0,At,B0); BAR; SCHED;
;     STAGE_B(SB(0,1),bcol+HALF,t+2);
;     WAIT_V(6); BAR; MMA(1,1,At,B1); BAR;
.LBB0_972:
	ds_read_b128 v[172:175], v159
	ds_read_b128 v[186:189], v159 offset:1024
	ds_read_b128 v[190:193], v159 offset:2048
	ds_read_b128 v[194:197], v159 offset:3072
	v_add_u32_e32 v169, 0xc000, v146
	v_lshl_add_u64 v[246:247], s[6:7], 0, v[136:137]
	v_readfirstlane_b32 s19, v169
	v_add_u32_e32 v170, 0xe000, v146
	v_lshl_add_u64 v[160:161], v[246:247], 0, s[22:23]
	s_mov_b32 m0, s19
	v_lshl_add_u64 v[248:249], s[6:7], 0, v[138:139]
	v_readfirstlane_b32 s19, v170
	ds_read_b128 v[198:201], v150
	ds_read_b128 v[202:205], v150 offset:1024
	ds_read_b128 v[206:209], v149
	ds_read_b128 v[210:213], v149 offset:1024
	ds_read_b128 v[214:217], v148
	ds_read_b128 v[218:221], v148 offset:1024
	ds_read_b128 v[222:225], v147
	ds_read_b128 v[226:229], v147 offset:1024
	global_load_lds_dwordx4 v[160:161], off
	v_lshl_add_u64 v[160:161], v[248:249], 0, s[22:23]
	s_mov_b32 m0, s19
	s_nop 0
	global_load_lds_dwordx4 v[160:161], off
	s_waitcnt lgkmcnt(8)
	s_barrier
	s_waitcnt lgkmcnt(0)
	s_setprio 1
	v_mfma_f32_16x16x32_bf16 v[126:129], v[172:175], v[198:201], v[126:129]
	v_mfma_f32_16x16x32_bf16 v[122:125], v[190:193], v[198:201], v[122:125]
	v_mfma_f32_16x16x32_bf16 v[118:121], v[172:175], v[206:209], v[118:121]
	v_mfma_f32_16x16x32_bf16 v[114:117], v[190:193], v[206:209], v[114:117]
	v_mfma_f32_16x16x32_bf16 v[110:113], v[172:175], v[214:217], v[110:113]
	v_mfma_f32_16x16x32_bf16 v[106:109], v[190:193], v[214:217], v[106:109]
	v_mfma_f32_16x16x32_bf16 v[102:105], v[172:175], v[222:225], v[102:105]
	v_mfma_f32_16x16x32_bf16 v[98:101], v[190:193], v[222:225], v[98:101]
	v_mfma_f32_16x16x32_bf16 v[126:129], v[186:189], v[202:205], v[126:129]
	v_mfma_f32_16x16x32_bf16 v[122:125], v[194:197], v[202:205], v[122:125]
	v_mfma_f32_16x16x32_bf16 v[118:121], v[186:189], v[210:213], v[118:121]
	v_mfma_f32_16x16x32_bf16 v[114:117], v[194:197], v[210:213], v[114:117]
	v_mfma_f32_16x16x32_bf16 v[110:113], v[186:189], v[218:221], v[110:113]
	v_mfma_f32_16x16x32_bf16 v[106:109], v[194:197], v[218:221], v[106:109]
	v_mfma_f32_16x16x32_bf16 v[102:105], v[186:189], v[226:229], v[102:105]
	v_mfma_f32_16x16x32_bf16 v[98:101], v[194:197], v[226:229], v[98:101]
	s_setprio 0
	s_barrier
	v_add_u32_e32 v160, s33, v151
	v_lshl_add_u64 v[250:251], s[6:7], 0, v[140:141]
	v_readfirstlane_b32 s19, v160
	v_add_u32_e32 v161, 0x2000, v160
	v_lshl_add_u64 v[162:163], v[250:251], 0, s[24:25]
	s_mov_b32 m0, s19
	v_lshl_add_u64 v[252:253], s[6:7], 0, v[142:143]
	v_readfirstlane_b32 s19, v161
	ds_read_b128 v[230:233], v157
	ds_read_b128 v[234:237], v157 offset:1024
	ds_read_b128 v[238:241], v157 offset:2048
	ds_read_b128 v[242:245], v157 offset:3072
	global_load_lds_dwordx4 v[162:163], off
	v_lshl_add_u64 v[162:163], v[252:253], 0, s[24:25]
	s_mov_b32 m0, s19
	s_nop 0
	global_load_lds_dwordx4 v[162:163], off
	s_barrier
	s_waitcnt lgkmcnt(0)
	s_setprio 1
	v_mfma_f32_16x16x32_bf16 v[94:97], v[230:233], v[198:201], v[94:97]
	v_mfma_f32_16x16x32_bf16 v[90:93], v[238:241], v[198:201], v[90:93]
	v_mfma_f32_16x16x32_bf16 v[86:89], v[230:233], v[206:209], v[86:89]
	v_mfma_f32_16x16x32_bf16 v[82:85], v[238:241], v[206:209], v[82:85]
	v_mfma_f32_16x16x32_bf16 v[78:81], v[230:233], v[214:217], v[78:81]
	v_mfma_f32_16x16x32_bf16 v[74:77], v[238:241], v[214:217], v[74:77]
	v_mfma_f32_16x16x32_bf16 v[70:73], v[230:233], v[222:225], v[70:73]
	v_mfma_f32_16x16x32_bf16 v[66:69], v[238:241], v[222:225], v[66:69]
	v_mfma_f32_16x16x32_bf16 v[94:97], v[234:237], v[202:205], v[94:97]
	v_mfma_f32_16x16x32_bf16 v[90:93], v[242:245], v[202:205], v[90:93]
	v_mfma_f32_16x16x32_bf16 v[86:89], v[234:237], v[210:213], v[86:89]
	v_mfma_f32_16x16x32_bf16 v[82:85], v[242:245], v[210:213], v[82:85]
	v_mfma_f32_16x16x32_bf16 v[78:81], v[234:237], v[218:221], v[78:81]
	v_mfma_f32_16x16x32_bf16 v[74:77], v[242:245], v[218:221], v[74:77]
	v_mfma_f32_16x16x32_bf16 v[70:73], v[234:237], v[226:229], v[70:73]
	v_mfma_f32_16x16x32_bf16 v[66:69], v[242:245], v[226:229], v[66:69]
	s_setprio 0
	v_readfirstlane_b32 s19, v146
	v_lshl_add_u64 v[162:163], v[246:247], 0, s[20:21]
	s_mov_b32 m0, s19
	s_barrier
	ds_read_b128 v[198:201], v150 offset:16384
	ds_read_b128 v[202:205], v150 offset:17408
	ds_read_b128 v[206:209], v149 offset:16384
	ds_read_b128 v[210:213], v149 offset:17408
	ds_read_b128 v[214:217], v148 offset:16384
	ds_read_b128 v[218:221], v148 offset:17408
	ds_read_b128 v[222:225], v147 offset:16384
	ds_read_b128 v[226:229], v147 offset:17408
	global_load_lds_dwordx4 v[162:163], off
	v_add_u32_e32 v162, 0x2000, v146
	v_lshl_add_u64 v[166:167], v[248:249], 0, s[20:21]
	v_readfirstlane_b32 s19, v162
	s_mov_b32 m0, s19
	s_nop 0
	global_load_lds_dwordx4 v[166:167], off
	s_barrier
	s_waitcnt lgkmcnt(0)
	s_setprio 1
	v_mfma_f32_16x16x32_bf16 v[62:65], v[172:175], v[198:201], v[62:65]
	v_mfma_f32_16x16x32_bf16 v[58:61], v[190:193], v[198:201], v[58:61]
	v_mfma_f32_16x16x32_bf16 v[54:57], v[172:175], v[206:209], v[54:57]
	v_mfma_f32_16x16x32_bf16 v[50:53], v[190:193], v[206:209], v[50:53]
	v_mfma_f32_16x16x32_bf16 v[46:49], v[172:175], v[214:217], v[46:49]
	v_mfma_f32_16x16x32_bf16 v[42:45], v[190:193], v[214:217], v[42:45]
	v_mfma_f32_16x16x32_bf16 v[38:41], v[172:175], v[222:225], v[38:41]
	v_mfma_f32_16x16x32_bf16 v[34:37], v[190:193], v[222:225], v[34:37]
	v_mfma_f32_16x16x32_bf16 v[62:65], v[186:189], v[202:205], v[62:65]
	v_mfma_f32_16x16x32_bf16 v[58:61], v[194:197], v[202:205], v[58:61]
	v_mfma_f32_16x16x32_bf16 v[54:57], v[186:189], v[210:213], v[54:57]
	v_mfma_f32_16x16x32_bf16 v[50:53], v[194:197], v[210:213], v[50:53]
	v_mfma_f32_16x16x32_bf16 v[46:49], v[186:189], v[218:221], v[46:49]
	v_mfma_f32_16x16x32_bf16 v[42:45], v[194:197], v[218:221], v[42:45]
	v_mfma_f32_16x16x32_bf16 v[38:41], v[186:189], v[226:229], v[38:41]
	v_mfma_f32_16x16x32_bf16 v[34:37], v[194:197], v[226:229], v[34:37]
	s_setprio 0
	s_barrier
; #define STAGE_A(P,br,kt) STAGE_G(P,c.A,c.lda,br,(long)(kt)*c.kstr)
; #define STAGE_B(P,br,kt) STAGE_G(P,c.Bt,c.K,br,(long)(kt)*BK)
; #define LDA(dst,b,h) for(int m=0;m<4;++m)for(int k=0;k<2;++k) \
;     dst[m][k]=*reinterpret_cast<const bf16x8*>((char*)SA(b,h)+lds_byte(wr*64+m*16+fr,k*32+fq*8))
; #define LDB(dst,b,h) for(int n=0;n<2;++n)for(int k=0;k<2;++k) \
;     dst[n][k]=*reinterpret_cast<const bf16x8*>((char*)SB(b,h)+lds_byte(wc*32+n*16+fr,k*32+fq*8))
; #define MMA(ai,bj,At,Bt_) do{__builtin_amdgcn_s_setprio(1); \
;     for(int m=0;m<4;++m)for(int n=0;n<2;++n)for(int k=0;k<2;++k) \
;       acc[ai][bj][m][n]=__builtin_amdgcn_mfma_f32_16x16x32_bf16(Bt_[n][k],At[m][k],acc[ai][bj][m][n],0,0,0); \
;     __builtin_amdgcn_s_setprio(0);}while(0)
; #define WAIT_V(n) asm volatile("s_waitcnt vmcnt(" #n ")":::"memory")
; #define WAIT_L(n) asm volatile("s_waitcnt lgkmcnt(" #n ")":::"memory")
; #define BAR __builtin_amdgcn_s_barrier()
; #define SCHED __builtin_amdgcn_sched_barrier(0)
; template <int EPI>
; __device__ __forceinline__ void gemm_run(const GD& c, const bool has_next, const GD& nx, const Ctx& e, bf16* shm, float* rs, float* rs_nxt, float* racc_) {
;     ...
;     WAIT_V(6); BAR; MMA(1,1,At,B1); BAR;
;     LDB(B0,1,0); SCHED; LDA(At,1,0); STAGE_A(SA(0,1),brow+HALF,t+2);
;     WAIT_L(8); BAR; WAIT_L(0); MMA(0,0,At,B0); BAR; SCHED;
;     LDB(B1,1,1); STAGE_B(SB(1,0),bcol,t+3);
;     BAR; WAIT_L(0); MMA(0,1,At,B1); BAR;
;     LDA(At,1,1); STAGE_A(SA(1,0),brow,t+3);
;     BAR; WAIT_L(0); MMA(1,0,At,B0); BAR; SCHED;
	v_add_u32_e32 v163, s86, v151
	v_lshl_add_u64 v[166:167], v[250:251], 0, s[26:27]
	v_readfirstlane_b32 s19, v163
	s_mov_b32 m0, s19
	v_lshl_add_u64 v[172:173], v[252:253], 0, s[26:27]
	global_load_lds_dwordx4 v[166:167], off
	v_add_u32_e32 v166, 0x2000, v163
	s_nop 0
	v_readfirstlane_b32 s19, v166
	s_mov_b32 m0, s19
	s_nop 0
	global_load_lds_dwordx4 v[172:173], off
	s_waitcnt vmcnt(6)
	s_barrier
	s_setprio 1
	v_mfma_f32_16x16x32_bf16 v[30:33], v[230:233], v[198:201], v[30:33]
	v_mfma_f32_16x16x32_bf16 v[26:29], v[238:241], v[198:201], v[26:29]
	v_mfma_f32_16x16x32_bf16 v[22:25], v[230:233], v[206:209], v[22:25]
	v_mfma_f32_16x16x32_bf16 v[18:21], v[238:241], v[206:209], v[18:21]
	v_mfma_f32_16x16x32_bf16 v[14:17], v[230:233], v[214:217], v[14:17]
	v_mfma_f32_16x16x32_bf16 v[10:13], v[238:241], v[214:217], v[10:13]
	v_mfma_f32_16x16x32_bf16 v[6:9], v[230:233], v[222:225], v[6:9]
	v_mfma_f32_16x16x32_bf16 v[2:5], v[238:241], v[222:225], v[2:5]
	v_mfma_f32_16x16x32_bf16 v[30:33], v[234:237], v[202:205], v[30:33]
	v_mfma_f32_16x16x32_bf16 v[26:29], v[242:245], v[202:205], v[26:29]
	v_mfma_f32_16x16x32_bf16 v[22:25], v[234:237], v[210:213], v[22:25]
	v_mfma_f32_16x16x32_bf16 v[18:21], v[242:245], v[210:213], v[18:21]
	v_mfma_f32_16x16x32_bf16 v[14:17], v[234:237], v[218:221], v[14:17]
	v_mfma_f32_16x16x32_bf16 v[10:13], v[242:245], v[218:221], v[10:13]
	v_mfma_f32_16x16x32_bf16 v[6:9], v[234:237], v[226:229], v[6:9]
	v_mfma_f32_16x16x32_bf16 v[2:5], v[242:245], v[226:229], v[2:5]
	s_setprio 0
	s_barrier
	ds_read_b128 v[172:175], v154
	ds_read_b128 v[186:189], v154 offset:1024
	ds_read_b128 v[190:193], v154 offset:2048
	ds_read_b128 v[194:197], v154 offset:3072
	v_add_u32_e32 v167, 0x4000, v146
	v_add_u32_e32 v168, 0x6000, v146
	v_readfirstlane_b32 s19, v167
	v_lshl_add_u64 v[230:231], v[246:247], 0, s[28:29]
	s_mov_b32 m0, s19
	v_readfirstlane_b32 s19, v168
	ds_read_b128 v[198:201], v150 offset:32768
	ds_read_b128 v[202:205], v150 offset:33792
	ds_read_b128 v[206:209], v149 offset:32768
	ds_read_b128 v[210:213], v149 offset:33792
	ds_read_b128 v[214:217], v148 offset:32768
	ds_read_b128 v[218:221], v148 offset:33792
	ds_read_b128 v[222:225], v147 offset:32768
	ds_read_b128 v[226:229], v147 offset:33792
	global_load_lds_dwordx4 v[230:231], off
	v_lshl_add_u64 v[230:231], v[248:249], 0, s[28:29]
	s_mov_b32 m0, s19
	s_nop 0
	global_load_lds_dwordx4 v[230:231], off
	s_waitcnt lgkmcnt(8)
	s_barrier
	s_waitcnt lgkmcnt(0)
	s_setprio 1
	v_mfma_f32_16x16x32_bf16 v[126:129], v[172:175], v[198:201], v[126:129]
	v_mfma_f32_16x16x32_bf16 v[122:125], v[190:193], v[198:201], v[122:125]
	v_mfma_f32_16x16x32_bf16 v[118:121], v[172:175], v[206:209], v[118:121]
	v_mfma_f32_16x16x32_bf16 v[114:117], v[190:193], v[206:209], v[114:117]
	v_mfma_f32_16x16x32_bf16 v[110:113], v[172:175], v[214:217], v[110:113]
	v_mfma_f32_16x16x32_bf16 v[106:109], v[190:193], v[214:217], v[106:109]
	v_mfma_f32_16x16x32_bf16 v[102:105], v[172:175], v[222:225], v[102:105]
	v_mfma_f32_16x16x32_bf16 v[98:101], v[190:193], v[222:225], v[98:101]
	v_mfma_f32_16x16x32_bf16 v[126:129], v[186:189], v[202:205], v[126:129]
	v_mfma_f32_16x16x32_bf16 v[122:125], v[194:197], v[202:205], v[122:125]
	v_mfma_f32_16x16x32_bf16 v[118:121], v[186:189], v[210:213], v[118:121]
	v_mfma_f32_16x16x32_bf16 v[114:117], v[194:197], v[210:213], v[114:117]
	v_mfma_f32_16x16x32_bf16 v[110:113], v[186:189], v[218:221], v[110:113]
	v_mfma_f32_16x16x32_bf16 v[106:109], v[194:197], v[218:221], v[106:109]
	v_mfma_f32_16x16x32_bf16 v[102:105], v[186:189], v[226:229], v[102:105]
	v_mfma_f32_16x16x32_bf16 v[98:101], v[194:197], v[226:229], v[98:101]
	s_setprio 0
	s_barrier
	v_readfirstlane_b32 s19, v153
	v_add_u32_e32 v171, 0x2000, v153
	v_lshl_add_u64 v[182:183], v[250:251], 0, s[42:43]
	s_mov_b32 m0, s19
	v_readfirstlane_b32 s19, v171
	ds_read_b128 v[230:233], v152
	ds_read_b128 v[234:237], v152 offset:1024
	ds_read_b128 v[238:241], v152 offset:2048
	ds_read_b128 v[242:245], v152 offset:3072
	global_load_lds_dwordx4 v[182:183], off
	v_lshl_add_u64 v[182:183], v[252:253], 0, s[42:43]
	s_mov_b32 m0, s19
	s_nop 0
	global_load_lds_dwordx4 v[182:183], off
	s_barrier
	s_waitcnt lgkmcnt(0)
	s_setprio 1
	v_mfma_f32_16x16x32_bf16 v[94:97], v[230:233], v[198:201], v[94:97]
	v_mfma_f32_16x16x32_bf16 v[90:93], v[238:241], v[198:201], v[90:93]
	v_mfma_f32_16x16x32_bf16 v[86:89], v[230:233], v[206:209], v[86:89]
	v_mfma_f32_16x16x32_bf16 v[82:85], v[238:241], v[206:209], v[82:85]
	v_mfma_f32_16x16x32_bf16 v[78:81], v[230:233], v[214:217], v[78:81]
	v_mfma_f32_16x16x32_bf16 v[74:77], v[238:241], v[214:217], v[74:77]
	v_mfma_f32_16x16x32_bf16 v[70:73], v[230:233], v[222:225], v[70:73]
	v_mfma_f32_16x16x32_bf16 v[66:69], v[238:241], v[222:225], v[66:69]
	v_mfma_f32_16x16x32_bf16 v[94:97], v[234:237], v[202:205], v[94:97]
	v_mfma_f32_16x16x32_bf16 v[90:93], v[242:245], v[202:205], v[90:93]
	v_mfma_f32_16x16x32_bf16 v[86:89], v[234:237], v[210:213], v[86:89]
	v_mfma_f32_16x16x32_bf16 v[82:85], v[242:245], v[210:213], v[82:85]
	v_mfma_f32_16x16x32_bf16 v[78:81], v[234:237], v[218:221], v[78:81]
	v_mfma_f32_16x16x32_bf16 v[74:77], v[242:245], v[218:221], v[74:77]
	v_mfma_f32_16x16x32_bf16 v[70:73], v[234:237], v[226:229], v[70:73]
	v_mfma_f32_16x16x32_bf16 v[66:69], v[242:245], v[226:229], v[66:69]
	s_setprio 0
	v_readfirstlane_b32 s19, v155
	v_lshl_add_u64 v[182:183], v[246:247], 0, s[44:45]
	s_mov_b32 m0, s19
	v_readfirstlane_b32 s19, v156
	s_barrier
; #define STAGE_A(P,br,kt) STAGE_G(P,c.A,c.lda,br,(long)(kt)*c.kstr)
; #define STAGE_B(P,br,kt) STAGE_G(P,c.Bt,c.K,br,(long)(kt)*BK)
; #define LDA(dst,b,h) for(int m=0;m<4;++m)for(int k=0;k<2;++k) \
;     dst[m][k]=*reinterpret_cast<const bf16x8*>((char*)SA(b,h)+lds_byte(wr*64+m*16+fr,k*32+fq*8))
; #define LDB(dst,b,h) for(int n=0;n<2;++n)for(int k=0;k<2;++k) \
;     dst[n][k]=*reinterpret_cast<const bf16x8*>((char*)SB(b,h)+lds_byte(wc*32+n*16+fr,k*32+fq*8))
; #define MMA(ai,bj,At,Bt_) do{__builtin_amdgcn_s_setprio(1); \
;     for(int m=0;m<4;++m)for(int n=0;n<2;++n)for(int k=0;k<2;++k) \
;       acc[ai][bj][m][n]=__builtin_amdgcn_mfma_f32_16x16x32_bf16(Bt_[n][k],At[m][k],acc[ai][bj][m][n],0,0,0); \
;     __builtin_amdgcn_s_setprio(0);}while(0)
; #define WAIT_V(n) asm volatile("s_waitcnt vmcnt(" #n ")":::"memory")
; #define WAIT_L(n) asm volatile("s_waitcnt lgkmcnt(" #n ")":::"memory")
; #define BAR __builtin_amdgcn_s_barrier()
; #define SCHED __builtin_amdgcn_sched_barrier(0)
; template <int EPI>
; __device__ __forceinline__ void gemm_run(const GD& c, const bool has_next, const GD& nx, const Ctx& e, bf16* shm, float* rs, float* rs_nxt, float* racc_) {
;     ...
;     BAR; WAIT_L(0); MMA(1,0,At,B0); BAR; SCHED;
;     STAGE_B(SB(1,1),bcol+HALF,t+3);
;     WAIT_V(6); BAR; MMA(1,1,At,B1); BAR;
;   }
;   { LDB(B0,0,0); LDA(At,0,0); STAGE_A(SA(1,1),brow+HALF,nt-1);
;     BAR; WAIT_L(0); MMA(0,0,At,B0); BAR;
	ds_read_b128 v[198:201], v150 offset:49152
	ds_read_b128 v[202:205], v150 offset:50176
	ds_read_b128 v[206:209], v149 offset:49152
	ds_read_b128 v[210:213], v149 offset:50176
	ds_read_b128 v[214:217], v148 offset:49152
	ds_read_b128 v[218:221], v148 offset:50176
	ds_read_b128 v[222:225], v147 offset:49152
	ds_read_b128 v[226:229], v147 offset:50176
	global_load_lds_dwordx4 v[182:183], off
	v_lshl_add_u64 v[182:183], v[248:249], 0, s[44:45]
	s_mov_b32 m0, s19
	s_nop 0
	global_load_lds_dwordx4 v[182:183], off
	s_barrier
	s_waitcnt lgkmcnt(0)
	s_setprio 1
	v_mfma_f32_16x16x32_bf16 v[62:65], v[172:175], v[198:201], v[62:65]
	v_mfma_f32_16x16x32_bf16 v[58:61], v[190:193], v[198:201], v[58:61]
	v_mfma_f32_16x16x32_bf16 v[54:57], v[172:175], v[206:209], v[54:57]
	v_mfma_f32_16x16x32_bf16 v[50:53], v[190:193], v[206:209], v[50:53]
	v_mfma_f32_16x16x32_bf16 v[46:49], v[172:175], v[214:217], v[46:49]
	v_mfma_f32_16x16x32_bf16 v[42:45], v[190:193], v[214:217], v[42:45]
	v_mfma_f32_16x16x32_bf16 v[38:41], v[172:175], v[222:225], v[38:41]
	v_mfma_f32_16x16x32_bf16 v[34:37], v[190:193], v[222:225], v[34:37]
	v_mfma_f32_16x16x32_bf16 v[62:65], v[186:189], v[202:205], v[62:65]
	v_mfma_f32_16x16x32_bf16 v[58:61], v[194:197], v[202:205], v[58:61]
	v_mfma_f32_16x16x32_bf16 v[54:57], v[186:189], v[210:213], v[54:57]
	v_mfma_f32_16x16x32_bf16 v[50:53], v[194:197], v[210:213], v[50:53]
	v_mfma_f32_16x16x32_bf16 v[46:49], v[186:189], v[218:221], v[46:49]
	v_mfma_f32_16x16x32_bf16 v[42:45], v[194:197], v[218:221], v[42:45]
	v_mfma_f32_16x16x32_bf16 v[38:41], v[186:189], v[226:229], v[38:41]
	v_mfma_f32_16x16x32_bf16 v[34:37], v[194:197], v[226:229], v[34:37]
	s_setprio 0
	s_barrier
	v_readfirstlane_b32 s19, v158
	v_add_u32_e32 v171, 0x2000, v158
	v_lshl_add_u64 v[172:173], v[250:251], 0, s[46:47]
	s_mov_b32 m0, s19
	v_readfirstlane_b32 s19, v171
	global_load_lds_dwordx4 v[172:173], off
	v_lshl_add_u64 v[172:173], v[252:253], 0, s[46:47]
	s_mov_b32 m0, s19
	s_nop 0
	global_load_lds_dwordx4 v[172:173], off
	s_waitcnt vmcnt(6)
	s_barrier
	s_setprio 1
	v_mfma_f32_16x16x32_bf16 v[30:33], v[230:233], v[198:201], v[30:33]
	v_mfma_f32_16x16x32_bf16 v[26:29], v[238:241], v[198:201], v[26:29]
	v_mfma_f32_16x16x32_bf16 v[22:25], v[230:233], v[206:209], v[22:25]
	v_mfma_f32_16x16x32_bf16 v[18:21], v[238:241], v[206:209], v[18:21]
	v_mfma_f32_16x16x32_bf16 v[14:17], v[230:233], v[214:217], v[14:17]
	v_mfma_f32_16x16x32_bf16 v[10:13], v[238:241], v[214:217], v[10:13]
	v_mfma_f32_16x16x32_bf16 v[6:9], v[230:233], v[222:225], v[6:9]
	v_mfma_f32_16x16x32_bf16 v[2:5], v[238:241], v[222:225], v[2:5]
	v_mfma_f32_16x16x32_bf16 v[30:33], v[234:237], v[202:205], v[30:33]
	v_mfma_f32_16x16x32_bf16 v[26:29], v[242:245], v[202:205], v[26:29]
	v_mfma_f32_16x16x32_bf16 v[22:25], v[234:237], v[210:213], v[22:25]
	v_mfma_f32_16x16x32_bf16 v[18:21], v[242:245], v[210:213], v[18:21]
	v_mfma_f32_16x16x32_bf16 v[14:17], v[234:237], v[218:221], v[14:17]
	v_mfma_f32_16x16x32_bf16 v[10:13], v[242:245], v[218:221], v[10:13]
	v_mfma_f32_16x16x32_bf16 v[6:9], v[234:237], v[226:229], v[6:9]
	v_mfma_f32_16x16x32_bf16 v[2:5], v[242:245], v[226:229], v[2:5]
	s_setprio 0
	s_add_i32 s18, s18, 2
	v_lshl_add_u64 v[136:137], v[136:137], 0, s[20:21]
	v_lshl_add_u64 v[138:139], v[138:139], 0, s[20:21]
	v_lshl_add_u64 v[140:141], v[140:141], 0, s[88:89]
	s_cmp_lt_u32 s18, 4
	v_lshl_add_u64 v[142:143], v[142:143], 0, s[88:89]
	s_barrier
	s_cbranch_scc1 .LBB0_972
	s_or_b32 s26, s12, 0x80
	s_ashr_i32 s27, s26, 31
	s_mul_i32 s18, s26, 0x600
	s_mul_hi_i32 s19, s26, 0x600
	s_add_u32 s18, s6, s18
	s_addc_u32 s19, s7, s19
	v_lshl_add_u64 v[132:133], s[18:19], 0, v[132:133]
	s_mov_b64 s[22:23], 0x540
	v_readfirstlane_b32 s20, v169
	v_lshl_add_u64 v[132:133], v[132:133], 0, s[22:23]
	s_mov_b32 m0, s20
	ds_read_b128 v[136:139], v159
	ds_read_b128 v[140:143], v159 offset:1024
	ds_read_b128 v[172:175], v159 offset:2048
	ds_read_b128 v[186:189], v159 offset:3072
	ds_read_b128 v[190:193], v150
	ds_read_b128 v[194:197], v150 offset:1024
	ds_read_b128 v[198:201], v149
	ds_read_b128 v[202:205], v149 offset:1024
	ds_read_b128 v[206:209], v148
	ds_read_b128 v[210:213], v148 offset:1024
	ds_read_b128 v[214:217], v147
	ds_read_b128 v[218:221], v147 offset:1024
	global_load_lds_dwordx4 v[132:133], off
	v_lshl_add_u64 v[132:133], s[18:19], 0, v[134:135]
	v_readfirstlane_b32 s18, v170
	v_lshl_add_u64 v[132:133], v[132:133], 0, s[22:23]
	s_mov_b32 m0, s18
	s_nop 0
	global_load_lds_dwordx4 v[132:133], off
	s_barrier
	s_waitcnt lgkmcnt(0)
	s_setprio 1
	v_mfma_f32_16x16x32_bf16 v[126:129], v[136:139], v[190:193], v[126:129]
	v_mfma_f32_16x16x32_bf16 v[122:125], v[172:175], v[190:193], v[122:125]
	v_mfma_f32_16x16x32_bf16 v[118:121], v[136:139], v[198:201], v[118:121]
	v_mfma_f32_16x16x32_bf16 v[114:117], v[172:175], v[198:201], v[114:117]
	v_mfma_f32_16x16x32_bf16 v[102:105], v[136:139], v[214:217], v[102:105]
	v_mfma_f32_16x16x32_bf16 v[98:101], v[172:175], v[214:217], v[98:101]
	v_mfma_f32_16x16x32_bf16 v[126:129], v[140:143], v[194:197], v[126:129]
	v_mfma_f32_16x16x32_bf16 v[122:125], v[186:189], v[194:197], v[122:125]
	v_mfma_f32_16x16x32_bf16 v[118:121], v[140:143], v[202:205], v[118:121]
	v_mfma_f32_16x16x32_bf16 v[114:117], v[186:189], v[202:205], v[114:117]
	v_mfma_f32_16x16x32_bf16 v[110:113], v[136:139], v[206:209], v[110:113]
	v_mfma_f32_16x16x32_bf16 v[106:109], v[172:175], v[206:209], v[106:109]
	v_mfma_f32_16x16x32_bf16 v[102:105], v[140:143], v[218:221], v[102:105]
	v_mfma_f32_16x16x32_bf16 v[98:101], v[186:189], v[218:221], v[98:101]
	v_mfma_f32_16x16x32_bf16 v[132:135], v[140:143], v[210:213], v[110:113]
	v_mfma_f32_16x16x32_bf16 v[222:225], v[186:189], v[210:213], v[106:109]
	s_setprio 0
	s_barrier
; #define LDA(dst,b,h) for(int m=0;m<4;++m)for(int k=0;k<2;++k) \
;     dst[m][k]=*reinterpret_cast<const bf16x8*>((char*)SA(b,h)+lds_byte(wr*64+m*16+fr,k*32+fq*8))
; #define LDB(dst,b,h) for(int n=0;n<2;++n)for(int k=0;k<2;++k) \
;     dst[n][k]=*reinterpret_cast<const bf16x8*>((char*)SB(b,h)+lds_byte(wc*32+n*16+fr,k*32+fq*8))
; #define MMA(ai,bj,At,Bt_) do{__builtin_amdgcn_s_setprio(1); \
;     for(int m=0;m<4;++m)for(int n=0;n<2;++n)for(int k=0;k<2;++k) \
;       acc[ai][bj][m][n]=__builtin_amdgcn_mfma_f32_16x16x32_bf16(Bt_[n][k],At[m][k],acc[ai][bj][m][n],0,0,0); \
;     __builtin_amdgcn_s_setprio(0);}while(0)
; #define WAIT_V(n) asm volatile("s_waitcnt vmcnt(" #n ")":::"memory")
; #define WAIT_L(n) asm volatile("s_waitcnt lgkmcnt(" #n ")":::"memory")
; #define BAR __builtin_amdgcn_s_barrier()
; template <int EPI>
; __device__ __forceinline__ void gemm_run(const GD& c, const bool has_next, const GD& nx, const Ctx& e, bf16* shm, float* rs, float* rs_nxt, float* racc_) {
;     ...
;     BAR; WAIT_L(0); MMA(0,0,At,B0); BAR;
;     LDB(B1,0,1); BAR; WAIT_L(0); MMA(0,1,At,B1); BAR;
;     LDA(At,0,1); WAIT_V(4); BAR; WAIT_L(0); MMA(1,0,At,B0); MMA(1,1,At,B1); BAR; }
;   { LDB(B0,1,0); LDA(At,1,0); WAIT_V(2); BAR; WAIT_L(0); MMA(0,0,At,B0); BAR;
	s_nop 1
	ds_read_b128 v[106:109], v157
	ds_read_b128 v[110:113], v157 offset:1024
	ds_read_b128 v[226:229], v157 offset:2048
	ds_read_b128 v[156:159], v157 offset:3072
	s_barrier
	s_waitcnt lgkmcnt(0)
	s_setprio 1
	v_mfma_f32_16x16x32_bf16 v[86:89], v[106:109], v[198:201], v[86:89]
	v_mfma_f32_16x16x32_bf16 v[82:85], v[226:229], v[198:201], v[82:85]
	v_mfma_f32_16x16x32_bf16 v[70:73], v[106:109], v[214:217], v[70:73]
	v_mfma_f32_16x16x32_bf16 v[66:69], v[226:229], v[214:217], v[66:69]
	v_mfma_f32_16x16x32_bf16 v[94:97], v[106:109], v[190:193], v[94:97]
	v_mfma_f32_16x16x32_bf16 v[90:93], v[226:229], v[190:193], v[90:93]
	v_mfma_f32_16x16x32_bf16 v[86:89], v[110:113], v[202:205], v[86:89]
	v_mfma_f32_16x16x32_bf16 v[82:85], v[156:159], v[202:205], v[82:85]
	v_mfma_f32_16x16x32_bf16 v[78:81], v[106:109], v[206:209], v[78:81]
	v_mfma_f32_16x16x32_bf16 v[74:77], v[226:229], v[206:209], v[74:77]
	v_mfma_f32_16x16x32_bf16 v[70:73], v[110:113], v[218:221], v[70:73]
	v_mfma_f32_16x16x32_bf16 v[66:69], v[156:159], v[218:221], v[66:69]
	v_mfma_f32_16x16x32_bf16 v[230:233], v[110:113], v[194:197], v[94:97]
	v_mfma_f32_16x16x32_bf16 v[190:193], v[156:159], v[194:197], v[90:93]
	v_mfma_f32_16x16x32_bf16 v[194:197], v[110:113], v[210:213], v[78:81]
	v_mfma_f32_16x16x32_bf16 v[198:201], v[156:159], v[210:213], v[74:77]
	s_setprio 0
	s_barrier
	s_nop 0
	ds_read_b128 v[74:77], v150 offset:16384
	ds_read_b128 v[78:81], v150 offset:17408
	ds_read_b128 v[90:93], v149 offset:16384
	ds_read_b128 v[94:97], v149 offset:17408
	ds_read_b128 v[202:205], v148 offset:16384
	ds_read_b128 v[206:209], v148 offset:17408
	ds_read_b128 v[210:213], v147 offset:16384
	ds_read_b128 v[214:217], v147 offset:17408
	s_waitcnt vmcnt(4)
	s_barrier
	s_waitcnt lgkmcnt(0)
	s_setprio 1
	v_mfma_f32_16x16x32_bf16 v[62:65], v[136:139], v[74:77], v[62:65]
	v_mfma_f32_16x16x32_bf16 v[58:61], v[172:175], v[74:77], v[58:61]
	v_mfma_f32_16x16x32_bf16 v[54:57], v[136:139], v[90:93], v[54:57]
	v_mfma_f32_16x16x32_bf16 v[50:53], v[172:175], v[90:93], v[50:53]
	v_mfma_f32_16x16x32_bf16 v[38:41], v[136:139], v[210:213], v[38:41]
	v_mfma_f32_16x16x32_bf16 v[34:37], v[172:175], v[210:213], v[34:37]
	v_mfma_f32_16x16x32_bf16 v[62:65], v[140:143], v[78:81], v[62:65]
	v_mfma_f32_16x16x32_bf16 v[58:61], v[186:189], v[78:81], v[58:61]
	v_mfma_f32_16x16x32_bf16 v[54:57], v[140:143], v[94:97], v[54:57]
	v_mfma_f32_16x16x32_bf16 v[50:53], v[186:189], v[94:97], v[50:53]
	v_mfma_f32_16x16x32_bf16 v[46:49], v[136:139], v[202:205], v[46:49]
	v_mfma_f32_16x16x32_bf16 v[42:45], v[172:175], v[202:205], v[42:45]
	v_mfma_f32_16x16x32_bf16 v[38:41], v[140:143], v[214:217], v[38:41]
	v_mfma_f32_16x16x32_bf16 v[34:37], v[186:189], v[214:217], v[34:37]
	v_mfma_f32_16x16x32_bf16 v[218:221], v[140:143], v[206:209], v[46:49]
	v_mfma_f32_16x16x32_bf16 v[234:237], v[186:189], v[206:209], v[42:45]
	s_setprio 0
	s_setprio 1
	v_mfma_f32_16x16x32_bf16 v[22:25], v[106:109], v[90:93], v[22:25]
	v_mfma_f32_16x16x32_bf16 v[18:21], v[226:229], v[90:93], v[18:21]
	v_mfma_f32_16x16x32_bf16 v[6:9], v[106:109], v[210:213], v[6:9]
	v_mfma_f32_16x16x32_bf16 v[2:5], v[226:229], v[210:213], v[2:5]
	v_mfma_f32_16x16x32_bf16 v[30:33], v[106:109], v[74:77], v[30:33]
	v_mfma_f32_16x16x32_bf16 v[26:29], v[226:229], v[74:77], v[26:29]
	v_mfma_f32_16x16x32_bf16 v[22:25], v[110:113], v[94:97], v[22:25]
	v_mfma_f32_16x16x32_bf16 v[18:21], v[156:159], v[94:97], v[18:21]
	v_mfma_f32_16x16x32_bf16 v[14:17], v[106:109], v[202:205], v[14:17]
	v_mfma_f32_16x16x32_bf16 v[10:13], v[226:229], v[202:205], v[10:13]
	v_mfma_f32_16x16x32_bf16 v[6:9], v[110:113], v[214:217], v[6:9]
	v_mfma_f32_16x16x32_bf16 v[2:5], v[156:159], v[214:217], v[2:5]
	v_mfma_f32_16x16x32_bf16 v[136:139], v[110:113], v[78:81], v[30:33]
	v_mfma_f32_16x16x32_bf16 v[140:143], v[156:159], v[78:81], v[26:29]
	v_mfma_f32_16x16x32_bf16 v[170:173], v[110:113], v[206:209], v[14:17]
	v_mfma_f32_16x16x32_bf16 v[186:189], v[156:159], v[206:209], v[10:13]
	s_setprio 0
	s_barrier
	s_nop 0
	ds_read_b128 v[10:13], v154
	ds_read_b128 v[14:17], v154 offset:1024
	ds_read_b128 v[156:159], v154 offset:2048
	ds_read_b128 v[202:205], v154 offset:3072
	ds_read_b128 v[26:29], v150 offset:32768
	ds_read_b128 v[30:33], v150 offset:33792
	ds_read_b128 v[42:45], v149 offset:32768
	ds_read_b128 v[46:49], v149 offset:33792
	ds_read_b128 v[206:209], v148 offset:32768
	ds_read_b128 v[210:213], v148 offset:33792
	ds_read_b128 v[214:217], v147 offset:32768
	ds_read_b128 v[226:229], v147 offset:33792
	s_waitcnt vmcnt(2)
	s_barrier
; #define LDA(dst,b,h) for(int m=0;m<4;++m)for(int k=0;k<2;++k) \
;     dst[m][k]=*reinterpret_cast<const bf16x8*>((char*)SA(b,h)+lds_byte(wr*64+m*16+fr,k*32+fq*8))
; #define LDB(dst,b,h) for(int n=0;n<2;++n)for(int k=0;k<2;++k) \
;     dst[n][k]=*reinterpret_cast<const bf16x8*>((char*)SB(b,h)+lds_byte(wc*32+n*16+fr,k*32+fq*8))
; #define MMA(ai,bj,At,Bt_) do{__builtin_amdgcn_s_setprio(1); \
;     for(int m=0;m<4;++m)for(int n=0;n<2;++n)for(int k=0;k<2;++k) \
;       acc[ai][bj][m][n]=__builtin_amdgcn_mfma_f32_16x16x32_bf16(Bt_[n][k],At[m][k],acc[ai][bj][m][n],0,0,0); \
;     __builtin_amdgcn_s_setprio(0);}while(0)
; #define WAIT_V(n) asm volatile("s_waitcnt vmcnt(" #n ")":::"memory")
; #define WAIT_L(n) asm volatile("s_waitcnt lgkmcnt(" #n ")":::"memory")
; #define BAR __builtin_amdgcn_s_barrier()
; template <int EPI>
; __device__ __forceinline__ void gemm_run(const GD& c, const bool has_next, const GD& nx, const Ctx& e, bf16* shm, float* rs, float* rs_nxt, float* racc_) {
;     ...
;   { LDB(B0,1,0); LDA(At,1,0); WAIT_V(2); BAR; WAIT_L(0); MMA(0,0,At,B0); BAR;
;     LDB(B1,1,1); WAIT_V(0); BAR; WAIT_L(0); MMA(0,1,At,B1); BAR;
;     LDA(At,1,1); BAR; WAIT_L(0); MMA(1,0,At,B0); MMA(1,1,At,B1); BAR; }
;   if(wr==0)BAR;
	s_waitcnt lgkmcnt(0)
	s_setprio 1
	v_mfma_f32_16x16x32_bf16 v[74:77], v[10:13], v[26:29], v[126:129]
	v_mfma_f32_16x16x32_bf16 v[126:129], v[14:17], v[30:33], v[74:77]
	v_mfma_f32_16x16x32_bf16 v[74:77], v[156:159], v[26:29], v[122:125]
	v_mfma_f32_16x16x32_bf16 v[122:125], v[202:205], v[30:33], v[74:77]
	v_mfma_f32_16x16x32_bf16 v[74:77], v[10:13], v[42:45], v[118:121]
	v_mfma_f32_16x16x32_bf16 v[110:113], v[14:17], v[46:49], v[74:77]
	v_mfma_f32_16x16x32_bf16 v[74:77], v[156:159], v[42:45], v[114:117]
	v_mfma_f32_16x16x32_bf16 v[106:109], v[202:205], v[46:49], v[74:77]
	v_mfma_f32_16x16x32_bf16 v[74:77], v[10:13], v[206:209], v[132:135]
	v_mfma_f32_16x16x32_bf16 v[94:97], v[14:17], v[210:213], v[74:77]
	v_mfma_f32_16x16x32_bf16 v[74:77], v[156:159], v[206:209], v[222:225]
	v_mfma_f32_16x16x32_bf16 v[90:93], v[202:205], v[210:213], v[74:77]
	v_mfma_f32_16x16x32_bf16 v[74:77], v[10:13], v[214:217], v[102:105]
	v_mfma_f32_16x16x32_bf16 v[78:81], v[14:17], v[226:229], v[74:77]
	v_mfma_f32_16x16x32_bf16 v[74:77], v[156:159], v[214:217], v[98:101]
	v_mfma_f32_16x16x32_bf16 v[74:77], v[202:205], v[226:229], v[74:77]
	s_setprio 0
	s_barrier
	ds_read_b128 v[132:135], v152
	ds_read_b128 v[222:225], v152 offset:1024
	ds_read_b128 v[238:241], v152 offset:2048
	ds_read_b128 v[152:155], v152 offset:3072
	s_waitcnt vmcnt(0)
	s_barrier
	s_waitcnt lgkmcnt(0)
	s_setprio 1
	v_mfma_f32_16x16x32_bf16 v[98:101], v[132:135], v[26:29], v[230:233]
	v_mfma_f32_16x16x32_bf16 v[26:29], v[238:241], v[26:29], v[190:193]
	v_mfma_f32_16x16x32_bf16 v[114:117], v[152:155], v[30:33], v[26:29]
	v_mfma_f32_16x16x32_bf16 v[26:29], v[132:135], v[42:45], v[86:89]
	v_mfma_f32_16x16x32_bf16 v[102:105], v[222:225], v[46:49], v[26:29]
	v_mfma_f32_16x16x32_bf16 v[26:29], v[238:241], v[42:45], v[82:85]
	v_mfma_f32_16x16x32_bf16 v[118:121], v[222:225], v[30:33], v[98:101]
	v_mfma_f32_16x16x32_bf16 v[98:101], v[152:155], v[46:49], v[26:29]
	v_mfma_f32_16x16x32_bf16 v[26:29], v[132:135], v[206:209], v[194:197]
	v_mfma_f32_16x16x32_bf16 v[86:89], v[222:225], v[210:213], v[26:29]
	v_mfma_f32_16x16x32_bf16 v[26:29], v[238:241], v[206:209], v[198:201]
	v_mfma_f32_16x16x32_bf16 v[82:85], v[152:155], v[210:213], v[26:29]
	v_mfma_f32_16x16x32_bf16 v[26:29], v[132:135], v[214:217], v[70:73]
	v_mfma_f32_16x16x32_bf16 v[70:73], v[222:225], v[226:229], v[26:29]
	v_mfma_f32_16x16x32_bf16 v[26:29], v[238:241], v[214:217], v[66:69]
	v_mfma_f32_16x16x32_bf16 v[66:69], v[152:155], v[226:229], v[26:29]
	s_setprio 0
	s_barrier
	ds_read_b128 v[190:193], v150 offset:49152
	ds_read_b128 v[194:197], v150 offset:50176
	ds_read_b128 v[198:201], v149 offset:49152
	ds_read_b128 v[206:209], v149 offset:50176
	ds_read_b128 v[210:213], v148 offset:49152
	ds_read_b128 v[148:151], v148 offset:50176
	ds_read_b128 v[214:217], v147 offset:49152
	ds_read_b128 v[226:229], v147 offset:50176
	s_barrier
	s_waitcnt lgkmcnt(0)
	s_setprio 1
	v_mfma_f32_16x16x32_bf16 v[26:29], v[10:13], v[190:193], v[62:65]
	v_mfma_f32_16x16x32_bf16 v[62:65], v[14:17], v[194:197], v[26:29]
	v_mfma_f32_16x16x32_bf16 v[26:29], v[156:159], v[190:193], v[58:61]
	v_mfma_f32_16x16x32_bf16 v[58:61], v[202:205], v[194:197], v[26:29]
	v_mfma_f32_16x16x32_bf16 v[26:29], v[10:13], v[198:201], v[54:57]
	v_mfma_f32_16x16x32_bf16 v[46:49], v[14:17], v[206:209], v[26:29]
	v_mfma_f32_16x16x32_bf16 v[26:29], v[156:159], v[198:201], v[50:53]
	v_mfma_f32_16x16x32_bf16 v[42:45], v[202:205], v[206:209], v[26:29]
	v_mfma_f32_16x16x32_bf16 v[26:29], v[10:13], v[210:213], v[218:221]
	v_mfma_f32_16x16x32_bf16 v[10:13], v[10:13], v[214:217], v[38:41]
	v_mfma_f32_16x16x32_bf16 v[30:33], v[14:17], v[148:151], v[26:29]
	v_mfma_f32_16x16x32_bf16 v[26:29], v[156:159], v[210:213], v[234:237]
	v_mfma_f32_16x16x32_bf16 v[14:17], v[14:17], v[226:229], v[10:13]
	v_mfma_f32_16x16x32_bf16 v[10:13], v[156:159], v[214:217], v[34:37]
	v_mfma_f32_16x16x32_bf16 v[26:29], v[202:205], v[148:151], v[26:29]
	v_mfma_f32_16x16x32_bf16 v[10:13], v[202:205], v[226:229], v[10:13]
	s_setprio 0
	s_setprio 1
	v_mfma_f32_16x16x32_bf16 v[34:37], v[132:135], v[190:193], v[136:139]
	v_mfma_f32_16x16x32_bf16 v[54:57], v[222:225], v[194:197], v[34:37]
	v_mfma_f32_16x16x32_bf16 v[34:37], v[238:241], v[190:193], v[140:143]
	v_mfma_f32_16x16x32_bf16 v[18:21], v[238:241], v[198:201], v[18:21]
	v_mfma_f32_16x16x32_bf16 v[50:53], v[152:155], v[194:197], v[34:37]
	v_mfma_f32_16x16x32_bf16 v[22:25], v[132:135], v[198:201], v[22:25]
	v_mfma_f32_16x16x32_bf16 v[34:37], v[152:155], v[206:209], v[18:21]
	v_mfma_f32_16x16x32_bf16 v[18:21], v[132:135], v[210:213], v[170:173]
	v_mfma_f32_16x16x32_bf16 v[38:41], v[222:225], v[206:209], v[22:25]
	v_mfma_f32_16x16x32_bf16 v[22:25], v[222:225], v[148:151], v[18:21]
	v_mfma_f32_16x16x32_bf16 v[18:21], v[238:241], v[210:213], v[186:189]
	v_mfma_f32_16x16x32_bf16 v[6:9], v[132:135], v[214:217], v[6:9]
	v_mfma_f32_16x16x32_bf16 v[2:5], v[238:241], v[214:217], v[2:5]
	v_mfma_f32_16x16x32_bf16 v[18:21], v[152:155], v[148:151], v[18:21]
	v_mfma_f32_16x16x32_bf16 v[6:9], v[222:225], v[226:229], v[6:9]
	v_mfma_f32_16x16x32_bf16 v[2:5], v[152:155], v[226:229], v[2:5]
	s_setprio 0
	v_cmp_gt_u32_e32 vcc, s96, v145
	s_barrier
	s_and_saveexec_b64 s[18:19], vcc
	s_cbranch_execz .LBB0_975
	s_barrier

; #define STAGE_A(P,br,kt) STAGE_G(P,c.A,c.lda,br,(long)(kt)*c.kstr)
; #define STAGE_B(P,br,kt) STAGE_G(P,c.Bt,c.K,br,(long)(kt)*BK)
; #define LDA(dst,b,h) for(int m=0;m<4;++m)for(int k=0;k<2;++k) \
;     dst[m][k]=*reinterpret_cast<const bf16x8*>((char*)SA(b,h)+lds_byte(wr*64+m*16+fr,k*32+fq*8))
; #define LDB(dst,b,h) for(int n=0;n<2;++n)for(int k=0;k<2;++k) \
;     dst[n][k]=*reinterpret_cast<const bf16x8*>((char*)SB(b,h)+lds_byte(wc*32+n*16+fr,k*32+fq*8))
; #define MMA(ai,bj,At,Bt_) do{__builtin_amdgcn_s_setprio(1); \
;     for(int m=0;m<4;++m)for(int n=0;n<2;++n)for(int k=0;k<2;++k) \
;       acc[ai][bj][m][n]=__builtin_amdgcn_mfma_f32_16x16x32_bf16(Bt_[n][k],At[m][k],acc[ai][bj][m][n],0,0,0); \
;     __builtin_amdgcn_s_setprio(0);}while(0)
; #define WAIT_V(n) asm volatile("s_waitcnt vmcnt(" #n ")":::"memory")
; #define WAIT_L(n) asm volatile("s_waitcnt lgkmcnt(" #n ")":::"memory")
; #define BAR __builtin_amdgcn_s_barrier()
; #define SCHED __builtin_amdgcn_sched_barrier(0)
; template <int EPI>
; __device__ __forceinline__ void gemm_run(const GD& c, const bool has_next, const GD& nx, const Ctx& e, bf16* shm, float* rs, float* rs_nxt, float* racc_) {
;     ...
;   for(int t=0;t<nt-2;t+=2){
;     LDB(B0,0,0); SCHED; LDA(At,0,0); STAGE_A(SA(1,1),brow+HALF,t+1);
;     WAIT_L(8); BAR; WAIT_L(0); MMA(0,0,At,B0); BAR; SCHED;
;     LDB(B1,0,1); STAGE_B(SB(0,0),bcol,t+2);
;     BAR; WAIT_L(0); MMA(0,1,At,B1); BAR;
;     LDA(At,0,1); STAGE_A(SA(0,0),brow,t+2);
;     BAR; WAIT_L(0); MMA(1,0,At,B0); BAR; SCHED;
;     STAGE_B(SB(0,1),bcol+HALF,t+2);
;     WAIT_V(6); BAR; MMA(1,1,At,B1); BAR;
.LBB0_980:
	ds_read_b128 v[172:175], v159
	ds_read_b128 v[186:189], v159 offset:1024
	ds_read_b128 v[190:193], v159 offset:2048
	ds_read_b128 v[194:197], v159 offset:3072
	v_add_u32_e32 v169, 0xc000, v146
	v_lshl_add_u64 v[182:183], s[6:7], 0, v[132:133]
	v_readfirstlane_b32 s3, v169
	v_add_u32_e32 v170, 0xe000, v146
	v_lshl_add_u64 v[160:161], v[182:183], 0, s[18:19]
	s_mov_b32 m0, s3
	v_lshl_add_u64 v[246:247], s[6:7], 0, v[134:135]
	v_readfirstlane_b32 s3, v170
	ds_read_b128 v[198:201], v150
	ds_read_b128 v[202:205], v150 offset:1024
	ds_read_b128 v[206:209], v149
	ds_read_b128 v[210:213], v149 offset:1024
	ds_read_b128 v[214:217], v148
	ds_read_b128 v[218:221], v148 offset:1024
	ds_read_b128 v[222:225], v147
	ds_read_b128 v[226:229], v147 offset:1024
	global_load_lds_dwordx4 v[160:161], off
	v_lshl_add_u64 v[160:161], v[246:247], 0, s[18:19]
	s_mov_b32 m0, s3
	s_nop 0
	global_load_lds_dwordx4 v[160:161], off
	s_waitcnt lgkmcnt(8)
	s_barrier
	s_waitcnt lgkmcnt(0)
	s_setprio 1
	v_mfma_f32_16x16x32_bf16 v[126:129], v[172:175], v[198:201], v[126:129]
	v_mfma_f32_16x16x32_bf16 v[122:125], v[190:193], v[198:201], v[122:125]
	v_mfma_f32_16x16x32_bf16 v[118:121], v[172:175], v[206:209], v[118:121]
	v_mfma_f32_16x16x32_bf16 v[114:117], v[190:193], v[206:209], v[114:117]
	v_mfma_f32_16x16x32_bf16 v[110:113], v[172:175], v[214:217], v[110:113]
	v_mfma_f32_16x16x32_bf16 v[106:109], v[190:193], v[214:217], v[106:109]
	v_mfma_f32_16x16x32_bf16 v[102:105], v[172:175], v[222:225], v[102:105]
	v_mfma_f32_16x16x32_bf16 v[98:101], v[190:193], v[222:225], v[98:101]
	v_mfma_f32_16x16x32_bf16 v[126:129], v[186:189], v[202:205], v[126:129]
	v_mfma_f32_16x16x32_bf16 v[122:125], v[194:197], v[202:205], v[122:125]
	v_mfma_f32_16x16x32_bf16 v[118:121], v[186:189], v[210:213], v[118:121]
	v_mfma_f32_16x16x32_bf16 v[114:117], v[194:197], v[210:213], v[114:117]
	v_mfma_f32_16x16x32_bf16 v[110:113], v[186:189], v[218:221], v[110:113]
	v_mfma_f32_16x16x32_bf16 v[106:109], v[194:197], v[218:221], v[106:109]
	v_mfma_f32_16x16x32_bf16 v[102:105], v[186:189], v[226:229], v[102:105]
	v_mfma_f32_16x16x32_bf16 v[98:101], v[194:197], v[226:229], v[98:101]
	s_setprio 0
	s_barrier
	v_add_u32_e32 v160, s33, v152
	v_lshl_add_u64 v[248:249], s[6:7], 0, v[136:137]
	v_readfirstlane_b32 s3, v160
	v_add_u32_e32 v161, 0x2000, v160
	v_lshl_add_u64 v[162:163], v[248:249], 0, s[20:21]
	s_mov_b32 m0, s3
	v_lshl_add_u64 v[250:251], s[6:7], 0, v[138:139]
	v_readfirstlane_b32 s3, v161
	ds_read_b128 v[230:233], v157
	ds_read_b128 v[234:237], v157 offset:1024
	ds_read_b128 v[238:241], v157 offset:2048
	ds_read_b128 v[242:245], v157 offset:3072
	global_load_lds_dwordx4 v[162:163], off
	v_lshl_add_u64 v[162:163], v[250:251], 0, s[20:21]
	s_mov_b32 m0, s3
	s_nop 0
	global_load_lds_dwordx4 v[162:163], off
	s_barrier
	s_waitcnt lgkmcnt(0)
	s_setprio 1
	v_mfma_f32_16x16x32_bf16 v[94:97], v[230:233], v[198:201], v[94:97]
	v_mfma_f32_16x16x32_bf16 v[90:93], v[238:241], v[198:201], v[90:93]
	v_mfma_f32_16x16x32_bf16 v[86:89], v[230:233], v[206:209], v[86:89]
	v_mfma_f32_16x16x32_bf16 v[82:85], v[238:241], v[206:209], v[82:85]
	v_mfma_f32_16x16x32_bf16 v[78:81], v[230:233], v[214:217], v[78:81]
	v_mfma_f32_16x16x32_bf16 v[74:77], v[238:241], v[214:217], v[74:77]
	v_mfma_f32_16x16x32_bf16 v[70:73], v[230:233], v[222:225], v[70:73]
	v_mfma_f32_16x16x32_bf16 v[66:69], v[238:241], v[222:225], v[66:69]
	v_mfma_f32_16x16x32_bf16 v[94:97], v[234:237], v[202:205], v[94:97]
	v_mfma_f32_16x16x32_bf16 v[90:93], v[242:245], v[202:205], v[90:93]
	v_mfma_f32_16x16x32_bf16 v[86:89], v[234:237], v[210:213], v[86:89]
	v_mfma_f32_16x16x32_bf16 v[82:85], v[242:245], v[210:213], v[82:85]
	v_mfma_f32_16x16x32_bf16 v[78:81], v[234:237], v[218:221], v[78:81]
	v_mfma_f32_16x16x32_bf16 v[74:77], v[242:245], v[218:221], v[74:77]
	v_mfma_f32_16x16x32_bf16 v[70:73], v[234:237], v[226:229], v[70:73]
	v_mfma_f32_16x16x32_bf16 v[66:69], v[242:245], v[226:229], v[66:69]
	s_setprio 0
	v_readfirstlane_b32 s3, v146
	v_lshl_add_u64 v[162:163], v[182:183], 0, s[22:23]
	s_mov_b32 m0, s3
	s_barrier
	ds_read_b128 v[198:201], v150 offset:16384
	ds_read_b128 v[202:205], v150 offset:17408
	ds_read_b128 v[206:209], v149 offset:16384
	ds_read_b128 v[210:213], v149 offset:17408
	ds_read_b128 v[214:217], v148 offset:16384
	ds_read_b128 v[218:221], v148 offset:17408
	ds_read_b128 v[222:225], v147 offset:16384
	ds_read_b128 v[226:229], v147 offset:17408
	global_load_lds_dwordx4 v[162:163], off
	v_add_u32_e32 v162, 0x2000, v146
	v_lshl_add_u64 v[166:167], v[246:247], 0, s[22:23]
	v_readfirstlane_b32 s3, v162
	s_mov_b32 m0, s3
	s_nop 0
	global_load_lds_dwordx4 v[166:167], off
	s_barrier
	s_waitcnt lgkmcnt(0)
	s_setprio 1
	v_mfma_f32_16x16x32_bf16 v[62:65], v[172:175], v[198:201], v[62:65]
	v_mfma_f32_16x16x32_bf16 v[58:61], v[190:193], v[198:201], v[58:61]
	v_mfma_f32_16x16x32_bf16 v[54:57], v[172:175], v[206:209], v[54:57]
	v_mfma_f32_16x16x32_bf16 v[50:53], v[190:193], v[206:209], v[50:53]
	v_mfma_f32_16x16x32_bf16 v[46:49], v[172:175], v[214:217], v[46:49]
	v_mfma_f32_16x16x32_bf16 v[42:45], v[190:193], v[214:217], v[42:45]
	v_mfma_f32_16x16x32_bf16 v[38:41], v[172:175], v[222:225], v[38:41]
	v_mfma_f32_16x16x32_bf16 v[34:37], v[190:193], v[222:225], v[34:37]
	v_mfma_f32_16x16x32_bf16 v[62:65], v[186:189], v[202:205], v[62:65]
	v_mfma_f32_16x16x32_bf16 v[58:61], v[194:197], v[202:205], v[58:61]
	v_mfma_f32_16x16x32_bf16 v[54:57], v[186:189], v[210:213], v[54:57]
	v_mfma_f32_16x16x32_bf16 v[50:53], v[194:197], v[210:213], v[50:53]
	v_mfma_f32_16x16x32_bf16 v[46:49], v[186:189], v[218:221], v[46:49]
	v_mfma_f32_16x16x32_bf16 v[42:45], v[194:197], v[218:221], v[42:45]
	v_mfma_f32_16x16x32_bf16 v[38:41], v[186:189], v[226:229], v[38:41]
	v_mfma_f32_16x16x32_bf16 v[34:37], v[194:197], v[226:229], v[34:37]
	s_setprio 0
	s_barrier
; #define STAGE_A(P,br,kt) STAGE_G(P,c.A,c.lda,br,(long)(kt)*c.kstr)
; #define STAGE_B(P,br,kt) STAGE_G(P,c.Bt,c.K,br,(long)(kt)*BK)
; #define LDA(dst,b,h) for(int m=0;m<4;++m)for(int k=0;k<2;++k) \
;     dst[m][k]=*reinterpret_cast<const bf16x8*>((char*)SA(b,h)+lds_byte(wr*64+m*16+fr,k*32+fq*8))
; #define LDB(dst,b,h) for(int n=0;n<2;++n)for(int k=0;k<2;++k) \
;     dst[n][k]=*reinterpret_cast<const bf16x8*>((char*)SB(b,h)+lds_byte(wc*32+n*16+fr,k*32+fq*8))
; #define MMA(ai,bj,At,Bt_) do{__builtin_amdgcn_s_setprio(1); \
;     for(int m=0;m<4;++m)for(int n=0;n<2;++n)for(int k=0;k<2;++k) \
;       acc[ai][bj][m][n]=__builtin_amdgcn_mfma_f32_16x16x32_bf16(Bt_[n][k],At[m][k],acc[ai][bj][m][n],0,0,0); \
;     __builtin_amdgcn_s_setprio(0);}while(0)
; #define WAIT_V(n) asm volatile("s_waitcnt vmcnt(" #n ")":::"memory")
; #define WAIT_L(n) asm volatile("s_waitcnt lgkmcnt(" #n ")":::"memory")
; #define BAR __builtin_amdgcn_s_barrier()
; #define SCHED __builtin_amdgcn_sched_barrier(0)
; template <int EPI>
; __device__ __forceinline__ void gemm_run(const GD& c, const bool has_next, const GD& nx, const Ctx& e, bf16* shm, float* rs, float* rs_nxt, float* racc_) {
;     ...
;     WAIT_V(6); BAR; MMA(1,1,At,B1); BAR;
;     LDB(B0,1,0); SCHED; LDA(At,1,0); STAGE_A(SA(0,1),brow+HALF,t+2);
;     WAIT_L(8); BAR; WAIT_L(0); MMA(0,0,At,B0); BAR; SCHED;
;     LDB(B1,1,1); STAGE_B(SB(1,0),bcol,t+3);
;     BAR; WAIT_L(0); MMA(0,1,At,B1); BAR;
;     LDA(At,1,1); STAGE_A(SA(1,0),brow,t+3);
;     BAR; WAIT_L(0); MMA(1,0,At,B0); BAR; SCHED;
	v_add_u32_e32 v163, s86, v152
	v_lshl_add_u64 v[166:167], v[248:249], 0, s[24:25]
	v_readfirstlane_b32 s3, v163
	s_mov_b32 m0, s3
	v_lshl_add_u64 v[172:173], v[250:251], 0, s[24:25]
	global_load_lds_dwordx4 v[166:167], off
	v_add_u32_e32 v166, 0x2000, v163
	s_nop 0
	v_readfirstlane_b32 s3, v166
	s_mov_b32 m0, s3
	s_nop 0
	global_load_lds_dwordx4 v[172:173], off
	s_waitcnt vmcnt(6)
	s_barrier
	s_setprio 1
	v_mfma_f32_16x16x32_bf16 v[30:33], v[230:233], v[198:201], v[30:33]
	v_mfma_f32_16x16x32_bf16 v[26:29], v[238:241], v[198:201], v[26:29]
	v_mfma_f32_16x16x32_bf16 v[22:25], v[230:233], v[206:209], v[22:25]
	v_mfma_f32_16x16x32_bf16 v[18:21], v[238:241], v[206:209], v[18:21]
	v_mfma_f32_16x16x32_bf16 v[14:17], v[230:233], v[214:217], v[14:17]
	v_mfma_f32_16x16x32_bf16 v[10:13], v[238:241], v[214:217], v[10:13]
	v_mfma_f32_16x16x32_bf16 v[6:9], v[230:233], v[222:225], v[6:9]
	v_mfma_f32_16x16x32_bf16 v[2:5], v[238:241], v[222:225], v[2:5]
	v_mfma_f32_16x16x32_bf16 v[30:33], v[234:237], v[202:205], v[30:33]
	v_mfma_f32_16x16x32_bf16 v[26:29], v[242:245], v[202:205], v[26:29]
	v_mfma_f32_16x16x32_bf16 v[22:25], v[234:237], v[210:213], v[22:25]
	v_mfma_f32_16x16x32_bf16 v[18:21], v[242:245], v[210:213], v[18:21]
	v_mfma_f32_16x16x32_bf16 v[14:17], v[234:237], v[218:221], v[14:17]
	v_mfma_f32_16x16x32_bf16 v[10:13], v[242:245], v[218:221], v[10:13]
	v_mfma_f32_16x16x32_bf16 v[6:9], v[234:237], v[226:229], v[6:9]
	v_mfma_f32_16x16x32_bf16 v[2:5], v[242:245], v[226:229], v[2:5]
	s_setprio 0
	s_barrier
	ds_read_b128 v[172:175], v153
	ds_read_b128 v[186:189], v153 offset:1024
	ds_read_b128 v[190:193], v153 offset:2048
	ds_read_b128 v[194:197], v153 offset:3072
	v_add_u32_e32 v167, 0x4000, v146
	v_add_u32_e32 v168, 0x6000, v146
	v_readfirstlane_b32 s3, v167
	v_lshl_add_u64 v[230:231], v[182:183], 0, s[28:29]
	s_mov_b32 m0, s3
	v_readfirstlane_b32 s3, v168
	ds_read_b128 v[198:201], v150 offset:32768
	ds_read_b128 v[202:205], v150 offset:33792
	ds_read_b128 v[206:209], v149 offset:32768
	ds_read_b128 v[210:213], v149 offset:33792
	ds_read_b128 v[214:217], v148 offset:32768
	ds_read_b128 v[218:221], v148 offset:33792
	ds_read_b128 v[222:225], v147 offset:32768
	ds_read_b128 v[226:229], v147 offset:33792
	global_load_lds_dwordx4 v[230:231], off
	v_lshl_add_u64 v[230:231], v[246:247], 0, s[28:29]
	s_mov_b32 m0, s3
	s_nop 0
	global_load_lds_dwordx4 v[230:231], off
	s_waitcnt lgkmcnt(8)
	s_barrier
	s_waitcnt lgkmcnt(0)
	s_setprio 1
	v_mfma_f32_16x16x32_bf16 v[126:129], v[172:175], v[198:201], v[126:129]
	v_mfma_f32_16x16x32_bf16 v[122:125], v[190:193], v[198:201], v[122:125]
	v_mfma_f32_16x16x32_bf16 v[118:121], v[172:175], v[206:209], v[118:121]
	v_mfma_f32_16x16x32_bf16 v[114:117], v[190:193], v[206:209], v[114:117]
	v_mfma_f32_16x16x32_bf16 v[110:113], v[172:175], v[214:217], v[110:113]
	v_mfma_f32_16x16x32_bf16 v[106:109], v[190:193], v[214:217], v[106:109]
	v_mfma_f32_16x16x32_bf16 v[102:105], v[172:175], v[222:225], v[102:105]
	v_mfma_f32_16x16x32_bf16 v[98:101], v[190:193], v[222:225], v[98:101]
	v_mfma_f32_16x16x32_bf16 v[126:129], v[186:189], v[202:205], v[126:129]
	v_mfma_f32_16x16x32_bf16 v[122:125], v[194:197], v[202:205], v[122:125]
	v_mfma_f32_16x16x32_bf16 v[118:121], v[186:189], v[210:213], v[118:121]
	v_mfma_f32_16x16x32_bf16 v[114:117], v[194:197], v[210:213], v[114:117]
	v_mfma_f32_16x16x32_bf16 v[110:113], v[186:189], v[218:221], v[110:113]
	v_mfma_f32_16x16x32_bf16 v[106:109], v[194:197], v[218:221], v[106:109]
	v_mfma_f32_16x16x32_bf16 v[102:105], v[186:189], v[226:229], v[102:105]
	v_mfma_f32_16x16x32_bf16 v[98:101], v[194:197], v[226:229], v[98:101]
	s_setprio 0
	s_barrier
	v_readfirstlane_b32 s3, v154
	v_add_u32_e32 v171, 0x2000, v154
	v_lshl_add_u64 v[252:253], v[248:249], 0, s[44:45]
	s_mov_b32 m0, s3
	v_readfirstlane_b32 s3, v171
	ds_read_b128 v[230:233], v151
	ds_read_b128 v[234:237], v151 offset:1024
	ds_read_b128 v[238:241], v151 offset:2048
	ds_read_b128 v[242:245], v151 offset:3072
	global_load_lds_dwordx4 v[252:253], off
	v_lshl_add_u64 v[252:253], v[250:251], 0, s[44:45]
	s_mov_b32 m0, s3
	s_nop 0
	global_load_lds_dwordx4 v[252:253], off
	s_barrier
	s_waitcnt lgkmcnt(0)
	s_setprio 1
	v_mfma_f32_16x16x32_bf16 v[94:97], v[230:233], v[198:201], v[94:97]
	v_mfma_f32_16x16x32_bf16 v[90:93], v[238:241], v[198:201], v[90:93]
	v_mfma_f32_16x16x32_bf16 v[86:89], v[230:233], v[206:209], v[86:89]
	v_mfma_f32_16x16x32_bf16 v[82:85], v[238:241], v[206:209], v[82:85]
	v_mfma_f32_16x16x32_bf16 v[78:81], v[230:233], v[214:217], v[78:81]
	v_mfma_f32_16x16x32_bf16 v[74:77], v[238:241], v[214:217], v[74:77]
	v_mfma_f32_16x16x32_bf16 v[70:73], v[230:233], v[222:225], v[70:73]
	v_mfma_f32_16x16x32_bf16 v[66:69], v[238:241], v[222:225], v[66:69]
	v_mfma_f32_16x16x32_bf16 v[94:97], v[234:237], v[202:205], v[94:97]
	v_mfma_f32_16x16x32_bf16 v[90:93], v[242:245], v[202:205], v[90:93]
	v_mfma_f32_16x16x32_bf16 v[86:89], v[234:237], v[210:213], v[86:89]
	v_mfma_f32_16x16x32_bf16 v[82:85], v[242:245], v[210:213], v[82:85]
	v_mfma_f32_16x16x32_bf16 v[78:81], v[234:237], v[218:221], v[78:81]
	v_mfma_f32_16x16x32_bf16 v[74:77], v[242:245], v[218:221], v[74:77]
	v_mfma_f32_16x16x32_bf16 v[70:73], v[234:237], v[226:229], v[70:73]
	v_mfma_f32_16x16x32_bf16 v[66:69], v[242:245], v[226:229], v[66:69]
	s_setprio 0
	v_readfirstlane_b32 s3, v155
	v_lshl_add_u64 v[182:183], v[182:183], 0, s[46:47]
	s_mov_b32 m0, s3
	v_readfirstlane_b32 s3, v156
	s_barrier
; #define STAGE_A(P,br,kt) STAGE_G(P,c.A,c.lda,br,(long)(kt)*c.kstr)
; #define STAGE_B(P,br,kt) STAGE_G(P,c.Bt,c.K,br,(long)(kt)*BK)
; #define LDA(dst,b,h) for(int m=0;m<4;++m)for(int k=0;k<2;++k) \
;     dst[m][k]=*reinterpret_cast<const bf16x8*>((char*)SA(b,h)+lds_byte(wr*64+m*16+fr,k*32+fq*8))
; #define LDB(dst,b,h) for(int n=0;n<2;++n)for(int k=0;k<2;++k) \
;     dst[n][k]=*reinterpret_cast<const bf16x8*>((char*)SB(b,h)+lds_byte(wc*32+n*16+fr,k*32+fq*8))
; #define MMA(ai,bj,At,Bt_) do{__builtin_amdgcn_s_setprio(1); \
;     for(int m=0;m<4;++m)for(int n=0;n<2;++n)for(int k=0;k<2;++k) \
;       acc[ai][bj][m][n]=__builtin_amdgcn_mfma_f32_16x16x32_bf16(Bt_[n][k],At[m][k],acc[ai][bj][m][n],0,0,0); \
;     __builtin_amdgcn_s_setprio(0);}while(0)
; #define WAIT_V(n) asm volatile("s_waitcnt vmcnt(" #n ")":::"memory")
; #define WAIT_L(n) asm volatile("s_waitcnt lgkmcnt(" #n ")":::"memory")
; #define BAR __builtin_amdgcn_s_barrier()
; #define SCHED __builtin_amdgcn_sched_barrier(0)
; template <int EPI>
; __device__ __forceinline__ void gemm_run(const GD& c, const bool has_next, const GD& nx, const Ctx& e, bf16* shm, float* rs, float* rs_nxt, float* racc_) {
;     ...
;     BAR; WAIT_L(0); MMA(1,0,At,B0); BAR; SCHED;
;     STAGE_B(SB(1,1),bcol+HALF,t+3);
;     WAIT_V(6); BAR; MMA(1,1,At,B1); BAR;
;   }
;   { LDB(B0,0,0); LDA(At,0,0); STAGE_A(SA(1,1),brow+HALF,nt-1);
;     BAR; WAIT_L(0); MMA(0,0,At,B0); BAR;
	ds_read_b128 v[198:201], v150 offset:49152
	ds_read_b128 v[202:205], v150 offset:50176
	ds_read_b128 v[206:209], v149 offset:49152
	ds_read_b128 v[210:213], v149 offset:50176
	ds_read_b128 v[214:217], v148 offset:49152
	ds_read_b128 v[218:221], v148 offset:50176
	ds_read_b128 v[222:225], v147 offset:49152
	ds_read_b128 v[226:229], v147 offset:50176
	global_load_lds_dwordx4 v[182:183], off
	v_lshl_add_u64 v[182:183], v[246:247], 0, s[46:47]
	s_mov_b32 m0, s3
	s_nop 0
	global_load_lds_dwordx4 v[182:183], off
	s_barrier
	s_waitcnt lgkmcnt(0)
	s_setprio 1
	v_mfma_f32_16x16x32_bf16 v[62:65], v[172:175], v[198:201], v[62:65]
	v_mfma_f32_16x16x32_bf16 v[58:61], v[190:193], v[198:201], v[58:61]
	v_mfma_f32_16x16x32_bf16 v[54:57], v[172:175], v[206:209], v[54:57]
	v_mfma_f32_16x16x32_bf16 v[50:53], v[190:193], v[206:209], v[50:53]
	v_mfma_f32_16x16x32_bf16 v[46:49], v[172:175], v[214:217], v[46:49]
	v_mfma_f32_16x16x32_bf16 v[42:45], v[190:193], v[214:217], v[42:45]
	v_mfma_f32_16x16x32_bf16 v[38:41], v[172:175], v[222:225], v[38:41]
	v_mfma_f32_16x16x32_bf16 v[34:37], v[190:193], v[222:225], v[34:37]
	v_mfma_f32_16x16x32_bf16 v[62:65], v[186:189], v[202:205], v[62:65]
	v_mfma_f32_16x16x32_bf16 v[58:61], v[194:197], v[202:205], v[58:61]
	v_mfma_f32_16x16x32_bf16 v[54:57], v[186:189], v[210:213], v[54:57]
	v_mfma_f32_16x16x32_bf16 v[50:53], v[194:197], v[210:213], v[50:53]
	v_mfma_f32_16x16x32_bf16 v[46:49], v[186:189], v[218:221], v[46:49]
	v_mfma_f32_16x16x32_bf16 v[42:45], v[194:197], v[218:221], v[42:45]
	v_mfma_f32_16x16x32_bf16 v[38:41], v[186:189], v[226:229], v[38:41]
	v_mfma_f32_16x16x32_bf16 v[34:37], v[194:197], v[226:229], v[34:37]
	s_setprio 0
	s_barrier
	v_readfirstlane_b32 s3, v158
	v_add_u32_e32 v171, 0x2000, v158
	v_lshl_add_u64 v[172:173], v[248:249], 0, s[48:49]
	s_mov_b32 m0, s3
	v_readfirstlane_b32 s3, v171
	global_load_lds_dwordx4 v[172:173], off
	v_lshl_add_u64 v[172:173], v[250:251], 0, s[48:49]
	s_mov_b32 m0, s3
	s_nop 0
	global_load_lds_dwordx4 v[172:173], off
	s_waitcnt vmcnt(6)
	s_barrier
	s_setprio 1
	v_mfma_f32_16x16x32_bf16 v[30:33], v[230:233], v[198:201], v[30:33]
	v_mfma_f32_16x16x32_bf16 v[26:29], v[238:241], v[198:201], v[26:29]
	v_mfma_f32_16x16x32_bf16 v[22:25], v[230:233], v[206:209], v[22:25]
	v_mfma_f32_16x16x32_bf16 v[18:21], v[238:241], v[206:209], v[18:21]
	v_mfma_f32_16x16x32_bf16 v[14:17], v[230:233], v[214:217], v[14:17]
	v_mfma_f32_16x16x32_bf16 v[10:13], v[238:241], v[214:217], v[10:13]
	v_mfma_f32_16x16x32_bf16 v[6:9], v[230:233], v[222:225], v[6:9]
	v_mfma_f32_16x16x32_bf16 v[2:5], v[238:241], v[222:225], v[2:5]
	v_mfma_f32_16x16x32_bf16 v[30:33], v[234:237], v[202:205], v[30:33]
	v_mfma_f32_16x16x32_bf16 v[26:29], v[242:245], v[202:205], v[26:29]
	v_mfma_f32_16x16x32_bf16 v[22:25], v[234:237], v[210:213], v[22:25]
	v_mfma_f32_16x16x32_bf16 v[18:21], v[242:245], v[210:213], v[18:21]
	v_mfma_f32_16x16x32_bf16 v[14:17], v[234:237], v[218:221], v[14:17]
	v_mfma_f32_16x16x32_bf16 v[10:13], v[242:245], v[218:221], v[10:13]
	v_mfma_f32_16x16x32_bf16 v[6:9], v[234:237], v[226:229], v[6:9]
	v_mfma_f32_16x16x32_bf16 v[2:5], v[242:245], v[226:229], v[2:5]
	s_setprio 0
	s_add_i32 s2, s2, 2
	v_lshl_add_u64 v[132:133], v[132:133], 0, s[88:89]
	v_lshl_add_u64 v[134:135], v[134:135], 0, s[88:89]
	v_lshl_add_u64 v[136:137], v[136:137], 0, s[88:89]
	s_cmp_lt_u32 s2, 4
	v_lshl_add_u64 v[138:139], v[138:139], 0, s[88:89]
	s_barrier
	s_cbranch_scc1 .LBB0_980
	v_lshl_add_u64 v[154:155], s[16:17], 0, v[0:1]
	s_mov_b64 s[18:19], 0x380
	v_readfirstlane_b32 s2, v169
	v_lshl_add_u64 v[154:155], v[154:155], 0, s[18:19]
	s_mov_b32 m0, s2
	ds_read_b128 v[132:135], v159
	ds_read_b128 v[136:139], v159 offset:1024
	ds_read_b128 v[172:175], v159 offset:2048
	ds_read_b128 v[186:189], v159 offset:3072
	ds_read_b128 v[190:193], v150
	ds_read_b128 v[194:197], v150 offset:1024
	ds_read_b128 v[198:201], v149
	ds_read_b128 v[202:205], v149 offset:1024
	ds_read_b128 v[206:209], v148
	ds_read_b128 v[210:213], v148 offset:1024
	ds_read_b128 v[214:217], v147
	ds_read_b128 v[218:221], v147 offset:1024
	global_load_lds_dwordx4 v[154:155], off
	v_lshl_add_u64 v[154:155], s[16:17], 0, v[130:131]
	v_readfirstlane_b32 s2, v170
	v_lshl_add_u64 v[154:155], v[154:155], 0, s[18:19]
	s_mov_b32 m0, s2
	s_nop 0
	global_load_lds_dwordx4 v[154:155], off
	s_barrier
	s_waitcnt lgkmcnt(0)
	s_setprio 1
	v_mfma_f32_16x16x32_bf16 v[126:129], v[132:135], v[190:193], v[126:129]
	v_mfma_f32_16x16x32_bf16 v[122:125], v[172:175], v[190:193], v[122:125]
	v_mfma_f32_16x16x32_bf16 v[118:121], v[132:135], v[198:201], v[118:121]
	v_mfma_f32_16x16x32_bf16 v[114:117], v[172:175], v[198:201], v[114:117]
	v_mfma_f32_16x16x32_bf16 v[102:105], v[132:135], v[214:217], v[102:105]
	v_mfma_f32_16x16x32_bf16 v[98:101], v[172:175], v[214:217], v[98:101]
	v_mfma_f32_16x16x32_bf16 v[126:129], v[136:139], v[194:197], v[126:129]
	v_mfma_f32_16x16x32_bf16 v[122:125], v[186:189], v[194:197], v[122:125]
	v_mfma_f32_16x16x32_bf16 v[118:121], v[136:139], v[202:205], v[118:121]
	v_mfma_f32_16x16x32_bf16 v[114:117], v[186:189], v[202:205], v[114:117]
	v_mfma_f32_16x16x32_bf16 v[110:113], v[132:135], v[206:209], v[110:113]
	v_mfma_f32_16x16x32_bf16 v[106:109], v[172:175], v[206:209], v[106:109]
	v_mfma_f32_16x16x32_bf16 v[102:105], v[136:139], v[218:221], v[102:105]
	v_mfma_f32_16x16x32_bf16 v[98:101], v[186:189], v[218:221], v[98:101]
	v_mfma_f32_16x16x32_bf16 v[222:225], v[136:139], v[210:213], v[110:113]
	v_mfma_f32_16x16x32_bf16 v[226:229], v[186:189], v[210:213], v[106:109]
	s_setprio 0
	s_barrier
; #define LDA(dst,b,h) for(int m=0;m<4;++m)for(int k=0;k<2;++k) \
;     dst[m][k]=*reinterpret_cast<const bf16x8*>((char*)SA(b,h)+lds_byte(wr*64+m*16+fr,k*32+fq*8))
; #define LDB(dst,b,h) for(int n=0;n<2;++n)for(int k=0;k<2;++k) \
;     dst[n][k]=*reinterpret_cast<const bf16x8*>((char*)SB(b,h)+lds_byte(wc*32+n*16+fr,k*32+fq*8))
; #define MMA(ai,bj,At,Bt_) do{__builtin_amdgcn_s_setprio(1); \
;     for(int m=0;m<4;++m)for(int n=0;n<2;++n)for(int k=0;k<2;++k) \
;       acc[ai][bj][m][n]=__builtin_amdgcn_mfma_f32_16x16x32_bf16(Bt_[n][k],At[m][k],acc[ai][bj][m][n],0,0,0); \
;     __builtin_amdgcn_s_setprio(0);}while(0)
; #define WAIT_V(n) asm volatile("s_waitcnt vmcnt(" #n ")":::"memory")
; #define WAIT_L(n) asm volatile("s_waitcnt lgkmcnt(" #n ")":::"memory")
; #define BAR __builtin_amdgcn_s_barrier()
; template <int EPI>
; __device__ __forceinline__ void gemm_run(const GD& c, const bool has_next, const GD& nx, const Ctx& e, bf16* shm, float* rs, float* rs_nxt, float* racc_) {
;     ...
;     BAR; WAIT_L(0); MMA(0,0,At,B0); BAR;
;     LDB(B1,0,1); BAR; WAIT_L(0); MMA(0,1,At,B1); BAR;
;     LDA(At,0,1); WAIT_V(4); BAR; WAIT_L(0); MMA(1,0,At,B0); MMA(1,1,At,B1); BAR; }
;   { LDB(B0,1,0); LDA(At,1,0); WAIT_V(2); BAR; WAIT_L(0); MMA(0,0,At,B0); BAR;
	s_nop 1
	ds_read_b128 v[106:109], v157
	ds_read_b128 v[110:113], v157 offset:1024
	ds_read_b128 v[230:233], v157 offset:2048
	ds_read_b128 v[154:157], v157 offset:3072
	s_barrier
	s_waitcnt lgkmcnt(0)
	s_setprio 1
	v_mfma_f32_16x16x32_bf16 v[86:89], v[106:109], v[198:201], v[86:89]
	v_mfma_f32_16x16x32_bf16 v[82:85], v[230:233], v[198:201], v[82:85]
	v_mfma_f32_16x16x32_bf16 v[70:73], v[106:109], v[214:217], v[70:73]
	v_mfma_f32_16x16x32_bf16 v[66:69], v[230:233], v[214:217], v[66:69]
	v_mfma_f32_16x16x32_bf16 v[94:97], v[106:109], v[190:193], v[94:97]
	v_mfma_f32_16x16x32_bf16 v[90:93], v[230:233], v[190:193], v[90:93]
	v_mfma_f32_16x16x32_bf16 v[86:89], v[110:113], v[202:205], v[86:89]
	v_mfma_f32_16x16x32_bf16 v[82:85], v[154:157], v[202:205], v[82:85]
	v_mfma_f32_16x16x32_bf16 v[78:81], v[106:109], v[206:209], v[78:81]
	v_mfma_f32_16x16x32_bf16 v[74:77], v[230:233], v[206:209], v[74:77]
	v_mfma_f32_16x16x32_bf16 v[70:73], v[110:113], v[218:221], v[70:73]
	v_mfma_f32_16x16x32_bf16 v[66:69], v[154:157], v[218:221], v[66:69]
	v_mfma_f32_16x16x32_bf16 v[234:237], v[110:113], v[194:197], v[94:97]
	v_mfma_f32_16x16x32_bf16 v[190:193], v[154:157], v[194:197], v[90:93]
	v_mfma_f32_16x16x32_bf16 v[194:197], v[110:113], v[210:213], v[78:81]
	v_mfma_f32_16x16x32_bf16 v[198:201], v[154:157], v[210:213], v[74:77]
	s_setprio 0
	s_barrier
	s_nop 0
	ds_read_b128 v[74:77], v150 offset:16384
	ds_read_b128 v[78:81], v150 offset:17408
	ds_read_b128 v[90:93], v149 offset:16384
	ds_read_b128 v[94:97], v149 offset:17408
	ds_read_b128 v[202:205], v148 offset:16384
	ds_read_b128 v[206:209], v148 offset:17408
	ds_read_b128 v[210:213], v147 offset:16384
	ds_read_b128 v[214:217], v147 offset:17408
	s_waitcnt vmcnt(4)
	s_barrier
	s_waitcnt lgkmcnt(0)
	s_setprio 1
	v_mfma_f32_16x16x32_bf16 v[62:65], v[132:135], v[74:77], v[62:65]
	v_mfma_f32_16x16x32_bf16 v[58:61], v[172:175], v[74:77], v[58:61]
	v_mfma_f32_16x16x32_bf16 v[54:57], v[132:135], v[90:93], v[54:57]
	v_mfma_f32_16x16x32_bf16 v[50:53], v[172:175], v[90:93], v[50:53]
	v_mfma_f32_16x16x32_bf16 v[38:41], v[132:135], v[210:213], v[38:41]
	v_mfma_f32_16x16x32_bf16 v[34:37], v[172:175], v[210:213], v[34:37]
	v_mfma_f32_16x16x32_bf16 v[62:65], v[136:139], v[78:81], v[62:65]
	v_mfma_f32_16x16x32_bf16 v[58:61], v[186:189], v[78:81], v[58:61]
	v_mfma_f32_16x16x32_bf16 v[54:57], v[136:139], v[94:97], v[54:57]
	v_mfma_f32_16x16x32_bf16 v[50:53], v[186:189], v[94:97], v[50:53]
	v_mfma_f32_16x16x32_bf16 v[46:49], v[132:135], v[202:205], v[46:49]
	v_mfma_f32_16x16x32_bf16 v[42:45], v[172:175], v[202:205], v[42:45]
	v_mfma_f32_16x16x32_bf16 v[38:41], v[136:139], v[214:217], v[38:41]
	v_mfma_f32_16x16x32_bf16 v[34:37], v[186:189], v[214:217], v[34:37]
	v_mfma_f32_16x16x32_bf16 v[218:221], v[136:139], v[206:209], v[46:49]
	v_mfma_f32_16x16x32_bf16 v[238:241], v[186:189], v[206:209], v[42:45]
	s_setprio 0
	s_setprio 1
	v_mfma_f32_16x16x32_bf16 v[22:25], v[106:109], v[90:93], v[22:25]
	v_mfma_f32_16x16x32_bf16 v[18:21], v[230:233], v[90:93], v[18:21]
	v_mfma_f32_16x16x32_bf16 v[6:9], v[106:109], v[210:213], v[6:9]
	v_mfma_f32_16x16x32_bf16 v[2:5], v[230:233], v[210:213], v[2:5]
	v_mfma_f32_16x16x32_bf16 v[30:33], v[106:109], v[74:77], v[30:33]
	v_mfma_f32_16x16x32_bf16 v[26:29], v[230:233], v[74:77], v[26:29]
	v_mfma_f32_16x16x32_bf16 v[22:25], v[110:113], v[94:97], v[22:25]
	v_mfma_f32_16x16x32_bf16 v[18:21], v[154:157], v[94:97], v[18:21]
	v_mfma_f32_16x16x32_bf16 v[14:17], v[106:109], v[202:205], v[14:17]
	v_mfma_f32_16x16x32_bf16 v[10:13], v[230:233], v[202:205], v[10:13]
	v_mfma_f32_16x16x32_bf16 v[6:9], v[110:113], v[214:217], v[6:9]
	v_mfma_f32_16x16x32_bf16 v[2:5], v[154:157], v[214:217], v[2:5]
	v_mfma_f32_16x16x32_bf16 v[132:135], v[110:113], v[78:81], v[30:33]
	v_mfma_f32_16x16x32_bf16 v[136:139], v[154:157], v[78:81], v[26:29]
	v_mfma_f32_16x16x32_bf16 v[170:173], v[110:113], v[206:209], v[14:17]
	v_mfma_f32_16x16x32_bf16 v[186:189], v[154:157], v[206:209], v[10:13]
	s_setprio 0
	s_barrier
	s_nop 0
	ds_read_b128 v[10:13], v153
	ds_read_b128 v[14:17], v153 offset:1024
	ds_read_b128 v[154:157], v153 offset:2048
	ds_read_b128 v[202:205], v153 offset:3072
	ds_read_b128 v[26:29], v150 offset:32768
	ds_read_b128 v[30:33], v150 offset:33792
	ds_read_b128 v[42:45], v149 offset:32768
	ds_read_b128 v[46:49], v149 offset:33792
	ds_read_b128 v[206:209], v148 offset:32768
	ds_read_b128 v[210:213], v148 offset:33792
	ds_read_b128 v[214:217], v147 offset:32768
	ds_read_b128 v[230:233], v147 offset:33792
	s_waitcnt vmcnt(2)
	s_barrier
; #define LDA(dst,b,h) for(int m=0;m<4;++m)for(int k=0;k<2;++k) \
;     dst[m][k]=*reinterpret_cast<const bf16x8*>((char*)SA(b,h)+lds_byte(wr*64+m*16+fr,k*32+fq*8))
; #define LDB(dst,b,h) for(int n=0;n<2;++n)for(int k=0;k<2;++k) \
;     dst[n][k]=*reinterpret_cast<const bf16x8*>((char*)SB(b,h)+lds_byte(wc*32+n*16+fr,k*32+fq*8))
; #define MMA(ai,bj,At,Bt_) do{__builtin_amdgcn_s_setprio(1); \
;     for(int m=0;m<4;++m)for(int n=0;n<2;++n)for(int k=0;k<2;++k) \
;       acc[ai][bj][m][n]=__builtin_amdgcn_mfma_f32_16x16x32_bf16(Bt_[n][k],At[m][k],acc[ai][bj][m][n],0,0,0); \
;     __builtin_amdgcn_s_setprio(0);}while(0)
; #define WAIT_V(n) asm volatile("s_waitcnt vmcnt(" #n ")":::"memory")
; #define WAIT_L(n) asm volatile("s_waitcnt lgkmcnt(" #n ")":::"memory")
; #define BAR __builtin_amdgcn_s_barrier()
; template <int EPI>
; __device__ __forceinline__ void gemm_run(const GD& c, const bool has_next, const GD& nx, const Ctx& e, bf16* shm, float* rs, float* rs_nxt, float* racc_) {
;     ...
;   { LDB(B0,1,0); LDA(At,1,0); WAIT_V(2); BAR; WAIT_L(0); MMA(0,0,At,B0); BAR;
;     LDB(B1,1,1); WAIT_V(0); BAR; WAIT_L(0); MMA(0,1,At,B1); BAR;
;     LDA(At,1,1); BAR; WAIT_L(0); MMA(1,0,At,B0); MMA(1,1,At,B1); BAR; }
;   if(wr==0)BAR;
	s_waitcnt lgkmcnt(0)
	s_setprio 1
	v_mfma_f32_16x16x32_bf16 v[74:77], v[10:13], v[26:29], v[126:129]
	v_mfma_f32_16x16x32_bf16 v[126:129], v[14:17], v[30:33], v[74:77]
	v_mfma_f32_16x16x32_bf16 v[74:77], v[154:157], v[26:29], v[122:125]
	v_mfma_f32_16x16x32_bf16 v[122:125], v[202:205], v[30:33], v[74:77]
	v_mfma_f32_16x16x32_bf16 v[74:77], v[10:13], v[42:45], v[118:121]
	v_mfma_f32_16x16x32_bf16 v[110:113], v[14:17], v[46:49], v[74:77]
	v_mfma_f32_16x16x32_bf16 v[74:77], v[154:157], v[42:45], v[114:117]
	v_mfma_f32_16x16x32_bf16 v[106:109], v[202:205], v[46:49], v[74:77]
	v_mfma_f32_16x16x32_bf16 v[74:77], v[10:13], v[206:209], v[222:225]
	v_mfma_f32_16x16x32_bf16 v[94:97], v[14:17], v[210:213], v[74:77]
	v_mfma_f32_16x16x32_bf16 v[74:77], v[154:157], v[206:209], v[226:229]
	v_mfma_f32_16x16x32_bf16 v[90:93], v[202:205], v[210:213], v[74:77]
	v_mfma_f32_16x16x32_bf16 v[74:77], v[10:13], v[214:217], v[102:105]
	v_mfma_f32_16x16x32_bf16 v[78:81], v[14:17], v[230:233], v[74:77]
	v_mfma_f32_16x16x32_bf16 v[74:77], v[154:157], v[214:217], v[98:101]
	v_mfma_f32_16x16x32_bf16 v[74:77], v[202:205], v[230:233], v[74:77]
	s_setprio 0
	s_barrier
	ds_read_b128 v[222:225], v151
	ds_read_b128 v[226:229], v151 offset:1024
	ds_read_b128 v[242:245], v151 offset:2048
	ds_read_b128 v[246:249], v151 offset:3072
	s_waitcnt vmcnt(0)
	s_barrier
	s_waitcnt lgkmcnt(0)
	s_setprio 1
	v_mfma_f32_16x16x32_bf16 v[98:101], v[222:225], v[26:29], v[234:237]
	v_mfma_f32_16x16x32_bf16 v[26:29], v[242:245], v[26:29], v[190:193]
	v_mfma_f32_16x16x32_bf16 v[114:117], v[246:249], v[30:33], v[26:29]
	v_mfma_f32_16x16x32_bf16 v[26:29], v[222:225], v[42:45], v[86:89]
	v_mfma_f32_16x16x32_bf16 v[102:105], v[226:229], v[46:49], v[26:29]
	v_mfma_f32_16x16x32_bf16 v[26:29], v[242:245], v[42:45], v[82:85]
	v_mfma_f32_16x16x32_bf16 v[118:121], v[226:229], v[30:33], v[98:101]
	v_mfma_f32_16x16x32_bf16 v[98:101], v[246:249], v[46:49], v[26:29]
	v_mfma_f32_16x16x32_bf16 v[26:29], v[222:225], v[206:209], v[194:197]
	v_mfma_f32_16x16x32_bf16 v[86:89], v[226:229], v[210:213], v[26:29]
	v_mfma_f32_16x16x32_bf16 v[26:29], v[242:245], v[206:209], v[198:201]
	v_mfma_f32_16x16x32_bf16 v[82:85], v[246:249], v[210:213], v[26:29]
	v_mfma_f32_16x16x32_bf16 v[26:29], v[222:225], v[214:217], v[70:73]
	v_mfma_f32_16x16x32_bf16 v[70:73], v[226:229], v[230:233], v[26:29]
	v_mfma_f32_16x16x32_bf16 v[26:29], v[242:245], v[214:217], v[66:69]
	v_mfma_f32_16x16x32_bf16 v[66:69], v[246:249], v[230:233], v[26:29]
	s_setprio 0
	s_barrier
	ds_read_b128 v[190:193], v150 offset:49152
	ds_read_b128 v[150:153], v150 offset:50176
	ds_read_b128 v[194:197], v149 offset:49152
	ds_read_b128 v[198:201], v149 offset:50176
	ds_read_b128 v[206:209], v148 offset:49152
	ds_read_b128 v[210:213], v148 offset:50176
	ds_read_b128 v[214:217], v147 offset:49152
	ds_read_b128 v[230:233], v147 offset:50176
	s_barrier
	s_waitcnt lgkmcnt(0)
	s_setprio 1
	v_mfma_f32_16x16x32_bf16 v[26:29], v[10:13], v[190:193], v[62:65]
	v_mfma_f32_16x16x32_bf16 v[62:65], v[14:17], v[150:153], v[26:29]
	v_mfma_f32_16x16x32_bf16 v[26:29], v[154:157], v[190:193], v[58:61]
	v_mfma_f32_16x16x32_bf16 v[58:61], v[202:205], v[150:153], v[26:29]
	v_mfma_f32_16x16x32_bf16 v[26:29], v[10:13], v[194:197], v[54:57]
	v_mfma_f32_16x16x32_bf16 v[46:49], v[14:17], v[198:201], v[26:29]
	v_mfma_f32_16x16x32_bf16 v[26:29], v[154:157], v[194:197], v[50:53]
	v_mfma_f32_16x16x32_bf16 v[42:45], v[202:205], v[198:201], v[26:29]
	v_mfma_f32_16x16x32_bf16 v[26:29], v[10:13], v[206:209], v[218:221]
	v_mfma_f32_16x16x32_bf16 v[10:13], v[10:13], v[214:217], v[38:41]
	v_mfma_f32_16x16x32_bf16 v[30:33], v[14:17], v[210:213], v[26:29]
	v_mfma_f32_16x16x32_bf16 v[26:29], v[154:157], v[206:209], v[238:241]
	v_mfma_f32_16x16x32_bf16 v[14:17], v[14:17], v[230:233], v[10:13]
	v_mfma_f32_16x16x32_bf16 v[10:13], v[154:157], v[214:217], v[34:37]
	v_mfma_f32_16x16x32_bf16 v[26:29], v[202:205], v[210:213], v[26:29]
	v_mfma_f32_16x16x32_bf16 v[10:13], v[202:205], v[230:233], v[10:13]
	s_setprio 0
	s_setprio 1
	v_mfma_f32_16x16x32_bf16 v[34:37], v[222:225], v[190:193], v[132:135]
	v_mfma_f32_16x16x32_bf16 v[54:57], v[226:229], v[150:153], v[34:37]
	v_mfma_f32_16x16x32_bf16 v[34:37], v[242:245], v[190:193], v[136:139]
	v_mfma_f32_16x16x32_bf16 v[18:21], v[242:245], v[194:197], v[18:21]
	v_mfma_f32_16x16x32_bf16 v[50:53], v[246:249], v[150:153], v[34:37]
	v_mfma_f32_16x16x32_bf16 v[22:25], v[222:225], v[194:197], v[22:25]
	v_mfma_f32_16x16x32_bf16 v[34:37], v[246:249], v[198:201], v[18:21]
	v_mfma_f32_16x16x32_bf16 v[18:21], v[222:225], v[206:209], v[170:173]
	v_mfma_f32_16x16x32_bf16 v[38:41], v[226:229], v[198:201], v[22:25]
	v_mfma_f32_16x16x32_bf16 v[22:25], v[226:229], v[210:213], v[18:21]
	v_mfma_f32_16x16x32_bf16 v[18:21], v[242:245], v[206:209], v[186:189]
	v_mfma_f32_16x16x32_bf16 v[6:9], v[222:225], v[214:217], v[6:9]
	v_mfma_f32_16x16x32_bf16 v[2:5], v[242:245], v[214:217], v[2:5]
	v_mfma_f32_16x16x32_bf16 v[18:21], v[246:249], v[210:213], v[18:21]
	v_mfma_f32_16x16x32_bf16 v[6:9], v[226:229], v[230:233], v[6:9]
	v_mfma_f32_16x16x32_bf16 v[2:5], v[246:249], v[230:233], v[2:5]
	s_setprio 0
	v_cmp_gt_u32_e32 vcc, s96, v142
	s_barrier
	s_and_saveexec_b64 s[2:3], vcc
	s_cbranch_execz .LBB0_983
	s_barrier

; #define STAGE_A(P,br,kt) STAGE_G(P,c.A,c.lda,br,(long)(kt)*c.kstr)
; #define STAGE_B(P,br,kt) STAGE_G(P,c.Bt,c.K,br,(long)(kt)*BK)
; #define LDA(dst,b,h) for(int m=0;m<4;++m)for(int k=0;k<2;++k) \
;     dst[m][k]=*reinterpret_cast<const bf16x8*>((char*)SA(b,h)+lds_byte(wr*64+m*16+fr,k*32+fq*8))
; #define LDB(dst,b,h) for(int n=0;n<2;++n)for(int k=0;k<2;++k) \
;     dst[n][k]=*reinterpret_cast<const bf16x8*>((char*)SB(b,h)+lds_byte(wc*32+n*16+fr,k*32+fq*8))
; #define MMA(ai,bj,At,Bt_) do{__builtin_amdgcn_s_setprio(1); \
;     for(int m=0;m<4;++m)for(int n=0;n<2;++n)for(int k=0;k<2;++k) \
;       acc[ai][bj][m][n]=__builtin_amdgcn_mfma_f32_16x16x32_bf16(Bt_[n][k],At[m][k],acc[ai][bj][m][n],0,0,0); \
;     __builtin_amdgcn_s_setprio(0);}while(0)
; #define WAIT_V(n) asm volatile("s_waitcnt vmcnt(" #n ")":::"memory")
; #define WAIT_L(n) asm volatile("s_waitcnt lgkmcnt(" #n ")":::"memory")
; #define BAR __builtin_amdgcn_s_barrier()
; #define SCHED __builtin_amdgcn_sched_barrier(0)
; template <int EPI>
; __device__ __forceinline__ void gemm_run(const GD& c, const bool has_next, const GD& nx, const Ctx& e, bf16* shm, float* rs, float* rs_nxt, float* racc_) {
;     ...
;   for(int t=0;t<nt-2;t+=2){
;     LDB(B0,0,0); SCHED; LDA(At,0,0); STAGE_A(SA(1,1),brow+HALF,t+1);
;     WAIT_L(8); BAR; WAIT_L(0); MMA(0,0,At,B0); BAR; SCHED;
;     LDB(B1,0,1); STAGE_B(SB(0,0),bcol,t+2);
;     BAR; WAIT_L(0); MMA(0,1,At,B1); BAR;
;     LDA(At,0,1); STAGE_A(SA(0,0),brow,t+2);
;     BAR; WAIT_L(0); MMA(1,0,At,B0); BAR; SCHED;
;     STAGE_B(SB(0,1),bcol+HALF,t+2);
;     WAIT_V(6); BAR; MMA(1,1,At,B1); BAR;
.LBB0_1035:
	ds_read_b128 v[168:171], v155
	ds_read_b128 v[172:175], v155 offset:1024
	ds_read_b128 v[186:189], v155 offset:2048
	ds_read_b128 v[190:193], v155 offset:3072
	v_add_u32_e32 v163, 0xc000, v142
	v_lshl_add_u64 v[182:183], s[6:7], 0, v[132:133]
	v_readfirstlane_b32 s3, v163
	v_add_u32_e32 v166, 0xe000, v142
	v_lshl_add_u64 v[156:157], v[182:183], 0, s[28:29]
	s_mov_b32 m0, s3
	v_lshl_add_u64 v[242:243], s[6:7], 0, v[134:135]
	v_readfirstlane_b32 s3, v166
	ds_read_b128 v[158:161], v146
	ds_read_b128 v[194:197], v146 offset:1024
	ds_read_b128 v[198:201], v145
	ds_read_b128 v[202:205], v145 offset:1024
	ds_read_b128 v[206:209], v144
	ds_read_b128 v[210:213], v144 offset:1024
	ds_read_b128 v[214:217], v143
	ds_read_b128 v[218:221], v143 offset:1024
	global_load_lds_dwordx4 v[156:157], off
	v_lshl_add_u64 v[156:157], v[242:243], 0, s[28:29]
	s_mov_b32 m0, s3
	s_nop 0
	global_load_lds_dwordx4 v[156:157], off
	s_waitcnt lgkmcnt(8)
	s_barrier
	s_waitcnt lgkmcnt(0)
	s_setprio 1
	v_mfma_f32_16x16x32_bf16 v[126:129], v[168:171], v[158:161], v[126:129]
	v_mfma_f32_16x16x32_bf16 v[122:125], v[186:189], v[158:161], v[122:125]
	v_mfma_f32_16x16x32_bf16 v[118:121], v[168:171], v[198:201], v[118:121]
	v_mfma_f32_16x16x32_bf16 v[114:117], v[186:189], v[198:201], v[114:117]
	v_mfma_f32_16x16x32_bf16 v[110:113], v[168:171], v[206:209], v[110:113]
	v_mfma_f32_16x16x32_bf16 v[106:109], v[186:189], v[206:209], v[106:109]
	v_mfma_f32_16x16x32_bf16 v[102:105], v[168:171], v[214:217], v[102:105]
	v_mfma_f32_16x16x32_bf16 v[98:101], v[186:189], v[214:217], v[98:101]
	v_mfma_f32_16x16x32_bf16 v[126:129], v[172:175], v[194:197], v[126:129]
	v_mfma_f32_16x16x32_bf16 v[122:125], v[190:193], v[194:197], v[122:125]
	v_mfma_f32_16x16x32_bf16 v[118:121], v[172:175], v[202:205], v[118:121]
	v_mfma_f32_16x16x32_bf16 v[114:117], v[190:193], v[202:205], v[114:117]
	v_mfma_f32_16x16x32_bf16 v[110:113], v[172:175], v[210:213], v[110:113]
	v_mfma_f32_16x16x32_bf16 v[106:109], v[190:193], v[210:213], v[106:109]
	v_mfma_f32_16x16x32_bf16 v[102:105], v[172:175], v[218:221], v[102:105]
	v_mfma_f32_16x16x32_bf16 v[98:101], v[190:193], v[218:221], v[98:101]
	s_setprio 0
	s_barrier
	v_add_u32_e32 v156, s33, v148
	v_lshl_add_u64 v[244:245], s[6:7], 0, v[136:137]
	v_readfirstlane_b32 s3, v156
	v_add_u32_e32 v157, 0x2000, v156
	v_lshl_add_u64 v[238:239], v[244:245], 0, s[30:31]
	s_mov_b32 m0, s3
	v_lshl_add_u64 v[246:247], s[6:7], 0, v[138:139]
	v_readfirstlane_b32 s3, v157
	ds_read_b128 v[222:225], v154
	ds_read_b128 v[226:229], v154 offset:1024
	ds_read_b128 v[230:233], v154 offset:2048
	ds_read_b128 v[234:237], v154 offset:3072
	global_load_lds_dwordx4 v[238:239], off
	v_lshl_add_u64 v[238:239], v[246:247], 0, s[30:31]
	s_mov_b32 m0, s3
	s_nop 0
	global_load_lds_dwordx4 v[238:239], off
	s_barrier
	s_waitcnt lgkmcnt(0)
	s_setprio 1
	v_mfma_f32_16x16x32_bf16 v[94:97], v[222:225], v[158:161], v[94:97]
	v_mfma_f32_16x16x32_bf16 v[90:93], v[230:233], v[158:161], v[90:93]
	v_mfma_f32_16x16x32_bf16 v[86:89], v[222:225], v[198:201], v[86:89]
	v_mfma_f32_16x16x32_bf16 v[82:85], v[230:233], v[198:201], v[82:85]
	v_mfma_f32_16x16x32_bf16 v[78:81], v[222:225], v[206:209], v[78:81]
	v_mfma_f32_16x16x32_bf16 v[74:77], v[230:233], v[206:209], v[74:77]
	v_mfma_f32_16x16x32_bf16 v[70:73], v[222:225], v[214:217], v[70:73]
	v_mfma_f32_16x16x32_bf16 v[66:69], v[230:233], v[214:217], v[66:69]
	v_mfma_f32_16x16x32_bf16 v[94:97], v[226:229], v[194:197], v[94:97]
	v_mfma_f32_16x16x32_bf16 v[90:93], v[234:237], v[194:197], v[90:93]
	v_mfma_f32_16x16x32_bf16 v[86:89], v[226:229], v[202:205], v[86:89]
	v_mfma_f32_16x16x32_bf16 v[82:85], v[234:237], v[202:205], v[82:85]
	v_mfma_f32_16x16x32_bf16 v[78:81], v[226:229], v[210:213], v[78:81]
	v_mfma_f32_16x16x32_bf16 v[74:77], v[234:237], v[210:213], v[74:77]
	v_mfma_f32_16x16x32_bf16 v[70:73], v[226:229], v[218:221], v[70:73]
	v_mfma_f32_16x16x32_bf16 v[66:69], v[234:237], v[218:221], v[66:69]
	s_setprio 0
	v_readfirstlane_b32 s3, v142
	v_lshl_add_u64 v[158:159], v[182:183], 0, s[34:35]
	s_mov_b32 m0, s3
	s_barrier
	ds_read_b128 v[194:197], v146 offset:16384
	ds_read_b128 v[198:201], v146 offset:17408
	ds_read_b128 v[202:205], v145 offset:16384
	ds_read_b128 v[206:209], v145 offset:17408
	ds_read_b128 v[210:213], v144 offset:16384
	ds_read_b128 v[214:217], v144 offset:17408
	ds_read_b128 v[218:221], v143 offset:16384
	ds_read_b128 v[238:241], v143 offset:17408
	global_load_lds_dwordx4 v[158:159], off
	v_add_u32_e32 v158, 0x2000, v142
	v_lshl_add_u64 v[160:161], v[242:243], 0, s[34:35]
	v_readfirstlane_b32 s3, v158
	s_mov_b32 m0, s3
	s_nop 0
	global_load_lds_dwordx4 v[160:161], off
	s_barrier
	s_waitcnt lgkmcnt(0)
	s_setprio 1
	v_mfma_f32_16x16x32_bf16 v[62:65], v[168:171], v[194:197], v[62:65]
	v_mfma_f32_16x16x32_bf16 v[58:61], v[186:189], v[194:197], v[58:61]
	v_mfma_f32_16x16x32_bf16 v[54:57], v[168:171], v[202:205], v[54:57]
	v_mfma_f32_16x16x32_bf16 v[50:53], v[186:189], v[202:205], v[50:53]
	v_mfma_f32_16x16x32_bf16 v[46:49], v[168:171], v[210:213], v[46:49]
	v_mfma_f32_16x16x32_bf16 v[42:45], v[186:189], v[210:213], v[42:45]
	v_mfma_f32_16x16x32_bf16 v[38:41], v[168:171], v[218:221], v[38:41]
	v_mfma_f32_16x16x32_bf16 v[34:37], v[186:189], v[218:221], v[34:37]
	v_mfma_f32_16x16x32_bf16 v[62:65], v[172:175], v[198:201], v[62:65]
	v_mfma_f32_16x16x32_bf16 v[58:61], v[190:193], v[198:201], v[58:61]
	v_mfma_f32_16x16x32_bf16 v[54:57], v[172:175], v[206:209], v[54:57]
	v_mfma_f32_16x16x32_bf16 v[50:53], v[190:193], v[206:209], v[50:53]
	v_mfma_f32_16x16x32_bf16 v[46:49], v[172:175], v[214:217], v[46:49]
	v_mfma_f32_16x16x32_bf16 v[42:45], v[190:193], v[214:217], v[42:45]
	v_mfma_f32_16x16x32_bf16 v[38:41], v[172:175], v[238:241], v[38:41]
	v_mfma_f32_16x16x32_bf16 v[34:37], v[190:193], v[238:241], v[34:37]
	s_setprio 0
	s_barrier
; #define STAGE_A(P,br,kt) STAGE_G(P,c.A,c.lda,br,(long)(kt)*c.kstr)
; #define STAGE_B(P,br,kt) STAGE_G(P,c.Bt,c.K,br,(long)(kt)*BK)
; #define LDA(dst,b,h) for(int m=0;m<4;++m)for(int k=0;k<2;++k) \
;     dst[m][k]=*reinterpret_cast<const bf16x8*>((char*)SA(b,h)+lds_byte(wr*64+m*16+fr,k*32+fq*8))
; #define LDB(dst,b,h) for(int n=0;n<2;++n)for(int k=0;k<2;++k) \
;     dst[n][k]=*reinterpret_cast<const bf16x8*>((char*)SB(b,h)+lds_byte(wc*32+n*16+fr,k*32+fq*8))
; #define MMA(ai,bj,At,Bt_) do{__builtin_amdgcn_s_setprio(1); \
;     for(int m=0;m<4;++m)for(int n=0;n<2;++n)for(int k=0;k<2;++k) \
;       acc[ai][bj][m][n]=__builtin_amdgcn_mfma_f32_16x16x32_bf16(Bt_[n][k],At[m][k],acc[ai][bj][m][n],0,0,0); \
;     __builtin_amdgcn_s_setprio(0);}while(0)
; #define WAIT_V(n) asm volatile("s_waitcnt vmcnt(" #n ")":::"memory")
; #define WAIT_L(n) asm volatile("s_waitcnt lgkmcnt(" #n ")":::"memory")
; #define BAR __builtin_amdgcn_s_barrier()
; #define SCHED __builtin_amdgcn_sched_barrier(0)
; template <int EPI>
; __device__ __forceinline__ void gemm_run(const GD& c, const bool has_next, const GD& nx, const Ctx& e, bf16* shm, float* rs, float* rs_nxt, float* racc_) {
;     ...
;     WAIT_V(6); BAR; MMA(1,1,At,B1); BAR;
;     LDB(B0,1,0); SCHED; LDA(At,1,0); STAGE_A(SA(0,1),brow+HALF,t+2);
;     WAIT_L(8); BAR; WAIT_L(0); MMA(0,0,At,B0); BAR; SCHED;
;     LDB(B1,1,1); STAGE_B(SB(1,0),bcol,t+3);
;     BAR; WAIT_L(0); MMA(0,1,At,B1); BAR;
;     LDA(At,1,1); STAGE_A(SA(1,0),brow,t+3);
;     BAR; WAIT_L(0); MMA(1,0,At,B0); BAR; SCHED;
	v_add_u32_e32 v159, s86, v148
	v_lshl_add_u64 v[160:161], v[244:245], 0, s[36:37]
	v_readfirstlane_b32 s3, v159
	s_mov_b32 m0, s3
	v_lshl_add_u64 v[168:169], v[246:247], 0, s[36:37]
	global_load_lds_dwordx4 v[160:161], off
	v_add_u32_e32 v160, 0x2000, v159
	s_nop 0
	v_readfirstlane_b32 s3, v160
	s_mov_b32 m0, s3
	s_nop 0
	global_load_lds_dwordx4 v[168:169], off
	s_waitcnt vmcnt(6)
	s_barrier
	s_setprio 1
	v_mfma_f32_16x16x32_bf16 v[30:33], v[222:225], v[194:197], v[30:33]
	v_mfma_f32_16x16x32_bf16 v[26:29], v[230:233], v[194:197], v[26:29]
	v_mfma_f32_16x16x32_bf16 v[22:25], v[222:225], v[202:205], v[22:25]
	v_mfma_f32_16x16x32_bf16 v[18:21], v[230:233], v[202:205], v[18:21]
	v_mfma_f32_16x16x32_bf16 v[14:17], v[222:225], v[210:213], v[14:17]
	v_mfma_f32_16x16x32_bf16 v[10:13], v[230:233], v[210:213], v[10:13]
	v_mfma_f32_16x16x32_bf16 v[6:9], v[222:225], v[218:221], v[6:9]
	v_mfma_f32_16x16x32_bf16 v[2:5], v[230:233], v[218:221], v[2:5]
	v_mfma_f32_16x16x32_bf16 v[30:33], v[226:229], v[198:201], v[30:33]
	v_mfma_f32_16x16x32_bf16 v[26:29], v[234:237], v[198:201], v[26:29]
	v_mfma_f32_16x16x32_bf16 v[22:25], v[226:229], v[206:209], v[22:25]
	v_mfma_f32_16x16x32_bf16 v[18:21], v[234:237], v[206:209], v[18:21]
	v_mfma_f32_16x16x32_bf16 v[14:17], v[226:229], v[214:217], v[14:17]
	v_mfma_f32_16x16x32_bf16 v[10:13], v[234:237], v[214:217], v[10:13]
	v_mfma_f32_16x16x32_bf16 v[6:9], v[226:229], v[238:241], v[6:9]
	v_mfma_f32_16x16x32_bf16 v[2:5], v[234:237], v[238:241], v[2:5]
	s_setprio 0
	s_barrier
	ds_read_b128 v[168:171], v149
	ds_read_b128 v[172:175], v149 offset:1024
	ds_read_b128 v[186:189], v149 offset:2048
	ds_read_b128 v[190:193], v149 offset:3072
	v_add_u32_e32 v161, 0x4000, v142
	v_add_u32_e32 v162, 0x6000, v142
	v_readfirstlane_b32 s3, v161
	v_lshl_add_u64 v[226:227], v[182:183], 0, s[38:39]
	s_mov_b32 m0, s3
	v_readfirstlane_b32 s3, v162
	ds_read_b128 v[194:197], v146 offset:32768
	ds_read_b128 v[198:201], v146 offset:33792
	ds_read_b128 v[202:205], v145 offset:32768
	ds_read_b128 v[206:209], v145 offset:33792
	ds_read_b128 v[210:213], v144 offset:32768
	ds_read_b128 v[214:217], v144 offset:33792
	ds_read_b128 v[218:221], v143 offset:32768
	ds_read_b128 v[222:225], v143 offset:33792
	global_load_lds_dwordx4 v[226:227], off
	v_lshl_add_u64 v[226:227], v[242:243], 0, s[38:39]
	s_mov_b32 m0, s3
	s_nop 0
	global_load_lds_dwordx4 v[226:227], off
	s_waitcnt lgkmcnt(8)
	s_barrier
	s_waitcnt lgkmcnt(0)
	s_setprio 1
	v_mfma_f32_16x16x32_bf16 v[126:129], v[168:171], v[194:197], v[126:129]
	v_mfma_f32_16x16x32_bf16 v[122:125], v[186:189], v[194:197], v[122:125]
	v_mfma_f32_16x16x32_bf16 v[118:121], v[168:171], v[202:205], v[118:121]
	v_mfma_f32_16x16x32_bf16 v[114:117], v[186:189], v[202:205], v[114:117]
	v_mfma_f32_16x16x32_bf16 v[110:113], v[168:171], v[210:213], v[110:113]
	v_mfma_f32_16x16x32_bf16 v[106:109], v[186:189], v[210:213], v[106:109]
	v_mfma_f32_16x16x32_bf16 v[102:105], v[168:171], v[218:221], v[102:105]
	v_mfma_f32_16x16x32_bf16 v[98:101], v[186:189], v[218:221], v[98:101]
	v_mfma_f32_16x16x32_bf16 v[126:129], v[172:175], v[198:201], v[126:129]
	v_mfma_f32_16x16x32_bf16 v[122:125], v[190:193], v[198:201], v[122:125]
	v_mfma_f32_16x16x32_bf16 v[118:121], v[172:175], v[206:209], v[118:121]
	v_mfma_f32_16x16x32_bf16 v[114:117], v[190:193], v[206:209], v[114:117]
	v_mfma_f32_16x16x32_bf16 v[110:113], v[172:175], v[214:217], v[110:113]
	v_mfma_f32_16x16x32_bf16 v[106:109], v[190:193], v[214:217], v[106:109]
	v_mfma_f32_16x16x32_bf16 v[102:105], v[172:175], v[222:225], v[102:105]
	v_mfma_f32_16x16x32_bf16 v[98:101], v[190:193], v[222:225], v[98:101]
	s_setprio 0
	s_barrier
	v_readfirstlane_b32 s3, v150
	v_add_u32_e32 v167, 0x2000, v150
	v_lshl_add_u64 v[248:249], v[244:245], 0, s[40:41]
	s_mov_b32 m0, s3
	v_readfirstlane_b32 s3, v167
	ds_read_b128 v[226:229], v147
	ds_read_b128 v[230:233], v147 offset:1024
	ds_read_b128 v[234:237], v147 offset:2048
	ds_read_b128 v[238:241], v147 offset:3072
	global_load_lds_dwordx4 v[248:249], off
	v_lshl_add_u64 v[248:249], v[246:247], 0, s[40:41]
	s_mov_b32 m0, s3
	s_nop 0
	global_load_lds_dwordx4 v[248:249], off
	s_barrier
	s_waitcnt lgkmcnt(0)
	s_setprio 1
	v_mfma_f32_16x16x32_bf16 v[94:97], v[226:229], v[194:197], v[94:97]
	v_mfma_f32_16x16x32_bf16 v[90:93], v[234:237], v[194:197], v[90:93]
	v_mfma_f32_16x16x32_bf16 v[86:89], v[226:229], v[202:205], v[86:89]
	v_mfma_f32_16x16x32_bf16 v[82:85], v[234:237], v[202:205], v[82:85]
	v_mfma_f32_16x16x32_bf16 v[78:81], v[226:229], v[210:213], v[78:81]
	v_mfma_f32_16x16x32_bf16 v[74:77], v[234:237], v[210:213], v[74:77]
	v_mfma_f32_16x16x32_bf16 v[70:73], v[226:229], v[218:221], v[70:73]
	v_mfma_f32_16x16x32_bf16 v[66:69], v[234:237], v[218:221], v[66:69]
	v_mfma_f32_16x16x32_bf16 v[94:97], v[230:233], v[198:201], v[94:97]
	v_mfma_f32_16x16x32_bf16 v[90:93], v[238:241], v[198:201], v[90:93]
	v_mfma_f32_16x16x32_bf16 v[86:89], v[230:233], v[206:209], v[86:89]
	v_mfma_f32_16x16x32_bf16 v[82:85], v[238:241], v[206:209], v[82:85]
	v_mfma_f32_16x16x32_bf16 v[78:81], v[230:233], v[214:217], v[78:81]
	v_mfma_f32_16x16x32_bf16 v[74:77], v[238:241], v[214:217], v[74:77]
	v_mfma_f32_16x16x32_bf16 v[70:73], v[230:233], v[222:225], v[70:73]
	v_mfma_f32_16x16x32_bf16 v[66:69], v[238:241], v[222:225], v[66:69]
	s_setprio 0
	v_readfirstlane_b32 s3, v151
	v_lshl_add_u64 v[182:183], v[182:183], 0, s[42:43]
	s_mov_b32 m0, s3
	v_readfirstlane_b32 s3, v152
	s_barrier
; #define STAGE_A(P,br,kt) STAGE_G(P,c.A,c.lda,br,(long)(kt)*c.kstr)
; #define STAGE_B(P,br,kt) STAGE_G(P,c.Bt,c.K,br,(long)(kt)*BK)
; #define LDA(dst,b,h) for(int m=0;m<4;++m)for(int k=0;k<2;++k) \
;     dst[m][k]=*reinterpret_cast<const bf16x8*>((char*)SA(b,h)+lds_byte(wr*64+m*16+fr,k*32+fq*8))
; #define LDB(dst,b,h) for(int n=0;n<2;++n)for(int k=0;k<2;++k) \
;     dst[n][k]=*reinterpret_cast<const bf16x8*>((char*)SB(b,h)+lds_byte(wc*32+n*16+fr,k*32+fq*8))
; #define MMA(ai,bj,At,Bt_) do{__builtin_amdgcn_s_setprio(1); \
;     for(int m=0;m<4;++m)for(int n=0;n<2;++n)for(int k=0;k<2;++k) \
;       acc[ai][bj][m][n]=__builtin_amdgcn_mfma_f32_16x16x32_bf16(Bt_[n][k],At[m][k],acc[ai][bj][m][n],0,0,0); \
;     __builtin_amdgcn_s_setprio(0);}while(0)
; #define WAIT_V(n) asm volatile("s_waitcnt vmcnt(" #n ")":::"memory")
; #define WAIT_L(n) asm volatile("s_waitcnt lgkmcnt(" #n ")":::"memory")
; #define BAR __builtin_amdgcn_s_barrier()
; #define SCHED __builtin_amdgcn_sched_barrier(0)
; template <int EPI>
; __device__ __forceinline__ void gemm_run(const GD& c, const bool has_next, const GD& nx, const Ctx& e, bf16* shm, float* rs, float* rs_nxt, float* racc_) {
;     ...
;     BAR; WAIT_L(0); MMA(1,0,At,B0); BAR; SCHED;
;     STAGE_B(SB(1,1),bcol+HALF,t+3);
;     WAIT_V(6); BAR; MMA(1,1,At,B1); BAR;
;   }
;   { LDB(B0,0,0); LDA(At,0,0); STAGE_A(SA(1,1),brow+HALF,nt-1);
;     BAR; WAIT_L(0); MMA(0,0,At,B0); BAR;
;     LDB(B1,0,1); BAR; WAIT_L(0); MMA(0,1,At,B1); BAR;
	ds_read_b128 v[194:197], v146 offset:49152
	ds_read_b128 v[198:201], v146 offset:50176
	ds_read_b128 v[202:205], v145 offset:49152
	ds_read_b128 v[206:209], v145 offset:50176
	ds_read_b128 v[210:213], v144 offset:49152
	ds_read_b128 v[214:217], v144 offset:50176
	ds_read_b128 v[218:221], v143 offset:49152
	ds_read_b128 v[222:225], v143 offset:50176
	global_load_lds_dwordx4 v[182:183], off
	v_lshl_add_u64 v[182:183], v[242:243], 0, s[42:43]
	s_mov_b32 m0, s3
	s_nop 0
	global_load_lds_dwordx4 v[182:183], off
	s_barrier
	s_waitcnt lgkmcnt(0)
	s_setprio 1
	v_mfma_f32_16x16x32_bf16 v[62:65], v[168:171], v[194:197], v[62:65]
	v_mfma_f32_16x16x32_bf16 v[58:61], v[186:189], v[194:197], v[58:61]
	v_mfma_f32_16x16x32_bf16 v[54:57], v[168:171], v[202:205], v[54:57]
	v_mfma_f32_16x16x32_bf16 v[50:53], v[186:189], v[202:205], v[50:53]
	v_mfma_f32_16x16x32_bf16 v[46:49], v[168:171], v[210:213], v[46:49]
	v_mfma_f32_16x16x32_bf16 v[42:45], v[186:189], v[210:213], v[42:45]
	v_mfma_f32_16x16x32_bf16 v[38:41], v[168:171], v[218:221], v[38:41]
	v_mfma_f32_16x16x32_bf16 v[34:37], v[186:189], v[218:221], v[34:37]
	v_mfma_f32_16x16x32_bf16 v[62:65], v[172:175], v[198:201], v[62:65]
	v_mfma_f32_16x16x32_bf16 v[58:61], v[190:193], v[198:201], v[58:61]
	v_mfma_f32_16x16x32_bf16 v[54:57], v[172:175], v[206:209], v[54:57]
	v_mfma_f32_16x16x32_bf16 v[50:53], v[190:193], v[206:209], v[50:53]
	v_mfma_f32_16x16x32_bf16 v[46:49], v[172:175], v[214:217], v[46:49]
	v_mfma_f32_16x16x32_bf16 v[42:45], v[190:193], v[214:217], v[42:45]
	v_mfma_f32_16x16x32_bf16 v[38:41], v[172:175], v[222:225], v[38:41]
	v_mfma_f32_16x16x32_bf16 v[34:37], v[190:193], v[222:225], v[34:37]
	s_setprio 0
	s_barrier
	v_readfirstlane_b32 s3, v153
	v_add_u32_e32 v167, 0x2000, v153
	v_lshl_add_u64 v[168:169], v[244:245], 0, s[44:45]
	s_mov_b32 m0, s3
	v_readfirstlane_b32 s3, v167
	global_load_lds_dwordx4 v[168:169], off
	v_lshl_add_u64 v[168:169], v[246:247], 0, s[44:45]
	s_mov_b32 m0, s3
	s_nop 0
	global_load_lds_dwordx4 v[168:169], off
	s_waitcnt vmcnt(6)
	s_barrier
	s_setprio 1
	v_mfma_f32_16x16x32_bf16 v[30:33], v[226:229], v[194:197], v[30:33]
	v_mfma_f32_16x16x32_bf16 v[26:29], v[234:237], v[194:197], v[26:29]
	v_mfma_f32_16x16x32_bf16 v[22:25], v[226:229], v[202:205], v[22:25]
	v_mfma_f32_16x16x32_bf16 v[18:21], v[234:237], v[202:205], v[18:21]
	v_mfma_f32_16x16x32_bf16 v[14:17], v[226:229], v[210:213], v[14:17]
	v_mfma_f32_16x16x32_bf16 v[10:13], v[234:237], v[210:213], v[10:13]
	v_mfma_f32_16x16x32_bf16 v[6:9], v[226:229], v[218:221], v[6:9]
	v_mfma_f32_16x16x32_bf16 v[2:5], v[234:237], v[218:221], v[2:5]
	v_mfma_f32_16x16x32_bf16 v[30:33], v[230:233], v[198:201], v[30:33]
	v_mfma_f32_16x16x32_bf16 v[26:29], v[238:241], v[198:201], v[26:29]
	v_mfma_f32_16x16x32_bf16 v[22:25], v[230:233], v[206:209], v[22:25]
	v_mfma_f32_16x16x32_bf16 v[18:21], v[238:241], v[206:209], v[18:21]
	v_mfma_f32_16x16x32_bf16 v[14:17], v[230:233], v[214:217], v[14:17]
	v_mfma_f32_16x16x32_bf16 v[10:13], v[238:241], v[214:217], v[10:13]
	v_mfma_f32_16x16x32_bf16 v[6:9], v[230:233], v[222:225], v[6:9]
	v_mfma_f32_16x16x32_bf16 v[2:5], v[238:241], v[222:225], v[2:5]
	s_setprio 0
	s_add_i32 s2, s2, 2
	v_lshl_add_u64 v[132:133], v[132:133], 0, s[88:89]
	v_lshl_add_u64 v[134:135], v[134:135], 0, s[88:89]
	v_lshl_add_u64 v[136:137], v[136:137], 0, s[88:89]
	s_cmp_lt_u32 s2, 12
	v_lshl_add_u64 v[138:139], v[138:139], 0, s[88:89]
	s_barrier
	s_cbranch_scc1 .LBB0_1035
	s_or_b32 s2, s14, 0x80
	s_ashr_i32 s3, s2, 31
	s_lshl_b64 s[2:3], s[2:3], 11
	s_add_u32 s2, s24, s2
	s_addc_u32 s3, s25, s3
	v_readfirstlane_b32 s5, v163
	v_lshl_add_u64 v[182:183], s[2:3], 0, v[0:1]
	s_mov_b32 m0, s5
	ds_read_b128 v[132:135], v155
	ds_read_b128 v[136:139], v155 offset:1024
	ds_read_b128 v[150:153], v155 offset:2048
	ds_read_b128 v[168:171], v155 offset:3072
	ds_read_b128 v[172:175], v146
	ds_read_b128 v[186:189], v146 offset:1024
	ds_read_b128 v[190:193], v145
	ds_read_b128 v[194:197], v145 offset:1024
	ds_read_b128 v[198:201], v144
	ds_read_b128 v[202:205], v144 offset:1024
	ds_read_b128 v[206:209], v143
	ds_read_b128 v[210:213], v143 offset:1024
	global_load_lds_dwordx4 v[182:183], off
	v_lshl_add_u64 v[182:183], s[2:3], 0, v[130:131]
	v_readfirstlane_b32 s2, v166
	s_mov_b32 m0, s2
	s_nop 0
	global_load_lds_dwordx4 v[182:183], off
	s_barrier
	s_waitcnt lgkmcnt(0)
	s_setprio 1
	v_mfma_f32_16x16x32_bf16 v[126:129], v[132:135], v[172:175], v[126:129]
	v_mfma_f32_16x16x32_bf16 v[122:125], v[150:153], v[172:175], v[122:125]
	v_mfma_f32_16x16x32_bf16 v[118:121], v[132:135], v[190:193], v[118:121]
	v_mfma_f32_16x16x32_bf16 v[114:117], v[150:153], v[190:193], v[114:117]
	v_mfma_f32_16x16x32_bf16 v[102:105], v[132:135], v[206:209], v[102:105]
	v_mfma_f32_16x16x32_bf16 v[98:101], v[150:153], v[206:209], v[98:101]
	v_mfma_f32_16x16x32_bf16 v[126:129], v[136:139], v[186:189], v[126:129]
	v_mfma_f32_16x16x32_bf16 v[122:125], v[168:171], v[186:189], v[122:125]
	v_mfma_f32_16x16x32_bf16 v[118:121], v[136:139], v[194:197], v[118:121]
	v_mfma_f32_16x16x32_bf16 v[114:117], v[168:171], v[194:197], v[114:117]
	v_mfma_f32_16x16x32_bf16 v[110:113], v[132:135], v[198:201], v[110:113]
	v_mfma_f32_16x16x32_bf16 v[106:109], v[150:153], v[198:201], v[106:109]
	v_mfma_f32_16x16x32_bf16 v[102:105], v[136:139], v[210:213], v[102:105]
	v_mfma_f32_16x16x32_bf16 v[98:101], v[168:171], v[210:213], v[98:101]
	v_mfma_f32_16x16x32_bf16 v[214:217], v[136:139], v[202:205], v[110:113]
	v_mfma_f32_16x16x32_bf16 v[218:221], v[168:171], v[202:205], v[106:109]
	s_setprio 0
	s_barrier
	s_nop 1
	ds_read_b128 v[106:109], v154
	ds_read_b128 v[110:113], v154 offset:1024
	ds_read_b128 v[222:225], v154 offset:2048
	ds_read_b128 v[226:229], v154 offset:3072
	s_barrier
; #define LDA(dst,b,h) for(int m=0;m<4;++m)for(int k=0;k<2;++k) \
;     dst[m][k]=*reinterpret_cast<const bf16x8*>((char*)SA(b,h)+lds_byte(wr*64+m*16+fr,k*32+fq*8))
; #define LDB(dst,b,h) for(int n=0;n<2;++n)for(int k=0;k<2;++k) \
;     dst[n][k]=*reinterpret_cast<const bf16x8*>((char*)SB(b,h)+lds_byte(wc*32+n*16+fr,k*32+fq*8))
; #define MMA(ai,bj,At,Bt_) do{__builtin_amdgcn_s_setprio(1); \
;     for(int m=0;m<4;++m)for(int n=0;n<2;++n)for(int k=0;k<2;++k) \
;       acc[ai][bj][m][n]=__builtin_amdgcn_mfma_f32_16x16x32_bf16(Bt_[n][k],At[m][k],acc[ai][bj][m][n],0,0,0); \
;     __builtin_amdgcn_s_setprio(0);}while(0)
; #define WAIT_V(n) asm volatile("s_waitcnt vmcnt(" #n ")":::"memory")
; #define WAIT_L(n) asm volatile("s_waitcnt lgkmcnt(" #n ")":::"memory")
; #define BAR __builtin_amdgcn_s_barrier()
; template <int EPI>
; __device__ __forceinline__ void gemm_run(const GD& c, const bool has_next, const GD& nx, const Ctx& e, bf16* shm, float* rs, float* rs_nxt, float* racc_) {
;     ...
;     LDB(B1,0,1); BAR; WAIT_L(0); MMA(0,1,At,B1); BAR;
;     LDA(At,0,1); WAIT_V(4); BAR; WAIT_L(0); MMA(1,0,At,B0); MMA(1,1,At,B1); BAR; }
;   { LDB(B0,1,0); LDA(At,1,0); WAIT_V(2); BAR; WAIT_L(0); MMA(0,0,At,B0); BAR;
	s_waitcnt lgkmcnt(0)
	s_setprio 1
	v_mfma_f32_16x16x32_bf16 v[86:89], v[106:109], v[190:193], v[86:89]
	v_mfma_f32_16x16x32_bf16 v[82:85], v[222:225], v[190:193], v[82:85]
	v_mfma_f32_16x16x32_bf16 v[70:73], v[106:109], v[206:209], v[70:73]
	v_mfma_f32_16x16x32_bf16 v[66:69], v[222:225], v[206:209], v[66:69]
	v_mfma_f32_16x16x32_bf16 v[94:97], v[106:109], v[172:175], v[94:97]
	v_mfma_f32_16x16x32_bf16 v[90:93], v[222:225], v[172:175], v[90:93]
	v_mfma_f32_16x16x32_bf16 v[86:89], v[110:113], v[194:197], v[86:89]
	v_mfma_f32_16x16x32_bf16 v[82:85], v[226:229], v[194:197], v[82:85]
	v_mfma_f32_16x16x32_bf16 v[78:81], v[106:109], v[198:201], v[78:81]
	v_mfma_f32_16x16x32_bf16 v[74:77], v[222:225], v[198:201], v[74:77]
	v_mfma_f32_16x16x32_bf16 v[70:73], v[110:113], v[210:213], v[70:73]
	v_mfma_f32_16x16x32_bf16 v[66:69], v[226:229], v[210:213], v[66:69]
	v_mfma_f32_16x16x32_bf16 v[230:233], v[110:113], v[186:189], v[94:97]
	v_mfma_f32_16x16x32_bf16 v[172:175], v[226:229], v[186:189], v[90:93]
	v_mfma_f32_16x16x32_bf16 v[186:189], v[110:113], v[202:205], v[78:81]
	v_mfma_f32_16x16x32_bf16 v[190:193], v[226:229], v[202:205], v[74:77]
	s_setprio 0
	s_barrier
	s_nop 0
	ds_read_b128 v[74:77], v146 offset:16384
	ds_read_b128 v[78:81], v146 offset:17408
	ds_read_b128 v[90:93], v145 offset:16384
	ds_read_b128 v[94:97], v145 offset:17408
	ds_read_b128 v[194:197], v144 offset:16384
	ds_read_b128 v[198:201], v144 offset:17408
	ds_read_b128 v[202:205], v143 offset:16384
	ds_read_b128 v[206:209], v143 offset:17408
	s_waitcnt vmcnt(4)
	s_barrier
	s_waitcnt lgkmcnt(0)
	s_setprio 1
	v_mfma_f32_16x16x32_bf16 v[62:65], v[132:135], v[74:77], v[62:65]
	v_mfma_f32_16x16x32_bf16 v[58:61], v[150:153], v[74:77], v[58:61]
	v_mfma_f32_16x16x32_bf16 v[54:57], v[132:135], v[90:93], v[54:57]
	v_mfma_f32_16x16x32_bf16 v[50:53], v[150:153], v[90:93], v[50:53]
	v_mfma_f32_16x16x32_bf16 v[38:41], v[132:135], v[202:205], v[38:41]
	v_mfma_f32_16x16x32_bf16 v[34:37], v[150:153], v[202:205], v[34:37]
	v_mfma_f32_16x16x32_bf16 v[62:65], v[136:139], v[78:81], v[62:65]
	v_mfma_f32_16x16x32_bf16 v[58:61], v[168:171], v[78:81], v[58:61]
	v_mfma_f32_16x16x32_bf16 v[54:57], v[136:139], v[94:97], v[54:57]
	v_mfma_f32_16x16x32_bf16 v[50:53], v[168:171], v[94:97], v[50:53]
	v_mfma_f32_16x16x32_bf16 v[46:49], v[132:135], v[194:197], v[46:49]
	v_mfma_f32_16x16x32_bf16 v[42:45], v[150:153], v[194:197], v[42:45]
	v_mfma_f32_16x16x32_bf16 v[38:41], v[136:139], v[206:209], v[38:41]
	v_mfma_f32_16x16x32_bf16 v[34:37], v[168:171], v[206:209], v[34:37]
	v_mfma_f32_16x16x32_bf16 v[210:213], v[136:139], v[198:201], v[46:49]
	v_mfma_f32_16x16x32_bf16 v[234:237], v[168:171], v[198:201], v[42:45]
	s_setprio 0
	s_setprio 1
	v_mfma_f32_16x16x32_bf16 v[22:25], v[106:109], v[90:93], v[22:25]
	v_mfma_f32_16x16x32_bf16 v[18:21], v[222:225], v[90:93], v[18:21]
	v_mfma_f32_16x16x32_bf16 v[6:9], v[106:109], v[202:205], v[6:9]
	v_mfma_f32_16x16x32_bf16 v[2:5], v[222:225], v[202:205], v[2:5]
	v_mfma_f32_16x16x32_bf16 v[30:33], v[106:109], v[74:77], v[30:33]
	v_mfma_f32_16x16x32_bf16 v[26:29], v[222:225], v[74:77], v[26:29]
	v_mfma_f32_16x16x32_bf16 v[22:25], v[110:113], v[94:97], v[22:25]
	v_mfma_f32_16x16x32_bf16 v[18:21], v[226:229], v[94:97], v[18:21]
	v_mfma_f32_16x16x32_bf16 v[14:17], v[106:109], v[194:197], v[14:17]
	v_mfma_f32_16x16x32_bf16 v[10:13], v[222:225], v[194:197], v[10:13]
	v_mfma_f32_16x16x32_bf16 v[6:9], v[110:113], v[206:209], v[6:9]
	v_mfma_f32_16x16x32_bf16 v[2:5], v[226:229], v[206:209], v[2:5]
	v_mfma_f32_16x16x32_bf16 v[132:135], v[110:113], v[78:81], v[30:33]
	v_mfma_f32_16x16x32_bf16 v[136:139], v[226:229], v[78:81], v[26:29]
	v_mfma_f32_16x16x32_bf16 v[150:153], v[110:113], v[198:201], v[14:17]
	v_mfma_f32_16x16x32_bf16 v[166:169], v[226:229], v[198:201], v[10:13]
	s_setprio 0
	s_barrier
	s_nop 0
	ds_read_b128 v[10:13], v149
	ds_read_b128 v[14:17], v149 offset:1024
	ds_read_b128 v[194:197], v149 offset:2048
	ds_read_b128 v[198:201], v149 offset:3072
	ds_read_b128 v[26:29], v146 offset:32768
	ds_read_b128 v[30:33], v146 offset:33792
	ds_read_b128 v[42:45], v145 offset:32768
	ds_read_b128 v[46:49], v145 offset:33792
	ds_read_b128 v[202:205], v144 offset:32768
	ds_read_b128 v[206:209], v144 offset:33792
	ds_read_b128 v[222:225], v143 offset:32768
	ds_read_b128 v[226:229], v143 offset:33792
	s_waitcnt vmcnt(2)
	s_barrier
; #define LDA(dst,b,h) for(int m=0;m<4;++m)for(int k=0;k<2;++k) \
;     dst[m][k]=*reinterpret_cast<const bf16x8*>((char*)SA(b,h)+lds_byte(wr*64+m*16+fr,k*32+fq*8))
; #define LDB(dst,b,h) for(int n=0;n<2;++n)for(int k=0;k<2;++k) \
;     dst[n][k]=*reinterpret_cast<const bf16x8*>((char*)SB(b,h)+lds_byte(wc*32+n*16+fr,k*32+fq*8))
; #define MMA(ai,bj,At,Bt_) do{__builtin_amdgcn_s_setprio(1); \
;     for(int m=0;m<4;++m)for(int n=0;n<2;++n)for(int k=0;k<2;++k) \
;       acc[ai][bj][m][n]=__builtin_amdgcn_mfma_f32_16x16x32_bf16(Bt_[n][k],At[m][k],acc[ai][bj][m][n],0,0,0); \
;     __builtin_amdgcn_s_setprio(0);}while(0)
; #define WAIT_V(n) asm volatile("s_waitcnt vmcnt(" #n ")":::"memory")
; #define WAIT_L(n) asm volatile("s_waitcnt lgkmcnt(" #n ")":::"memory")
; #define BAR __builtin_amdgcn_s_barrier()
; template <int EPI>
; __device__ __forceinline__ void gemm_run(const GD& c, const bool has_next, const GD& nx, const Ctx& e, bf16* shm, float* rs, float* rs_nxt, float* racc_) {
;     ...
;   { LDB(B0,1,0); LDA(At,1,0); WAIT_V(2); BAR; WAIT_L(0); MMA(0,0,At,B0); BAR;
;     LDB(B1,1,1); WAIT_V(0); BAR; WAIT_L(0); MMA(0,1,At,B1); BAR;
;     LDA(At,1,1); BAR; WAIT_L(0); MMA(1,0,At,B0); MMA(1,1,At,B1); BAR; }
;   if(wr==0)BAR;
	s_waitcnt lgkmcnt(0)
	s_setprio 1
	v_mfma_f32_16x16x32_bf16 v[74:77], v[10:13], v[26:29], v[126:129]
	v_mfma_f32_16x16x32_bf16 v[126:129], v[14:17], v[30:33], v[74:77]
	v_mfma_f32_16x16x32_bf16 v[74:77], v[194:197], v[26:29], v[122:125]
	v_mfma_f32_16x16x32_bf16 v[122:125], v[198:201], v[30:33], v[74:77]
	v_mfma_f32_16x16x32_bf16 v[74:77], v[10:13], v[42:45], v[118:121]
	v_mfma_f32_16x16x32_bf16 v[110:113], v[14:17], v[46:49], v[74:77]
	v_mfma_f32_16x16x32_bf16 v[74:77], v[194:197], v[42:45], v[114:117]
	v_mfma_f32_16x16x32_bf16 v[106:109], v[198:201], v[46:49], v[74:77]
	v_mfma_f32_16x16x32_bf16 v[74:77], v[10:13], v[202:205], v[214:217]
	v_mfma_f32_16x16x32_bf16 v[94:97], v[14:17], v[206:209], v[74:77]
	v_mfma_f32_16x16x32_bf16 v[74:77], v[194:197], v[202:205], v[218:221]
	v_mfma_f32_16x16x32_bf16 v[90:93], v[198:201], v[206:209], v[74:77]
	v_mfma_f32_16x16x32_bf16 v[74:77], v[10:13], v[222:225], v[102:105]
	v_mfma_f32_16x16x32_bf16 v[78:81], v[14:17], v[226:229], v[74:77]
	v_mfma_f32_16x16x32_bf16 v[74:77], v[194:197], v[222:225], v[98:101]
	v_mfma_f32_16x16x32_bf16 v[74:77], v[198:201], v[226:229], v[74:77]
	s_setprio 0
	s_barrier
	ds_read_b128 v[214:217], v147
	ds_read_b128 v[218:221], v147 offset:1024
	ds_read_b128 v[238:241], v147 offset:2048
	ds_read_b128 v[242:245], v147 offset:3072
	s_waitcnt vmcnt(0)
	s_barrier
	s_waitcnt lgkmcnt(0)
	s_setprio 1
	v_mfma_f32_16x16x32_bf16 v[98:101], v[214:217], v[26:29], v[230:233]
	v_mfma_f32_16x16x32_bf16 v[26:29], v[238:241], v[26:29], v[172:175]
	v_mfma_f32_16x16x32_bf16 v[114:117], v[242:245], v[30:33], v[26:29]
	v_mfma_f32_16x16x32_bf16 v[26:29], v[214:217], v[42:45], v[86:89]
	v_mfma_f32_16x16x32_bf16 v[102:105], v[218:221], v[46:49], v[26:29]
	v_mfma_f32_16x16x32_bf16 v[26:29], v[238:241], v[42:45], v[82:85]
	v_mfma_f32_16x16x32_bf16 v[118:121], v[218:221], v[30:33], v[98:101]
	v_mfma_f32_16x16x32_bf16 v[98:101], v[242:245], v[46:49], v[26:29]
	v_mfma_f32_16x16x32_bf16 v[26:29], v[214:217], v[202:205], v[186:189]
	v_mfma_f32_16x16x32_bf16 v[86:89], v[218:221], v[206:209], v[26:29]
	v_mfma_f32_16x16x32_bf16 v[26:29], v[238:241], v[202:205], v[190:193]
	v_mfma_f32_16x16x32_bf16 v[82:85], v[242:245], v[206:209], v[26:29]
	v_mfma_f32_16x16x32_bf16 v[26:29], v[214:217], v[222:225], v[70:73]
	v_mfma_f32_16x16x32_bf16 v[70:73], v[218:221], v[226:229], v[26:29]
	v_mfma_f32_16x16x32_bf16 v[26:29], v[238:241], v[222:225], v[66:69]
	v_mfma_f32_16x16x32_bf16 v[66:69], v[242:245], v[226:229], v[26:29]
	s_setprio 0
	s_barrier
	ds_read_b128 v[170:173], v146 offset:49152
	ds_read_b128 v[146:149], v146 offset:50176
	ds_read_b128 v[186:189], v145 offset:49152
	ds_read_b128 v[190:193], v145 offset:50176
	ds_read_b128 v[202:205], v144 offset:49152
	ds_read_b128 v[206:209], v144 offset:50176
	ds_read_b128 v[222:225], v143 offset:49152
	ds_read_b128 v[226:229], v143 offset:50176
	s_barrier
	s_waitcnt lgkmcnt(0)
	s_setprio 1
	v_mfma_f32_16x16x32_bf16 v[26:29], v[10:13], v[170:173], v[62:65]
	v_mfma_f32_16x16x32_bf16 v[62:65], v[14:17], v[146:149], v[26:29]
	v_mfma_f32_16x16x32_bf16 v[26:29], v[194:197], v[170:173], v[58:61]
	v_mfma_f32_16x16x32_bf16 v[58:61], v[198:201], v[146:149], v[26:29]
	v_mfma_f32_16x16x32_bf16 v[26:29], v[10:13], v[186:189], v[54:57]
	v_mfma_f32_16x16x32_bf16 v[46:49], v[14:17], v[190:193], v[26:29]
	v_mfma_f32_16x16x32_bf16 v[26:29], v[194:197], v[186:189], v[50:53]
	v_mfma_f32_16x16x32_bf16 v[42:45], v[198:201], v[190:193], v[26:29]
	v_mfma_f32_16x16x32_bf16 v[26:29], v[10:13], v[202:205], v[210:213]
	v_mfma_f32_16x16x32_bf16 v[10:13], v[10:13], v[222:225], v[38:41]
	v_mfma_f32_16x16x32_bf16 v[30:33], v[14:17], v[206:209], v[26:29]
	v_mfma_f32_16x16x32_bf16 v[26:29], v[194:197], v[202:205], v[234:237]
	v_mfma_f32_16x16x32_bf16 v[14:17], v[14:17], v[226:229], v[10:13]
	v_mfma_f32_16x16x32_bf16 v[10:13], v[194:197], v[222:225], v[34:37]
	v_mfma_f32_16x16x32_bf16 v[26:29], v[198:201], v[206:209], v[26:29]
	v_mfma_f32_16x16x32_bf16 v[10:13], v[198:201], v[226:229], v[10:13]
	s_setprio 0
	s_setprio 1
	v_mfma_f32_16x16x32_bf16 v[34:37], v[214:217], v[170:173], v[132:135]
	v_mfma_f32_16x16x32_bf16 v[54:57], v[218:221], v[146:149], v[34:37]
	v_mfma_f32_16x16x32_bf16 v[34:37], v[238:241], v[170:173], v[136:139]
	v_mfma_f32_16x16x32_bf16 v[18:21], v[238:241], v[186:189], v[18:21]
	v_mfma_f32_16x16x32_bf16 v[50:53], v[242:245], v[146:149], v[34:37]
	v_mfma_f32_16x16x32_bf16 v[22:25], v[214:217], v[186:189], v[22:25]
	v_mfma_f32_16x16x32_bf16 v[34:37], v[242:245], v[190:193], v[18:21]
	v_mfma_f32_16x16x32_bf16 v[18:21], v[214:217], v[202:205], v[150:153]
	v_mfma_f32_16x16x32_bf16 v[38:41], v[218:221], v[190:193], v[22:25]
	v_mfma_f32_16x16x32_bf16 v[22:25], v[218:221], v[206:209], v[18:21]
	v_mfma_f32_16x16x32_bf16 v[18:21], v[238:241], v[202:205], v[166:169]
	v_mfma_f32_16x16x32_bf16 v[6:9], v[214:217], v[222:225], v[6:9]
	v_mfma_f32_16x16x32_bf16 v[2:5], v[238:241], v[222:225], v[2:5]
	v_mfma_f32_16x16x32_bf16 v[18:21], v[242:245], v[206:209], v[18:21]
	v_mfma_f32_16x16x32_bf16 v[6:9], v[218:221], v[226:229], v[6:9]
	v_mfma_f32_16x16x32_bf16 v[2:5], v[242:245], v[226:229], v[2:5]
	s_setprio 0
	v_cmp_gt_u32_e32 vcc, s96, v141
	s_barrier
	s_and_saveexec_b64 s[2:3], vcc
	s_cbranch_execz .LBB0_1038
	s_barrier

; #define STAGE_A(P,br,kt) STAGE_G(P,c.A,c.lda,br,(long)(kt)*c.kstr)
; #define STAGE_B(P,br,kt) STAGE_G(P,c.Bt,c.K,br,(long)(kt)*BK)
; #define LDA(dst,b,h) for(int m=0;m<4;++m)for(int k=0;k<2;++k) \
;     dst[m][k]=*reinterpret_cast<const bf16x8*>((char*)SA(b,h)+lds_byte(wr*64+m*16+fr,k*32+fq*8))
; #define LDB(dst,b,h) for(int n=0;n<2;++n)for(int k=0;k<2;++k) \
;     dst[n][k]=*reinterpret_cast<const bf16x8*>((char*)SB(b,h)+lds_byte(wc*32+n*16+fr,k*32+fq*8))
; #define MMA(ai,bj,At,Bt_) do{__builtin_amdgcn_s_setprio(1); \
;     for(int m=0;m<4;++m)for(int n=0;n<2;++n)for(int k=0;k<2;++k) \
;       acc[ai][bj][m][n]=__builtin_amdgcn_mfma_f32_16x16x32_bf16(Bt_[n][k],At[m][k],acc[ai][bj][m][n],0,0,0); \
;     __builtin_amdgcn_s_setprio(0);}while(0)
; #define WAIT_V(n) asm volatile("s_waitcnt vmcnt(" #n ")":::"memory")
; #define WAIT_L(n) asm volatile("s_waitcnt lgkmcnt(" #n ")":::"memory")
; #define BAR __builtin_amdgcn_s_barrier()
; #define SCHED __builtin_amdgcn_sched_barrier(0)
; template <int EPI>
; __device__ __forceinline__ void gemm_run(const GD& c, const bool has_next, const GD& nx, const Ctx& e, bf16* shm, float* rs, float* rs_nxt, float* racc_) {
;     ...
;   for(int t=0;t<nt-2;t+=2){
;     LDB(B0,0,0); SCHED; LDA(At,0,0); STAGE_A(SA(1,1),brow+HALF,t+1);
;     WAIT_L(8); BAR; WAIT_L(0); MMA(0,0,At,B0); BAR; SCHED;
;     LDB(B1,0,1); STAGE_B(SB(0,0),bcol,t+2);
;     BAR; WAIT_L(0); MMA(0,1,At,B1); BAR;
;     LDA(At,0,1); STAGE_A(SA(0,0),brow,t+2);
;     BAR; WAIT_L(0); MMA(1,0,At,B0); BAR; SCHED;
;     STAGE_B(SB(0,1),bcol+HALF,t+2);
;     WAIT_V(6); BAR; MMA(1,1,At,B1); BAR;
.LBB0_1119:
	ds_read_b128 v[168:171], v155
	ds_read_b128 v[172:175], v155 offset:1024
	ds_read_b128 v[186:189], v155 offset:2048
	ds_read_b128 v[190:193], v155 offset:3072
	v_add_u32_e32 v163, 0xc000, v142
	v_lshl_add_u64 v[182:183], s[4:5], 0, v[130:131]
	v_readfirstlane_b32 s3, v163
	v_add_u32_e32 v166, 0xe000, v142
	v_lshl_add_u64 v[156:157], v[182:183], 0, s[94:95]
	s_mov_b32 m0, s3
	v_lshl_add_u64 v[242:243], s[4:5], 0, v[132:133]
	v_readfirstlane_b32 s3, v166
	ds_read_b128 v[158:161], v146
	ds_read_b128 v[194:197], v146 offset:1024
	ds_read_b128 v[198:201], v145
	ds_read_b128 v[202:205], v145 offset:1024
	ds_read_b128 v[206:209], v144
	ds_read_b128 v[210:213], v144 offset:1024
	ds_read_b128 v[214:217], v143
	ds_read_b128 v[218:221], v143 offset:1024
	global_load_lds_dwordx4 v[156:157], off
	v_lshl_add_u64 v[156:157], v[242:243], 0, s[94:95]
	s_mov_b32 m0, s3
	s_nop 0
	global_load_lds_dwordx4 v[156:157], off
	s_waitcnt lgkmcnt(8)
	s_barrier
	s_waitcnt lgkmcnt(0)
	s_setprio 1
	v_mfma_f32_16x16x32_bf16 v[126:129], v[168:171], v[158:161], v[126:129]
	v_mfma_f32_16x16x32_bf16 v[122:125], v[186:189], v[158:161], v[122:125]
	v_mfma_f32_16x16x32_bf16 v[118:121], v[168:171], v[198:201], v[118:121]
	v_mfma_f32_16x16x32_bf16 v[114:117], v[186:189], v[198:201], v[114:117]
	v_mfma_f32_16x16x32_bf16 v[110:113], v[168:171], v[206:209], v[110:113]
	v_mfma_f32_16x16x32_bf16 v[106:109], v[186:189], v[206:209], v[106:109]
	v_mfma_f32_16x16x32_bf16 v[102:105], v[168:171], v[214:217], v[102:105]
	v_mfma_f32_16x16x32_bf16 v[98:101], v[186:189], v[214:217], v[98:101]
	v_mfma_f32_16x16x32_bf16 v[126:129], v[172:175], v[194:197], v[126:129]
	v_mfma_f32_16x16x32_bf16 v[122:125], v[190:193], v[194:197], v[122:125]
	v_mfma_f32_16x16x32_bf16 v[118:121], v[172:175], v[202:205], v[118:121]
	v_mfma_f32_16x16x32_bf16 v[114:117], v[190:193], v[202:205], v[114:117]
	v_mfma_f32_16x16x32_bf16 v[110:113], v[172:175], v[210:213], v[110:113]
	v_mfma_f32_16x16x32_bf16 v[106:109], v[190:193], v[210:213], v[106:109]
	v_mfma_f32_16x16x32_bf16 v[102:105], v[172:175], v[218:221], v[102:105]
	v_mfma_f32_16x16x32_bf16 v[98:101], v[190:193], v[218:221], v[98:101]
	s_setprio 0
	s_barrier
	v_add_u32_e32 v156, s33, v148
	v_lshl_add_u64 v[244:245], s[4:5], 0, v[136:137]
	v_readfirstlane_b32 s3, v156
	v_add_u32_e32 v157, 0x2000, v156
	v_lshl_add_u64 v[238:239], v[244:245], 0, s[14:15]
	s_mov_b32 m0, s3
	v_lshl_add_u64 v[246:247], s[4:5], 0, v[138:139]
	v_readfirstlane_b32 s3, v157
	ds_read_b128 v[222:225], v154
	ds_read_b128 v[226:229], v154 offset:1024
	ds_read_b128 v[230:233], v154 offset:2048
	ds_read_b128 v[234:237], v154 offset:3072
	global_load_lds_dwordx4 v[238:239], off
	v_lshl_add_u64 v[238:239], v[246:247], 0, s[14:15]
	s_mov_b32 m0, s3
	s_nop 0
	global_load_lds_dwordx4 v[238:239], off
	s_barrier
	s_waitcnt lgkmcnt(0)
	s_setprio 1
	v_mfma_f32_16x16x32_bf16 v[94:97], v[222:225], v[158:161], v[94:97]
	v_mfma_f32_16x16x32_bf16 v[90:93], v[230:233], v[158:161], v[90:93]
	v_mfma_f32_16x16x32_bf16 v[86:89], v[222:225], v[198:201], v[86:89]
	v_mfma_f32_16x16x32_bf16 v[82:85], v[230:233], v[198:201], v[82:85]
	v_mfma_f32_16x16x32_bf16 v[78:81], v[222:225], v[206:209], v[78:81]
	v_mfma_f32_16x16x32_bf16 v[74:77], v[230:233], v[206:209], v[74:77]
	v_mfma_f32_16x16x32_bf16 v[70:73], v[222:225], v[214:217], v[70:73]
	v_mfma_f32_16x16x32_bf16 v[66:69], v[230:233], v[214:217], v[66:69]
	v_mfma_f32_16x16x32_bf16 v[94:97], v[226:229], v[194:197], v[94:97]
	v_mfma_f32_16x16x32_bf16 v[90:93], v[234:237], v[194:197], v[90:93]
	v_mfma_f32_16x16x32_bf16 v[86:89], v[226:229], v[202:205], v[86:89]
	v_mfma_f32_16x16x32_bf16 v[82:85], v[234:237], v[202:205], v[82:85]
	v_mfma_f32_16x16x32_bf16 v[78:81], v[226:229], v[210:213], v[78:81]
	v_mfma_f32_16x16x32_bf16 v[74:77], v[234:237], v[210:213], v[74:77]
	v_mfma_f32_16x16x32_bf16 v[70:73], v[226:229], v[218:221], v[70:73]
	v_mfma_f32_16x16x32_bf16 v[66:69], v[234:237], v[218:221], v[66:69]
	s_setprio 0
	v_readfirstlane_b32 s3, v142
	v_lshl_add_u64 v[158:159], v[182:183], 0, s[84:85]
	s_mov_b32 m0, s3
	s_barrier
	ds_read_b128 v[194:197], v146 offset:16384
	ds_read_b128 v[198:201], v146 offset:17408
	ds_read_b128 v[202:205], v145 offset:16384
	ds_read_b128 v[206:209], v145 offset:17408
	ds_read_b128 v[210:213], v144 offset:16384
	ds_read_b128 v[214:217], v144 offset:17408
	ds_read_b128 v[218:221], v143 offset:16384
	ds_read_b128 v[238:241], v143 offset:17408
	global_load_lds_dwordx4 v[158:159], off
	v_add_u32_e32 v158, 0x2000, v142
	v_lshl_add_u64 v[160:161], v[242:243], 0, s[84:85]
	v_readfirstlane_b32 s3, v158
	s_mov_b32 m0, s3
	s_nop 0
	global_load_lds_dwordx4 v[160:161], off
	s_barrier
	s_waitcnt lgkmcnt(0)
	s_setprio 1
	v_mfma_f32_16x16x32_bf16 v[62:65], v[168:171], v[194:197], v[62:65]
	v_mfma_f32_16x16x32_bf16 v[58:61], v[186:189], v[194:197], v[58:61]
	v_mfma_f32_16x16x32_bf16 v[54:57], v[168:171], v[202:205], v[54:57]
	v_mfma_f32_16x16x32_bf16 v[50:53], v[186:189], v[202:205], v[50:53]
	v_mfma_f32_16x16x32_bf16 v[46:49], v[168:171], v[210:213], v[46:49]
	v_mfma_f32_16x16x32_bf16 v[42:45], v[186:189], v[210:213], v[42:45]
	v_mfma_f32_16x16x32_bf16 v[38:41], v[168:171], v[218:221], v[38:41]
	v_mfma_f32_16x16x32_bf16 v[34:37], v[186:189], v[218:221], v[34:37]
	v_mfma_f32_16x16x32_bf16 v[62:65], v[172:175], v[198:201], v[62:65]
	v_mfma_f32_16x16x32_bf16 v[58:61], v[190:193], v[198:201], v[58:61]
	v_mfma_f32_16x16x32_bf16 v[54:57], v[172:175], v[206:209], v[54:57]
	v_mfma_f32_16x16x32_bf16 v[50:53], v[190:193], v[206:209], v[50:53]
	v_mfma_f32_16x16x32_bf16 v[46:49], v[172:175], v[214:217], v[46:49]
	v_mfma_f32_16x16x32_bf16 v[42:45], v[190:193], v[214:217], v[42:45]
	v_mfma_f32_16x16x32_bf16 v[38:41], v[172:175], v[238:241], v[38:41]
	v_mfma_f32_16x16x32_bf16 v[34:37], v[190:193], v[238:241], v[34:37]
	s_setprio 0
	s_barrier
; #define STAGE_A(P,br,kt) STAGE_G(P,c.A,c.lda,br,(long)(kt)*c.kstr)
; #define STAGE_B(P,br,kt) STAGE_G(P,c.Bt,c.K,br,(long)(kt)*BK)
; #define LDA(dst,b,h) for(int m=0;m<4;++m)for(int k=0;k<2;++k) \
;     dst[m][k]=*reinterpret_cast<const bf16x8*>((char*)SA(b,h)+lds_byte(wr*64+m*16+fr,k*32+fq*8))
; #define LDB(dst,b,h) for(int n=0;n<2;++n)for(int k=0;k<2;++k) \
;     dst[n][k]=*reinterpret_cast<const bf16x8*>((char*)SB(b,h)+lds_byte(wc*32+n*16+fr,k*32+fq*8))
; #define MMA(ai,bj,At,Bt_) do{__builtin_amdgcn_s_setprio(1); \
;     for(int m=0;m<4;++m)for(int n=0;n<2;++n)for(int k=0;k<2;++k) \
;       acc[ai][bj][m][n]=__builtin_amdgcn_mfma_f32_16x16x32_bf16(Bt_[n][k],At[m][k],acc[ai][bj][m][n],0,0,0); \
;     __builtin_amdgcn_s_setprio(0);}while(0)
; #define WAIT_V(n) asm volatile("s_waitcnt vmcnt(" #n ")":::"memory")
; #define WAIT_L(n) asm volatile("s_waitcnt lgkmcnt(" #n ")":::"memory")
; #define BAR __builtin_amdgcn_s_barrier()
; #define SCHED __builtin_amdgcn_sched_barrier(0)
; template <int EPI>
; __device__ __forceinline__ void gemm_run(const GD& c, const bool has_next, const GD& nx, const Ctx& e, bf16* shm, float* rs, float* rs_nxt, float* racc_) {
;     ...
;     WAIT_V(6); BAR; MMA(1,1,At,B1); BAR;
;     LDB(B0,1,0); SCHED; LDA(At,1,0); STAGE_A(SA(0,1),brow+HALF,t+2);
;     WAIT_L(8); BAR; WAIT_L(0); MMA(0,0,At,B0); BAR; SCHED;
;     LDB(B1,1,1); STAGE_B(SB(1,0),bcol,t+3);
;     BAR; WAIT_L(0); MMA(0,1,At,B1); BAR;
;     LDA(At,1,1); STAGE_A(SA(1,0),brow,t+3);
;     BAR; WAIT_L(0); MMA(1,0,At,B0); BAR; SCHED;
	v_add_u32_e32 v159, s86, v148
	v_lshl_add_u64 v[160:161], v[244:245], 0, s[26:27]
	v_readfirstlane_b32 s3, v159
	s_mov_b32 m0, s3
	v_lshl_add_u64 v[168:169], v[246:247], 0, s[26:27]
	global_load_lds_dwordx4 v[160:161], off
	v_add_u32_e32 v160, 0x2000, v159
	s_nop 0
	v_readfirstlane_b32 s3, v160
	s_mov_b32 m0, s3
	s_nop 0
	global_load_lds_dwordx4 v[168:169], off
	s_waitcnt vmcnt(6)
	s_barrier
	s_setprio 1
	v_mfma_f32_16x16x32_bf16 v[30:33], v[222:225], v[194:197], v[30:33]
	v_mfma_f32_16x16x32_bf16 v[26:29], v[230:233], v[194:197], v[26:29]
	v_mfma_f32_16x16x32_bf16 v[22:25], v[222:225], v[202:205], v[22:25]
	v_mfma_f32_16x16x32_bf16 v[18:21], v[230:233], v[202:205], v[18:21]
	v_mfma_f32_16x16x32_bf16 v[14:17], v[222:225], v[210:213], v[14:17]
	v_mfma_f32_16x16x32_bf16 v[10:13], v[230:233], v[210:213], v[10:13]
	v_mfma_f32_16x16x32_bf16 v[6:9], v[222:225], v[218:221], v[6:9]
	v_mfma_f32_16x16x32_bf16 v[2:5], v[230:233], v[218:221], v[2:5]
	v_mfma_f32_16x16x32_bf16 v[30:33], v[226:229], v[198:201], v[30:33]
	v_mfma_f32_16x16x32_bf16 v[26:29], v[234:237], v[198:201], v[26:29]
	v_mfma_f32_16x16x32_bf16 v[22:25], v[226:229], v[206:209], v[22:25]
	v_mfma_f32_16x16x32_bf16 v[18:21], v[234:237], v[206:209], v[18:21]
	v_mfma_f32_16x16x32_bf16 v[14:17], v[226:229], v[214:217], v[14:17]
	v_mfma_f32_16x16x32_bf16 v[10:13], v[234:237], v[214:217], v[10:13]
	v_mfma_f32_16x16x32_bf16 v[6:9], v[226:229], v[238:241], v[6:9]
	v_mfma_f32_16x16x32_bf16 v[2:5], v[234:237], v[238:241], v[2:5]
	s_setprio 0
	s_barrier
	ds_read_b128 v[168:171], v149
	ds_read_b128 v[172:175], v149 offset:1024
	ds_read_b128 v[186:189], v149 offset:2048
	ds_read_b128 v[190:193], v149 offset:3072
	v_add_u32_e32 v161, 0x4000, v142
	v_add_u32_e32 v162, 0x6000, v142
	v_readfirstlane_b32 s3, v161
	v_lshl_add_u64 v[226:227], v[182:183], 0, s[92:93]
	s_mov_b32 m0, s3
	v_readfirstlane_b32 s3, v162
	ds_read_b128 v[194:197], v146 offset:32768
	ds_read_b128 v[198:201], v146 offset:33792
	ds_read_b128 v[202:205], v145 offset:32768
	ds_read_b128 v[206:209], v145 offset:33792
	ds_read_b128 v[210:213], v144 offset:32768
	ds_read_b128 v[214:217], v144 offset:33792
	ds_read_b128 v[218:221], v143 offset:32768
	ds_read_b128 v[222:225], v143 offset:33792
	global_load_lds_dwordx4 v[226:227], off
	v_lshl_add_u64 v[226:227], v[242:243], 0, s[92:93]
	s_mov_b32 m0, s3
	s_nop 0
	global_load_lds_dwordx4 v[226:227], off
	s_waitcnt lgkmcnt(8)
	s_barrier
	s_waitcnt lgkmcnt(0)
	s_setprio 1
	v_mfma_f32_16x16x32_bf16 v[126:129], v[168:171], v[194:197], v[126:129]
	v_mfma_f32_16x16x32_bf16 v[122:125], v[186:189], v[194:197], v[122:125]
	v_mfma_f32_16x16x32_bf16 v[118:121], v[168:171], v[202:205], v[118:121]
	v_mfma_f32_16x16x32_bf16 v[114:117], v[186:189], v[202:205], v[114:117]
	v_mfma_f32_16x16x32_bf16 v[110:113], v[168:171], v[210:213], v[110:113]
	v_mfma_f32_16x16x32_bf16 v[106:109], v[186:189], v[210:213], v[106:109]
	v_mfma_f32_16x16x32_bf16 v[102:105], v[168:171], v[218:221], v[102:105]
	v_mfma_f32_16x16x32_bf16 v[98:101], v[186:189], v[218:221], v[98:101]
	v_mfma_f32_16x16x32_bf16 v[126:129], v[172:175], v[198:201], v[126:129]
	v_mfma_f32_16x16x32_bf16 v[122:125], v[190:193], v[198:201], v[122:125]
	v_mfma_f32_16x16x32_bf16 v[118:121], v[172:175], v[206:209], v[118:121]
	v_mfma_f32_16x16x32_bf16 v[114:117], v[190:193], v[206:209], v[114:117]
	v_mfma_f32_16x16x32_bf16 v[110:113], v[172:175], v[214:217], v[110:113]
	v_mfma_f32_16x16x32_bf16 v[106:109], v[190:193], v[214:217], v[106:109]
	v_mfma_f32_16x16x32_bf16 v[102:105], v[172:175], v[222:225], v[102:105]
	v_mfma_f32_16x16x32_bf16 v[98:101], v[190:193], v[222:225], v[98:101]
	s_setprio 0
	s_barrier
	v_readfirstlane_b32 s3, v150
	v_add_u32_e32 v167, 0x2000, v150
	v_lshl_add_u64 v[248:249], v[244:245], 0, s[28:29]
	s_mov_b32 m0, s3
	v_readfirstlane_b32 s3, v167
	ds_read_b128 v[226:229], v147
	ds_read_b128 v[230:233], v147 offset:1024
	ds_read_b128 v[234:237], v147 offset:2048
	ds_read_b128 v[238:241], v147 offset:3072
	global_load_lds_dwordx4 v[248:249], off
	v_lshl_add_u64 v[248:249], v[246:247], 0, s[28:29]
	s_mov_b32 m0, s3
	s_nop 0
	global_load_lds_dwordx4 v[248:249], off
	s_barrier
	s_waitcnt lgkmcnt(0)
	s_setprio 1
	v_mfma_f32_16x16x32_bf16 v[94:97], v[226:229], v[194:197], v[94:97]
	v_mfma_f32_16x16x32_bf16 v[90:93], v[234:237], v[194:197], v[90:93]
	v_mfma_f32_16x16x32_bf16 v[86:89], v[226:229], v[202:205], v[86:89]
	v_mfma_f32_16x16x32_bf16 v[82:85], v[234:237], v[202:205], v[82:85]
	v_mfma_f32_16x16x32_bf16 v[78:81], v[226:229], v[210:213], v[78:81]
	v_mfma_f32_16x16x32_bf16 v[74:77], v[234:237], v[210:213], v[74:77]
	v_mfma_f32_16x16x32_bf16 v[70:73], v[226:229], v[218:221], v[70:73]
	v_mfma_f32_16x16x32_bf16 v[66:69], v[234:237], v[218:221], v[66:69]
	v_mfma_f32_16x16x32_bf16 v[94:97], v[230:233], v[198:201], v[94:97]
	v_mfma_f32_16x16x32_bf16 v[90:93], v[238:241], v[198:201], v[90:93]
	v_mfma_f32_16x16x32_bf16 v[86:89], v[230:233], v[206:209], v[86:89]
	v_mfma_f32_16x16x32_bf16 v[82:85], v[238:241], v[206:209], v[82:85]
	v_mfma_f32_16x16x32_bf16 v[78:81], v[230:233], v[214:217], v[78:81]
	v_mfma_f32_16x16x32_bf16 v[74:77], v[238:241], v[214:217], v[74:77]
	v_mfma_f32_16x16x32_bf16 v[70:73], v[230:233], v[222:225], v[70:73]
	v_mfma_f32_16x16x32_bf16 v[66:69], v[238:241], v[222:225], v[66:69]
	s_setprio 0
	v_readfirstlane_b32 s3, v151
	v_lshl_add_u64 v[182:183], v[182:183], 0, s[80:81]
	s_mov_b32 m0, s3
	v_readfirstlane_b32 s3, v152
	s_barrier
; #define STAGE_A(P,br,kt) STAGE_G(P,c.A,c.lda,br,(long)(kt)*c.kstr)
; #define STAGE_B(P,br,kt) STAGE_G(P,c.Bt,c.K,br,(long)(kt)*BK)
; #define LDA(dst,b,h) for(int m=0;m<4;++m)for(int k=0;k<2;++k) \
;     dst[m][k]=*reinterpret_cast<const bf16x8*>((char*)SA(b,h)+lds_byte(wr*64+m*16+fr,k*32+fq*8))
; #define LDB(dst,b,h) for(int n=0;n<2;++n)for(int k=0;k<2;++k) \
;     dst[n][k]=*reinterpret_cast<const bf16x8*>((char*)SB(b,h)+lds_byte(wc*32+n*16+fr,k*32+fq*8))
; #define MMA(ai,bj,At,Bt_) do{__builtin_amdgcn_s_setprio(1); \
;     for(int m=0;m<4;++m)for(int n=0;n<2;++n)for(int k=0;k<2;++k) \
;       acc[ai][bj][m][n]=__builtin_amdgcn_mfma_f32_16x16x32_bf16(Bt_[n][k],At[m][k],acc[ai][bj][m][n],0,0,0); \
;     __builtin_amdgcn_s_setprio(0);}while(0)
; #define WAIT_V(n) asm volatile("s_waitcnt vmcnt(" #n ")":::"memory")
; #define WAIT_L(n) asm volatile("s_waitcnt lgkmcnt(" #n ")":::"memory")
; #define BAR __builtin_amdgcn_s_barrier()
; #define SCHED __builtin_amdgcn_sched_barrier(0)
; template <int EPI>
; __device__ __forceinline__ void gemm_run(const GD& c, const bool has_next, const GD& nx, const Ctx& e, bf16* shm, float* rs, float* rs_nxt, float* racc_) {
;     ...
;     BAR; WAIT_L(0); MMA(1,0,At,B0); BAR; SCHED;
;     STAGE_B(SB(1,1),bcol+HALF,t+3);
;     WAIT_V(6); BAR; MMA(1,1,At,B1); BAR;
;   }
;   { LDB(B0,0,0); LDA(At,0,0); STAGE_A(SA(1,1),brow+HALF,nt-1);
;     BAR; WAIT_L(0); MMA(0,0,At,B0); BAR;
	ds_read_b128 v[194:197], v146 offset:49152
	ds_read_b128 v[198:201], v146 offset:50176
	ds_read_b128 v[202:205], v145 offset:49152
	ds_read_b128 v[206:209], v145 offset:50176
	ds_read_b128 v[210:213], v144 offset:49152
	ds_read_b128 v[214:217], v144 offset:50176
	ds_read_b128 v[218:221], v143 offset:49152
	ds_read_b128 v[222:225], v143 offset:50176
	global_load_lds_dwordx4 v[182:183], off
	v_lshl_add_u64 v[182:183], v[242:243], 0, s[80:81]
	s_mov_b32 m0, s3
	s_nop 0
	global_load_lds_dwordx4 v[182:183], off
	s_barrier
	s_waitcnt lgkmcnt(0)
	s_setprio 1
	v_mfma_f32_16x16x32_bf16 v[62:65], v[168:171], v[194:197], v[62:65]
	v_mfma_f32_16x16x32_bf16 v[58:61], v[186:189], v[194:197], v[58:61]
	v_mfma_f32_16x16x32_bf16 v[54:57], v[168:171], v[202:205], v[54:57]
	v_mfma_f32_16x16x32_bf16 v[50:53], v[186:189], v[202:205], v[50:53]
	v_mfma_f32_16x16x32_bf16 v[46:49], v[168:171], v[210:213], v[46:49]
	v_mfma_f32_16x16x32_bf16 v[42:45], v[186:189], v[210:213], v[42:45]
	v_mfma_f32_16x16x32_bf16 v[38:41], v[168:171], v[218:221], v[38:41]
	v_mfma_f32_16x16x32_bf16 v[34:37], v[186:189], v[218:221], v[34:37]
	v_mfma_f32_16x16x32_bf16 v[62:65], v[172:175], v[198:201], v[62:65]
	v_mfma_f32_16x16x32_bf16 v[58:61], v[190:193], v[198:201], v[58:61]
	v_mfma_f32_16x16x32_bf16 v[54:57], v[172:175], v[206:209], v[54:57]
	v_mfma_f32_16x16x32_bf16 v[50:53], v[190:193], v[206:209], v[50:53]
	v_mfma_f32_16x16x32_bf16 v[46:49], v[172:175], v[214:217], v[46:49]
	v_mfma_f32_16x16x32_bf16 v[42:45], v[190:193], v[214:217], v[42:45]
	v_mfma_f32_16x16x32_bf16 v[38:41], v[172:175], v[222:225], v[38:41]
	v_mfma_f32_16x16x32_bf16 v[34:37], v[190:193], v[222:225], v[34:37]
	s_setprio 0
	s_barrier
	v_readfirstlane_b32 s3, v153
	v_add_u32_e32 v167, 0x2000, v153
	v_lshl_add_u64 v[168:169], v[244:245], 0, s[30:31]
	s_mov_b32 m0, s3
	v_readfirstlane_b32 s3, v167
	global_load_lds_dwordx4 v[168:169], off
	v_lshl_add_u64 v[168:169], v[246:247], 0, s[30:31]
	s_mov_b32 m0, s3
	s_nop 0
	global_load_lds_dwordx4 v[168:169], off
	s_waitcnt vmcnt(6)
	s_barrier
	s_setprio 1
	v_mfma_f32_16x16x32_bf16 v[30:33], v[226:229], v[194:197], v[30:33]
	v_mfma_f32_16x16x32_bf16 v[26:29], v[234:237], v[194:197], v[26:29]
	v_mfma_f32_16x16x32_bf16 v[22:25], v[226:229], v[202:205], v[22:25]
	v_mfma_f32_16x16x32_bf16 v[18:21], v[234:237], v[202:205], v[18:21]
	v_mfma_f32_16x16x32_bf16 v[14:17], v[226:229], v[210:213], v[14:17]
	v_mfma_f32_16x16x32_bf16 v[10:13], v[234:237], v[210:213], v[10:13]
	v_mfma_f32_16x16x32_bf16 v[6:9], v[226:229], v[218:221], v[6:9]
	v_mfma_f32_16x16x32_bf16 v[2:5], v[234:237], v[218:221], v[2:5]
	v_mfma_f32_16x16x32_bf16 v[30:33], v[230:233], v[198:201], v[30:33]
	v_mfma_f32_16x16x32_bf16 v[26:29], v[238:241], v[198:201], v[26:29]
	v_mfma_f32_16x16x32_bf16 v[22:25], v[230:233], v[206:209], v[22:25]
	v_mfma_f32_16x16x32_bf16 v[18:21], v[238:241], v[206:209], v[18:21]
	v_mfma_f32_16x16x32_bf16 v[14:17], v[230:233], v[214:217], v[14:17]
	v_mfma_f32_16x16x32_bf16 v[10:13], v[238:241], v[214:217], v[10:13]
	v_mfma_f32_16x16x32_bf16 v[6:9], v[230:233], v[222:225], v[6:9]
	v_mfma_f32_16x16x32_bf16 v[2:5], v[238:241], v[222:225], v[2:5]
	s_setprio 0
	s_add_i32 s2, s2, 2
	v_lshl_add_u64 v[130:131], v[130:131], 0, s[88:89]
	v_lshl_add_u64 v[132:133], v[132:133], 0, s[88:89]
	v_lshl_add_u64 v[136:137], v[136:137], 0, s[88:89]
	s_cmp_lt_u32 s2, 12
	v_lshl_add_u64 v[138:139], v[138:139], 0, s[88:89]
	s_barrier
	s_cbranch_scc1 .LBB0_1119
	s_or_b32 s2, s10, 0x80
	s_ashr_i32 s3, s2, 31
	s_lshl_b64 s[2:3], s[2:3], 11
	s_add_u32 s2, s18, s2
	s_addc_u32 s3, s19, s3
	v_lshl_add_u64 v[182:183], s[2:3], 0, v[0:1]
	s_mov_b64 s[14:15], 0x780
	v_readfirstlane_b32 s11, v163
	v_lshl_add_u64 v[182:183], v[182:183], 0, s[14:15]
	s_mov_b32 m0, s11
	ds_read_b128 v[130:133], v155
	ds_read_b128 v[136:139], v155 offset:1024
	ds_read_b128 v[150:153], v155 offset:2048
	ds_read_b128 v[168:171], v155 offset:3072
	ds_read_b128 v[172:175], v146
	ds_read_b128 v[186:189], v146 offset:1024
	ds_read_b128 v[190:193], v145
	ds_read_b128 v[194:197], v145 offset:1024
	ds_read_b128 v[198:201], v144
	ds_read_b128 v[202:205], v144 offset:1024
	ds_read_b128 v[206:209], v143
	ds_read_b128 v[210:213], v143 offset:1024
	global_load_lds_dwordx4 v[182:183], off
	v_lshl_add_u64 v[182:183], s[2:3], 0, v[134:135]
	v_readfirstlane_b32 s2, v166
	v_lshl_add_u64 v[182:183], v[182:183], 0, s[14:15]
	s_mov_b32 m0, s2
	s_nop 0
	global_load_lds_dwordx4 v[182:183], off
	s_barrier
	s_waitcnt lgkmcnt(0)
	s_setprio 1
	v_mfma_f32_16x16x32_bf16 v[126:129], v[130:133], v[172:175], v[126:129]
	v_mfma_f32_16x16x32_bf16 v[122:125], v[150:153], v[172:175], v[122:125]
	v_mfma_f32_16x16x32_bf16 v[118:121], v[130:133], v[190:193], v[118:121]
	v_mfma_f32_16x16x32_bf16 v[106:109], v[150:153], v[198:201], v[106:109]
	v_mfma_f32_16x16x32_bf16 v[102:105], v[130:133], v[206:209], v[102:105]
	v_mfma_f32_16x16x32_bf16 v[126:129], v[136:139], v[186:189], v[126:129]
	v_mfma_f32_16x16x32_bf16 v[122:125], v[168:171], v[186:189], v[122:125]
	v_mfma_f32_16x16x32_bf16 v[118:121], v[136:139], v[194:197], v[118:121]
	v_mfma_f32_16x16x32_bf16 v[114:117], v[150:153], v[190:193], v[114:117]
	v_mfma_f32_16x16x32_bf16 v[110:113], v[130:133], v[198:201], v[110:113]
	v_mfma_f32_16x16x32_bf16 v[106:109], v[168:171], v[202:205], v[106:109]
	v_mfma_f32_16x16x32_bf16 v[102:105], v[136:139], v[210:213], v[102:105]
	v_mfma_f32_16x16x32_bf16 v[98:101], v[150:153], v[206:209], v[98:101]
	v_mfma_f32_16x16x32_bf16 v[214:217], v[168:171], v[194:197], v[114:117]
	v_mfma_f32_16x16x32_bf16 v[218:221], v[136:139], v[202:205], v[110:113]
	v_mfma_f32_16x16x32_bf16 v[222:225], v[168:171], v[210:213], v[98:101]
	s_setprio 0
	s_barrier
; #define STAGE_A(P,br,kt) STAGE_G(P,c.A,c.lda,br,(long)(kt)*c.kstr)
; #define LDA(dst,b,h) for(int m=0;m<4;++m)for(int k=0;k<2;++k) \
;     dst[m][k]=*reinterpret_cast<const bf16x8*>((char*)SA(b,h)+lds_byte(wr*64+m*16+fr,k*32+fq*8))
; #define LDB(dst,b,h) for(int n=0;n<2;++n)for(int k=0;k<2;++k) \
;     dst[n][k]=*reinterpret_cast<const bf16x8*>((char*)SB(b,h)+lds_byte(wc*32+n*16+fr,k*32+fq*8))
; #define MMA(ai,bj,At,Bt_) do{__builtin_amdgcn_s_setprio(1); \
;     for(int m=0;m<4;++m)for(int n=0;n<2;++n)for(int k=0;k<2;++k) \
;       acc[ai][bj][m][n]=__builtin_amdgcn_mfma_f32_16x16x32_bf16(Bt_[n][k],At[m][k],acc[ai][bj][m][n],0,0,0); \
;     __builtin_amdgcn_s_setprio(0);}while(0)
; #define WAIT_V(n) asm volatile("s_waitcnt vmcnt(" #n ")":::"memory")
; #define WAIT_L(n) asm volatile("s_waitcnt lgkmcnt(" #n ")":::"memory")
; #define BAR __builtin_amdgcn_s_barrier()
; template <int EPI>
; __device__ __forceinline__ void gemm_run(const GD& c, const bool has_next, const GD& nx, const Ctx& e, bf16* shm, float* rs, float* rs_nxt, float* racc_) {
;     ...
;   { LDB(B0,0,0); LDA(At,0,0); STAGE_A(SA(1,1),brow+HALF,nt-1);
;     BAR; WAIT_L(0); MMA(0,0,At,B0); BAR;
;     LDB(B1,0,1); BAR; WAIT_L(0); MMA(0,1,At,B1); BAR;
;     LDA(At,0,1); WAIT_V(4); BAR; WAIT_L(0); MMA(1,0,At,B0); MMA(1,1,At,B1); BAR; }
;   { LDB(B0,1,0); LDA(At,1,0); WAIT_V(2); BAR; WAIT_L(0); MMA(0,0,At,B0); BAR;
	s_nop 2
	ds_read_b128 v[98:101], v154
	ds_read_b128 v[110:113], v154 offset:1024
	ds_read_b128 v[114:117], v154 offset:2048
	ds_read_b128 v[226:229], v154 offset:3072
	s_barrier
	s_waitcnt lgkmcnt(0)
	s_setprio 1
	v_mfma_f32_16x16x32_bf16 v[90:93], v[114:117], v[172:175], v[90:93]
	v_mfma_f32_16x16x32_bf16 v[86:89], v[98:101], v[190:193], v[86:89]
	v_mfma_f32_16x16x32_bf16 v[74:77], v[114:117], v[198:201], v[74:77]
	v_mfma_f32_16x16x32_bf16 v[70:73], v[98:101], v[206:209], v[70:73]
	v_mfma_f32_16x16x32_bf16 v[66:69], v[114:117], v[206:209], v[66:69]
	v_mfma_f32_16x16x32_bf16 v[94:97], v[98:101], v[172:175], v[94:97]
	v_mfma_f32_16x16x32_bf16 v[90:93], v[226:229], v[186:189], v[90:93]
	v_mfma_f32_16x16x32_bf16 v[86:89], v[110:113], v[194:197], v[86:89]
	v_mfma_f32_16x16x32_bf16 v[82:85], v[114:117], v[190:193], v[82:85]
	v_mfma_f32_16x16x32_bf16 v[78:81], v[98:101], v[198:201], v[78:81]
	v_mfma_f32_16x16x32_bf16 v[74:77], v[226:229], v[202:205], v[74:77]
	v_mfma_f32_16x16x32_bf16 v[70:73], v[110:113], v[210:213], v[70:73]
	v_mfma_f32_16x16x32_bf16 v[66:69], v[226:229], v[210:213], v[66:69]
	v_mfma_f32_16x16x32_bf16 v[230:233], v[110:113], v[186:189], v[94:97]
	v_mfma_f32_16x16x32_bf16 v[172:175], v[226:229], v[194:197], v[82:85]
	v_mfma_f32_16x16x32_bf16 v[186:189], v[110:113], v[202:205], v[78:81]
	s_setprio 0
	s_barrier
	s_nop 0
	ds_read_b128 v[78:81], v146 offset:16384
	ds_read_b128 v[82:85], v146 offset:17408
	ds_read_b128 v[94:97], v145 offset:16384
	ds_read_b128 v[190:193], v145 offset:17408
	ds_read_b128 v[194:197], v144 offset:16384
	ds_read_b128 v[198:201], v144 offset:17408
	ds_read_b128 v[202:205], v143 offset:16384
	ds_read_b128 v[206:209], v143 offset:17408
	s_waitcnt vmcnt(4)
	s_barrier
	s_waitcnt lgkmcnt(0)
	s_setprio 1
	v_mfma_f32_16x16x32_bf16 v[62:65], v[130:133], v[78:81], v[62:65]
	v_mfma_f32_16x16x32_bf16 v[58:61], v[150:153], v[78:81], v[58:61]
	v_mfma_f32_16x16x32_bf16 v[54:57], v[130:133], v[94:97], v[54:57]
	v_mfma_f32_16x16x32_bf16 v[42:45], v[150:153], v[194:197], v[42:45]
	v_mfma_f32_16x16x32_bf16 v[38:41], v[130:133], v[202:205], v[38:41]
	v_mfma_f32_16x16x32_bf16 v[62:65], v[136:139], v[82:85], v[62:65]
	v_mfma_f32_16x16x32_bf16 v[58:61], v[168:171], v[82:85], v[58:61]
	v_mfma_f32_16x16x32_bf16 v[54:57], v[136:139], v[190:193], v[54:57]
	v_mfma_f32_16x16x32_bf16 v[50:53], v[150:153], v[94:97], v[50:53]
	v_mfma_f32_16x16x32_bf16 v[46:49], v[130:133], v[194:197], v[46:49]
	v_mfma_f32_16x16x32_bf16 v[42:45], v[168:171], v[198:201], v[42:45]
	v_mfma_f32_16x16x32_bf16 v[38:41], v[136:139], v[206:209], v[38:41]
	v_mfma_f32_16x16x32_bf16 v[34:37], v[150:153], v[202:205], v[34:37]
	v_mfma_f32_16x16x32_bf16 v[210:213], v[168:171], v[190:193], v[50:53]
	v_mfma_f32_16x16x32_bf16 v[234:237], v[136:139], v[198:201], v[46:49]
	v_mfma_f32_16x16x32_bf16 v[136:139], v[168:171], v[206:209], v[34:37]
	s_setprio 0
	s_setprio 1
	v_mfma_f32_16x16x32_bf16 v[26:29], v[114:117], v[78:81], v[26:29]
	v_mfma_f32_16x16x32_bf16 v[22:25], v[98:101], v[94:97], v[22:25]
	v_mfma_f32_16x16x32_bf16 v[10:13], v[114:117], v[194:197], v[10:13]
	v_mfma_f32_16x16x32_bf16 v[6:9], v[98:101], v[202:205], v[6:9]
	v_mfma_f32_16x16x32_bf16 v[30:33], v[98:101], v[78:81], v[30:33]
	v_mfma_f32_16x16x32_bf16 v[26:29], v[226:229], v[82:85], v[26:29]
	v_mfma_f32_16x16x32_bf16 v[22:25], v[110:113], v[190:193], v[22:25]
	v_mfma_f32_16x16x32_bf16 v[18:21], v[114:117], v[94:97], v[18:21]
	v_mfma_f32_16x16x32_bf16 v[14:17], v[98:101], v[194:197], v[14:17]
	v_mfma_f32_16x16x32_bf16 v[10:13], v[226:229], v[198:201], v[10:13]
	v_mfma_f32_16x16x32_bf16 v[6:9], v[110:113], v[206:209], v[6:9]
	v_mfma_f32_16x16x32_bf16 v[2:5], v[114:117], v[202:205], v[2:5]
	v_mfma_f32_16x16x32_bf16 v[150:153], v[110:113], v[82:85], v[30:33]
	v_mfma_f32_16x16x32_bf16 v[166:169], v[226:229], v[190:193], v[18:21]
	v_mfma_f32_16x16x32_bf16 v[190:193], v[110:113], v[198:201], v[14:17]
	v_mfma_f32_16x16x32_bf16 v[2:5], v[226:229], v[206:209], v[2:5]
	s_setprio 0
	s_barrier
	ds_read_b128 v[14:17], v149
	ds_read_b128 v[18:21], v149 offset:1024
	ds_read_b128 v[194:197], v149 offset:2048
	ds_read_b128 v[198:201], v149 offset:3072
	ds_read_b128 v[30:33], v146 offset:32768
	ds_read_b128 v[34:37], v146 offset:33792
	ds_read_b128 v[46:49], v145 offset:32768
	ds_read_b128 v[50:53], v145 offset:33792
	ds_read_b128 v[202:205], v144 offset:32768
	ds_read_b128 v[206:209], v144 offset:33792
	ds_read_b128 v[226:229], v143 offset:32768
	ds_read_b128 v[238:241], v143 offset:33792
	s_waitcnt vmcnt(2)
	s_barrier
; #define LDA(dst,b,h) for(int m=0;m<4;++m)for(int k=0;k<2;++k) \
;     dst[m][k]=*reinterpret_cast<const bf16x8*>((char*)SA(b,h)+lds_byte(wr*64+m*16+fr,k*32+fq*8))
; #define LDB(dst,b,h) for(int n=0;n<2;++n)for(int k=0;k<2;++k) \
;     dst[n][k]=*reinterpret_cast<const bf16x8*>((char*)SB(b,h)+lds_byte(wc*32+n*16+fr,k*32+fq*8))
; #define MMA(ai,bj,At,Bt_) do{__builtin_amdgcn_s_setprio(1); \
;     for(int m=0;m<4;++m)for(int n=0;n<2;++n)for(int k=0;k<2;++k) \
;       acc[ai][bj][m][n]=__builtin_amdgcn_mfma_f32_16x16x32_bf16(Bt_[n][k],At[m][k],acc[ai][bj][m][n],0,0,0); \
;     __builtin_amdgcn_s_setprio(0);}while(0)
; #define WAIT_V(n) asm volatile("s_waitcnt vmcnt(" #n ")":::"memory")
; #define WAIT_L(n) asm volatile("s_waitcnt lgkmcnt(" #n ")":::"memory")
; #define BAR __builtin_amdgcn_s_barrier()
; template <int EPI>
; __device__ __forceinline__ void gemm_run(const GD& c, const bool has_next, const GD& nx, const Ctx& e, bf16* shm, float* rs, float* rs_nxt, float* racc_) {
;     ...
;   { LDB(B0,1,0); LDA(At,1,0); WAIT_V(2); BAR; WAIT_L(0); MMA(0,0,At,B0); BAR;
;     LDB(B1,1,1); WAIT_V(0); BAR; WAIT_L(0); MMA(0,1,At,B1); BAR;
;     LDA(At,1,1); BAR; WAIT_L(0); MMA(1,0,At,B0); MMA(1,1,At,B1); BAR; }
;   if(wr==0)BAR;
	s_waitcnt lgkmcnt(0)
	s_setprio 1
	v_mfma_f32_16x16x32_bf16 v[78:81], v[14:17], v[30:33], v[126:129]
	v_mfma_f32_16x16x32_bf16 v[130:133], v[18:21], v[34:37], v[78:81]
	v_mfma_f32_16x16x32_bf16 v[78:81], v[194:197], v[30:33], v[122:125]
	v_mfma_f32_16x16x32_bf16 v[126:129], v[198:201], v[34:37], v[78:81]
	v_mfma_f32_16x16x32_bf16 v[78:81], v[14:17], v[46:49], v[118:121]
	v_mfma_f32_16x16x32_bf16 v[114:117], v[18:21], v[50:53], v[78:81]
	v_mfma_f32_16x16x32_bf16 v[78:81], v[194:197], v[46:49], v[214:217]
	v_mfma_f32_16x16x32_bf16 v[110:113], v[198:201], v[50:53], v[78:81]
	v_mfma_f32_16x16x32_bf16 v[78:81], v[14:17], v[202:205], v[218:221]
	v_mfma_f32_16x16x32_bf16 v[98:101], v[18:21], v[206:209], v[78:81]
	v_mfma_f32_16x16x32_bf16 v[78:81], v[194:197], v[202:205], v[106:109]
	v_mfma_f32_16x16x32_bf16 v[94:97], v[198:201], v[206:209], v[78:81]
	v_mfma_f32_16x16x32_bf16 v[78:81], v[14:17], v[226:229], v[102:105]
	v_mfma_f32_16x16x32_bf16 v[82:85], v[18:21], v[238:241], v[78:81]
	v_mfma_f32_16x16x32_bf16 v[78:81], v[194:197], v[226:229], v[222:225]
	v_mfma_f32_16x16x32_bf16 v[78:81], v[198:201], v[238:241], v[78:81]
	s_setprio 0
	s_barrier
	ds_read_b128 v[214:217], v147
	ds_read_b128 v[218:221], v147 offset:1024
	ds_read_b128 v[222:225], v147 offset:2048
	ds_read_b128 v[242:245], v147 offset:3072
	s_waitcnt vmcnt(0)
	s_barrier
	s_waitcnt lgkmcnt(0)
	s_setprio 1
	v_mfma_f32_16x16x32_bf16 v[102:105], v[214:217], v[30:33], v[230:233]
	v_mfma_f32_16x16x32_bf16 v[30:33], v[222:225], v[30:33], v[90:93]
	v_mfma_f32_16x16x32_bf16 v[118:121], v[242:245], v[34:37], v[30:33]
	v_mfma_f32_16x16x32_bf16 v[30:33], v[214:217], v[46:49], v[86:89]
	v_mfma_f32_16x16x32_bf16 v[106:109], v[218:221], v[50:53], v[30:33]
	v_mfma_f32_16x16x32_bf16 v[30:33], v[222:225], v[46:49], v[172:175]
	v_mfma_f32_16x16x32_bf16 v[122:125], v[218:221], v[34:37], v[102:105]
	v_mfma_f32_16x16x32_bf16 v[102:105], v[242:245], v[50:53], v[30:33]
	v_mfma_f32_16x16x32_bf16 v[30:33], v[214:217], v[202:205], v[186:189]
	v_mfma_f32_16x16x32_bf16 v[90:93], v[218:221], v[206:209], v[30:33]
	v_mfma_f32_16x16x32_bf16 v[30:33], v[222:225], v[202:205], v[74:77]
	v_mfma_f32_16x16x32_bf16 v[86:89], v[242:245], v[206:209], v[30:33]
	v_mfma_f32_16x16x32_bf16 v[30:33], v[214:217], v[226:229], v[70:73]
	v_mfma_f32_16x16x32_bf16 v[74:77], v[218:221], v[238:241], v[30:33]
	v_mfma_f32_16x16x32_bf16 v[30:33], v[222:225], v[226:229], v[66:69]
	v_mfma_f32_16x16x32_bf16 v[70:73], v[242:245], v[238:241], v[30:33]
	s_setprio 0
	s_barrier
	ds_read_b128 v[170:173], v146 offset:49152
	ds_read_b128 v[146:149], v146 offset:50176
	ds_read_b128 v[186:189], v145 offset:49152
	ds_read_b128 v[202:205], v145 offset:50176
	ds_read_b128 v[206:209], v144 offset:49152
	ds_read_b128 v[226:229], v144 offset:50176
	ds_read_b128 v[230:233], v143 offset:49152
	ds_read_b128 v[238:241], v143 offset:50176
	s_barrier
	s_waitcnt lgkmcnt(0)
	s_setprio 1
	v_mfma_f32_16x16x32_bf16 v[30:33], v[14:17], v[170:173], v[62:65]
	v_mfma_f32_16x16x32_bf16 v[66:69], v[18:21], v[146:149], v[30:33]
	v_mfma_f32_16x16x32_bf16 v[30:33], v[194:197], v[170:173], v[58:61]
	v_mfma_f32_16x16x32_bf16 v[62:65], v[198:201], v[146:149], v[30:33]
	v_mfma_f32_16x16x32_bf16 v[30:33], v[14:17], v[186:189], v[54:57]
	v_mfma_f32_16x16x32_bf16 v[50:53], v[18:21], v[202:205], v[30:33]
	v_mfma_f32_16x16x32_bf16 v[30:33], v[194:197], v[186:189], v[210:213]
	v_mfma_f32_16x16x32_bf16 v[46:49], v[198:201], v[202:205], v[30:33]
	v_mfma_f32_16x16x32_bf16 v[30:33], v[14:17], v[206:209], v[234:237]
	v_mfma_f32_16x16x32_bf16 v[14:17], v[14:17], v[230:233], v[38:41]
	v_mfma_f32_16x16x32_bf16 v[34:37], v[18:21], v[226:229], v[30:33]
	v_mfma_f32_16x16x32_bf16 v[30:33], v[194:197], v[206:209], v[42:45]
	v_mfma_f32_16x16x32_bf16 v[18:21], v[18:21], v[238:241], v[14:17]
	v_mfma_f32_16x16x32_bf16 v[14:17], v[194:197], v[230:233], v[136:139]
	v_mfma_f32_16x16x32_bf16 v[30:33], v[198:201], v[226:229], v[30:33]
	v_mfma_f32_16x16x32_bf16 v[14:17], v[198:201], v[238:241], v[14:17]
	s_setprio 0
	s_setprio 1
	v_mfma_f32_16x16x32_bf16 v[22:25], v[214:217], v[186:189], v[22:25]
	v_mfma_f32_16x16x32_bf16 v[38:41], v[214:217], v[170:173], v[150:153]
	v_mfma_f32_16x16x32_bf16 v[42:45], v[218:221], v[202:205], v[22:25]
	v_mfma_f32_16x16x32_bf16 v[22:25], v[222:225], v[186:189], v[166:169]
	v_mfma_f32_16x16x32_bf16 v[58:61], v[218:221], v[146:149], v[38:41]
	v_mfma_f32_16x16x32_bf16 v[26:29], v[222:225], v[170:173], v[26:29]
	v_mfma_f32_16x16x32_bf16 v[38:41], v[242:245], v[202:205], v[22:25]
	v_mfma_f32_16x16x32_bf16 v[22:25], v[214:217], v[206:209], v[190:193]
	v_mfma_f32_16x16x32_bf16 v[10:13], v[222:225], v[206:209], v[10:13]
	v_mfma_f32_16x16x32_bf16 v[6:9], v[214:217], v[230:233], v[6:9]
	v_mfma_f32_16x16x32_bf16 v[2:5], v[222:225], v[230:233], v[2:5]
	v_mfma_f32_16x16x32_bf16 v[54:57], v[242:245], v[146:149], v[26:29]
	v_mfma_f32_16x16x32_bf16 v[26:29], v[218:221], v[226:229], v[22:25]
	v_mfma_f32_16x16x32_bf16 v[22:25], v[242:245], v[226:229], v[10:13]
	v_mfma_f32_16x16x32_bf16 v[10:13], v[218:221], v[238:241], v[6:9]
	v_mfma_f32_16x16x32_bf16 v[6:9], v[242:245], v[238:241], v[2:5]
	s_setprio 0
	v_cmp_gt_u32_e32 vcc, s96, v140
	s_barrier
	s_and_saveexec_b64 s[2:3], vcc
	s_cbranch_execz .LBB0_1122
	s_barrier

; #define STAGE_A(P,br,kt) STAGE_G(P,c.A,c.lda,br,(long)(kt)*c.kstr)
; #define STAGE_B(P,br,kt) STAGE_G(P,c.Bt,c.K,br,(long)(kt)*BK)
; #define LDA(dst,b,h) for(int m=0;m<4;++m)for(int k=0;k<2;++k) \
;     dst[m][k]=*reinterpret_cast<const bf16x8*>((char*)SA(b,h)+lds_byte(wr*64+m*16+fr,k*32+fq*8))
; #define LDB(dst,b,h) for(int n=0;n<2;++n)for(int k=0;k<2;++k) \
;     dst[n][k]=*reinterpret_cast<const bf16x8*>((char*)SB(b,h)+lds_byte(wc*32+n*16+fr,k*32+fq*8))
; #define MMA(ai,bj,At,Bt_) do{__builtin_amdgcn_s_setprio(1); \
;     for(int m=0;m<4;++m)for(int n=0;n<2;++n)for(int k=0;k<2;++k) \
;       acc[ai][bj][m][n]=__builtin_amdgcn_mfma_f32_16x16x32_bf16(Bt_[n][k],At[m][k],acc[ai][bj][m][n],0,0,0); \
;     __builtin_amdgcn_s_setprio(0);}while(0)
; #define WAIT_L(n) asm volatile("s_waitcnt lgkmcnt(" #n ")":::"memory")
; #define BAR __builtin_amdgcn_s_barrier()
; #define SCHED __builtin_amdgcn_sched_barrier(0)
; template <int EPI>
; __device__ __forceinline__ void gemm_run(const GD& c, const bool has_next, const GD& nx, const Ctx& e, bf16* shm, float* rs, float* rs_nxt, float* racc_) {
;     ...
;     LDB(B0,0,0); SCHED; LDA(At,0,0); STAGE_A(SA(1,1),brow+HALF,t+1);
;     WAIT_L(8); BAR; WAIT_L(0); MMA(0,0,At,B0); BAR; SCHED;
;     LDB(B1,0,1); STAGE_B(SB(0,0),bcol,t+2);
;     BAR; WAIT_L(0); MMA(0,1,At,B1); BAR;
;     LDA(At,0,1); STAGE_A(SA(0,0),brow,t+2);
;     BAR; WAIT_L(0); MMA(1,0,At,B0); BAR; SCHED;
.LBB0_1178:
	ds_read_b128 v[168:171], v155
	ds_read_b128 v[172:175], v155 offset:1024
	ds_read_b128 v[186:189], v155 offset:2048
	ds_read_b128 v[190:193], v155 offset:3072
	v_add_u32_e32 v163, 0xc000, v142
	v_lshl_add_u64 v[182:183], s[6:7], 0, v[132:133]
	v_readfirstlane_b32 s3, v163
	v_add_u32_e32 v166, 0xe000, v142
	v_lshl_add_u64 v[156:157], v[182:183], 0, s[90:91]
	s_mov_b32 m0, s3
	v_lshl_add_u64 v[242:243], s[6:7], 0, v[134:135]
	v_readfirstlane_b32 s3, v166
	ds_read_b128 v[158:161], v146
	ds_read_b128 v[194:197], v146 offset:1024
	ds_read_b128 v[198:201], v145
	ds_read_b128 v[202:205], v145 offset:1024
	ds_read_b128 v[206:209], v144
	ds_read_b128 v[210:213], v144 offset:1024
	ds_read_b128 v[214:217], v143
	ds_read_b128 v[218:221], v143 offset:1024
	global_load_lds_dwordx4 v[156:157], off
	v_lshl_add_u64 v[156:157], v[242:243], 0, s[90:91]
	s_mov_b32 m0, s3
	s_nop 0
	global_load_lds_dwordx4 v[156:157], off
	s_waitcnt lgkmcnt(8)
	s_barrier
	s_waitcnt lgkmcnt(0)
	s_setprio 1
	v_mfma_f32_16x16x32_bf16 v[126:129], v[168:171], v[158:161], v[126:129]
	v_mfma_f32_16x16x32_bf16 v[122:125], v[186:189], v[158:161], v[122:125]
	v_mfma_f32_16x16x32_bf16 v[118:121], v[168:171], v[198:201], v[118:121]
	v_mfma_f32_16x16x32_bf16 v[114:117], v[186:189], v[198:201], v[114:117]
	v_mfma_f32_16x16x32_bf16 v[110:113], v[168:171], v[206:209], v[110:113]
	v_mfma_f32_16x16x32_bf16 v[106:109], v[186:189], v[206:209], v[106:109]
	v_mfma_f32_16x16x32_bf16 v[102:105], v[168:171], v[214:217], v[102:105]
	v_mfma_f32_16x16x32_bf16 v[98:101], v[186:189], v[214:217], v[98:101]
	v_mfma_f32_16x16x32_bf16 v[126:129], v[172:175], v[194:197], v[126:129]
	v_mfma_f32_16x16x32_bf16 v[122:125], v[190:193], v[194:197], v[122:125]
	v_mfma_f32_16x16x32_bf16 v[118:121], v[172:175], v[202:205], v[118:121]
	v_mfma_f32_16x16x32_bf16 v[114:117], v[190:193], v[202:205], v[114:117]
	v_mfma_f32_16x16x32_bf16 v[110:113], v[172:175], v[210:213], v[110:113]
	v_mfma_f32_16x16x32_bf16 v[106:109], v[190:193], v[210:213], v[106:109]
	v_mfma_f32_16x16x32_bf16 v[102:105], v[172:175], v[218:221], v[102:105]
	v_mfma_f32_16x16x32_bf16 v[98:101], v[190:193], v[218:221], v[98:101]
	s_setprio 0
	s_barrier
	v_add_u32_e32 v156, s33, v147
	v_lshl_add_u64 v[244:245], s[6:7], 0, v[136:137]
	v_readfirstlane_b32 s3, v156
	v_add_u32_e32 v157, 0x2000, v156
	v_lshl_add_u64 v[238:239], v[244:245], 0, s[28:29]
	s_mov_b32 m0, s3
	v_lshl_add_u64 v[246:247], s[6:7], 0, v[138:139]
	v_readfirstlane_b32 s3, v157
	ds_read_b128 v[222:225], v154
	ds_read_b128 v[226:229], v154 offset:1024
	ds_read_b128 v[230:233], v154 offset:2048
	ds_read_b128 v[234:237], v154 offset:3072
	global_load_lds_dwordx4 v[238:239], off
	v_lshl_add_u64 v[238:239], v[246:247], 0, s[28:29]
	s_mov_b32 m0, s3
	s_nop 0
	global_load_lds_dwordx4 v[238:239], off
	s_barrier
	s_waitcnt lgkmcnt(0)
	s_setprio 1
	v_mfma_f32_16x16x32_bf16 v[94:97], v[222:225], v[158:161], v[94:97]
	v_mfma_f32_16x16x32_bf16 v[90:93], v[230:233], v[158:161], v[90:93]
	v_mfma_f32_16x16x32_bf16 v[86:89], v[222:225], v[198:201], v[86:89]
	v_mfma_f32_16x16x32_bf16 v[82:85], v[230:233], v[198:201], v[82:85]
	v_mfma_f32_16x16x32_bf16 v[78:81], v[222:225], v[206:209], v[78:81]
	v_mfma_f32_16x16x32_bf16 v[74:77], v[230:233], v[206:209], v[74:77]
	v_mfma_f32_16x16x32_bf16 v[70:73], v[222:225], v[214:217], v[70:73]
	v_mfma_f32_16x16x32_bf16 v[66:69], v[230:233], v[214:217], v[66:69]
	v_mfma_f32_16x16x32_bf16 v[94:97], v[226:229], v[194:197], v[94:97]
	v_mfma_f32_16x16x32_bf16 v[90:93], v[234:237], v[194:197], v[90:93]
	v_mfma_f32_16x16x32_bf16 v[86:89], v[226:229], v[202:205], v[86:89]
	v_mfma_f32_16x16x32_bf16 v[82:85], v[234:237], v[202:205], v[82:85]
	v_mfma_f32_16x16x32_bf16 v[78:81], v[226:229], v[210:213], v[78:81]
	v_mfma_f32_16x16x32_bf16 v[74:77], v[234:237], v[210:213], v[74:77]
	v_mfma_f32_16x16x32_bf16 v[70:73], v[226:229], v[218:221], v[70:73]
	v_mfma_f32_16x16x32_bf16 v[66:69], v[234:237], v[218:221], v[66:69]
	s_setprio 0
	v_readfirstlane_b32 s3, v142
	v_lshl_add_u64 v[158:159], v[182:183], 0, s[0:1]
	s_mov_b32 m0, s3
	s_barrier
	ds_read_b128 v[194:197], v146 offset:16384
	ds_read_b128 v[198:201], v146 offset:17408
	ds_read_b128 v[202:205], v145 offset:16384
	ds_read_b128 v[206:209], v145 offset:17408
	ds_read_b128 v[210:213], v144 offset:16384
	ds_read_b128 v[214:217], v144 offset:17408
	ds_read_b128 v[218:221], v143 offset:16384
	ds_read_b128 v[238:241], v143 offset:17408
	global_load_lds_dwordx4 v[158:159], off
	v_add_u32_e32 v158, 0x2000, v142
	v_lshl_add_u64 v[160:161], v[242:243], 0, s[0:1]
	v_readfirstlane_b32 s3, v158
	s_mov_b32 m0, s3
	s_nop 0
	global_load_lds_dwordx4 v[160:161], off
	s_barrier
	s_waitcnt lgkmcnt(0)
	s_setprio 1
	v_mfma_f32_16x16x32_bf16 v[62:65], v[168:171], v[194:197], v[62:65]
	v_mfma_f32_16x16x32_bf16 v[58:61], v[186:189], v[194:197], v[58:61]
	v_mfma_f32_16x16x32_bf16 v[54:57], v[168:171], v[202:205], v[54:57]
	v_mfma_f32_16x16x32_bf16 v[50:53], v[186:189], v[202:205], v[50:53]
	v_mfma_f32_16x16x32_bf16 v[46:49], v[168:171], v[210:213], v[46:49]
	v_mfma_f32_16x16x32_bf16 v[42:45], v[186:189], v[210:213], v[42:45]
	v_mfma_f32_16x16x32_bf16 v[38:41], v[168:171], v[218:221], v[38:41]
	v_mfma_f32_16x16x32_bf16 v[34:37], v[186:189], v[218:221], v[34:37]
	v_mfma_f32_16x16x32_bf16 v[62:65], v[172:175], v[198:201], v[62:65]
	v_mfma_f32_16x16x32_bf16 v[58:61], v[190:193], v[198:201], v[58:61]
	v_mfma_f32_16x16x32_bf16 v[54:57], v[172:175], v[206:209], v[54:57]
	v_mfma_f32_16x16x32_bf16 v[50:53], v[190:193], v[206:209], v[50:53]
	v_mfma_f32_16x16x32_bf16 v[46:49], v[172:175], v[214:217], v[46:49]
	v_mfma_f32_16x16x32_bf16 v[42:45], v[190:193], v[214:217], v[42:45]
	v_mfma_f32_16x16x32_bf16 v[38:41], v[172:175], v[238:241], v[38:41]
	v_mfma_f32_16x16x32_bf16 v[34:37], v[190:193], v[238:241], v[34:37]
	s_setprio 0
	s_barrier
; #define STAGE_A(P,br,kt) STAGE_G(P,c.A,c.lda,br,(long)(kt)*c.kstr)
; #define STAGE_B(P,br,kt) STAGE_G(P,c.Bt,c.K,br,(long)(kt)*BK)
; #define LDA(dst,b,h) for(int m=0;m<4;++m)for(int k=0;k<2;++k) \
;     dst[m][k]=*reinterpret_cast<const bf16x8*>((char*)SA(b,h)+lds_byte(wr*64+m*16+fr,k*32+fq*8))
; #define LDB(dst,b,h) for(int n=0;n<2;++n)for(int k=0;k<2;++k) \
;     dst[n][k]=*reinterpret_cast<const bf16x8*>((char*)SB(b,h)+lds_byte(wc*32+n*16+fr,k*32+fq*8))
; #define MMA(ai,bj,At,Bt_) do{__builtin_amdgcn_s_setprio(1); \
;     for(int m=0;m<4;++m)for(int n=0;n<2;++n)for(int k=0;k<2;++k) \
;       acc[ai][bj][m][n]=__builtin_amdgcn_mfma_f32_16x16x32_bf16(Bt_[n][k],At[m][k],acc[ai][bj][m][n],0,0,0); \
;     __builtin_amdgcn_s_setprio(0);}while(0)
; #define WAIT_V(n) asm volatile("s_waitcnt vmcnt(" #n ")":::"memory")
; #define WAIT_L(n) asm volatile("s_waitcnt lgkmcnt(" #n ")":::"memory")
; #define BAR __builtin_amdgcn_s_barrier()
; #define SCHED __builtin_amdgcn_sched_barrier(0)
; template <int EPI>
; __device__ __forceinline__ void gemm_run(const GD& c, const bool has_next, const GD& nx, const Ctx& e, bf16* shm, float* rs, float* rs_nxt, float* racc_) {
;     ...
;     STAGE_B(SB(0,1),bcol+HALF,t+2);
;     WAIT_V(6); BAR; MMA(1,1,At,B1); BAR;
;     LDB(B0,1,0); SCHED; LDA(At,1,0); STAGE_A(SA(0,1),brow+HALF,t+2);
;     WAIT_L(8); BAR; WAIT_L(0); MMA(0,0,At,B0); BAR; SCHED;
;     LDB(B1,1,1); STAGE_B(SB(1,0),bcol,t+3);
;     BAR; WAIT_L(0); MMA(0,1,At,B1); BAR;
	v_add_u32_e32 v159, s86, v147
	v_lshl_add_u64 v[160:161], v[244:245], 0, s[30:31]
	v_readfirstlane_b32 s3, v159
	s_mov_b32 m0, s3
	v_lshl_add_u64 v[168:169], v[246:247], 0, s[30:31]
	global_load_lds_dwordx4 v[160:161], off
	v_add_u32_e32 v160, 0x2000, v159
	s_nop 0
	v_readfirstlane_b32 s3, v160
	s_mov_b32 m0, s3
	s_nop 0
	global_load_lds_dwordx4 v[168:169], off
	s_waitcnt vmcnt(6)
	s_barrier
	s_setprio 1
	v_mfma_f32_16x16x32_bf16 v[30:33], v[222:225], v[194:197], v[30:33]
	v_mfma_f32_16x16x32_bf16 v[26:29], v[230:233], v[194:197], v[26:29]
	v_mfma_f32_16x16x32_bf16 v[22:25], v[222:225], v[202:205], v[22:25]
	v_mfma_f32_16x16x32_bf16 v[18:21], v[230:233], v[202:205], v[18:21]
	v_mfma_f32_16x16x32_bf16 v[14:17], v[222:225], v[210:213], v[14:17]
	v_mfma_f32_16x16x32_bf16 v[10:13], v[230:233], v[210:213], v[10:13]
	v_mfma_f32_16x16x32_bf16 v[6:9], v[222:225], v[218:221], v[6:9]
	v_mfma_f32_16x16x32_bf16 v[2:5], v[230:233], v[218:221], v[2:5]
	v_mfma_f32_16x16x32_bf16 v[30:33], v[226:229], v[198:201], v[30:33]
	v_mfma_f32_16x16x32_bf16 v[26:29], v[234:237], v[198:201], v[26:29]
	v_mfma_f32_16x16x32_bf16 v[22:25], v[226:229], v[206:209], v[22:25]
	v_mfma_f32_16x16x32_bf16 v[18:21], v[234:237], v[206:209], v[18:21]
	v_mfma_f32_16x16x32_bf16 v[14:17], v[226:229], v[214:217], v[14:17]
	v_mfma_f32_16x16x32_bf16 v[10:13], v[234:237], v[214:217], v[10:13]
	v_mfma_f32_16x16x32_bf16 v[6:9], v[226:229], v[238:241], v[6:9]
	v_mfma_f32_16x16x32_bf16 v[2:5], v[234:237], v[238:241], v[2:5]
	s_setprio 0
	s_barrier
	ds_read_b128 v[168:171], v150
	ds_read_b128 v[172:175], v150 offset:1024
	ds_read_b128 v[186:189], v150 offset:2048
	ds_read_b128 v[190:193], v150 offset:3072
	v_add_u32_e32 v161, 0x4000, v142
	v_add_u32_e32 v162, 0x6000, v142
	v_readfirstlane_b32 s3, v161
	v_lshl_add_u64 v[226:227], v[182:183], 0, s[76:77]
	s_mov_b32 m0, s3
	v_readfirstlane_b32 s3, v162
	ds_read_b128 v[194:197], v146 offset:32768
	ds_read_b128 v[198:201], v146 offset:33792
	ds_read_b128 v[202:205], v145 offset:32768
	ds_read_b128 v[206:209], v145 offset:33792
	ds_read_b128 v[210:213], v144 offset:32768
	ds_read_b128 v[214:217], v144 offset:33792
	ds_read_b128 v[218:221], v143 offset:32768
	ds_read_b128 v[222:225], v143 offset:33792
	global_load_lds_dwordx4 v[226:227], off
	v_lshl_add_u64 v[226:227], v[242:243], 0, s[76:77]
	s_mov_b32 m0, s3
	s_nop 0
	global_load_lds_dwordx4 v[226:227], off
	s_waitcnt lgkmcnt(8)
	s_barrier
	s_waitcnt lgkmcnt(0)
	s_setprio 1
	v_mfma_f32_16x16x32_bf16 v[126:129], v[168:171], v[194:197], v[126:129]
	v_mfma_f32_16x16x32_bf16 v[122:125], v[186:189], v[194:197], v[122:125]
	v_mfma_f32_16x16x32_bf16 v[118:121], v[168:171], v[202:205], v[118:121]
	v_mfma_f32_16x16x32_bf16 v[114:117], v[186:189], v[202:205], v[114:117]
	v_mfma_f32_16x16x32_bf16 v[110:113], v[168:171], v[210:213], v[110:113]
	v_mfma_f32_16x16x32_bf16 v[106:109], v[186:189], v[210:213], v[106:109]
	v_mfma_f32_16x16x32_bf16 v[102:105], v[168:171], v[218:221], v[102:105]
	v_mfma_f32_16x16x32_bf16 v[98:101], v[186:189], v[218:221], v[98:101]
	v_mfma_f32_16x16x32_bf16 v[126:129], v[172:175], v[198:201], v[126:129]
	v_mfma_f32_16x16x32_bf16 v[122:125], v[190:193], v[198:201], v[122:125]
	v_mfma_f32_16x16x32_bf16 v[118:121], v[172:175], v[206:209], v[118:121]
	v_mfma_f32_16x16x32_bf16 v[114:117], v[190:193], v[206:209], v[114:117]
	v_mfma_f32_16x16x32_bf16 v[110:113], v[172:175], v[214:217], v[110:113]
	v_mfma_f32_16x16x32_bf16 v[106:109], v[190:193], v[214:217], v[106:109]
	v_mfma_f32_16x16x32_bf16 v[102:105], v[172:175], v[222:225], v[102:105]
	v_mfma_f32_16x16x32_bf16 v[98:101], v[190:193], v[222:225], v[98:101]
	s_setprio 0
	s_barrier
	v_readfirstlane_b32 s3, v149
	v_add_u32_e32 v167, 0x2000, v149
	v_lshl_add_u64 v[248:249], v[244:245], 0, s[34:35]
	s_mov_b32 m0, s3
	v_readfirstlane_b32 s3, v167
	ds_read_b128 v[226:229], v148
	ds_read_b128 v[230:233], v148 offset:1024
	ds_read_b128 v[234:237], v148 offset:2048
	ds_read_b128 v[238:241], v148 offset:3072
	global_load_lds_dwordx4 v[248:249], off
	v_lshl_add_u64 v[248:249], v[246:247], 0, s[34:35]
	s_mov_b32 m0, s3
	s_nop 0
	global_load_lds_dwordx4 v[248:249], off
	s_barrier
	s_waitcnt lgkmcnt(0)
	s_setprio 1
	v_mfma_f32_16x16x32_bf16 v[94:97], v[226:229], v[194:197], v[94:97]
	v_mfma_f32_16x16x32_bf16 v[90:93], v[234:237], v[194:197], v[90:93]
	v_mfma_f32_16x16x32_bf16 v[86:89], v[226:229], v[202:205], v[86:89]
	v_mfma_f32_16x16x32_bf16 v[82:85], v[234:237], v[202:205], v[82:85]
	v_mfma_f32_16x16x32_bf16 v[78:81], v[226:229], v[210:213], v[78:81]
	v_mfma_f32_16x16x32_bf16 v[74:77], v[234:237], v[210:213], v[74:77]
	v_mfma_f32_16x16x32_bf16 v[70:73], v[226:229], v[218:221], v[70:73]
	v_mfma_f32_16x16x32_bf16 v[66:69], v[234:237], v[218:221], v[66:69]
	v_mfma_f32_16x16x32_bf16 v[94:97], v[230:233], v[198:201], v[94:97]
	v_mfma_f32_16x16x32_bf16 v[90:93], v[238:241], v[198:201], v[90:93]
	v_mfma_f32_16x16x32_bf16 v[86:89], v[230:233], v[206:209], v[86:89]
	v_mfma_f32_16x16x32_bf16 v[82:85], v[238:241], v[206:209], v[82:85]
	v_mfma_f32_16x16x32_bf16 v[78:81], v[230:233], v[214:217], v[78:81]
	v_mfma_f32_16x16x32_bf16 v[74:77], v[238:241], v[214:217], v[74:77]
	v_mfma_f32_16x16x32_bf16 v[70:73], v[230:233], v[222:225], v[70:73]
	v_mfma_f32_16x16x32_bf16 v[66:69], v[238:241], v[222:225], v[66:69]
	s_setprio 0
	v_readfirstlane_b32 s3, v151
	v_lshl_add_u64 v[182:183], v[182:183], 0, s[74:75]
	s_mov_b32 m0, s3
	v_readfirstlane_b32 s3, v152
	s_barrier
; #define STAGE_A(P,br,kt) STAGE_G(P,c.A,c.lda,br,(long)(kt)*c.kstr)
; #define STAGE_B(P,br,kt) STAGE_G(P,c.Bt,c.K,br,(long)(kt)*BK)
; #define LDA(dst,b,h) for(int m=0;m<4;++m)for(int k=0;k<2;++k) \
;     dst[m][k]=*reinterpret_cast<const bf16x8*>((char*)SA(b,h)+lds_byte(wr*64+m*16+fr,k*32+fq*8))
; #define LDB(dst,b,h) for(int n=0;n<2;++n)for(int k=0;k<2;++k) \
;     dst[n][k]=*reinterpret_cast<const bf16x8*>((char*)SB(b,h)+lds_byte(wc*32+n*16+fr,k*32+fq*8))
; #define MMA(ai,bj,At,Bt_) do{__builtin_amdgcn_s_setprio(1); \
;     for(int m=0;m<4;++m)for(int n=0;n<2;++n)for(int k=0;k<2;++k) \
;       acc[ai][bj][m][n]=__builtin_amdgcn_mfma_f32_16x16x32_bf16(Bt_[n][k],At[m][k],acc[ai][bj][m][n],0,0,0); \
;     __builtin_amdgcn_s_setprio(0);}while(0)
; #define WAIT_V(n) asm volatile("s_waitcnt vmcnt(" #n ")":::"memory")
; #define WAIT_L(n) asm volatile("s_waitcnt lgkmcnt(" #n ")":::"memory")
; #define BAR __builtin_amdgcn_s_barrier()
; #define SCHED __builtin_amdgcn_sched_barrier(0)
; template <int EPI>
; __device__ __forceinline__ void gemm_run(const GD& c, const bool has_next, const GD& nx, const Ctx& e, bf16* shm, float* rs, float* rs_nxt, float* racc_) {
;     ...
;     LDA(At,1,1); STAGE_A(SA(1,0),brow,t+3);
;     BAR; WAIT_L(0); MMA(1,0,At,B0); BAR; SCHED;
;     STAGE_B(SB(1,1),bcol+HALF,t+3);
;     WAIT_V(6); BAR; MMA(1,1,At,B1); BAR;
;   }
;   { LDB(B0,0,0); LDA(At,0,0); STAGE_A(SA(1,1),brow+HALF,nt-1);
;     BAR; WAIT_L(0); MMA(0,0,At,B0); BAR;
;     LDB(B1,0,1); BAR; WAIT_L(0); MMA(0,1,At,B1); BAR;
	ds_read_b128 v[194:197], v146 offset:49152
	ds_read_b128 v[198:201], v146 offset:50176
	ds_read_b128 v[202:205], v145 offset:49152
	ds_read_b128 v[206:209], v145 offset:50176
	ds_read_b128 v[210:213], v144 offset:49152
	ds_read_b128 v[214:217], v144 offset:50176
	ds_read_b128 v[218:221], v143 offset:49152
	ds_read_b128 v[222:225], v143 offset:50176
	global_load_lds_dwordx4 v[182:183], off
	v_lshl_add_u64 v[182:183], v[242:243], 0, s[74:75]
	s_mov_b32 m0, s3
	s_nop 0
	global_load_lds_dwordx4 v[182:183], off
	s_barrier
	s_waitcnt lgkmcnt(0)
	s_setprio 1
	v_mfma_f32_16x16x32_bf16 v[62:65], v[168:171], v[194:197], v[62:65]
	v_mfma_f32_16x16x32_bf16 v[58:61], v[186:189], v[194:197], v[58:61]
	v_mfma_f32_16x16x32_bf16 v[54:57], v[168:171], v[202:205], v[54:57]
	v_mfma_f32_16x16x32_bf16 v[50:53], v[186:189], v[202:205], v[50:53]
	v_mfma_f32_16x16x32_bf16 v[46:49], v[168:171], v[210:213], v[46:49]
	v_mfma_f32_16x16x32_bf16 v[42:45], v[186:189], v[210:213], v[42:45]
	v_mfma_f32_16x16x32_bf16 v[38:41], v[168:171], v[218:221], v[38:41]
	v_mfma_f32_16x16x32_bf16 v[34:37], v[186:189], v[218:221], v[34:37]
	v_mfma_f32_16x16x32_bf16 v[62:65], v[172:175], v[198:201], v[62:65]
	v_mfma_f32_16x16x32_bf16 v[58:61], v[190:193], v[198:201], v[58:61]
	v_mfma_f32_16x16x32_bf16 v[54:57], v[172:175], v[206:209], v[54:57]
	v_mfma_f32_16x16x32_bf16 v[50:53], v[190:193], v[206:209], v[50:53]
	v_mfma_f32_16x16x32_bf16 v[46:49], v[172:175], v[214:217], v[46:49]
	v_mfma_f32_16x16x32_bf16 v[42:45], v[190:193], v[214:217], v[42:45]
	v_mfma_f32_16x16x32_bf16 v[38:41], v[172:175], v[222:225], v[38:41]
	v_mfma_f32_16x16x32_bf16 v[34:37], v[190:193], v[222:225], v[34:37]
	s_setprio 0
	s_barrier
	v_readfirstlane_b32 s3, v153
	v_add_u32_e32 v167, 0x2000, v153
	v_lshl_add_u64 v[168:169], v[244:245], 0, s[36:37]
	s_mov_b32 m0, s3
	v_readfirstlane_b32 s3, v167
	global_load_lds_dwordx4 v[168:169], off
	v_lshl_add_u64 v[168:169], v[246:247], 0, s[36:37]
	s_mov_b32 m0, s3
	s_nop 0
	global_load_lds_dwordx4 v[168:169], off
	s_waitcnt vmcnt(6)
	s_barrier
	s_setprio 1
	v_mfma_f32_16x16x32_bf16 v[30:33], v[226:229], v[194:197], v[30:33]
	v_mfma_f32_16x16x32_bf16 v[26:29], v[234:237], v[194:197], v[26:29]
	v_mfma_f32_16x16x32_bf16 v[22:25], v[226:229], v[202:205], v[22:25]
	v_mfma_f32_16x16x32_bf16 v[18:21], v[234:237], v[202:205], v[18:21]
	v_mfma_f32_16x16x32_bf16 v[14:17], v[226:229], v[210:213], v[14:17]
	v_mfma_f32_16x16x32_bf16 v[10:13], v[234:237], v[210:213], v[10:13]
	v_mfma_f32_16x16x32_bf16 v[6:9], v[226:229], v[218:221], v[6:9]
	v_mfma_f32_16x16x32_bf16 v[2:5], v[234:237], v[218:221], v[2:5]
	v_mfma_f32_16x16x32_bf16 v[30:33], v[230:233], v[198:201], v[30:33]
	v_mfma_f32_16x16x32_bf16 v[26:29], v[238:241], v[198:201], v[26:29]
	v_mfma_f32_16x16x32_bf16 v[22:25], v[230:233], v[206:209], v[22:25]
	v_mfma_f32_16x16x32_bf16 v[18:21], v[238:241], v[206:209], v[18:21]
	v_mfma_f32_16x16x32_bf16 v[14:17], v[230:233], v[214:217], v[14:17]
	v_mfma_f32_16x16x32_bf16 v[10:13], v[238:241], v[214:217], v[10:13]
	v_mfma_f32_16x16x32_bf16 v[6:9], v[230:233], v[222:225], v[6:9]
	v_mfma_f32_16x16x32_bf16 v[2:5], v[238:241], v[222:225], v[2:5]
	s_setprio 0
	s_add_i32 s2, s2, 2
	v_lshl_add_u64 v[132:133], v[132:133], 0, s[88:89]
	v_lshl_add_u64 v[134:135], v[134:135], 0, s[88:89]
	v_lshl_add_u64 v[136:137], v[136:137], 0, s[88:89]
	s_cmp_lt_u32 s2, 38
	v_lshl_add_u64 v[138:139], v[138:139], 0, s[88:89]
	s_barrier
	s_cbranch_scc1 .LBB0_1178
	s_or_b32 s2, s15, 0x80
	s_mul_hi_i32 s3, s2, 0x1500
	s_mulk_i32 s2, 0x1500
	s_add_u32 s2, s23, s2
	s_addc_u32 s3, s24, s3
	v_readfirstlane_b32 s28, v163
	v_lshl_add_u64 v[152:153], s[2:3], 0, v[0:1]
	s_mov_b32 m0, s28
	ds_read_b128 v[132:135], v155
	ds_read_b128 v[136:139], v155 offset:1024
	ds_read_b128 v[168:171], v155 offset:2048
	ds_read_b128 v[172:175], v155 offset:3072
	ds_read_b128 v[186:189], v146
	ds_read_b128 v[190:193], v146 offset:1024
	ds_read_b128 v[194:197], v145
	ds_read_b128 v[198:201], v145 offset:1024
	ds_read_b128 v[202:205], v144
	ds_read_b128 v[206:209], v144 offset:1024
	ds_read_b128 v[210:213], v143
	ds_read_b128 v[214:217], v143 offset:1024
	global_load_lds_dwordx4 v[152:153], off
	v_lshl_add_u64 v[152:153], s[2:3], 0, v[130:131]
	v_readfirstlane_b32 s2, v166
	s_mov_b32 m0, s2
	s_nop 0
	global_load_lds_dwordx4 v[152:153], off
	s_barrier
	s_waitcnt lgkmcnt(0)
	s_setprio 1
	v_mfma_f32_16x16x32_bf16 v[126:129], v[132:135], v[186:189], v[126:129]
	v_mfma_f32_16x16x32_bf16 v[122:125], v[168:171], v[186:189], v[122:125]
	v_mfma_f32_16x16x32_bf16 v[118:121], v[132:135], v[194:197], v[118:121]
	v_mfma_f32_16x16x32_bf16 v[114:117], v[168:171], v[194:197], v[114:117]
	v_mfma_f32_16x16x32_bf16 v[102:105], v[132:135], v[210:213], v[102:105]
	v_mfma_f32_16x16x32_bf16 v[98:101], v[168:171], v[210:213], v[98:101]
	v_mfma_f32_16x16x32_bf16 v[126:129], v[136:139], v[190:193], v[126:129]
	v_mfma_f32_16x16x32_bf16 v[122:125], v[172:175], v[190:193], v[122:125]
	v_mfma_f32_16x16x32_bf16 v[118:121], v[136:139], v[198:201], v[118:121]
	v_mfma_f32_16x16x32_bf16 v[114:117], v[172:175], v[198:201], v[114:117]
	v_mfma_f32_16x16x32_bf16 v[110:113], v[132:135], v[202:205], v[110:113]
	v_mfma_f32_16x16x32_bf16 v[106:109], v[168:171], v[202:205], v[106:109]
	v_mfma_f32_16x16x32_bf16 v[102:105], v[136:139], v[214:217], v[102:105]
	v_mfma_f32_16x16x32_bf16 v[98:101], v[172:175], v[214:217], v[98:101]
	v_mfma_f32_16x16x32_bf16 v[218:221], v[136:139], v[206:209], v[110:113]
	v_mfma_f32_16x16x32_bf16 v[222:225], v[172:175], v[206:209], v[106:109]
	s_setprio 0
	s_barrier
	s_nop 1
	ds_read_b128 v[106:109], v154
	ds_read_b128 v[110:113], v154 offset:1024
	ds_read_b128 v[226:229], v154 offset:2048
	ds_read_b128 v[152:155], v154 offset:3072
	s_barrier
; #define LDA(dst,b,h) for(int m=0;m<4;++m)for(int k=0;k<2;++k) \
;     dst[m][k]=*reinterpret_cast<const bf16x8*>((char*)SA(b,h)+lds_byte(wr*64+m*16+fr,k*32+fq*8))
; #define LDB(dst,b,h) for(int n=0;n<2;++n)for(int k=0;k<2;++k) \
;     dst[n][k]=*reinterpret_cast<const bf16x8*>((char*)SB(b,h)+lds_byte(wc*32+n*16+fr,k*32+fq*8))
; #define MMA(ai,bj,At,Bt_) do{__builtin_amdgcn_s_setprio(1); \
;     for(int m=0;m<4;++m)for(int n=0;n<2;++n)for(int k=0;k<2;++k) \
;       acc[ai][bj][m][n]=__builtin_amdgcn_mfma_f32_16x16x32_bf16(Bt_[n][k],At[m][k],acc[ai][bj][m][n],0,0,0); \
;     __builtin_amdgcn_s_setprio(0);}while(0)
; #define WAIT_V(n) asm volatile("s_waitcnt vmcnt(" #n ")":::"memory")
; #define WAIT_L(n) asm volatile("s_waitcnt lgkmcnt(" #n ")":::"memory")
; #define BAR __builtin_amdgcn_s_barrier()
; template <int EPI>
; __device__ __forceinline__ void gemm_run(const GD& c, const bool has_next, const GD& nx, const Ctx& e, bf16* shm, float* rs, float* rs_nxt, float* racc_) {
;     ...
;     LDB(B1,0,1); BAR; WAIT_L(0); MMA(0,1,At,B1); BAR;
;     LDA(At,0,1); WAIT_V(4); BAR; WAIT_L(0); MMA(1,0,At,B0); MMA(1,1,At,B1); BAR; }
;   { LDB(B0,1,0); LDA(At,1,0); WAIT_V(2); BAR; WAIT_L(0); MMA(0,0,At,B0); BAR;
	s_waitcnt lgkmcnt(0)
	s_setprio 1
	v_mfma_f32_16x16x32_bf16 v[86:89], v[106:109], v[194:197], v[86:89]
	v_mfma_f32_16x16x32_bf16 v[82:85], v[226:229], v[194:197], v[82:85]
	v_mfma_f32_16x16x32_bf16 v[70:73], v[106:109], v[210:213], v[70:73]
	v_mfma_f32_16x16x32_bf16 v[66:69], v[226:229], v[210:213], v[66:69]
	v_mfma_f32_16x16x32_bf16 v[94:97], v[106:109], v[186:189], v[94:97]
	v_mfma_f32_16x16x32_bf16 v[90:93], v[226:229], v[186:189], v[90:93]
	v_mfma_f32_16x16x32_bf16 v[86:89], v[110:113], v[198:201], v[86:89]
	v_mfma_f32_16x16x32_bf16 v[82:85], v[152:155], v[198:201], v[82:85]
	v_mfma_f32_16x16x32_bf16 v[78:81], v[106:109], v[202:205], v[78:81]
	v_mfma_f32_16x16x32_bf16 v[74:77], v[226:229], v[202:205], v[74:77]
	v_mfma_f32_16x16x32_bf16 v[70:73], v[110:113], v[214:217], v[70:73]
	v_mfma_f32_16x16x32_bf16 v[66:69], v[152:155], v[214:217], v[66:69]
	v_mfma_f32_16x16x32_bf16 v[230:233], v[110:113], v[190:193], v[94:97]
	v_mfma_f32_16x16x32_bf16 v[186:189], v[152:155], v[190:193], v[90:93]
	v_mfma_f32_16x16x32_bf16 v[190:193], v[110:113], v[206:209], v[78:81]
	v_mfma_f32_16x16x32_bf16 v[194:197], v[152:155], v[206:209], v[74:77]
	s_setprio 0
	s_barrier
	s_nop 0
	ds_read_b128 v[74:77], v146 offset:16384
	ds_read_b128 v[78:81], v146 offset:17408
	ds_read_b128 v[90:93], v145 offset:16384
	ds_read_b128 v[94:97], v145 offset:17408
	ds_read_b128 v[198:201], v144 offset:16384
	ds_read_b128 v[202:205], v144 offset:17408
	ds_read_b128 v[206:209], v143 offset:16384
	ds_read_b128 v[210:213], v143 offset:17408
	s_waitcnt vmcnt(4)
	s_barrier
	s_waitcnt lgkmcnt(0)
	s_setprio 1
	v_mfma_f32_16x16x32_bf16 v[62:65], v[132:135], v[74:77], v[62:65]
	v_mfma_f32_16x16x32_bf16 v[58:61], v[168:171], v[74:77], v[58:61]
	v_mfma_f32_16x16x32_bf16 v[54:57], v[132:135], v[90:93], v[54:57]
	v_mfma_f32_16x16x32_bf16 v[50:53], v[168:171], v[90:93], v[50:53]
	v_mfma_f32_16x16x32_bf16 v[38:41], v[132:135], v[206:209], v[38:41]
	v_mfma_f32_16x16x32_bf16 v[34:37], v[168:171], v[206:209], v[34:37]
	v_mfma_f32_16x16x32_bf16 v[62:65], v[136:139], v[78:81], v[62:65]
	v_mfma_f32_16x16x32_bf16 v[58:61], v[172:175], v[78:81], v[58:61]
	v_mfma_f32_16x16x32_bf16 v[54:57], v[136:139], v[94:97], v[54:57]
	v_mfma_f32_16x16x32_bf16 v[50:53], v[172:175], v[94:97], v[50:53]
	v_mfma_f32_16x16x32_bf16 v[46:49], v[132:135], v[198:201], v[46:49]
	v_mfma_f32_16x16x32_bf16 v[42:45], v[168:171], v[198:201], v[42:45]
	v_mfma_f32_16x16x32_bf16 v[38:41], v[136:139], v[210:213], v[38:41]
	v_mfma_f32_16x16x32_bf16 v[34:37], v[172:175], v[210:213], v[34:37]
	v_mfma_f32_16x16x32_bf16 v[214:217], v[136:139], v[202:205], v[46:49]
	v_mfma_f32_16x16x32_bf16 v[234:237], v[172:175], v[202:205], v[42:45]
	s_setprio 0
	s_setprio 1
	v_mfma_f32_16x16x32_bf16 v[22:25], v[106:109], v[90:93], v[22:25]
	v_mfma_f32_16x16x32_bf16 v[18:21], v[226:229], v[90:93], v[18:21]
	v_mfma_f32_16x16x32_bf16 v[6:9], v[106:109], v[206:209], v[6:9]
	v_mfma_f32_16x16x32_bf16 v[2:5], v[226:229], v[206:209], v[2:5]
	v_mfma_f32_16x16x32_bf16 v[30:33], v[106:109], v[74:77], v[30:33]
	v_mfma_f32_16x16x32_bf16 v[26:29], v[226:229], v[74:77], v[26:29]
	v_mfma_f32_16x16x32_bf16 v[22:25], v[110:113], v[94:97], v[22:25]
	v_mfma_f32_16x16x32_bf16 v[18:21], v[152:155], v[94:97], v[18:21]
	v_mfma_f32_16x16x32_bf16 v[14:17], v[106:109], v[198:201], v[14:17]
	v_mfma_f32_16x16x32_bf16 v[10:13], v[226:229], v[198:201], v[10:13]
	v_mfma_f32_16x16x32_bf16 v[6:9], v[110:113], v[210:213], v[6:9]
	v_mfma_f32_16x16x32_bf16 v[2:5], v[152:155], v[210:213], v[2:5]
	v_mfma_f32_16x16x32_bf16 v[132:135], v[110:113], v[78:81], v[30:33]
	v_mfma_f32_16x16x32_bf16 v[136:139], v[152:155], v[78:81], v[26:29]
	v_mfma_f32_16x16x32_bf16 v[166:169], v[110:113], v[202:205], v[14:17]
	v_mfma_f32_16x16x32_bf16 v[170:173], v[152:155], v[202:205], v[10:13]
	s_setprio 0
	s_barrier
	s_nop 0
	ds_read_b128 v[10:13], v150
	ds_read_b128 v[14:17], v150 offset:1024
	ds_read_b128 v[152:155], v150 offset:2048
	ds_read_b128 v[198:201], v150 offset:3072
	ds_read_b128 v[26:29], v146 offset:32768
	ds_read_b128 v[30:33], v146 offset:33792
	ds_read_b128 v[42:45], v145 offset:32768
	ds_read_b128 v[46:49], v145 offset:33792
	ds_read_b128 v[202:205], v144 offset:32768
	ds_read_b128 v[206:209], v144 offset:33792
	ds_read_b128 v[210:213], v143 offset:32768
	ds_read_b128 v[226:229], v143 offset:33792
	s_waitcnt vmcnt(2)
	s_barrier
; #define LDA(dst,b,h) for(int m=0;m<4;++m)for(int k=0;k<2;++k) \
;     dst[m][k]=*reinterpret_cast<const bf16x8*>((char*)SA(b,h)+lds_byte(wr*64+m*16+fr,k*32+fq*8))
; #define LDB(dst,b,h) for(int n=0;n<2;++n)for(int k=0;k<2;++k) \
;     dst[n][k]=*reinterpret_cast<const bf16x8*>((char*)SB(b,h)+lds_byte(wc*32+n*16+fr,k*32+fq*8))
; #define MMA(ai,bj,At,Bt_) do{__builtin_amdgcn_s_setprio(1); \
;     for(int m=0;m<4;++m)for(int n=0;n<2;++n)for(int k=0;k<2;++k) \
;       acc[ai][bj][m][n]=__builtin_amdgcn_mfma_f32_16x16x32_bf16(Bt_[n][k],At[m][k],acc[ai][bj][m][n],0,0,0); \
;     __builtin_amdgcn_s_setprio(0);}while(0)
; #define WAIT_V(n) asm volatile("s_waitcnt vmcnt(" #n ")":::"memory")
; #define WAIT_L(n) asm volatile("s_waitcnt lgkmcnt(" #n ")":::"memory")
; #define BAR __builtin_amdgcn_s_barrier()
; template <int EPI>
; __device__ __forceinline__ void gemm_run(const GD& c, const bool has_next, const GD& nx, const Ctx& e, bf16* shm, float* rs, float* rs_nxt, float* racc_) {
;     ...
;   { LDB(B0,1,0); LDA(At,1,0); WAIT_V(2); BAR; WAIT_L(0); MMA(0,0,At,B0); BAR;
;     LDB(B1,1,1); WAIT_V(0); BAR; WAIT_L(0); MMA(0,1,At,B1); BAR;
;     LDA(At,1,1); BAR; WAIT_L(0); MMA(1,0,At,B0); MMA(1,1,At,B1); BAR; }
;   if(wr==0)BAR;
	s_waitcnt lgkmcnt(0)
	s_setprio 1
	v_mfma_f32_16x16x32_bf16 v[74:77], v[10:13], v[26:29], v[126:129]
	v_mfma_f32_16x16x32_bf16 v[126:129], v[14:17], v[30:33], v[74:77]
	v_mfma_f32_16x16x32_bf16 v[74:77], v[152:155], v[26:29], v[122:125]
	v_mfma_f32_16x16x32_bf16 v[122:125], v[198:201], v[30:33], v[74:77]
	v_mfma_f32_16x16x32_bf16 v[74:77], v[10:13], v[42:45], v[118:121]
	v_mfma_f32_16x16x32_bf16 v[110:113], v[14:17], v[46:49], v[74:77]
	v_mfma_f32_16x16x32_bf16 v[74:77], v[152:155], v[42:45], v[114:117]
	v_mfma_f32_16x16x32_bf16 v[106:109], v[198:201], v[46:49], v[74:77]
	v_mfma_f32_16x16x32_bf16 v[74:77], v[10:13], v[202:205], v[218:221]
	v_mfma_f32_16x16x32_bf16 v[94:97], v[14:17], v[206:209], v[74:77]
	v_mfma_f32_16x16x32_bf16 v[74:77], v[152:155], v[202:205], v[222:225]
	v_mfma_f32_16x16x32_bf16 v[90:93], v[198:201], v[206:209], v[74:77]
	v_mfma_f32_16x16x32_bf16 v[74:77], v[10:13], v[210:213], v[102:105]
	v_mfma_f32_16x16x32_bf16 v[78:81], v[14:17], v[226:229], v[74:77]
	v_mfma_f32_16x16x32_bf16 v[74:77], v[152:155], v[210:213], v[98:101]
	v_mfma_f32_16x16x32_bf16 v[74:77], v[198:201], v[226:229], v[74:77]
	s_setprio 0
	s_barrier
	ds_read_b128 v[218:221], v148
	ds_read_b128 v[222:225], v148 offset:1024
	ds_read_b128 v[238:241], v148 offset:2048
	ds_read_b128 v[148:151], v148 offset:3072
	s_waitcnt vmcnt(0)
	s_barrier
	s_waitcnt lgkmcnt(0)
	s_setprio 1
	v_mfma_f32_16x16x32_bf16 v[98:101], v[218:221], v[26:29], v[230:233]
	v_mfma_f32_16x16x32_bf16 v[26:29], v[238:241], v[26:29], v[186:189]
	v_mfma_f32_16x16x32_bf16 v[114:117], v[148:151], v[30:33], v[26:29]
	v_mfma_f32_16x16x32_bf16 v[26:29], v[218:221], v[42:45], v[86:89]
	v_mfma_f32_16x16x32_bf16 v[102:105], v[222:225], v[46:49], v[26:29]
	v_mfma_f32_16x16x32_bf16 v[26:29], v[238:241], v[42:45], v[82:85]
	v_mfma_f32_16x16x32_bf16 v[118:121], v[222:225], v[30:33], v[98:101]
	v_mfma_f32_16x16x32_bf16 v[98:101], v[148:151], v[46:49], v[26:29]
	v_mfma_f32_16x16x32_bf16 v[26:29], v[218:221], v[202:205], v[190:193]
	v_mfma_f32_16x16x32_bf16 v[86:89], v[222:225], v[206:209], v[26:29]
	v_mfma_f32_16x16x32_bf16 v[26:29], v[238:241], v[202:205], v[194:197]
	v_mfma_f32_16x16x32_bf16 v[82:85], v[148:151], v[206:209], v[26:29]
	v_mfma_f32_16x16x32_bf16 v[26:29], v[218:221], v[210:213], v[70:73]
	v_mfma_f32_16x16x32_bf16 v[70:73], v[222:225], v[226:229], v[26:29]
	v_mfma_f32_16x16x32_bf16 v[26:29], v[238:241], v[210:213], v[66:69]
	v_mfma_f32_16x16x32_bf16 v[66:69], v[148:151], v[226:229], v[26:29]
	s_setprio 0
	s_barrier
	ds_read_b128 v[186:189], v146 offset:49152
	ds_read_b128 v[190:193], v146 offset:50176
	ds_read_b128 v[194:197], v145 offset:49152
	ds_read_b128 v[202:205], v145 offset:50176
	ds_read_b128 v[206:209], v144 offset:49152
	ds_read_b128 v[144:147], v144 offset:50176
	ds_read_b128 v[210:213], v143 offset:49152
	ds_read_b128 v[226:229], v143 offset:50176
	s_barrier
	s_waitcnt lgkmcnt(0)
	s_setprio 1
	v_mfma_f32_16x16x32_bf16 v[26:29], v[10:13], v[186:189], v[62:65]
	v_mfma_f32_16x16x32_bf16 v[62:65], v[14:17], v[190:193], v[26:29]
	v_mfma_f32_16x16x32_bf16 v[26:29], v[152:155], v[186:189], v[58:61]
	v_mfma_f32_16x16x32_bf16 v[58:61], v[198:201], v[190:193], v[26:29]
	v_mfma_f32_16x16x32_bf16 v[26:29], v[10:13], v[194:197], v[54:57]
	v_mfma_f32_16x16x32_bf16 v[46:49], v[14:17], v[202:205], v[26:29]
	v_mfma_f32_16x16x32_bf16 v[26:29], v[152:155], v[194:197], v[50:53]
	v_mfma_f32_16x16x32_bf16 v[42:45], v[198:201], v[202:205], v[26:29]
	v_mfma_f32_16x16x32_bf16 v[26:29], v[10:13], v[206:209], v[214:217]
	v_mfma_f32_16x16x32_bf16 v[10:13], v[10:13], v[210:213], v[38:41]
	v_mfma_f32_16x16x32_bf16 v[30:33], v[14:17], v[144:147], v[26:29]
	v_mfma_f32_16x16x32_bf16 v[26:29], v[152:155], v[206:209], v[234:237]
	v_mfma_f32_16x16x32_bf16 v[14:17], v[14:17], v[226:229], v[10:13]
	v_mfma_f32_16x16x32_bf16 v[10:13], v[152:155], v[210:213], v[34:37]
	v_mfma_f32_16x16x32_bf16 v[26:29], v[198:201], v[144:147], v[26:29]
	v_mfma_f32_16x16x32_bf16 v[10:13], v[198:201], v[226:229], v[10:13]
	s_setprio 0
	s_setprio 1
	v_mfma_f32_16x16x32_bf16 v[34:37], v[218:221], v[186:189], v[132:135]
	v_mfma_f32_16x16x32_bf16 v[54:57], v[222:225], v[190:193], v[34:37]
	v_mfma_f32_16x16x32_bf16 v[34:37], v[238:241], v[186:189], v[136:139]
	v_mfma_f32_16x16x32_bf16 v[18:21], v[238:241], v[194:197], v[18:21]
	v_mfma_f32_16x16x32_bf16 v[50:53], v[148:151], v[190:193], v[34:37]
	v_mfma_f32_16x16x32_bf16 v[22:25], v[218:221], v[194:197], v[22:25]
	v_mfma_f32_16x16x32_bf16 v[34:37], v[148:151], v[202:205], v[18:21]
	v_mfma_f32_16x16x32_bf16 v[18:21], v[218:221], v[206:209], v[166:169]
	v_mfma_f32_16x16x32_bf16 v[38:41], v[222:225], v[202:205], v[22:25]
	v_mfma_f32_16x16x32_bf16 v[22:25], v[222:225], v[144:147], v[18:21]
	v_mfma_f32_16x16x32_bf16 v[18:21], v[238:241], v[206:209], v[170:173]
	v_mfma_f32_16x16x32_bf16 v[6:9], v[218:221], v[210:213], v[6:9]
	v_mfma_f32_16x16x32_bf16 v[2:5], v[238:241], v[210:213], v[2:5]
	v_mfma_f32_16x16x32_bf16 v[18:21], v[148:151], v[144:147], v[18:21]
	v_mfma_f32_16x16x32_bf16 v[6:9], v[222:225], v[226:229], v[6:9]
	v_mfma_f32_16x16x32_bf16 v[2:5], v[148:151], v[226:229], v[2:5]
	s_setprio 0
	v_cmp_gt_u32_e32 vcc, s96, v141
	s_barrier
	s_and_saveexec_b64 s[2:3], vcc
	s_cbranch_execz .LBB0_1181
	s_barrier

; #define STAGE_A(P,br,kt) STAGE_G(P,c.A,c.lda,br,(long)(kt)*c.kstr)
; #define STAGE_B(P,br,kt) STAGE_G(P,c.Bt,c.K,br,(long)(kt)*BK)
; #define LDA(dst,b,h) for(int m=0;m<4;++m)for(int k=0;k<2;++k) \
;     dst[m][k]=*reinterpret_cast<const bf16x8*>((char*)SA(b,h)+lds_byte(wr*64+m*16+fr,k*32+fq*8))
; #define LDB(dst,b,h) for(int n=0;n<2;++n)for(int k=0;k<2;++k) \
;     dst[n][k]=*reinterpret_cast<const bf16x8*>((char*)SB(b,h)+lds_byte(wc*32+n*16+fr,k*32+fq*8))
; #define MMA(ai,bj,At,Bt_) do{__builtin_amdgcn_s_setprio(1); \
;     for(int m=0;m<4;++m)for(int n=0;n<2;++n)for(int k=0;k<2;++k) \
;       acc[ai][bj][m][n]=__builtin_amdgcn_mfma_f32_16x16x32_bf16(Bt_[n][k],At[m][k],acc[ai][bj][m][n],0,0,0); \
;     __builtin_amdgcn_s_setprio(0);}while(0)
; #define WAIT_L(n) asm volatile("s_waitcnt lgkmcnt(" #n ")":::"memory")
; #define BAR __builtin_amdgcn_s_barrier()
; #define SCHED __builtin_amdgcn_sched_barrier(0)
; template <int EPI>
; __device__ __forceinline__ void gemm_run(const GD& c, const bool has_next, const GD& nx, const Ctx& e, bf16* shm, float* rs, float* rs_nxt, float* racc_) {
;     ...
;     LDB(B0,0,0); SCHED; LDA(At,0,0); STAGE_A(SA(1,1),brow+HALF,t+1);
;     WAIT_L(8); BAR; WAIT_L(0); MMA(0,0,At,B0); BAR; SCHED;
;     LDB(B1,0,1); STAGE_B(SB(0,0),bcol,t+2);
;     BAR; WAIT_L(0); MMA(0,1,At,B1); BAR;
;     LDA(At,0,1); STAGE_A(SA(0,0),brow,t+2);
;     BAR; WAIT_L(0); MMA(1,0,At,B0); BAR; SCHED;
.LBB0_1426:
	ds_read_b128 v[168:171], v155
	ds_read_b128 v[172:175], v155 offset:1024
	ds_read_b128 v[186:189], v155 offset:2048
	ds_read_b128 v[190:193], v155 offset:3072
	v_add_u32_e32 v163, 0xc000, v142
	v_lshl_add_u64 v[182:183], s[2:3], 0, v[132:133]
	v_readfirstlane_b32 s15, v163
	v_add_u32_e32 v166, 0xe000, v142
	v_lshl_add_u64 v[156:157], v[182:183], 0, s[90:91]
	s_mov_b32 m0, s15
	v_lshl_add_u64 v[242:243], s[2:3], 0, v[134:135]
	v_readfirstlane_b32 s15, v166
	ds_read_b128 v[158:161], v146
	ds_read_b128 v[194:197], v146 offset:1024
	ds_read_b128 v[198:201], v145
	ds_read_b128 v[202:205], v145 offset:1024
	ds_read_b128 v[206:209], v144
	ds_read_b128 v[210:213], v144 offset:1024
	ds_read_b128 v[214:217], v143
	ds_read_b128 v[218:221], v143 offset:1024
	global_load_lds_dwordx4 v[156:157], off
	v_lshl_add_u64 v[156:157], v[242:243], 0, s[90:91]
	s_mov_b32 m0, s15
	s_nop 0
	global_load_lds_dwordx4 v[156:157], off
	s_waitcnt lgkmcnt(8)
	s_barrier
	s_waitcnt lgkmcnt(0)
	s_setprio 1
	v_mfma_f32_16x16x32_bf16 v[126:129], v[168:171], v[158:161], v[126:129]
	v_mfma_f32_16x16x32_bf16 v[122:125], v[186:189], v[158:161], v[122:125]
	v_mfma_f32_16x16x32_bf16 v[118:121], v[168:171], v[198:201], v[118:121]
	v_mfma_f32_16x16x32_bf16 v[114:117], v[186:189], v[198:201], v[114:117]
	v_mfma_f32_16x16x32_bf16 v[110:113], v[168:171], v[206:209], v[110:113]
	v_mfma_f32_16x16x32_bf16 v[106:109], v[186:189], v[206:209], v[106:109]
	v_mfma_f32_16x16x32_bf16 v[102:105], v[168:171], v[214:217], v[102:105]
	v_mfma_f32_16x16x32_bf16 v[98:101], v[186:189], v[214:217], v[98:101]
	v_mfma_f32_16x16x32_bf16 v[126:129], v[172:175], v[194:197], v[126:129]
	v_mfma_f32_16x16x32_bf16 v[122:125], v[190:193], v[194:197], v[122:125]
	v_mfma_f32_16x16x32_bf16 v[118:121], v[172:175], v[202:205], v[118:121]
	v_mfma_f32_16x16x32_bf16 v[114:117], v[190:193], v[202:205], v[114:117]
	v_mfma_f32_16x16x32_bf16 v[110:113], v[172:175], v[210:213], v[110:113]
	v_mfma_f32_16x16x32_bf16 v[106:109], v[190:193], v[210:213], v[106:109]
	v_mfma_f32_16x16x32_bf16 v[102:105], v[172:175], v[218:221], v[102:105]
	v_mfma_f32_16x16x32_bf16 v[98:101], v[190:193], v[218:221], v[98:101]
	s_setprio 0
	s_barrier
	v_add_u32_e32 v156, s33, v148
	v_lshl_add_u64 v[244:245], s[2:3], 0, v[136:137]
	v_readfirstlane_b32 s15, v156
	v_add_u32_e32 v157, 0x2000, v156
	v_lshl_add_u64 v[238:239], v[244:245], 0, s[28:29]
	s_mov_b32 m0, s15
	v_lshl_add_u64 v[246:247], s[2:3], 0, v[138:139]
	v_readfirstlane_b32 s15, v157
	ds_read_b128 v[222:225], v154
	ds_read_b128 v[226:229], v154 offset:1024
	ds_read_b128 v[230:233], v154 offset:2048
	ds_read_b128 v[234:237], v154 offset:3072
	global_load_lds_dwordx4 v[238:239], off
	v_lshl_add_u64 v[238:239], v[246:247], 0, s[28:29]
	s_mov_b32 m0, s15
	s_nop 0
	global_load_lds_dwordx4 v[238:239], off
	s_barrier
	s_waitcnt lgkmcnt(0)
	s_setprio 1
	v_mfma_f32_16x16x32_bf16 v[94:97], v[222:225], v[158:161], v[94:97]
	v_mfma_f32_16x16x32_bf16 v[90:93], v[230:233], v[158:161], v[90:93]
	v_mfma_f32_16x16x32_bf16 v[86:89], v[222:225], v[198:201], v[86:89]
	v_mfma_f32_16x16x32_bf16 v[82:85], v[230:233], v[198:201], v[82:85]
	v_mfma_f32_16x16x32_bf16 v[78:81], v[222:225], v[206:209], v[78:81]
	v_mfma_f32_16x16x32_bf16 v[74:77], v[230:233], v[206:209], v[74:77]
	v_mfma_f32_16x16x32_bf16 v[70:73], v[222:225], v[214:217], v[70:73]
	v_mfma_f32_16x16x32_bf16 v[66:69], v[230:233], v[214:217], v[66:69]
	v_mfma_f32_16x16x32_bf16 v[94:97], v[226:229], v[194:197], v[94:97]
	v_mfma_f32_16x16x32_bf16 v[90:93], v[234:237], v[194:197], v[90:93]
	v_mfma_f32_16x16x32_bf16 v[86:89], v[226:229], v[202:205], v[86:89]
	v_mfma_f32_16x16x32_bf16 v[82:85], v[234:237], v[202:205], v[82:85]
	v_mfma_f32_16x16x32_bf16 v[78:81], v[226:229], v[210:213], v[78:81]
	v_mfma_f32_16x16x32_bf16 v[74:77], v[234:237], v[210:213], v[74:77]
	v_mfma_f32_16x16x32_bf16 v[70:73], v[226:229], v[218:221], v[70:73]
	v_mfma_f32_16x16x32_bf16 v[66:69], v[234:237], v[218:221], v[66:69]
	s_setprio 0
	v_readfirstlane_b32 s15, v142
	v_lshl_add_u64 v[158:159], v[182:183], 0, s[0:1]
	s_mov_b32 m0, s15
	s_barrier
	ds_read_b128 v[194:197], v146 offset:16384
	ds_read_b128 v[198:201], v146 offset:17408
	ds_read_b128 v[202:205], v145 offset:16384
	ds_read_b128 v[206:209], v145 offset:17408
	ds_read_b128 v[210:213], v144 offset:16384
	ds_read_b128 v[214:217], v144 offset:17408
	ds_read_b128 v[218:221], v143 offset:16384
	ds_read_b128 v[238:241], v143 offset:17408
	global_load_lds_dwordx4 v[158:159], off
	v_add_u32_e32 v158, 0x2000, v142
	v_lshl_add_u64 v[160:161], v[242:243], 0, s[0:1]
	v_readfirstlane_b32 s15, v158
	s_mov_b32 m0, s15
	s_nop 0
	global_load_lds_dwordx4 v[160:161], off
	s_barrier
	s_waitcnt lgkmcnt(0)
	s_setprio 1
	v_mfma_f32_16x16x32_bf16 v[62:65], v[168:171], v[194:197], v[62:65]
	v_mfma_f32_16x16x32_bf16 v[58:61], v[186:189], v[194:197], v[58:61]
	v_mfma_f32_16x16x32_bf16 v[54:57], v[168:171], v[202:205], v[54:57]
	v_mfma_f32_16x16x32_bf16 v[50:53], v[186:189], v[202:205], v[50:53]
	v_mfma_f32_16x16x32_bf16 v[46:49], v[168:171], v[210:213], v[46:49]
	v_mfma_f32_16x16x32_bf16 v[42:45], v[186:189], v[210:213], v[42:45]
	v_mfma_f32_16x16x32_bf16 v[38:41], v[168:171], v[218:221], v[38:41]
	v_mfma_f32_16x16x32_bf16 v[34:37], v[186:189], v[218:221], v[34:37]
	v_mfma_f32_16x16x32_bf16 v[62:65], v[172:175], v[198:201], v[62:65]
	v_mfma_f32_16x16x32_bf16 v[58:61], v[190:193], v[198:201], v[58:61]
	v_mfma_f32_16x16x32_bf16 v[54:57], v[172:175], v[206:209], v[54:57]
	v_mfma_f32_16x16x32_bf16 v[50:53], v[190:193], v[206:209], v[50:53]
	v_mfma_f32_16x16x32_bf16 v[46:49], v[172:175], v[214:217], v[46:49]
	v_mfma_f32_16x16x32_bf16 v[42:45], v[190:193], v[214:217], v[42:45]
	v_mfma_f32_16x16x32_bf16 v[38:41], v[172:175], v[238:241], v[38:41]
	v_mfma_f32_16x16x32_bf16 v[34:37], v[190:193], v[238:241], v[34:37]
	s_setprio 0
	s_barrier
; #define STAGE_A(P,br,kt) STAGE_G(P,c.A,c.lda,br,(long)(kt)*c.kstr)
; #define STAGE_B(P,br,kt) STAGE_G(P,c.Bt,c.K,br,(long)(kt)*BK)
; #define LDA(dst,b,h) for(int m=0;m<4;++m)for(int k=0;k<2;++k) \
;     dst[m][k]=*reinterpret_cast<const bf16x8*>((char*)SA(b,h)+lds_byte(wr*64+m*16+fr,k*32+fq*8))
; #define LDB(dst,b,h) for(int n=0;n<2;++n)for(int k=0;k<2;++k) \
;     dst[n][k]=*reinterpret_cast<const bf16x8*>((char*)SB(b,h)+lds_byte(wc*32+n*16+fr,k*32+fq*8))
; #define MMA(ai,bj,At,Bt_) do{__builtin_amdgcn_s_setprio(1); \
;     for(int m=0;m<4;++m)for(int n=0;n<2;++n)for(int k=0;k<2;++k) \
;       acc[ai][bj][m][n]=__builtin_amdgcn_mfma_f32_16x16x32_bf16(Bt_[n][k],At[m][k],acc[ai][bj][m][n],0,0,0); \
;     __builtin_amdgcn_s_setprio(0);}while(0)
; #define WAIT_V(n) asm volatile("s_waitcnt vmcnt(" #n ")":::"memory")
; #define WAIT_L(n) asm volatile("s_waitcnt lgkmcnt(" #n ")":::"memory")
; #define BAR __builtin_amdgcn_s_barrier()
; #define SCHED __builtin_amdgcn_sched_barrier(0)
; template <int EPI>
; __device__ __forceinline__ void gemm_run(const GD& c, const bool has_next, const GD& nx, const Ctx& e, bf16* shm, float* rs, float* rs_nxt, float* racc_) {
;     ...
;     STAGE_B(SB(0,1),bcol+HALF,t+2);
;     WAIT_V(6); BAR; MMA(1,1,At,B1); BAR;
;     LDB(B0,1,0); SCHED; LDA(At,1,0); STAGE_A(SA(0,1),brow+HALF,t+2);
;     WAIT_L(8); BAR; WAIT_L(0); MMA(0,0,At,B0); BAR; SCHED;
;     LDB(B1,1,1); STAGE_B(SB(1,0),bcol,t+3);
;     BAR; WAIT_L(0); MMA(0,1,At,B1); BAR;
	v_add_u32_e32 v159, s86, v148
	v_lshl_add_u64 v[160:161], v[244:245], 0, s[30:31]
	v_readfirstlane_b32 s15, v159
	s_mov_b32 m0, s15
	v_lshl_add_u64 v[168:169], v[246:247], 0, s[30:31]
	global_load_lds_dwordx4 v[160:161], off
	v_add_u32_e32 v160, 0x2000, v159
	s_nop 0
	v_readfirstlane_b32 s15, v160
	s_mov_b32 m0, s15
	s_nop 0
	global_load_lds_dwordx4 v[168:169], off
	s_waitcnt vmcnt(6)
	s_barrier
	s_setprio 1
	v_mfma_f32_16x16x32_bf16 v[30:33], v[222:225], v[194:197], v[30:33]
	v_mfma_f32_16x16x32_bf16 v[26:29], v[230:233], v[194:197], v[26:29]
	v_mfma_f32_16x16x32_bf16 v[22:25], v[222:225], v[202:205], v[22:25]
	v_mfma_f32_16x16x32_bf16 v[18:21], v[230:233], v[202:205], v[18:21]
	v_mfma_f32_16x16x32_bf16 v[14:17], v[222:225], v[210:213], v[14:17]
	v_mfma_f32_16x16x32_bf16 v[10:13], v[230:233], v[210:213], v[10:13]
	v_mfma_f32_16x16x32_bf16 v[6:9], v[222:225], v[218:221], v[6:9]
	v_mfma_f32_16x16x32_bf16 v[2:5], v[230:233], v[218:221], v[2:5]
	v_mfma_f32_16x16x32_bf16 v[30:33], v[226:229], v[198:201], v[30:33]
	v_mfma_f32_16x16x32_bf16 v[26:29], v[234:237], v[198:201], v[26:29]
	v_mfma_f32_16x16x32_bf16 v[22:25], v[226:229], v[206:209], v[22:25]
	v_mfma_f32_16x16x32_bf16 v[18:21], v[234:237], v[206:209], v[18:21]
	v_mfma_f32_16x16x32_bf16 v[14:17], v[226:229], v[214:217], v[14:17]
	v_mfma_f32_16x16x32_bf16 v[10:13], v[234:237], v[214:217], v[10:13]
	v_mfma_f32_16x16x32_bf16 v[6:9], v[226:229], v[238:241], v[6:9]
	v_mfma_f32_16x16x32_bf16 v[2:5], v[234:237], v[238:241], v[2:5]
	s_setprio 0
	s_barrier
	ds_read_b128 v[168:171], v149
	ds_read_b128 v[172:175], v149 offset:1024
	ds_read_b128 v[186:189], v149 offset:2048
	ds_read_b128 v[190:193], v149 offset:3072
	v_add_u32_e32 v161, 0x4000, v142
	v_add_u32_e32 v162, 0x6000, v142
	v_readfirstlane_b32 s15, v161
	v_lshl_add_u64 v[226:227], v[182:183], 0, s[76:77]
	s_mov_b32 m0, s15
	v_readfirstlane_b32 s15, v162
	ds_read_b128 v[194:197], v146 offset:32768
	ds_read_b128 v[198:201], v146 offset:33792
	ds_read_b128 v[202:205], v145 offset:32768
	ds_read_b128 v[206:209], v145 offset:33792
	ds_read_b128 v[210:213], v144 offset:32768
	ds_read_b128 v[214:217], v144 offset:33792
	ds_read_b128 v[218:221], v143 offset:32768
	ds_read_b128 v[222:225], v143 offset:33792
	global_load_lds_dwordx4 v[226:227], off
	v_lshl_add_u64 v[226:227], v[242:243], 0, s[76:77]
	s_mov_b32 m0, s15
	s_nop 0
	global_load_lds_dwordx4 v[226:227], off
	s_waitcnt lgkmcnt(8)
	s_barrier
	s_waitcnt lgkmcnt(0)
	s_setprio 1
	v_mfma_f32_16x16x32_bf16 v[126:129], v[168:171], v[194:197], v[126:129]
	v_mfma_f32_16x16x32_bf16 v[122:125], v[186:189], v[194:197], v[122:125]
	v_mfma_f32_16x16x32_bf16 v[118:121], v[168:171], v[202:205], v[118:121]
	v_mfma_f32_16x16x32_bf16 v[114:117], v[186:189], v[202:205], v[114:117]
	v_mfma_f32_16x16x32_bf16 v[110:113], v[168:171], v[210:213], v[110:113]
	v_mfma_f32_16x16x32_bf16 v[106:109], v[186:189], v[210:213], v[106:109]
	v_mfma_f32_16x16x32_bf16 v[102:105], v[168:171], v[218:221], v[102:105]
	v_mfma_f32_16x16x32_bf16 v[98:101], v[186:189], v[218:221], v[98:101]
	v_mfma_f32_16x16x32_bf16 v[126:129], v[172:175], v[198:201], v[126:129]
	v_mfma_f32_16x16x32_bf16 v[122:125], v[190:193], v[198:201], v[122:125]
	v_mfma_f32_16x16x32_bf16 v[118:121], v[172:175], v[206:209], v[118:121]
	v_mfma_f32_16x16x32_bf16 v[114:117], v[190:193], v[206:209], v[114:117]
	v_mfma_f32_16x16x32_bf16 v[110:113], v[172:175], v[214:217], v[110:113]
	v_mfma_f32_16x16x32_bf16 v[106:109], v[190:193], v[214:217], v[106:109]
	v_mfma_f32_16x16x32_bf16 v[102:105], v[172:175], v[222:225], v[102:105]
	v_mfma_f32_16x16x32_bf16 v[98:101], v[190:193], v[222:225], v[98:101]
	s_setprio 0
	s_barrier
	v_readfirstlane_b32 s15, v150
	v_add_u32_e32 v167, 0x2000, v150
	v_lshl_add_u64 v[248:249], v[244:245], 0, s[34:35]
	s_mov_b32 m0, s15
	v_readfirstlane_b32 s15, v167
	ds_read_b128 v[226:229], v147
	ds_read_b128 v[230:233], v147 offset:1024
	ds_read_b128 v[234:237], v147 offset:2048
	ds_read_b128 v[238:241], v147 offset:3072
	global_load_lds_dwordx4 v[248:249], off
	v_lshl_add_u64 v[248:249], v[246:247], 0, s[34:35]
	s_mov_b32 m0, s15
	s_nop 0
	global_load_lds_dwordx4 v[248:249], off
	s_barrier
	s_waitcnt lgkmcnt(0)
	s_setprio 1
	v_mfma_f32_16x16x32_bf16 v[94:97], v[226:229], v[194:197], v[94:97]
	v_mfma_f32_16x16x32_bf16 v[90:93], v[234:237], v[194:197], v[90:93]
	v_mfma_f32_16x16x32_bf16 v[86:89], v[226:229], v[202:205], v[86:89]
	v_mfma_f32_16x16x32_bf16 v[82:85], v[234:237], v[202:205], v[82:85]
	v_mfma_f32_16x16x32_bf16 v[78:81], v[226:229], v[210:213], v[78:81]
	v_mfma_f32_16x16x32_bf16 v[74:77], v[234:237], v[210:213], v[74:77]
	v_mfma_f32_16x16x32_bf16 v[70:73], v[226:229], v[218:221], v[70:73]
	v_mfma_f32_16x16x32_bf16 v[66:69], v[234:237], v[218:221], v[66:69]
	v_mfma_f32_16x16x32_bf16 v[94:97], v[230:233], v[198:201], v[94:97]
	v_mfma_f32_16x16x32_bf16 v[90:93], v[238:241], v[198:201], v[90:93]
	v_mfma_f32_16x16x32_bf16 v[86:89], v[230:233], v[206:209], v[86:89]
	v_mfma_f32_16x16x32_bf16 v[82:85], v[238:241], v[206:209], v[82:85]
	v_mfma_f32_16x16x32_bf16 v[78:81], v[230:233], v[214:217], v[78:81]
	v_mfma_f32_16x16x32_bf16 v[74:77], v[238:241], v[214:217], v[74:77]
	v_mfma_f32_16x16x32_bf16 v[70:73], v[230:233], v[222:225], v[70:73]
	v_mfma_f32_16x16x32_bf16 v[66:69], v[238:241], v[222:225], v[66:69]
	s_setprio 0
	v_readfirstlane_b32 s15, v151
	v_lshl_add_u64 v[182:183], v[182:183], 0, s[74:75]
	s_mov_b32 m0, s15
	v_readfirstlane_b32 s15, v152
	s_barrier
; #define STAGE_A(P,br,kt) STAGE_G(P,c.A,c.lda,br,(long)(kt)*c.kstr)
; #define STAGE_B(P,br,kt) STAGE_G(P,c.Bt,c.K,br,(long)(kt)*BK)
; #define LDA(dst,b,h) for(int m=0;m<4;++m)for(int k=0;k<2;++k) \
;     dst[m][k]=*reinterpret_cast<const bf16x8*>((char*)SA(b,h)+lds_byte(wr*64+m*16+fr,k*32+fq*8))
; #define LDB(dst,b,h) for(int n=0;n<2;++n)for(int k=0;k<2;++k) \
;     dst[n][k]=*reinterpret_cast<const bf16x8*>((char*)SB(b,h)+lds_byte(wc*32+n*16+fr,k*32+fq*8))
; #define MMA(ai,bj,At,Bt_) do{__builtin_amdgcn_s_setprio(1); \
;     for(int m=0;m<4;++m)for(int n=0;n<2;++n)for(int k=0;k<2;++k) \
;       acc[ai][bj][m][n]=__builtin_amdgcn_mfma_f32_16x16x32_bf16(Bt_[n][k],At[m][k],acc[ai][bj][m][n],0,0,0); \
;     __builtin_amdgcn_s_setprio(0);}while(0)
; #define WAIT_V(n) asm volatile("s_waitcnt vmcnt(" #n ")":::"memory")
; #define WAIT_L(n) asm volatile("s_waitcnt lgkmcnt(" #n ")":::"memory")
; #define BAR __builtin_amdgcn_s_barrier()
; #define SCHED __builtin_amdgcn_sched_barrier(0)
; template <int EPI>
; __device__ __forceinline__ void gemm_run(const GD& c, const bool has_next, const GD& nx, const Ctx& e, bf16* shm, float* rs, float* rs_nxt, float* racc_) {
;     ...
;     LDA(At,1,1); STAGE_A(SA(1,0),brow,t+3);
;     BAR; WAIT_L(0); MMA(1,0,At,B0); BAR; SCHED;
;     STAGE_B(SB(1,1),bcol+HALF,t+3);
;     WAIT_V(6); BAR; MMA(1,1,At,B1); BAR;
;   }
;   { LDB(B0,0,0); LDA(At,0,0); STAGE_A(SA(1,1),brow+HALF,nt-1);
;     BAR; WAIT_L(0); MMA(0,0,At,B0); BAR;
;     LDB(B1,0,1); BAR; WAIT_L(0); MMA(0,1,At,B1); BAR;
	ds_read_b128 v[194:197], v146 offset:49152
	ds_read_b128 v[198:201], v146 offset:50176
	ds_read_b128 v[202:205], v145 offset:49152
	ds_read_b128 v[206:209], v145 offset:50176
	ds_read_b128 v[210:213], v144 offset:49152
	ds_read_b128 v[214:217], v144 offset:50176
	ds_read_b128 v[218:221], v143 offset:49152
	ds_read_b128 v[222:225], v143 offset:50176
	global_load_lds_dwordx4 v[182:183], off
	v_lshl_add_u64 v[182:183], v[242:243], 0, s[74:75]
	s_mov_b32 m0, s15
	s_nop 0
	global_load_lds_dwordx4 v[182:183], off
	s_barrier
	s_waitcnt lgkmcnt(0)
	s_setprio 1
	v_mfma_f32_16x16x32_bf16 v[62:65], v[168:171], v[194:197], v[62:65]
	v_mfma_f32_16x16x32_bf16 v[58:61], v[186:189], v[194:197], v[58:61]
	v_mfma_f32_16x16x32_bf16 v[54:57], v[168:171], v[202:205], v[54:57]
	v_mfma_f32_16x16x32_bf16 v[50:53], v[186:189], v[202:205], v[50:53]
	v_mfma_f32_16x16x32_bf16 v[46:49], v[168:171], v[210:213], v[46:49]
	v_mfma_f32_16x16x32_bf16 v[42:45], v[186:189], v[210:213], v[42:45]
	v_mfma_f32_16x16x32_bf16 v[38:41], v[168:171], v[218:221], v[38:41]
	v_mfma_f32_16x16x32_bf16 v[34:37], v[186:189], v[218:221], v[34:37]
	v_mfma_f32_16x16x32_bf16 v[62:65], v[172:175], v[198:201], v[62:65]
	v_mfma_f32_16x16x32_bf16 v[58:61], v[190:193], v[198:201], v[58:61]
	v_mfma_f32_16x16x32_bf16 v[54:57], v[172:175], v[206:209], v[54:57]
	v_mfma_f32_16x16x32_bf16 v[50:53], v[190:193], v[206:209], v[50:53]
	v_mfma_f32_16x16x32_bf16 v[46:49], v[172:175], v[214:217], v[46:49]
	v_mfma_f32_16x16x32_bf16 v[42:45], v[190:193], v[214:217], v[42:45]
	v_mfma_f32_16x16x32_bf16 v[38:41], v[172:175], v[222:225], v[38:41]
	v_mfma_f32_16x16x32_bf16 v[34:37], v[190:193], v[222:225], v[34:37]
	s_setprio 0
	s_barrier
	v_readfirstlane_b32 s15, v153
	v_add_u32_e32 v167, 0x2000, v153
	v_lshl_add_u64 v[168:169], v[244:245], 0, s[36:37]
	s_mov_b32 m0, s15
	v_readfirstlane_b32 s15, v167
	global_load_lds_dwordx4 v[168:169], off
	v_lshl_add_u64 v[168:169], v[246:247], 0, s[36:37]
	s_mov_b32 m0, s15
	s_nop 0
	global_load_lds_dwordx4 v[168:169], off
	s_waitcnt vmcnt(6)
	s_barrier
	s_setprio 1
	v_mfma_f32_16x16x32_bf16 v[30:33], v[226:229], v[194:197], v[30:33]
	v_mfma_f32_16x16x32_bf16 v[26:29], v[234:237], v[194:197], v[26:29]
	v_mfma_f32_16x16x32_bf16 v[22:25], v[226:229], v[202:205], v[22:25]
	v_mfma_f32_16x16x32_bf16 v[18:21], v[234:237], v[202:205], v[18:21]
	v_mfma_f32_16x16x32_bf16 v[14:17], v[226:229], v[210:213], v[14:17]
	v_mfma_f32_16x16x32_bf16 v[10:13], v[234:237], v[210:213], v[10:13]
	v_mfma_f32_16x16x32_bf16 v[6:9], v[226:229], v[218:221], v[6:9]
	v_mfma_f32_16x16x32_bf16 v[2:5], v[234:237], v[218:221], v[2:5]
	v_mfma_f32_16x16x32_bf16 v[30:33], v[230:233], v[198:201], v[30:33]
	v_mfma_f32_16x16x32_bf16 v[26:29], v[238:241], v[198:201], v[26:29]
	v_mfma_f32_16x16x32_bf16 v[22:25], v[230:233], v[206:209], v[22:25]
	v_mfma_f32_16x16x32_bf16 v[18:21], v[238:241], v[206:209], v[18:21]
	v_mfma_f32_16x16x32_bf16 v[14:17], v[230:233], v[214:217], v[14:17]
	v_mfma_f32_16x16x32_bf16 v[10:13], v[238:241], v[214:217], v[10:13]
	v_mfma_f32_16x16x32_bf16 v[6:9], v[230:233], v[222:225], v[6:9]
	v_mfma_f32_16x16x32_bf16 v[2:5], v[238:241], v[222:225], v[2:5]
	s_setprio 0
	s_add_i32 s14, s14, 2
	s_add_u32 s2, s2, 0x100
	s_addc_u32 s3, s3, 0
	s_cmp_lt_u32 s14, 38
	s_barrier
	s_cbranch_scc1 .LBB0_1426
	s_or_b32 s27, s25, 0x80
	s_mul_i32 s2, s27, 0x1500
	s_mul_hi_i32 s3, s27, 0x1500
	s_add_u32 s2, s21, s2
	s_addc_u32 s3, s22, s3
	v_readfirstlane_b32 s14, v163
	v_lshl_add_u64 v[182:183], s[2:3], 0, v[0:1]
	s_mov_b32 m0, s14
	ds_read_b128 v[132:135], v155
	ds_read_b128 v[136:139], v155 offset:1024
	ds_read_b128 v[150:153], v155 offset:2048
	ds_read_b128 v[168:171], v155 offset:3072
	ds_read_b128 v[172:175], v146
	ds_read_b128 v[186:189], v146 offset:1024
	ds_read_b128 v[190:193], v145
	ds_read_b128 v[194:197], v145 offset:1024
	ds_read_b128 v[198:201], v144
	ds_read_b128 v[202:205], v144 offset:1024
	ds_read_b128 v[206:209], v143
	ds_read_b128 v[210:213], v143 offset:1024
	global_load_lds_dwordx4 v[182:183], off
	v_lshl_add_u64 v[182:183], s[2:3], 0, v[130:131]
	v_readfirstlane_b32 s2, v166
	s_mov_b32 m0, s2
	s_nop 0
	global_load_lds_dwordx4 v[182:183], off
	s_barrier
	s_waitcnt lgkmcnt(0)
	s_setprio 1
	v_mfma_f32_16x16x32_bf16 v[126:129], v[132:135], v[172:175], v[126:129]
	v_mfma_f32_16x16x32_bf16 v[122:125], v[150:153], v[172:175], v[122:125]
	v_mfma_f32_16x16x32_bf16 v[118:121], v[132:135], v[190:193], v[118:121]
	v_mfma_f32_16x16x32_bf16 v[114:117], v[150:153], v[190:193], v[114:117]
	v_mfma_f32_16x16x32_bf16 v[106:109], v[150:153], v[198:201], v[106:109]
	v_mfma_f32_16x16x32_bf16 v[98:101], v[150:153], v[206:209], v[98:101]
	v_mfma_f32_16x16x32_bf16 v[126:129], v[136:139], v[186:189], v[126:129]
	v_mfma_f32_16x16x32_bf16 v[122:125], v[168:171], v[186:189], v[122:125]
	v_mfma_f32_16x16x32_bf16 v[118:121], v[136:139], v[194:197], v[118:121]
	v_mfma_f32_16x16x32_bf16 v[114:117], v[168:171], v[194:197], v[114:117]
	v_mfma_f32_16x16x32_bf16 v[110:113], v[132:135], v[198:201], v[110:113]
	v_mfma_f32_16x16x32_bf16 v[106:109], v[168:171], v[202:205], v[106:109]
	v_mfma_f32_16x16x32_bf16 v[102:105], v[132:135], v[206:209], v[102:105]
	v_mfma_f32_16x16x32_bf16 v[98:101], v[168:171], v[210:213], v[98:101]
	v_mfma_f32_16x16x32_bf16 v[214:217], v[136:139], v[202:205], v[110:113]
	v_mfma_f32_16x16x32_bf16 v[218:221], v[136:139], v[210:213], v[102:105]
	s_setprio 0
	s_barrier
	s_nop 2
	ds_read_b128 v[102:105], v154
	ds_read_b128 v[110:113], v154 offset:1024
	ds_read_b128 v[222:225], v154 offset:2048
	ds_read_b128 v[226:229], v154 offset:3072
	s_barrier
; #define LDA(dst,b,h) for(int m=0;m<4;++m)for(int k=0;k<2;++k) \
;     dst[m][k]=*reinterpret_cast<const bf16x8*>((char*)SA(b,h)+lds_byte(wr*64+m*16+fr,k*32+fq*8))
; #define LDB(dst,b,h) for(int n=0;n<2;++n)for(int k=0;k<2;++k) \
;     dst[n][k]=*reinterpret_cast<const bf16x8*>((char*)SB(b,h)+lds_byte(wc*32+n*16+fr,k*32+fq*8))
; #define MMA(ai,bj,At,Bt_) do{__builtin_amdgcn_s_setprio(1); \
;     for(int m=0;m<4;++m)for(int n=0;n<2;++n)for(int k=0;k<2;++k) \
;       acc[ai][bj][m][n]=__builtin_amdgcn_mfma_f32_16x16x32_bf16(Bt_[n][k],At[m][k],acc[ai][bj][m][n],0,0,0); \
;     __builtin_amdgcn_s_setprio(0);}while(0)
; #define WAIT_V(n) asm volatile("s_waitcnt vmcnt(" #n ")":::"memory")
; #define WAIT_L(n) asm volatile("s_waitcnt lgkmcnt(" #n ")":::"memory")
; #define BAR __builtin_amdgcn_s_barrier()
; template <int EPI>
; __device__ __forceinline__ void gemm_run(const GD& c, const bool has_next, const GD& nx, const Ctx& e, bf16* shm, float* rs, float* rs_nxt, float* racc_) {
;     ...
;     LDB(B1,0,1); BAR; WAIT_L(0); MMA(0,1,At,B1); BAR;
;     LDA(At,0,1); WAIT_V(4); BAR; WAIT_L(0); MMA(1,0,At,B0); MMA(1,1,At,B1); BAR; }
;   { LDB(B0,1,0); LDA(At,1,0); WAIT_V(2); BAR; WAIT_L(0); MMA(0,0,At,B0); BAR;
	s_waitcnt lgkmcnt(0)
	s_setprio 1
	v_mfma_f32_16x16x32_bf16 v[90:93], v[222:225], v[172:175], v[90:93]
	v_mfma_f32_16x16x32_bf16 v[82:85], v[222:225], v[190:193], v[82:85]
	v_mfma_f32_16x16x32_bf16 v[74:77], v[222:225], v[198:201], v[74:77]
	v_mfma_f32_16x16x32_bf16 v[66:69], v[222:225], v[206:209], v[66:69]
	v_mfma_f32_16x16x32_bf16 v[94:97], v[102:105], v[172:175], v[94:97]
	v_mfma_f32_16x16x32_bf16 v[90:93], v[226:229], v[186:189], v[90:93]
	v_mfma_f32_16x16x32_bf16 v[86:89], v[102:105], v[190:193], v[86:89]
	v_mfma_f32_16x16x32_bf16 v[82:85], v[226:229], v[194:197], v[82:85]
	v_mfma_f32_16x16x32_bf16 v[78:81], v[102:105], v[198:201], v[78:81]
	v_mfma_f32_16x16x32_bf16 v[74:77], v[226:229], v[202:205], v[74:77]
	v_mfma_f32_16x16x32_bf16 v[70:73], v[102:105], v[206:209], v[70:73]
	v_mfma_f32_16x16x32_bf16 v[66:69], v[226:229], v[210:213], v[66:69]
	v_mfma_f32_16x16x32_bf16 v[230:233], v[110:113], v[186:189], v[94:97]
	v_mfma_f32_16x16x32_bf16 v[172:175], v[110:113], v[194:197], v[86:89]
	v_mfma_f32_16x16x32_bf16 v[186:189], v[110:113], v[202:205], v[78:81]
	v_mfma_f32_16x16x32_bf16 v[190:193], v[110:113], v[210:213], v[70:73]
	s_setprio 0
	s_barrier
	s_nop 0
	ds_read_b128 v[70:73], v146 offset:16384
	ds_read_b128 v[78:81], v146 offset:17408
	ds_read_b128 v[86:89], v145 offset:16384
	ds_read_b128 v[94:97], v145 offset:17408
	ds_read_b128 v[194:197], v144 offset:16384
	ds_read_b128 v[198:201], v144 offset:17408
	ds_read_b128 v[202:205], v143 offset:16384
	ds_read_b128 v[206:209], v143 offset:17408
	s_waitcnt vmcnt(4)
	s_barrier
	s_waitcnt lgkmcnt(0)
	s_setprio 1
	v_mfma_f32_16x16x32_bf16 v[62:65], v[132:135], v[70:73], v[62:65]
	v_mfma_f32_16x16x32_bf16 v[58:61], v[150:153], v[70:73], v[58:61]
	v_mfma_f32_16x16x32_bf16 v[54:57], v[132:135], v[86:89], v[54:57]
	v_mfma_f32_16x16x32_bf16 v[50:53], v[150:153], v[86:89], v[50:53]
	v_mfma_f32_16x16x32_bf16 v[38:41], v[132:135], v[202:205], v[38:41]
	v_mfma_f32_16x16x32_bf16 v[34:37], v[150:153], v[202:205], v[34:37]
	v_mfma_f32_16x16x32_bf16 v[62:65], v[136:139], v[78:81], v[62:65]
	v_mfma_f32_16x16x32_bf16 v[58:61], v[168:171], v[78:81], v[58:61]
	v_mfma_f32_16x16x32_bf16 v[54:57], v[136:139], v[94:97], v[54:57]
	v_mfma_f32_16x16x32_bf16 v[50:53], v[168:171], v[94:97], v[50:53]
	v_mfma_f32_16x16x32_bf16 v[46:49], v[132:135], v[194:197], v[46:49]
	v_mfma_f32_16x16x32_bf16 v[42:45], v[150:153], v[194:197], v[42:45]
	v_mfma_f32_16x16x32_bf16 v[38:41], v[136:139], v[206:209], v[38:41]
	v_mfma_f32_16x16x32_bf16 v[34:37], v[168:171], v[206:209], v[34:37]
	v_mfma_f32_16x16x32_bf16 v[210:213], v[136:139], v[198:201], v[46:49]
	v_mfma_f32_16x16x32_bf16 v[234:237], v[168:171], v[198:201], v[42:45]
	s_setprio 0
	s_setprio 1
	v_mfma_f32_16x16x32_bf16 v[22:25], v[102:105], v[86:89], v[22:25]
	v_mfma_f32_16x16x32_bf16 v[18:21], v[222:225], v[86:89], v[18:21]
	v_mfma_f32_16x16x32_bf16 v[6:9], v[102:105], v[202:205], v[6:9]
	v_mfma_f32_16x16x32_bf16 v[2:5], v[222:225], v[202:205], v[2:5]
	v_mfma_f32_16x16x32_bf16 v[30:33], v[102:105], v[70:73], v[30:33]
	v_mfma_f32_16x16x32_bf16 v[26:29], v[222:225], v[70:73], v[26:29]
	v_mfma_f32_16x16x32_bf16 v[22:25], v[110:113], v[94:97], v[22:25]
	v_mfma_f32_16x16x32_bf16 v[18:21], v[226:229], v[94:97], v[18:21]
	v_mfma_f32_16x16x32_bf16 v[14:17], v[102:105], v[194:197], v[14:17]
	v_mfma_f32_16x16x32_bf16 v[10:13], v[222:225], v[194:197], v[10:13]
	v_mfma_f32_16x16x32_bf16 v[6:9], v[110:113], v[206:209], v[6:9]
	v_mfma_f32_16x16x32_bf16 v[2:5], v[226:229], v[206:209], v[2:5]
	v_mfma_f32_16x16x32_bf16 v[132:135], v[110:113], v[78:81], v[30:33]
	v_mfma_f32_16x16x32_bf16 v[136:139], v[226:229], v[78:81], v[26:29]
	v_mfma_f32_16x16x32_bf16 v[150:153], v[110:113], v[198:201], v[14:17]
	v_mfma_f32_16x16x32_bf16 v[166:169], v[226:229], v[198:201], v[10:13]
	s_setprio 0
	s_barrier
	s_nop 0
	ds_read_b128 v[10:13], v149
	ds_read_b128 v[14:17], v149 offset:1024
	ds_read_b128 v[194:197], v149 offset:2048
	ds_read_b128 v[198:201], v149 offset:3072
	ds_read_b128 v[26:29], v146 offset:32768
	ds_read_b128 v[30:33], v146 offset:33792
	ds_read_b128 v[42:45], v145 offset:32768
	ds_read_b128 v[46:49], v145 offset:33792
	ds_read_b128 v[202:205], v144 offset:32768
	ds_read_b128 v[206:209], v144 offset:33792
	ds_read_b128 v[222:225], v143 offset:32768
	ds_read_b128 v[226:229], v143 offset:33792
	s_waitcnt vmcnt(2)
	s_barrier
; #define LDA(dst,b,h) for(int m=0;m<4;++m)for(int k=0;k<2;++k) \
;     dst[m][k]=*reinterpret_cast<const bf16x8*>((char*)SA(b,h)+lds_byte(wr*64+m*16+fr,k*32+fq*8))
; #define LDB(dst,b,h) for(int n=0;n<2;++n)for(int k=0;k<2;++k) \
;     dst[n][k]=*reinterpret_cast<const bf16x8*>((char*)SB(b,h)+lds_byte(wc*32+n*16+fr,k*32+fq*8))
; #define MMA(ai,bj,At,Bt_) do{__builtin_amdgcn_s_setprio(1); \
;     for(int m=0;m<4;++m)for(int n=0;n<2;++n)for(int k=0;k<2;++k) \
;       acc[ai][bj][m][n]=__builtin_amdgcn_mfma_f32_16x16x32_bf16(Bt_[n][k],At[m][k],acc[ai][bj][m][n],0,0,0); \
;     __builtin_amdgcn_s_setprio(0);}while(0)
; #define WAIT_V(n) asm volatile("s_waitcnt vmcnt(" #n ")":::"memory")
; #define WAIT_L(n) asm volatile("s_waitcnt lgkmcnt(" #n ")":::"memory")
; #define BAR __builtin_amdgcn_s_barrier()
; template <int EPI>
; __device__ __forceinline__ void gemm_run(const GD& c, const bool has_next, const GD& nx, const Ctx& e, bf16* shm, float* rs, float* rs_nxt, float* racc_) {
;     ...
;   { LDB(B0,1,0); LDA(At,1,0); WAIT_V(2); BAR; WAIT_L(0); MMA(0,0,At,B0); BAR;
;     LDB(B1,1,1); WAIT_V(0); BAR; WAIT_L(0); MMA(0,1,At,B1); BAR;
;     LDA(At,1,1); BAR; WAIT_L(0); MMA(1,0,At,B0); MMA(1,1,At,B1); BAR; }
;   if(wr==0)BAR;
	s_waitcnt lgkmcnt(0)
	s_setprio 1
	v_mfma_f32_16x16x32_bf16 v[70:73], v[10:13], v[26:29], v[126:129]
	v_mfma_f32_16x16x32_bf16 v[126:129], v[14:17], v[30:33], v[70:73]
	v_mfma_f32_16x16x32_bf16 v[70:73], v[194:197], v[26:29], v[122:125]
	v_mfma_f32_16x16x32_bf16 v[122:125], v[198:201], v[30:33], v[70:73]
	v_mfma_f32_16x16x32_bf16 v[70:73], v[10:13], v[42:45], v[118:121]
	v_mfma_f32_16x16x32_bf16 v[110:113], v[14:17], v[46:49], v[70:73]
	v_mfma_f32_16x16x32_bf16 v[70:73], v[194:197], v[42:45], v[114:117]
	v_mfma_f32_16x16x32_bf16 v[102:105], v[198:201], v[46:49], v[70:73]
	v_mfma_f32_16x16x32_bf16 v[70:73], v[10:13], v[202:205], v[214:217]
	v_mfma_f32_16x16x32_bf16 v[94:97], v[14:17], v[206:209], v[70:73]
	v_mfma_f32_16x16x32_bf16 v[70:73], v[194:197], v[202:205], v[106:109]
	v_mfma_f32_16x16x32_bf16 v[86:89], v[198:201], v[206:209], v[70:73]
	v_mfma_f32_16x16x32_bf16 v[70:73], v[10:13], v[222:225], v[218:221]
	v_mfma_f32_16x16x32_bf16 v[78:81], v[14:17], v[226:229], v[70:73]
	v_mfma_f32_16x16x32_bf16 v[70:73], v[194:197], v[222:225], v[98:101]
	v_mfma_f32_16x16x32_bf16 v[70:73], v[198:201], v[226:229], v[70:73]
	s_setprio 0
	s_barrier
	ds_read_b128 v[214:217], v147
	ds_read_b128 v[218:221], v147 offset:1024
	ds_read_b128 v[238:241], v147 offset:2048
	ds_read_b128 v[242:245], v147 offset:3072
	s_waitcnt vmcnt(0)
	s_barrier
	s_waitcnt lgkmcnt(0)
	s_setprio 1
	v_mfma_f32_16x16x32_bf16 v[98:101], v[214:217], v[26:29], v[230:233]
	v_mfma_f32_16x16x32_bf16 v[26:29], v[238:241], v[26:29], v[90:93]
	v_mfma_f32_16x16x32_bf16 v[114:117], v[242:245], v[30:33], v[26:29]
	v_mfma_f32_16x16x32_bf16 v[26:29], v[214:217], v[42:45], v[172:175]
	v_mfma_f32_16x16x32_bf16 v[106:109], v[218:221], v[46:49], v[26:29]
	v_mfma_f32_16x16x32_bf16 v[26:29], v[238:241], v[42:45], v[82:85]
	v_mfma_f32_16x16x32_bf16 v[118:121], v[218:221], v[30:33], v[98:101]
	v_mfma_f32_16x16x32_bf16 v[98:101], v[242:245], v[46:49], v[26:29]
	v_mfma_f32_16x16x32_bf16 v[26:29], v[214:217], v[202:205], v[186:189]
	v_mfma_f32_16x16x32_bf16 v[90:93], v[218:221], v[206:209], v[26:29]
	v_mfma_f32_16x16x32_bf16 v[26:29], v[238:241], v[202:205], v[74:77]
	v_mfma_f32_16x16x32_bf16 v[82:85], v[242:245], v[206:209], v[26:29]
	v_mfma_f32_16x16x32_bf16 v[26:29], v[214:217], v[222:225], v[190:193]
	v_mfma_f32_16x16x32_bf16 v[74:77], v[218:221], v[226:229], v[26:29]
	v_mfma_f32_16x16x32_bf16 v[26:29], v[238:241], v[222:225], v[66:69]
	v_mfma_f32_16x16x32_bf16 v[66:69], v[242:245], v[226:229], v[26:29]
	s_setprio 0
	s_barrier
	ds_read_b128 v[170:173], v146 offset:49152
	ds_read_b128 v[146:149], v146 offset:50176
	ds_read_b128 v[186:189], v145 offset:49152
	ds_read_b128 v[190:193], v145 offset:50176
	ds_read_b128 v[202:205], v144 offset:49152
	ds_read_b128 v[206:209], v144 offset:50176
	ds_read_b128 v[222:225], v143 offset:49152
	ds_read_b128 v[226:229], v143 offset:50176
	s_barrier
	s_waitcnt lgkmcnt(0)
	s_setprio 1
	v_mfma_f32_16x16x32_bf16 v[26:29], v[10:13], v[170:173], v[62:65]
	v_mfma_f32_16x16x32_bf16 v[62:65], v[14:17], v[146:149], v[26:29]
	v_mfma_f32_16x16x32_bf16 v[26:29], v[194:197], v[170:173], v[58:61]
	v_mfma_f32_16x16x32_bf16 v[58:61], v[198:201], v[146:149], v[26:29]
	v_mfma_f32_16x16x32_bf16 v[26:29], v[10:13], v[186:189], v[54:57]
	v_mfma_f32_16x16x32_bf16 v[46:49], v[14:17], v[190:193], v[26:29]
	v_mfma_f32_16x16x32_bf16 v[26:29], v[194:197], v[186:189], v[50:53]
	v_mfma_f32_16x16x32_bf16 v[42:45], v[198:201], v[190:193], v[26:29]
	v_mfma_f32_16x16x32_bf16 v[26:29], v[10:13], v[202:205], v[210:213]
	v_mfma_f32_16x16x32_bf16 v[10:13], v[10:13], v[222:225], v[38:41]
	v_mfma_f32_16x16x32_bf16 v[30:33], v[14:17], v[206:209], v[26:29]
	v_mfma_f32_16x16x32_bf16 v[26:29], v[194:197], v[202:205], v[234:237]
	v_mfma_f32_16x16x32_bf16 v[14:17], v[14:17], v[226:229], v[10:13]
	v_mfma_f32_16x16x32_bf16 v[10:13], v[194:197], v[222:225], v[34:37]
	v_mfma_f32_16x16x32_bf16 v[26:29], v[198:201], v[206:209], v[26:29]
	v_mfma_f32_16x16x32_bf16 v[10:13], v[198:201], v[226:229], v[10:13]
	s_setprio 0
	s_setprio 1
	v_mfma_f32_16x16x32_bf16 v[34:37], v[214:217], v[170:173], v[132:135]
	v_mfma_f32_16x16x32_bf16 v[54:57], v[218:221], v[146:149], v[34:37]
	v_mfma_f32_16x16x32_bf16 v[34:37], v[238:241], v[170:173], v[136:139]
	v_mfma_f32_16x16x32_bf16 v[18:21], v[238:241], v[186:189], v[18:21]
	v_mfma_f32_16x16x32_bf16 v[50:53], v[242:245], v[146:149], v[34:37]
	v_mfma_f32_16x16x32_bf16 v[22:25], v[214:217], v[186:189], v[22:25]
	v_mfma_f32_16x16x32_bf16 v[34:37], v[242:245], v[190:193], v[18:21]
	v_mfma_f32_16x16x32_bf16 v[18:21], v[214:217], v[202:205], v[150:153]
	v_mfma_f32_16x16x32_bf16 v[38:41], v[218:221], v[190:193], v[22:25]
	v_mfma_f32_16x16x32_bf16 v[22:25], v[218:221], v[206:209], v[18:21]
	v_mfma_f32_16x16x32_bf16 v[18:21], v[238:241], v[202:205], v[166:169]
	v_mfma_f32_16x16x32_bf16 v[6:9], v[214:217], v[222:225], v[6:9]
	v_mfma_f32_16x16x32_bf16 v[2:5], v[238:241], v[222:225], v[2:5]
	v_mfma_f32_16x16x32_bf16 v[18:21], v[242:245], v[206:209], v[18:21]
	v_mfma_f32_16x16x32_bf16 v[6:9], v[218:221], v[226:229], v[6:9]
	v_mfma_f32_16x16x32_bf16 v[2:5], v[242:245], v[226:229], v[2:5]
	s_setprio 0
	v_cmp_gt_u32_e32 vcc, s96, v141
	s_barrier
	s_and_saveexec_b64 s[2:3], vcc
	s_cbranch_execz .LBB0_1429
	s_barrier

; #define STAGE_A(P,br,kt) STAGE_G(P,c.A,c.lda,br,(long)(kt)*c.kstr)
; #define STAGE_B(P,br,kt) STAGE_G(P,c.Bt,c.K,br,(long)(kt)*BK)
; #define LDA(dst,b,h) for(int m=0;m<4;++m)for(int k=0;k<2;++k) \
;     dst[m][k]=*reinterpret_cast<const bf16x8*>((char*)SA(b,h)+lds_byte(wr*64+m*16+fr,k*32+fq*8))
; #define LDB(dst,b,h) for(int n=0;n<2;++n)for(int k=0;k<2;++k) \
;     dst[n][k]=*reinterpret_cast<const bf16x8*>((char*)SB(b,h)+lds_byte(wc*32+n*16+fr,k*32+fq*8))
; #define MMA(ai,bj,At,Bt_) do{__builtin_amdgcn_s_setprio(1); \
;     for(int m=0;m<4;++m)for(int n=0;n<2;++n)for(int k=0;k<2;++k) \
;       acc[ai][bj][m][n]=__builtin_amdgcn_mfma_f32_16x16x32_bf16(Bt_[n][k],At[m][k],acc[ai][bj][m][n],0,0,0); \
;     __builtin_amdgcn_s_setprio(0);}while(0)
; #define WAIT_L(n) asm volatile("s_waitcnt lgkmcnt(" #n ")":::"memory")
; #define BAR __builtin_amdgcn_s_barrier()
; #define SCHED __builtin_amdgcn_sched_barrier(0)
; template <int EPI>
; __device__ __forceinline__ void gemm_run(const GD& c, const bool has_next, const GD& nx, const Ctx& e, bf16* shm, float* rs, float* rs_nxt, float* racc_) {
;     ...
;     LDB(B0,0,0); SCHED; LDA(At,0,0); STAGE_A(SA(1,1),brow+HALF,t+1);
;     WAIT_L(8); BAR; WAIT_L(0); MMA(0,0,At,B0); BAR; SCHED;
;     LDB(B1,0,1); STAGE_B(SB(0,0),bcol,t+2);
;     BAR; WAIT_L(0); MMA(0,1,At,B1); BAR;
;     LDA(At,0,1); STAGE_A(SA(0,0),brow,t+2);
;     BAR; WAIT_L(0); MMA(1,0,At,B0); BAR; SCHED;
.LBB0_1505:
	ds_read_b128 v[158:161], v155
	ds_read_b128 v[166:169], v155 offset:1024
	ds_read_b128 v[170:173], v155 offset:2048
	ds_read_b128 v[186:189], v155 offset:3072
	v_add_u32_e32 v156, 0xc000, v150
	v_lshl_add_u64 v[162:163], v[132:133], 0, s[8:9]
	v_readfirstlane_b32 s12, v156
	v_lshl_add_u64 v[174:175], v[162:163], 0, s[90:91]
	s_mov_b32 m0, s12
	v_add_u32_e32 v157, 0xe000, v150
	ds_read_b128 v[190:193], v145
	ds_read_b128 v[194:197], v145 offset:1024
	ds_read_b128 v[198:201], v144
	ds_read_b128 v[202:205], v144 offset:1024
	ds_read_b128 v[206:209], v143
	ds_read_b128 v[210:213], v143 offset:1024
	ds_read_b128 v[214:217], v142
	ds_read_b128 v[218:221], v142 offset:1024
	global_load_lds_dwordx4 v[174:175], off
	v_lshl_add_u64 v[174:175], v[134:135], 0, s[8:9]
	v_readfirstlane_b32 s12, v157
	v_lshl_add_u64 v[182:183], v[174:175], 0, s[90:91]
	s_mov_b32 m0, s12
	s_nop 0
	global_load_lds_dwordx4 v[182:183], off
	s_waitcnt lgkmcnt(8)
	s_barrier
	s_waitcnt lgkmcnt(0)
	s_setprio 1
	v_mfma_f32_16x16x32_bf16 v[126:129], v[158:161], v[190:193], v[126:129]
	v_mfma_f32_16x16x32_bf16 v[122:125], v[170:173], v[190:193], v[122:125]
	v_mfma_f32_16x16x32_bf16 v[118:121], v[158:161], v[198:201], v[118:121]
	v_mfma_f32_16x16x32_bf16 v[114:117], v[170:173], v[198:201], v[114:117]
	v_mfma_f32_16x16x32_bf16 v[110:113], v[158:161], v[206:209], v[110:113]
	v_mfma_f32_16x16x32_bf16 v[106:109], v[170:173], v[206:209], v[106:109]
	v_mfma_f32_16x16x32_bf16 v[102:105], v[158:161], v[214:217], v[102:105]
	v_mfma_f32_16x16x32_bf16 v[98:101], v[170:173], v[214:217], v[98:101]
	v_mfma_f32_16x16x32_bf16 v[126:129], v[166:169], v[194:197], v[126:129]
	v_mfma_f32_16x16x32_bf16 v[122:125], v[186:189], v[194:197], v[122:125]
	v_mfma_f32_16x16x32_bf16 v[118:121], v[166:169], v[202:205], v[118:121]
	v_mfma_f32_16x16x32_bf16 v[114:117], v[186:189], v[202:205], v[114:117]
	v_mfma_f32_16x16x32_bf16 v[110:113], v[166:169], v[210:213], v[110:113]
	v_mfma_f32_16x16x32_bf16 v[106:109], v[186:189], v[210:213], v[106:109]
	v_mfma_f32_16x16x32_bf16 v[102:105], v[166:169], v[218:221], v[102:105]
	v_mfma_f32_16x16x32_bf16 v[98:101], v[186:189], v[218:221], v[98:101]
	s_setprio 0
	s_barrier
	v_add_u32_e32 v176, s33, v146
	v_lshl_add_u64 v[182:183], v[136:137], 0, s[8:9]
	v_readfirstlane_b32 s12, v176
	v_lshl_add_u64 v[238:239], v[182:183], 0, s[24:25]
	s_mov_b32 m0, s12
	v_add_u32_e32 v176, 0x2000, v176
	ds_read_b128 v[222:225], v154
	ds_read_b128 v[226:229], v154 offset:1024
	ds_read_b128 v[230:233], v154 offset:2048
	ds_read_b128 v[234:237], v154 offset:3072
	global_load_lds_dwordx4 v[238:239], off
	v_lshl_add_u64 v[238:239], v[138:139], 0, s[8:9]
	v_readfirstlane_b32 s12, v176
	v_lshl_add_u64 v[240:241], v[238:239], 0, s[24:25]
	s_mov_b32 m0, s12
	s_add_i32 s11, s11, 2
	global_load_lds_dwordx4 v[240:241], off
	s_barrier
	s_waitcnt lgkmcnt(0)
	s_setprio 1
	v_mfma_f32_16x16x32_bf16 v[94:97], v[222:225], v[190:193], v[94:97]
	v_mfma_f32_16x16x32_bf16 v[90:93], v[230:233], v[190:193], v[90:93]
	v_mfma_f32_16x16x32_bf16 v[86:89], v[222:225], v[198:201], v[86:89]
	v_mfma_f32_16x16x32_bf16 v[82:85], v[230:233], v[198:201], v[82:85]
	v_mfma_f32_16x16x32_bf16 v[78:81], v[222:225], v[206:209], v[78:81]
	v_mfma_f32_16x16x32_bf16 v[74:77], v[230:233], v[206:209], v[74:77]
	v_mfma_f32_16x16x32_bf16 v[70:73], v[222:225], v[214:217], v[70:73]
	v_mfma_f32_16x16x32_bf16 v[66:69], v[230:233], v[214:217], v[66:69]
	v_mfma_f32_16x16x32_bf16 v[94:97], v[226:229], v[194:197], v[94:97]
	v_mfma_f32_16x16x32_bf16 v[90:93], v[234:237], v[194:197], v[90:93]
	v_mfma_f32_16x16x32_bf16 v[86:89], v[226:229], v[202:205], v[86:89]
	v_mfma_f32_16x16x32_bf16 v[82:85], v[234:237], v[202:205], v[82:85]
	v_mfma_f32_16x16x32_bf16 v[78:81], v[226:229], v[210:213], v[78:81]
	v_mfma_f32_16x16x32_bf16 v[74:77], v[234:237], v[210:213], v[74:77]
	v_mfma_f32_16x16x32_bf16 v[70:73], v[226:229], v[218:221], v[70:73]
	v_mfma_f32_16x16x32_bf16 v[66:69], v[234:237], v[218:221], v[66:69]
	s_setprio 0
	v_readfirstlane_b32 s12, v150
	v_add_u32_e32 v176, 0x2000, v150
	v_lshl_add_u64 v[240:241], v[162:163], 0, s[0:1]
	s_mov_b32 m0, s12
	v_readfirstlane_b32 s12, v176
	s_barrier
	ds_read_b128 v[190:193], v145 offset:16384
	ds_read_b128 v[194:197], v145 offset:17408
	ds_read_b128 v[198:201], v144 offset:16384
	ds_read_b128 v[202:205], v144 offset:17408
	ds_read_b128 v[206:209], v143 offset:16384
	ds_read_b128 v[210:213], v143 offset:17408
	ds_read_b128 v[214:217], v142 offset:16384
	ds_read_b128 v[218:221], v142 offset:17408
	global_load_lds_dwordx4 v[240:241], off
	v_lshl_add_u64 v[240:241], v[174:175], 0, s[0:1]
	s_mov_b32 m0, s12
	s_nop 0
	global_load_lds_dwordx4 v[240:241], off
	s_barrier
	s_waitcnt lgkmcnt(0)
	s_setprio 1
	v_mfma_f32_16x16x32_bf16 v[62:65], v[158:161], v[190:193], v[62:65]
	v_mfma_f32_16x16x32_bf16 v[58:61], v[170:173], v[190:193], v[58:61]
	v_mfma_f32_16x16x32_bf16 v[54:57], v[158:161], v[198:201], v[54:57]
	v_mfma_f32_16x16x32_bf16 v[50:53], v[170:173], v[198:201], v[50:53]
	v_mfma_f32_16x16x32_bf16 v[46:49], v[158:161], v[206:209], v[46:49]
	v_mfma_f32_16x16x32_bf16 v[42:45], v[170:173], v[206:209], v[42:45]
	v_mfma_f32_16x16x32_bf16 v[38:41], v[158:161], v[214:217], v[38:41]
	v_mfma_f32_16x16x32_bf16 v[34:37], v[170:173], v[214:217], v[34:37]
	v_mfma_f32_16x16x32_bf16 v[62:65], v[166:169], v[194:197], v[62:65]
	v_mfma_f32_16x16x32_bf16 v[58:61], v[186:189], v[194:197], v[58:61]
	v_mfma_f32_16x16x32_bf16 v[54:57], v[166:169], v[202:205], v[54:57]
	v_mfma_f32_16x16x32_bf16 v[50:53], v[186:189], v[202:205], v[50:53]
	v_mfma_f32_16x16x32_bf16 v[46:49], v[166:169], v[210:213], v[46:49]
	v_mfma_f32_16x16x32_bf16 v[42:45], v[186:189], v[210:213], v[42:45]
	v_mfma_f32_16x16x32_bf16 v[38:41], v[166:169], v[218:221], v[38:41]
	v_mfma_f32_16x16x32_bf16 v[34:37], v[186:189], v[218:221], v[34:37]
	s_setprio 0
	s_barrier
; #define STAGE_A(P,br,kt) STAGE_G(P,c.A,c.lda,br,(long)(kt)*c.kstr)
; #define STAGE_B(P,br,kt) STAGE_G(P,c.Bt,c.K,br,(long)(kt)*BK)
; #define LDA(dst,b,h) for(int m=0;m<4;++m)for(int k=0;k<2;++k) \
;     dst[m][k]=*reinterpret_cast<const bf16x8*>((char*)SA(b,h)+lds_byte(wr*64+m*16+fr,k*32+fq*8))
; #define LDB(dst,b,h) for(int n=0;n<2;++n)for(int k=0;k<2;++k) \
;     dst[n][k]=*reinterpret_cast<const bf16x8*>((char*)SB(b,h)+lds_byte(wc*32+n*16+fr,k*32+fq*8))
; #define MMA(ai,bj,At,Bt_) do{__builtin_amdgcn_s_setprio(1); \
;     for(int m=0;m<4;++m)for(int n=0;n<2;++n)for(int k=0;k<2;++k) \
;       acc[ai][bj][m][n]=__builtin_amdgcn_mfma_f32_16x16x32_bf16(Bt_[n][k],At[m][k],acc[ai][bj][m][n],0,0,0); \
;     __builtin_amdgcn_s_setprio(0);}while(0)
; #define WAIT_V(n) asm volatile("s_waitcnt vmcnt(" #n ")":::"memory")
; #define WAIT_L(n) asm volatile("s_waitcnt lgkmcnt(" #n ")":::"memory")
; #define BAR __builtin_amdgcn_s_barrier()
; #define SCHED __builtin_amdgcn_sched_barrier(0)
; template <int EPI>
; __device__ __forceinline__ void gemm_run(const GD& c, const bool has_next, const GD& nx, const Ctx& e, bf16* shm, float* rs, float* rs_nxt, float* racc_) {
;     ...
;     STAGE_B(SB(0,1),bcol+HALF,t+2);
;     WAIT_V(6); BAR; MMA(1,1,At,B1); BAR;
;     LDB(B0,1,0); SCHED; LDA(At,1,0); STAGE_A(SA(0,1),brow+HALF,t+2);
;     WAIT_L(8); BAR; WAIT_L(0); MMA(0,0,At,B0); BAR; SCHED;
;     LDB(B1,1,1); STAGE_B(SB(1,0),bcol,t+3);
;     BAR; WAIT_L(0); MMA(0,1,At,B1); BAR;
	v_add_u32_e32 v160, s86, v146
	v_lshl_add_u64 v[158:159], v[182:183], 0, s[26:27]
	v_readfirstlane_b32 s12, v160
	v_add_u32_e32 v160, 0x2000, v160
	s_mov_b32 m0, s12
	v_readfirstlane_b32 s12, v160
	global_load_lds_dwordx4 v[158:159], off
	v_lshl_add_u64 v[158:159], v[238:239], 0, s[26:27]
	s_mov_b32 m0, s12
	s_nop 0
	global_load_lds_dwordx4 v[158:159], off
	s_waitcnt vmcnt(6)
	s_barrier
	s_setprio 1
	v_mfma_f32_16x16x32_bf16 v[30:33], v[222:225], v[190:193], v[30:33]
	v_mfma_f32_16x16x32_bf16 v[26:29], v[230:233], v[190:193], v[26:29]
	v_mfma_f32_16x16x32_bf16 v[22:25], v[222:225], v[198:201], v[22:25]
	v_mfma_f32_16x16x32_bf16 v[18:21], v[230:233], v[198:201], v[18:21]
	v_mfma_f32_16x16x32_bf16 v[14:17], v[222:225], v[206:209], v[14:17]
	v_mfma_f32_16x16x32_bf16 v[10:13], v[230:233], v[206:209], v[10:13]
	v_mfma_f32_16x16x32_bf16 v[6:9], v[222:225], v[214:217], v[6:9]
	v_mfma_f32_16x16x32_bf16 v[2:5], v[230:233], v[214:217], v[2:5]
	v_mfma_f32_16x16x32_bf16 v[30:33], v[226:229], v[194:197], v[30:33]
	v_mfma_f32_16x16x32_bf16 v[26:29], v[234:237], v[194:197], v[26:29]
	v_mfma_f32_16x16x32_bf16 v[22:25], v[226:229], v[202:205], v[22:25]
	v_mfma_f32_16x16x32_bf16 v[18:21], v[234:237], v[202:205], v[18:21]
	v_mfma_f32_16x16x32_bf16 v[14:17], v[226:229], v[210:213], v[14:17]
	v_mfma_f32_16x16x32_bf16 v[10:13], v[234:237], v[210:213], v[10:13]
	v_mfma_f32_16x16x32_bf16 v[6:9], v[226:229], v[218:221], v[6:9]
	v_mfma_f32_16x16x32_bf16 v[2:5], v[234:237], v[218:221], v[2:5]
	s_setprio 0
	s_barrier
	ds_read_b128 v[158:161], v149
	ds_read_b128 v[166:169], v149 offset:1024
	ds_read_b128 v[170:173], v149 offset:2048
	ds_read_b128 v[186:189], v149 offset:3072
	v_add_u32_e32 v176, 0x4000, v150
	v_lshl_add_u64 v[222:223], v[162:163], 0, s[76:77]
	v_readfirstlane_b32 s12, v176
	v_add_u32_e32 v176, 0x6000, v150
	s_mov_b32 m0, s12
	v_readfirstlane_b32 s12, v176
	ds_read_b128 v[190:193], v145 offset:32768
	ds_read_b128 v[194:197], v145 offset:33792
	ds_read_b128 v[198:201], v144 offset:32768
	ds_read_b128 v[202:205], v144 offset:33792
	ds_read_b128 v[206:209], v143 offset:32768
	ds_read_b128 v[210:213], v143 offset:33792
	ds_read_b128 v[214:217], v142 offset:32768
	ds_read_b128 v[218:221], v142 offset:33792
	global_load_lds_dwordx4 v[222:223], off
	v_lshl_add_u64 v[222:223], v[174:175], 0, s[76:77]
	s_mov_b32 m0, s12
	s_nop 0
	global_load_lds_dwordx4 v[222:223], off
	s_waitcnt lgkmcnt(8)
	s_barrier
	s_waitcnt lgkmcnt(0)
	s_setprio 1
	v_mfma_f32_16x16x32_bf16 v[126:129], v[158:161], v[190:193], v[126:129]
	v_mfma_f32_16x16x32_bf16 v[122:125], v[170:173], v[190:193], v[122:125]
	v_mfma_f32_16x16x32_bf16 v[118:121], v[158:161], v[198:201], v[118:121]
	v_mfma_f32_16x16x32_bf16 v[114:117], v[170:173], v[198:201], v[114:117]
	v_mfma_f32_16x16x32_bf16 v[110:113], v[158:161], v[206:209], v[110:113]
	v_mfma_f32_16x16x32_bf16 v[106:109], v[170:173], v[206:209], v[106:109]
	v_mfma_f32_16x16x32_bf16 v[102:105], v[158:161], v[214:217], v[102:105]
	v_mfma_f32_16x16x32_bf16 v[98:101], v[170:173], v[214:217], v[98:101]
	v_mfma_f32_16x16x32_bf16 v[126:129], v[166:169], v[194:197], v[126:129]
	v_mfma_f32_16x16x32_bf16 v[122:125], v[186:189], v[194:197], v[122:125]
	v_mfma_f32_16x16x32_bf16 v[118:121], v[166:169], v[202:205], v[118:121]
	v_mfma_f32_16x16x32_bf16 v[114:117], v[186:189], v[202:205], v[114:117]
	v_mfma_f32_16x16x32_bf16 v[110:113], v[166:169], v[210:213], v[110:113]
	v_mfma_f32_16x16x32_bf16 v[106:109], v[186:189], v[210:213], v[106:109]
	v_mfma_f32_16x16x32_bf16 v[102:105], v[166:169], v[218:221], v[102:105]
	v_mfma_f32_16x16x32_bf16 v[98:101], v[186:189], v[218:221], v[98:101]
	s_setprio 0
	s_barrier
	v_readfirstlane_b32 s12, v148
	v_add_u32_e32 v176, 0x2000, v148
	v_lshl_add_u64 v[240:241], v[182:183], 0, s[28:29]
	s_mov_b32 m0, s12
	v_readfirstlane_b32 s12, v176
	ds_read_b128 v[222:225], v147
	ds_read_b128 v[226:229], v147 offset:1024
	ds_read_b128 v[230:233], v147 offset:2048
	ds_read_b128 v[234:237], v147 offset:3072
	global_load_lds_dwordx4 v[240:241], off
	v_lshl_add_u64 v[240:241], v[238:239], 0, s[28:29]
	s_mov_b32 m0, s12
	s_nop 0
	global_load_lds_dwordx4 v[240:241], off
	s_barrier
	s_waitcnt lgkmcnt(0)
	s_setprio 1
	v_mfma_f32_16x16x32_bf16 v[94:97], v[222:225], v[190:193], v[94:97]
	v_mfma_f32_16x16x32_bf16 v[90:93], v[230:233], v[190:193], v[90:93]
	v_mfma_f32_16x16x32_bf16 v[86:89], v[222:225], v[198:201], v[86:89]
	v_mfma_f32_16x16x32_bf16 v[82:85], v[230:233], v[198:201], v[82:85]
	v_mfma_f32_16x16x32_bf16 v[78:81], v[222:225], v[206:209], v[78:81]
	v_mfma_f32_16x16x32_bf16 v[74:77], v[230:233], v[206:209], v[74:77]
	v_mfma_f32_16x16x32_bf16 v[70:73], v[222:225], v[214:217], v[70:73]
	v_mfma_f32_16x16x32_bf16 v[66:69], v[230:233], v[214:217], v[66:69]
	v_mfma_f32_16x16x32_bf16 v[94:97], v[226:229], v[194:197], v[94:97]
	v_mfma_f32_16x16x32_bf16 v[90:93], v[234:237], v[194:197], v[90:93]
	v_mfma_f32_16x16x32_bf16 v[86:89], v[226:229], v[202:205], v[86:89]
	v_mfma_f32_16x16x32_bf16 v[82:85], v[234:237], v[202:205], v[82:85]
	v_mfma_f32_16x16x32_bf16 v[78:81], v[226:229], v[210:213], v[78:81]
	v_mfma_f32_16x16x32_bf16 v[74:77], v[234:237], v[210:213], v[74:77]
	v_mfma_f32_16x16x32_bf16 v[70:73], v[226:229], v[218:221], v[70:73]
	v_mfma_f32_16x16x32_bf16 v[66:69], v[234:237], v[218:221], v[66:69]
	s_setprio 0
	v_readfirstlane_b32 s12, v151
	v_lshl_add_u64 v[162:163], v[162:163], 0, s[74:75]
	s_mov_b32 m0, s12
	v_readfirstlane_b32 s12, v152
	s_barrier
; #define STAGE_A(P,br,kt) STAGE_G(P,c.A,c.lda,br,(long)(kt)*c.kstr)
; #define STAGE_B(P,br,kt) STAGE_G(P,c.Bt,c.K,br,(long)(kt)*BK)
; #define LDA(dst,b,h) for(int m=0;m<4;++m)for(int k=0;k<2;++k) \
;     dst[m][k]=*reinterpret_cast<const bf16x8*>((char*)SA(b,h)+lds_byte(wr*64+m*16+fr,k*32+fq*8))
; #define LDB(dst,b,h) for(int n=0;n<2;++n)for(int k=0;k<2;++k) \
;     dst[n][k]=*reinterpret_cast<const bf16x8*>((char*)SB(b,h)+lds_byte(wc*32+n*16+fr,k*32+fq*8))
; #define MMA(ai,bj,At,Bt_) do{__builtin_amdgcn_s_setprio(1); \
;     for(int m=0;m<4;++m)for(int n=0;n<2;++n)for(int k=0;k<2;++k) \
;       acc[ai][bj][m][n]=__builtin_amdgcn_mfma_f32_16x16x32_bf16(Bt_[n][k],At[m][k],acc[ai][bj][m][n],0,0,0); \
;     __builtin_amdgcn_s_setprio(0);}while(0)
; #define WAIT_V(n) asm volatile("s_waitcnt vmcnt(" #n ")":::"memory")
; #define WAIT_L(n) asm volatile("s_waitcnt lgkmcnt(" #n ")":::"memory")
; #define BAR __builtin_amdgcn_s_barrier()
; #define SCHED __builtin_amdgcn_sched_barrier(0)
; template <int EPI>
; __device__ __forceinline__ void gemm_run(const GD& c, const bool has_next, const GD& nx, const Ctx& e, bf16* shm, float* rs, float* rs_nxt, float* racc_) {
;     ...
;     LDA(At,1,1); STAGE_A(SA(1,0),brow,t+3);
;     BAR; WAIT_L(0); MMA(1,0,At,B0); BAR; SCHED;
;     STAGE_B(SB(1,1),bcol+HALF,t+3);
;     WAIT_V(6); BAR; MMA(1,1,At,B1); BAR;
;   }
;   { LDB(B0,0,0); LDA(At,0,0); STAGE_A(SA(1,1),brow+HALF,nt-1);
;     BAR; WAIT_L(0); MMA(0,0,At,B0); BAR;
;     LDB(B1,0,1); BAR; WAIT_L(0); MMA(0,1,At,B1); BAR;
	ds_read_b128 v[190:193], v145 offset:49152
	ds_read_b128 v[194:197], v145 offset:50176
	ds_read_b128 v[198:201], v144 offset:49152
	ds_read_b128 v[202:205], v144 offset:50176
	ds_read_b128 v[206:209], v143 offset:49152
	ds_read_b128 v[210:213], v143 offset:50176
	ds_read_b128 v[214:217], v142 offset:49152
	ds_read_b128 v[218:221], v142 offset:50176
	global_load_lds_dwordx4 v[162:163], off
	v_lshl_add_u64 v[162:163], v[174:175], 0, s[74:75]
	s_mov_b32 m0, s12
	s_nop 0
	global_load_lds_dwordx4 v[162:163], off
	s_barrier
	s_waitcnt lgkmcnt(0)
	s_setprio 1
	v_mfma_f32_16x16x32_bf16 v[62:65], v[158:161], v[190:193], v[62:65]
	v_mfma_f32_16x16x32_bf16 v[58:61], v[170:173], v[190:193], v[58:61]
	v_mfma_f32_16x16x32_bf16 v[54:57], v[158:161], v[198:201], v[54:57]
	v_mfma_f32_16x16x32_bf16 v[50:53], v[170:173], v[198:201], v[50:53]
	v_mfma_f32_16x16x32_bf16 v[46:49], v[158:161], v[206:209], v[46:49]
	v_mfma_f32_16x16x32_bf16 v[42:45], v[170:173], v[206:209], v[42:45]
	v_mfma_f32_16x16x32_bf16 v[38:41], v[158:161], v[214:217], v[38:41]
	v_mfma_f32_16x16x32_bf16 v[34:37], v[170:173], v[214:217], v[34:37]
	v_mfma_f32_16x16x32_bf16 v[62:65], v[166:169], v[194:197], v[62:65]
	v_mfma_f32_16x16x32_bf16 v[58:61], v[186:189], v[194:197], v[58:61]
	v_mfma_f32_16x16x32_bf16 v[54:57], v[166:169], v[202:205], v[54:57]
	v_mfma_f32_16x16x32_bf16 v[50:53], v[186:189], v[202:205], v[50:53]
	v_mfma_f32_16x16x32_bf16 v[46:49], v[166:169], v[210:213], v[46:49]
	v_mfma_f32_16x16x32_bf16 v[42:45], v[186:189], v[210:213], v[42:45]
	v_mfma_f32_16x16x32_bf16 v[38:41], v[166:169], v[218:221], v[38:41]
	v_mfma_f32_16x16x32_bf16 v[34:37], v[186:189], v[218:221], v[34:37]
	s_setprio 0
	s_barrier
	v_readfirstlane_b32 s12, v153
	v_add_u32_e32 v160, 0x2000, v153
	v_lshl_add_u64 v[158:159], v[182:183], 0, s[30:31]
	s_mov_b32 m0, s12
	v_readfirstlane_b32 s12, v160
	global_load_lds_dwordx4 v[158:159], off
	v_lshl_add_u64 v[158:159], v[238:239], 0, s[30:31]
	s_mov_b32 m0, s12
	s_nop 0
	global_load_lds_dwordx4 v[158:159], off
	s_waitcnt vmcnt(6)
	s_barrier
	s_setprio 1
	v_mfma_f32_16x16x32_bf16 v[30:33], v[222:225], v[190:193], v[30:33]
	v_mfma_f32_16x16x32_bf16 v[26:29], v[230:233], v[190:193], v[26:29]
	v_mfma_f32_16x16x32_bf16 v[22:25], v[222:225], v[198:201], v[22:25]
	v_mfma_f32_16x16x32_bf16 v[18:21], v[230:233], v[198:201], v[18:21]
	v_mfma_f32_16x16x32_bf16 v[14:17], v[222:225], v[206:209], v[14:17]
	v_mfma_f32_16x16x32_bf16 v[10:13], v[230:233], v[206:209], v[10:13]
	v_mfma_f32_16x16x32_bf16 v[6:9], v[222:225], v[214:217], v[6:9]
	v_mfma_f32_16x16x32_bf16 v[2:5], v[230:233], v[214:217], v[2:5]
	v_mfma_f32_16x16x32_bf16 v[30:33], v[226:229], v[194:197], v[30:33]
	v_mfma_f32_16x16x32_bf16 v[26:29], v[234:237], v[194:197], v[26:29]
	v_mfma_f32_16x16x32_bf16 v[22:25], v[226:229], v[202:205], v[22:25]
	v_mfma_f32_16x16x32_bf16 v[18:21], v[234:237], v[202:205], v[18:21]
	v_mfma_f32_16x16x32_bf16 v[14:17], v[226:229], v[210:213], v[14:17]
	v_mfma_f32_16x16x32_bf16 v[10:13], v[234:237], v[210:213], v[10:13]
	v_mfma_f32_16x16x32_bf16 v[6:9], v[226:229], v[218:221], v[6:9]
	v_mfma_f32_16x16x32_bf16 v[2:5], v[234:237], v[218:221], v[2:5]
	s_setprio 0
	v_lshl_add_u64 v[132:133], v[132:133], 0, s[88:89]
	v_lshl_add_u64 v[134:135], v[134:135], 0, s[88:89]
	v_lshl_add_u64 v[136:137], v[136:137], 0, s[88:89]
	s_cmp_lt_u32 s11, s10
	v_lshl_add_u64 v[138:139], v[138:139], 0, s[88:89]
	s_barrier
	s_cbranch_scc1 .LBB0_1505
	s_lshl_b32 s7, s7, 7
	s_add_u32 s2, s2, s7
	s_addc_u32 s3, s3, 0
	s_movk_i32 s8, 0xff80
	v_lshl_add_u64 v[162:163], s[2:3], 0, v[0:1]
	s_mov_b32 s9, -1
	v_readfirstlane_b32 s7, v156
	v_lshl_add_u64 v[162:163], v[162:163], 0, s[8:9]
	s_mov_b32 m0, s7
	v_lshl_add_u64 v[130:131], s[2:3], 0, v[130:131]
	v_readfirstlane_b32 s2, v157
	ds_read_b128 v[132:135], v155
	ds_read_b128 v[136:139], v155 offset:1024
	ds_read_b128 v[150:153], v155 offset:2048
	ds_read_b128 v[158:161], v155 offset:3072
	ds_read_b128 v[166:169], v145
	ds_read_b128 v[170:173], v145 offset:1024
	ds_read_b128 v[186:189], v144
	ds_read_b128 v[190:193], v144 offset:1024
	ds_read_b128 v[194:197], v143
	ds_read_b128 v[198:201], v143 offset:1024
	ds_read_b128 v[202:205], v142
	ds_read_b128 v[206:209], v142 offset:1024
	global_load_lds_dwordx4 v[162:163], off
	v_lshl_add_u64 v[130:131], v[130:131], 0, s[8:9]
	s_mov_b32 m0, s2
	s_nop 0
	global_load_lds_dwordx4 v[130:131], off
	s_barrier
	s_waitcnt lgkmcnt(0)
	s_setprio 1
	v_mfma_f32_16x16x32_bf16 v[126:129], v[132:135], v[166:169], v[126:129]
	v_mfma_f32_16x16x32_bf16 v[122:125], v[150:153], v[166:169], v[122:125]
	v_mfma_f32_16x16x32_bf16 v[118:121], v[132:135], v[186:189], v[118:121]
	v_mfma_f32_16x16x32_bf16 v[114:117], v[150:153], v[186:189], v[114:117]
	v_mfma_f32_16x16x32_bf16 v[110:113], v[132:135], v[194:197], v[110:113]
	v_mfma_f32_16x16x32_bf16 v[106:109], v[150:153], v[194:197], v[106:109]
	v_mfma_f32_16x16x32_bf16 v[102:105], v[132:135], v[202:205], v[102:105]
	v_mfma_f32_16x16x32_bf16 v[98:101], v[150:153], v[202:205], v[98:101]
	v_mfma_f32_16x16x32_bf16 v[126:129], v[136:139], v[170:173], v[126:129]
	v_mfma_f32_16x16x32_bf16 v[122:125], v[158:161], v[170:173], v[122:125]
	v_mfma_f32_16x16x32_bf16 v[118:121], v[136:139], v[190:193], v[118:121]
	v_mfma_f32_16x16x32_bf16 v[114:117], v[158:161], v[190:193], v[114:117]
	v_mfma_f32_16x16x32_bf16 v[110:113], v[136:139], v[198:201], v[110:113]
	v_mfma_f32_16x16x32_bf16 v[106:109], v[158:161], v[198:201], v[106:109]
	v_mfma_f32_16x16x32_bf16 v[102:105], v[136:139], v[206:209], v[102:105]
	v_mfma_f32_16x16x32_bf16 v[98:101], v[158:161], v[206:209], v[98:101]
	s_setprio 0
	s_barrier
; #define LDA(dst,b,h) for(int m=0;m<4;++m)for(int k=0;k<2;++k) \
;     dst[m][k]=*reinterpret_cast<const bf16x8*>((char*)SA(b,h)+lds_byte(wr*64+m*16+fr,k*32+fq*8))
; #define LDB(dst,b,h) for(int n=0;n<2;++n)for(int k=0;k<2;++k) \
;     dst[n][k]=*reinterpret_cast<const bf16x8*>((char*)SB(b,h)+lds_byte(wc*32+n*16+fr,k*32+fq*8))
; #define MMA(ai,bj,At,Bt_) do{__builtin_amdgcn_s_setprio(1); \
;     for(int m=0;m<4;++m)for(int n=0;n<2;++n)for(int k=0;k<2;++k) \
;       acc[ai][bj][m][n]=__builtin_amdgcn_mfma_f32_16x16x32_bf16(Bt_[n][k],At[m][k],acc[ai][bj][m][n],0,0,0); \
;     __builtin_amdgcn_s_setprio(0);}while(0)
; #define WAIT_V(n) asm volatile("s_waitcnt vmcnt(" #n ")":::"memory")
; #define WAIT_L(n) asm volatile("s_waitcnt lgkmcnt(" #n ")":::"memory")
; #define BAR __builtin_amdgcn_s_barrier()
; template <int EPI>
; __device__ __forceinline__ void gemm_run(const GD& c, const bool has_next, const GD& nx, const Ctx& e, bf16* shm, float* rs, float* rs_nxt, float* racc_) {
;     ...
;     LDB(B1,0,1); BAR; WAIT_L(0); MMA(0,1,At,B1); BAR;
;     LDA(At,0,1); WAIT_V(4); BAR; WAIT_L(0); MMA(1,0,At,B0); MMA(1,1,At,B1); BAR; }
;   { LDB(B0,1,0); LDA(At,1,0); WAIT_V(2); BAR; WAIT_L(0); MMA(0,0,At,B0); BAR;
	ds_read_b128 v[210:213], v154
	ds_read_b128 v[214:217], v154 offset:1024
	ds_read_b128 v[218:221], v154 offset:2048
	ds_read_b128 v[154:157], v154 offset:3072
	s_barrier
	s_waitcnt lgkmcnt(0)
	s_setprio 1
	v_mfma_f32_16x16x32_bf16 v[94:97], v[210:213], v[166:169], v[94:97]
	v_mfma_f32_16x16x32_bf16 v[90:93], v[218:221], v[166:169], v[90:93]
	v_mfma_f32_16x16x32_bf16 v[86:89], v[210:213], v[186:189], v[86:89]
	v_mfma_f32_16x16x32_bf16 v[82:85], v[218:221], v[186:189], v[82:85]
	v_mfma_f32_16x16x32_bf16 v[74:77], v[218:221], v[194:197], v[74:77]
	v_mfma_f32_16x16x32_bf16 v[70:73], v[210:213], v[202:205], v[70:73]
	v_mfma_f32_16x16x32_bf16 v[94:97], v[214:217], v[170:173], v[94:97]
	v_mfma_f32_16x16x32_bf16 v[90:93], v[154:157], v[170:173], v[90:93]
	v_mfma_f32_16x16x32_bf16 v[86:89], v[214:217], v[190:193], v[86:89]
	v_mfma_f32_16x16x32_bf16 v[82:85], v[154:157], v[190:193], v[82:85]
	v_mfma_f32_16x16x32_bf16 v[78:81], v[210:213], v[194:197], v[78:81]
	v_mfma_f32_16x16x32_bf16 v[74:77], v[154:157], v[198:201], v[74:77]
	v_mfma_f32_16x16x32_bf16 v[70:73], v[214:217], v[206:209], v[70:73]
	v_mfma_f32_16x16x32_bf16 v[66:69], v[218:221], v[202:205], v[66:69]
	v_mfma_f32_16x16x32_bf16 v[166:169], v[214:217], v[198:201], v[78:81]
	v_mfma_f32_16x16x32_bf16 v[170:173], v[154:157], v[206:209], v[66:69]
	s_setprio 0
	s_barrier
	s_nop 3
	ds_read_b128 v[66:69], v145 offset:16384
	ds_read_b128 v[78:81], v145 offset:17408
	ds_read_b128 v[186:189], v144 offset:16384
	ds_read_b128 v[190:193], v144 offset:17408
	ds_read_b128 v[194:197], v143 offset:16384
	ds_read_b128 v[198:201], v143 offset:17408
	ds_read_b128 v[202:205], v142 offset:16384
	ds_read_b128 v[206:209], v142 offset:17408
	s_waitcnt vmcnt(4)
	s_barrier
	s_waitcnt lgkmcnt(0)
	s_setprio 1
	v_mfma_f32_16x16x32_bf16 v[62:65], v[132:135], v[66:69], v[62:65]
	v_mfma_f32_16x16x32_bf16 v[54:57], v[132:135], v[186:189], v[54:57]
	v_mfma_f32_16x16x32_bf16 v[46:49], v[132:135], v[194:197], v[46:49]
	v_mfma_f32_16x16x32_bf16 v[38:41], v[132:135], v[202:205], v[38:41]
	v_mfma_f32_16x16x32_bf16 v[62:65], v[136:139], v[78:81], v[62:65]
	v_mfma_f32_16x16x32_bf16 v[58:61], v[150:153], v[66:69], v[58:61]
	v_mfma_f32_16x16x32_bf16 v[54:57], v[136:139], v[190:193], v[54:57]
	v_mfma_f32_16x16x32_bf16 v[50:53], v[150:153], v[186:189], v[50:53]
	v_mfma_f32_16x16x32_bf16 v[46:49], v[136:139], v[198:201], v[46:49]
	v_mfma_f32_16x16x32_bf16 v[42:45], v[150:153], v[194:197], v[42:45]
	v_mfma_f32_16x16x32_bf16 v[38:41], v[136:139], v[206:209], v[38:41]
	v_mfma_f32_16x16x32_bf16 v[34:37], v[150:153], v[202:205], v[34:37]
	v_mfma_f32_16x16x32_bf16 v[222:225], v[158:161], v[78:81], v[58:61]
	v_mfma_f32_16x16x32_bf16 v[226:229], v[158:161], v[190:193], v[50:53]
	v_mfma_f32_16x16x32_bf16 v[230:233], v[158:161], v[198:201], v[42:45]
	v_mfma_f32_16x16x32_bf16 v[130:133], v[158:161], v[206:209], v[34:37]
	s_setprio 0
	s_setprio 1
	v_mfma_f32_16x16x32_bf16 v[30:33], v[210:213], v[66:69], v[30:33]
	v_mfma_f32_16x16x32_bf16 v[26:29], v[218:221], v[66:69], v[26:29]
	v_mfma_f32_16x16x32_bf16 v[22:25], v[210:213], v[186:189], v[22:25]
	v_mfma_f32_16x16x32_bf16 v[18:21], v[218:221], v[186:189], v[18:21]
	v_mfma_f32_16x16x32_bf16 v[14:17], v[210:213], v[194:197], v[14:17]
	v_mfma_f32_16x16x32_bf16 v[10:13], v[218:221], v[194:197], v[10:13]
	v_mfma_f32_16x16x32_bf16 v[6:9], v[210:213], v[202:205], v[6:9]
	v_mfma_f32_16x16x32_bf16 v[2:5], v[218:221], v[202:205], v[2:5]
	v_mfma_f32_16x16x32_bf16 v[134:137], v[214:217], v[78:81], v[30:33]
	v_mfma_f32_16x16x32_bf16 v[150:153], v[154:157], v[78:81], v[26:29]
	v_mfma_f32_16x16x32_bf16 v[158:161], v[214:217], v[190:193], v[22:25]
	v_mfma_f32_16x16x32_bf16 v[186:189], v[154:157], v[190:193], v[18:21]
	v_mfma_f32_16x16x32_bf16 v[190:193], v[214:217], v[198:201], v[14:17]
	v_mfma_f32_16x16x32_bf16 v[194:197], v[154:157], v[198:201], v[10:13]
	v_mfma_f32_16x16x32_bf16 v[198:201], v[214:217], v[206:209], v[6:9]
	v_mfma_f32_16x16x32_bf16 v[154:157], v[154:157], v[206:209], v[2:5]
	s_setprio 0
	s_barrier
	ds_read_b128 v[34:37], v149
	ds_read_b128 v[202:205], v149 offset:1024
	ds_read_b128 v[206:209], v149 offset:2048
	ds_read_b128 v[210:213], v149 offset:3072
	ds_read_b128 v[42:45], v145 offset:32768
	ds_read_b128 v[50:53], v145 offset:33792
	ds_read_b128 v[58:61], v144 offset:32768
	ds_read_b128 v[66:69], v144 offset:33792
	ds_read_b128 v[214:217], v143 offset:32768
	ds_read_b128 v[218:221], v143 offset:33792
	ds_read_b128 v[234:237], v142 offset:32768
	ds_read_b128 v[238:241], v142 offset:33792
	s_waitcnt vmcnt(2)
	s_barrier
; #define LDA(dst,b,h) for(int m=0;m<4;++m)for(int k=0;k<2;++k) \
;     dst[m][k]=*reinterpret_cast<const bf16x8*>((char*)SA(b,h)+lds_byte(wr*64+m*16+fr,k*32+fq*8))
; #define LDB(dst,b,h) for(int n=0;n<2;++n)for(int k=0;k<2;++k) \
;     dst[n][k]=*reinterpret_cast<const bf16x8*>((char*)SB(b,h)+lds_byte(wc*32+n*16+fr,k*32+fq*8))
; #define MMA(ai,bj,At,Bt_) do{__builtin_amdgcn_s_setprio(1); \
;     for(int m=0;m<4;++m)for(int n=0;n<2;++n)for(int k=0;k<2;++k) \
;       acc[ai][bj][m][n]=__builtin_amdgcn_mfma_f32_16x16x32_bf16(Bt_[n][k],At[m][k],acc[ai][bj][m][n],0,0,0); \
;     __builtin_amdgcn_s_setprio(0);}while(0)
; #define WAIT_V(n) asm volatile("s_waitcnt vmcnt(" #n ")":::"memory")
; #define WAIT_L(n) asm volatile("s_waitcnt lgkmcnt(" #n ")":::"memory")
; #define BAR __builtin_amdgcn_s_barrier()
; template <int EPI>
; __device__ __forceinline__ void gemm_run(const GD& c, const bool has_next, const GD& nx, const Ctx& e, bf16* shm, float* rs, float* rs_nxt, float* racc_) {
;     ...
;   { LDB(B0,1,0); LDA(At,1,0); WAIT_V(2); BAR; WAIT_L(0); MMA(0,0,At,B0); BAR;
;     LDB(B1,1,1); WAIT_V(0); BAR; WAIT_L(0); MMA(0,1,At,B1); BAR;
;     LDA(At,1,1); BAR; WAIT_L(0); MMA(1,0,At,B0); MMA(1,1,At,B1); BAR; }
;   if(wr==0)BAR;
	s_waitcnt lgkmcnt(0)
	s_setprio 1
	v_mfma_f32_16x16x32_bf16 v[2:5], v[34:37], v[42:45], v[126:129]
	v_mfma_f32_16x16x32_bf16 v[26:29], v[202:205], v[50:53], v[2:5]
	v_mfma_f32_16x16x32_bf16 v[2:5], v[206:209], v[42:45], v[122:125]
	v_mfma_f32_16x16x32_bf16 v[30:33], v[210:213], v[50:53], v[2:5]
	v_mfma_f32_16x16x32_bf16 v[2:5], v[34:37], v[58:61], v[118:121]
	v_mfma_f32_16x16x32_bf16 v[18:21], v[202:205], v[66:69], v[2:5]
	v_mfma_f32_16x16x32_bf16 v[2:5], v[206:209], v[58:61], v[114:117]
	v_mfma_f32_16x16x32_bf16 v[22:25], v[210:213], v[66:69], v[2:5]
	v_mfma_f32_16x16x32_bf16 v[2:5], v[34:37], v[214:217], v[110:113]
	v_mfma_f32_16x16x32_bf16 v[10:13], v[202:205], v[218:221], v[2:5]
	v_mfma_f32_16x16x32_bf16 v[2:5], v[206:209], v[214:217], v[106:109]
	v_mfma_f32_16x16x32_bf16 v[14:17], v[210:213], v[218:221], v[2:5]
	v_mfma_f32_16x16x32_bf16 v[2:5], v[34:37], v[234:237], v[102:105]
	v_mfma_f32_16x16x32_bf16 v[6:9], v[206:209], v[234:237], v[98:101]
	v_mfma_f32_16x16x32_bf16 v[2:5], v[202:205], v[238:241], v[2:5]
	v_mfma_f32_16x16x32_bf16 v[6:9], v[210:213], v[238:241], v[6:9]
	s_setprio 0
	s_barrier
	ds_read_b128 v[242:245], v147
	ds_read_b128 v[246:249], v147 offset:1024
	ds_read_b128 v[250:253], v147 offset:2048
	ds_read_b128 v[146:149], v147 offset:3072
	s_waitcnt vmcnt(0)
	s_barrier
	s_waitcnt lgkmcnt(0)
	s_setprio 1
	v_mfma_f32_16x16x32_bf16 v[78:81], v[242:245], v[42:45], v[94:97]
	v_mfma_f32_16x16x32_bf16 v[42:45], v[250:253], v[42:45], v[90:93]
	v_mfma_f32_16x16x32_bf16 v[102:105], v[146:149], v[50:53], v[42:45]
	v_mfma_f32_16x16x32_bf16 v[42:45], v[242:245], v[58:61], v[86:89]
	v_mfma_f32_16x16x32_bf16 v[98:101], v[246:249], v[50:53], v[78:81]
	v_mfma_f32_16x16x32_bf16 v[78:81], v[246:249], v[66:69], v[42:45]
	v_mfma_f32_16x16x32_bf16 v[42:45], v[250:253], v[58:61], v[82:85]
	v_mfma_f32_16x16x32_bf16 v[86:89], v[146:149], v[66:69], v[42:45]
	v_mfma_f32_16x16x32_bf16 v[42:45], v[242:245], v[214:217], v[166:169]
	v_mfma_f32_16x16x32_bf16 v[58:61], v[246:249], v[218:221], v[42:45]
	v_mfma_f32_16x16x32_bf16 v[42:45], v[250:253], v[214:217], v[74:77]
	v_mfma_f32_16x16x32_bf16 v[66:69], v[146:149], v[218:221], v[42:45]
	v_mfma_f32_16x16x32_bf16 v[42:45], v[242:245], v[234:237], v[70:73]
	v_mfma_f32_16x16x32_bf16 v[50:53], v[250:253], v[234:237], v[170:173]
	v_mfma_f32_16x16x32_bf16 v[42:45], v[246:249], v[238:241], v[42:45]
	v_mfma_f32_16x16x32_bf16 v[50:53], v[146:149], v[238:241], v[50:53]
	s_setprio 0
	s_barrier
	ds_read_b128 v[74:77], v145 offset:49152
	ds_read_b128 v[94:97], v145 offset:50176
	ds_read_b128 v[106:109], v144 offset:49152
	ds_read_b128 v[110:113], v144 offset:50176
	ds_read_b128 v[166:169], v143 offset:49152
	ds_read_b128 v[170:173], v143 offset:50176
	ds_read_b128 v[214:217], v142 offset:49152
	ds_read_b128 v[142:145], v142 offset:50176
	s_barrier
	s_waitcnt lgkmcnt(0)
	s_setprio 1
	v_mfma_f32_16x16x32_bf16 v[62:65], v[34:37], v[74:77], v[62:65]
	v_mfma_f32_16x16x32_bf16 v[82:85], v[202:205], v[94:97], v[62:65]
	v_mfma_f32_16x16x32_bf16 v[62:65], v[206:209], v[74:77], v[222:225]
	v_mfma_f32_16x16x32_bf16 v[54:57], v[34:37], v[106:109], v[54:57]
	v_mfma_f32_16x16x32_bf16 v[90:93], v[210:213], v[94:97], v[62:65]
	v_mfma_f32_16x16x32_bf16 v[62:65], v[202:205], v[110:113], v[54:57]
	v_mfma_f32_16x16x32_bf16 v[54:57], v[206:209], v[106:109], v[226:229]
	v_mfma_f32_16x16x32_bf16 v[70:73], v[210:213], v[110:113], v[54:57]
	v_mfma_f32_16x16x32_bf16 v[46:49], v[34:37], v[166:169], v[46:49]
	v_mfma_f32_16x16x32_bf16 v[54:57], v[206:209], v[166:169], v[230:233]
	v_mfma_f32_16x16x32_bf16 v[34:37], v[34:37], v[214:217], v[38:41]
	v_mfma_f32_16x16x32_bf16 v[38:41], v[206:209], v[214:217], v[130:133]
	v_mfma_f32_16x16x32_bf16 v[46:49], v[202:205], v[170:173], v[46:49]
	v_mfma_f32_16x16x32_bf16 v[54:57], v[210:213], v[170:173], v[54:57]
	v_mfma_f32_16x16x32_bf16 v[34:37], v[202:205], v[142:145], v[34:37]
	v_mfma_f32_16x16x32_bf16 v[38:41], v[210:213], v[142:145], v[38:41]
	s_setprio 0
	s_setprio 1
	v_mfma_f32_16x16x32_bf16 v[114:117], v[242:245], v[74:77], v[134:137]
	v_mfma_f32_16x16x32_bf16 v[74:77], v[250:253], v[74:77], v[150:153]
	v_mfma_f32_16x16x32_bf16 v[126:129], v[146:149], v[94:97], v[74:77]
	v_mfma_f32_16x16x32_bf16 v[74:77], v[242:245], v[106:109], v[158:161]
	v_mfma_f32_16x16x32_bf16 v[122:125], v[246:249], v[94:97], v[114:117]
	v_mfma_f32_16x16x32_bf16 v[114:117], v[246:249], v[110:113], v[74:77]
	v_mfma_f32_16x16x32_bf16 v[74:77], v[250:253], v[106:109], v[186:189]
	v_mfma_f32_16x16x32_bf16 v[118:121], v[146:149], v[110:113], v[74:77]
	v_mfma_f32_16x16x32_bf16 v[74:77], v[242:245], v[166:169], v[190:193]
	v_mfma_f32_16x16x32_bf16 v[106:109], v[246:249], v[170:173], v[74:77]
	v_mfma_f32_16x16x32_bf16 v[74:77], v[250:253], v[166:169], v[194:197]
	v_mfma_f32_16x16x32_bf16 v[110:113], v[146:149], v[170:173], v[74:77]
	v_mfma_f32_16x16x32_bf16 v[74:77], v[242:245], v[214:217], v[198:201]
	v_mfma_f32_16x16x32_bf16 v[94:97], v[246:249], v[142:145], v[74:77]
	v_mfma_f32_16x16x32_bf16 v[74:77], v[250:253], v[214:217], v[154:157]
	v_mfma_f32_16x16x32_bf16 v[74:77], v[146:149], v[142:145], v[74:77]
	s_setprio 0
	v_cmp_gt_u32_e32 vcc, s96, v141
	s_barrier
	s_and_saveexec_b64 s[2:3], vcc
	s_cbranch_execz .LBB0_1501
	s_barrier
	s_branch .LBB0_1501
